# v054 + no epilogue-alignment barrier for the leading half (trailing half skips the unit's last post-MFMA barrier; last-iteration handling out of line so the per-iteration path has no taken branch)
# baseline (speedup 1.0000x reference)
; #define PG8_STAGE(bufoff, gbase, voff) do { _Pragma("unroll") for (int _i = 0; _i < 2; ++_i) \
;         __builtin_amdgcn_global_load_lds((const unsigned*)((const char*)(gbase) + (voff)[_i]), (PG8_LAS unsigned*)(lds + (bufoff) + ldsw + _i * 8192), 16, 0, AUX_A); } while (0)
; #define PG8_STAGEB(bufoff, gbase, voff) do { _Pragma("unroll") for (int _i = 0; _i < 2; ++_i) \
;         __builtin_amdgcn_global_load_lds((const unsigned*)((const char*)(gbase) + (voff)[_i]), (PG8_LAS unsigned*)(lds + (bufoff) + ldsw + _i * 8192), 16, 0, AUX_B); } while (0)
; #define PG8_WAIT_V(n) asm volatile("s_waitcnt vmcnt(" #n ")" ::: "memory")
; #define PG8_WAIT_L(n) asm volatile("s_waitcnt lgkmcnt(" #n ")" ::: "memory")
; template <class Epi, class Sched, bool ALIGN_EPI = false, bool SP2 = false>
; __device__ __forceinline__ void gemm_phase(PG8_LAS unsigned char* lds, const Gemm g, const Sched& S, const Epi& E) {
;     ...
;         for (int t = 0; t < nt; t += 2) {
;             const bool last = (t == nt - 2);
;             const char* a1 = PG8_KP(cA, t + 1, rot, nt);
;             const char* a2 = last ? nAr : PG8_KP(cA, t + 2, rot, nt); const char* b2 = last ? nBr : PG8_KP(cB, t + 2, rot, nt);
;             const char* a3 = a2 + kstep; const char* b3 = b2 + kstep;
;             if (last && has_next) S.a_ready(nxt);
;             if constexpr (SP2) {
;             PG8_LDB(B0, 0, 0); PG8_LDB(B1, 0, 1); PG8_SCHED; PG8_LDA(At, 0, 0); PG8_STAGE(PG8_SA(1, 1), a1 + hstep, voffA);
;             PG8_WAIT_V(8); PG8_WAIT_L(0); PG8_BAR; PG8_MMA(0, 0, At, B0); PG8_MMA(0, 1, At, B1); PG8_BAR; PG8_SCHED;
;             PG8_LDA(At, 0, 1); PG8_STAGEB(PG8_SB(0, 0), b2, voffB); PG8_STAGEB(PG8_SB(0, 1), b2 + hstep, voffB); PG8_STAGE(PG8_SA(0, 0), a2, voffA);
;             PG8_WAIT_V(8); PG8_WAIT_L(0); PG8_BAR; PG8_MMA(1, 0, At, B0); PG8_MMA(1, 1, At, B1); PG8_BAR; PG8_SCHED;
;             PG8_LDB(B0, 1, 0); PG8_LDB(B1, 1, 1); PG8_SCHED; PG8_LDA(At, 1, 0); PG8_STAGE(PG8_SA(0, 1), a2 + hstep, voffA);
;             PG8_WAIT_V(8); PG8_WAIT_L(0); PG8_BAR; PG8_MMA(0, 0, At, B0); PG8_MMA(0, 1, At, B1); PG8_BAR; PG8_SCHED;
;             PG8_LDA(At, 1, 1); PG8_STAGEB(PG8_SB(1, 0), b3, voffB); PG8_STAGEB(PG8_SB(1, 1), b3 + hstep, voffB); PG8_STAGE(PG8_SA(1, 0), a3, voffA);
;             PG8_WAIT_V(8); PG8_WAIT_L(0); PG8_BAR; PG8_MMA(1, 0, At, B0); PG8_MMA(1, 1, At, B1); PG8_BAR; PG8_SCHED;
.Lpk_270:
	s_add_i32 s81, s29, 2
	s_cmp_lt_u32 s29, 30
	s_cselect_b32 s0, 0, 0xffffffe0
	s_add_i32 s0, s81, s0
	s_ashr_i32 s1, s0, 31
	s_lshl_b64 s[0:1], s[0:1], 7
	s_add_u32 s42, s40, s0
	s_addc_u32 s43, s41, s1
	s_add_u32 s0, s38, s0
	s_addc_u32 s1, s39, s1
	s_cmp_eq_u32 s29, 30
	s_cselect_b32 s59, s49, s43
	s_cselect_b32 s58, s51, s42
	s_cselect_b32 s61, vcc_lo, s1
	s_cselect_b32 s60, vcc_hi, s0
	s_add_i32 s43, 0, 0x10000
	s_add_i32 s97, s43, s70
	s_add_i32 s46, 0, 0x14000
	s_add_i32 m0, s96, 0xc000
	s_add_i32 s69, s96, 0xe000
	s_add_i32 s84, s97, 0x2000
	s_add_u32 s62, s60, 0x80000
	s_addc_u32 s63, s61, 0
	s_add_i32 s4, s46, s70
	v_add_u32_e32 v148, s43, v221
	v_add_u32_e32 v164, s46, v221
	s_add_i32 s5, s4, 0x2000
	s_add_i32 s1, 0, 0x18000
	s_add_i32 s47, 0, 0x1c000
	ds_read_b128 v[136:139], v148
	ds_read_b128 v[140:143], v148 offset:1024
	ds_read_b128 v[144:147], v148 offset:2048
	ds_read_b128 v[148:151], v148 offset:3072
	ds_read_b128 v[152:155], v164
	ds_read_b128 v[156:159], v164 offset:1024
	ds_read_b128 v[160:163], v164 offset:2048
	ds_read_b128 v[164:167], v164 offset:3072
	s_add_u32 s56, s58, 0x80000
	s_addc_u32 s57, s59, 0
	s_add_i32 s0, s1, s70
	s_add_i32 s89, s0, 0x2000
	s_add_u32 s42, s60, 0x80080
	s_addc_u32 s43, s61, 0
	s_add_i32 s46, s47, s70
	s_add_i32 s92, s46, 0x2000
	s_cmp_gt_u32 s29, 29
	ds_read_b128 v[192:195], v222
	ds_read_b128 v[196:199], v222 offset:1024
	ds_read_b128 v[200:203], v222 offset:2048
	ds_read_b128 v[224:227], v222 offset:3072
	ds_read_b128 v[228:231], v222 offset:4096
	ds_read_b128 v[232:235], v222 offset:5120
	ds_read_b128 v[236:239], v222 offset:6144
	ds_read_b128 v[240:243], v222 offset:7168
	global_load_lds_dwordx4 v[134:135], off
	s_mov_b32 m0, s69
	s_nop 0
	global_load_lds_dwordx4 v[132:133], off
	s_waitcnt vmcnt(8)
	s_waitcnt lgkmcnt(0)
	s_setprio 1
	s_barrier
	v_mfma_f32_16x16x32_bf16 v[128:131], v[136:139], v[192:195], 0
	v_mfma_f32_16x16x32_bf16 v[128:131], v[140:143], v[196:199], v[128:131]
	v_mfma_f32_16x16x32_bf16 v[124:127], v[144:147], v[192:195], 0
	v_mfma_f32_16x16x32_bf16 v[124:127], v[148:151], v[196:199], v[124:127]
	v_mfma_f32_16x16x32_bf16 v[112:115], v[136:139], v[200:203], 0
	v_mfma_f32_16x16x32_bf16 v[112:115], v[140:143], v[224:227], v[112:115]
	v_mfma_f32_16x16x32_bf16 v[108:111], v[144:147], v[200:203], 0
	v_mfma_f32_16x16x32_bf16 v[108:111], v[148:151], v[224:227], v[108:111]
	v_mfma_f32_16x16x32_bf16 v[94:97], v[136:139], v[228:231], 0
	v_mfma_f32_16x16x32_bf16 v[94:97], v[140:143], v[232:235], v[94:97]
	v_mfma_f32_16x16x32_bf16 v[90:93], v[144:147], v[228:231], 0
	v_mfma_f32_16x16x32_bf16 v[90:93], v[148:151], v[232:235], v[90:93]
	v_mfma_f32_16x16x32_bf16 v[78:81], v[136:139], v[236:239], 0
	v_mfma_f32_16x16x32_bf16 v[78:81], v[140:143], v[240:243], v[78:81]
	v_mfma_f32_16x16x32_bf16 v[74:77], v[144:147], v[236:239], 0
	v_mfma_f32_16x16x32_bf16 v[74:77], v[148:151], v[240:243], v[74:77]
	s_setprio 0
	s_setprio 1
	v_mfma_f32_16x16x32_bf16 v[120:123], v[152:155], v[192:195], 0
	v_mfma_f32_16x16x32_bf16 v[120:123], v[156:159], v[196:199], v[120:123]
	v_mfma_f32_16x16x32_bf16 v[116:119], v[160:163], v[192:195], 0
	v_mfma_f32_16x16x32_bf16 v[116:119], v[164:167], v[196:199], v[116:119]
	v_mfma_f32_16x16x32_bf16 v[104:107], v[152:155], v[200:203], 0
	v_mfma_f32_16x16x32_bf16 v[104:107], v[156:159], v[224:227], v[104:107]
	v_mfma_f32_16x16x32_bf16 v[100:103], v[160:163], v[200:203], 0
	v_mfma_f32_16x16x32_bf16 v[100:103], v[164:167], v[224:227], v[100:103]
	v_mfma_f32_16x16x32_bf16 v[86:89], v[152:155], v[228:231], 0
	v_mfma_f32_16x16x32_bf16 v[86:89], v[156:159], v[232:235], v[86:89]
	v_mfma_f32_16x16x32_bf16 v[82:85], v[160:163], v[228:231], 0
	v_mfma_f32_16x16x32_bf16 v[82:85], v[164:167], v[232:235], v[82:85]
	v_mfma_f32_16x16x32_bf16 v[70:73], v[152:155], v[236:239], 0
	v_mfma_f32_16x16x32_bf16 v[70:73], v[156:159], v[240:243], v[70:73]
	s_setprio 2
	s_barrier
	v_mfma_f32_16x16x32_bf16 v[66:69], v[160:163], v[236:239], 0
	v_mfma_f32_16x16x32_bf16 v[66:69], v[164:167], v[240:243], v[66:69]
	s_setprio 0
	s_mov_b32 m0, s97
	v_lshl_add_u64 v[244:245], s[60:61], 0, v[184:185]
	ds_read_b128 v[192:195], v222 offset:16384
	ds_read_b128 v[196:199], v222 offset:17408
	ds_read_b128 v[200:203], v222 offset:18432
	ds_read_b128 v[224:227], v222 offset:19456
	ds_read_b128 v[228:231], v222 offset:20480
	ds_read_b128 v[232:235], v222 offset:21504
	ds_read_b128 v[236:239], v222 offset:22528
	ds_read_b128 v[240:243], v222 offset:23552
	global_load_lds_dwordx4 v[244:245], off
	v_lshl_add_u64 v[246:247], s[60:61], 0, v[180:181]
	s_mov_b32 m0, s84
	v_lshl_add_u64 v[212:213], s[62:63], 0, v[184:185]
	global_load_lds_dwordx4 v[246:247], off
	s_mov_b32 m0, s4
	v_lshl_add_u64 v[172:173], s[58:59], 0, v[182:183]
	global_load_lds_dwordx4 v[212:213], off
	v_lshl_add_u64 v[212:213], s[62:63], 0, v[180:181]
	s_mov_b32 m0, s5
	s_nop 0
	global_load_lds_dwordx4 v[212:213], off
	v_lshl_add_u64 v[212:213], s[58:59], 0, v[186:187]
	s_mov_b32 m0, s96
	s_nop 0
	global_load_lds_dwordx4 v[212:213], off
	s_mov_b32 m0, s71
	s_nop 0
	global_load_lds_dwordx4 v[172:173], off
	s_waitcnt vmcnt(8)
	s_waitcnt lgkmcnt(0)
	s_setprio 1
	s_barrier
; #define PG8_STAGE(bufoff, gbase, voff) do { _Pragma("unroll") for (int _i = 0; _i < 2; ++_i) \
;         __builtin_amdgcn_global_load_lds((const unsigned*)((const char*)(gbase) + (voff)[_i]), (PG8_LAS unsigned*)(lds + (bufoff) + ldsw + _i * 8192), 16, 0, AUX_A); } while (0)
; #define PG8_STAGEB(bufoff, gbase, voff) do { _Pragma("unroll") for (int _i = 0; _i < 2; ++_i) \
;         __builtin_amdgcn_global_load_lds((const unsigned*)((const char*)(gbase) + (voff)[_i]), (PG8_LAS unsigned*)(lds + (bufoff) + ldsw + _i * 8192), 16, 0, AUX_B); } while (0)
; #define PG8_WAIT_V(n) asm volatile("s_waitcnt vmcnt(" #n ")" ::: "memory")
; #define PG8_WAIT_L(n) asm volatile("s_waitcnt lgkmcnt(" #n ")" ::: "memory")
; template <class Epi, class Sched, bool ALIGN_EPI = false, bool SP2 = false>
; __device__ __forceinline__ void gemm_phase(PG8_LAS unsigned char* lds, const Gemm g, const Sched& S, const Epi& E) {
;     ...
;         for (int t = 0; t < nt; t += 2) {
;             const bool last = (t == nt - 2);
;             const char* a1 = PG8_KP(cA, t + 1, rot, nt);
;             const char* a2 = last ? nAr : PG8_KP(cA, t + 2, rot, nt); const char* b2 = last ? nBr : PG8_KP(cB, t + 2, rot, nt);
;             const char* a3 = a2 + kstep; const char* b3 = b2 + kstep;
;             if (last && has_next) S.a_ready(nxt);
;             if constexpr (SP2) {
;             PG8_LDB(B0, 0, 0); PG8_LDB(B1, 0, 1); PG8_SCHED; PG8_LDA(At, 0, 0); PG8_STAGE(PG8_SA(1, 1), a1 + hstep, voffA);
;             PG8_WAIT_V(8); PG8_WAIT_L(0); PG8_BAR; PG8_MMA(0, 0, At, B0); PG8_MMA(0, 1, At, B1); PG8_BAR; PG8_SCHED;
;             PG8_LDA(At, 0, 1); PG8_STAGEB(PG8_SB(0, 0), b2, voffB); PG8_STAGEB(PG8_SB(0, 1), b2 + hstep, voffB); PG8_STAGE(PG8_SA(0, 0), a2, voffA);
;             PG8_WAIT_V(8); PG8_WAIT_L(0); PG8_BAR; PG8_MMA(1, 0, At, B0); PG8_MMA(1, 1, At, B1); PG8_BAR; PG8_SCHED;
;             PG8_LDB(B0, 1, 0); PG8_LDB(B1, 1, 1); PG8_SCHED; PG8_LDA(At, 1, 0); PG8_STAGE(PG8_SA(0, 1), a2 + hstep, voffA);
;             PG8_WAIT_V(8); PG8_WAIT_L(0); PG8_BAR; PG8_MMA(0, 0, At, B0); PG8_MMA(0, 1, At, B1); PG8_BAR; PG8_SCHED;
;             PG8_LDA(At, 1, 1); PG8_STAGEB(PG8_SB(1, 0), b3, voffB); PG8_STAGEB(PG8_SB(1, 1), b3 + hstep, voffB); PG8_STAGE(PG8_SA(1, 0), a3, voffA);
;             PG8_WAIT_V(8); PG8_WAIT_L(0); PG8_BAR; PG8_MMA(1, 0, At, B0); PG8_MMA(1, 1, At, B1); PG8_BAR; PG8_SCHED;
	v_mfma_f32_16x16x32_bf16 v[62:65], v[136:139], v[192:195], 0
	v_mfma_f32_16x16x32_bf16 v[62:65], v[140:143], v[196:199], v[62:65]
	v_mfma_f32_16x16x32_bf16 v[58:61], v[144:147], v[192:195], 0
	v_mfma_f32_16x16x32_bf16 v[58:61], v[148:151], v[196:199], v[58:61]
	v_mfma_f32_16x16x32_bf16 v[46:49], v[136:139], v[200:203], 0
	v_mfma_f32_16x16x32_bf16 v[46:49], v[140:143], v[224:227], v[46:49]
	v_mfma_f32_16x16x32_bf16 v[42:45], v[144:147], v[200:203], 0
	v_mfma_f32_16x16x32_bf16 v[42:45], v[148:151], v[224:227], v[42:45]
	v_mfma_f32_16x16x32_bf16 v[30:33], v[136:139], v[228:231], 0
	v_mfma_f32_16x16x32_bf16 v[30:33], v[140:143], v[232:235], v[30:33]
	v_mfma_f32_16x16x32_bf16 v[26:29], v[144:147], v[228:231], 0
	v_mfma_f32_16x16x32_bf16 v[26:29], v[148:151], v[232:235], v[26:29]
	v_mfma_f32_16x16x32_bf16 v[14:17], v[136:139], v[236:239], 0
	v_mfma_f32_16x16x32_bf16 v[14:17], v[140:143], v[240:243], v[14:17]
	v_mfma_f32_16x16x32_bf16 v[10:13], v[144:147], v[236:239], 0
	v_mfma_f32_16x16x32_bf16 v[10:13], v[148:151], v[240:243], v[10:13]
	s_setprio 0
	s_setprio 1
	v_mfma_f32_16x16x32_bf16 v[54:57], v[152:155], v[192:195], 0
	v_mfma_f32_16x16x32_bf16 v[54:57], v[156:159], v[196:199], v[54:57]
	v_mfma_f32_16x16x32_bf16 v[50:53], v[160:163], v[192:195], 0
	v_mfma_f32_16x16x32_bf16 v[50:53], v[164:167], v[196:199], v[50:53]
	v_mfma_f32_16x16x32_bf16 v[38:41], v[152:155], v[200:203], 0
	v_mfma_f32_16x16x32_bf16 v[38:41], v[156:159], v[224:227], v[38:41]
	v_mfma_f32_16x16x32_bf16 v[34:37], v[160:163], v[200:203], 0
	v_mfma_f32_16x16x32_bf16 v[34:37], v[164:167], v[224:227], v[34:37]
	v_mfma_f32_16x16x32_bf16 v[22:25], v[152:155], v[228:231], 0
	v_mfma_f32_16x16x32_bf16 v[22:25], v[156:159], v[232:235], v[22:25]
	v_mfma_f32_16x16x32_bf16 v[18:21], v[160:163], v[228:231], 0
	v_mfma_f32_16x16x32_bf16 v[18:21], v[164:167], v[232:235], v[18:21]
	v_mfma_f32_16x16x32_bf16 v[6:9], v[152:155], v[236:239], 0
	v_mfma_f32_16x16x32_bf16 v[6:9], v[156:159], v[240:243], v[6:9]
	s_setprio 2
	s_barrier
	v_mfma_f32_16x16x32_bf16 v[2:5], v[160:163], v[236:239], 0
	v_mfma_f32_16x16x32_bf16 v[2:5], v[164:167], v[240:243], v[2:5]
	s_setprio 0
	v_add_u32_e32 v148, s1, v221
	v_add_u32_e32 v164, s47, v221
	ds_read_b128 v[136:139], v148
	ds_read_b128 v[140:143], v148 offset:1024
	ds_read_b128 v[144:147], v148 offset:2048
	ds_read_b128 v[148:151], v148 offset:3072
	ds_read_b128 v[152:155], v164
	ds_read_b128 v[156:159], v164 offset:1024
	ds_read_b128 v[160:163], v164 offset:2048
	ds_read_b128 v[164:167], v164 offset:3072
	s_mov_b32 m0, s33
	v_lshl_add_u64 v[168:169], s[56:57], 0, v[186:187]
	ds_read_b128 v[192:195], v222 offset:32768
	ds_read_b128 v[196:199], v222 offset:33792
	ds_read_b128 v[200:203], v222 offset:34816
	ds_read_b128 v[224:227], v222 offset:35840
	ds_read_b128 v[228:231], v222 offset:36864
	ds_read_b128 v[232:235], v222 offset:37888
	ds_read_b128 v[236:239], v222 offset:38912
	ds_read_b128 v[240:243], v222 offset:39936
	global_load_lds_dwordx4 v[168:169], off
	v_lshl_add_u64 v[168:169], s[56:57], 0, v[182:183]
	s_mov_b32 m0, s30
	s_nop 0
	global_load_lds_dwordx4 v[168:169], off
	s_waitcnt vmcnt(8)
	s_waitcnt lgkmcnt(0)
	s_setprio 1
	s_barrier
	v_mfma_f32_16x16x32_bf16 v[128:131], v[136:139], v[192:195], v[128:131]
	v_mfma_f32_16x16x32_bf16 v[128:131], v[140:143], v[196:199], v[128:131]
	v_mfma_f32_16x16x32_bf16 v[124:127], v[144:147], v[192:195], v[124:127]
	v_mfma_f32_16x16x32_bf16 v[124:127], v[148:151], v[196:199], v[124:127]
	v_mfma_f32_16x16x32_bf16 v[112:115], v[136:139], v[200:203], v[112:115]
	v_mfma_f32_16x16x32_bf16 v[112:115], v[140:143], v[224:227], v[112:115]
	v_mfma_f32_16x16x32_bf16 v[108:111], v[144:147], v[200:203], v[108:111]
	v_mfma_f32_16x16x32_bf16 v[108:111], v[148:151], v[224:227], v[108:111]
	v_mfma_f32_16x16x32_bf16 v[94:97], v[136:139], v[228:231], v[94:97]
	v_mfma_f32_16x16x32_bf16 v[94:97], v[140:143], v[232:235], v[94:97]
	v_mfma_f32_16x16x32_bf16 v[90:93], v[144:147], v[228:231], v[90:93]
	v_mfma_f32_16x16x32_bf16 v[90:93], v[148:151], v[232:235], v[90:93]
	v_mfma_f32_16x16x32_bf16 v[78:81], v[136:139], v[236:239], v[78:81]
	v_mfma_f32_16x16x32_bf16 v[78:81], v[140:143], v[240:243], v[78:81]
	v_mfma_f32_16x16x32_bf16 v[74:77], v[144:147], v[236:239], v[74:77]
	v_mfma_f32_16x16x32_bf16 v[74:77], v[148:151], v[240:243], v[74:77]
	s_setprio 0
	s_setprio 1
	v_mfma_f32_16x16x32_bf16 v[120:123], v[152:155], v[192:195], v[120:123]
	v_mfma_f32_16x16x32_bf16 v[120:123], v[156:159], v[196:199], v[120:123]
	v_mfma_f32_16x16x32_bf16 v[116:119], v[160:163], v[192:195], v[116:119]
	v_mfma_f32_16x16x32_bf16 v[116:119], v[164:167], v[196:199], v[116:119]
	v_mfma_f32_16x16x32_bf16 v[104:107], v[152:155], v[200:203], v[104:107]
	v_mfma_f32_16x16x32_bf16 v[104:107], v[156:159], v[224:227], v[104:107]
	v_mfma_f32_16x16x32_bf16 v[100:103], v[160:163], v[200:203], v[100:103]
	v_mfma_f32_16x16x32_bf16 v[100:103], v[164:167], v[224:227], v[100:103]
	v_mfma_f32_16x16x32_bf16 v[86:89], v[152:155], v[228:231], v[86:89]
	v_mfma_f32_16x16x32_bf16 v[86:89], v[156:159], v[232:235], v[86:89]
	v_mfma_f32_16x16x32_bf16 v[82:85], v[160:163], v[228:231], v[82:85]
	v_mfma_f32_16x16x32_bf16 v[82:85], v[164:167], v[232:235], v[82:85]
	v_mfma_f32_16x16x32_bf16 v[70:73], v[152:155], v[236:239], v[70:73]
	v_mfma_f32_16x16x32_bf16 v[70:73], v[156:159], v[240:243], v[70:73]
	s_setprio 2
	s_barrier
; #define PG8_STAGE(bufoff, gbase, voff) do { _Pragma("unroll") for (int _i = 0; _i < 2; ++_i) \
;         __builtin_amdgcn_global_load_lds((const unsigned*)((const char*)(gbase) + (voff)[_i]), (PG8_LAS unsigned*)(lds + (bufoff) + ldsw + _i * 8192), 16, 0, AUX_A); } while (0)
; #define PG8_STAGEB(bufoff, gbase, voff) do { _Pragma("unroll") for (int _i = 0; _i < 2; ++_i) \
;         __builtin_amdgcn_global_load_lds((const unsigned*)((const char*)(gbase) + (voff)[_i]), (PG8_LAS unsigned*)(lds + (bufoff) + ldsw + _i * 8192), 16, 0, AUX_B); } while (0)
; #define PG8_WAIT_V(n) asm volatile("s_waitcnt vmcnt(" #n ")" ::: "memory")
; #define PG8_WAIT_L(n) asm volatile("s_waitcnt lgkmcnt(" #n ")" ::: "memory")
; template <class Epi, class Sched, bool ALIGN_EPI = false, bool SP2 = false>
; __device__ __forceinline__ void gemm_phase(PG8_LAS unsigned char* lds, const Gemm g, const Sched& S, const Epi& E) {
;     ...
;         for (int t = 0; t < nt; t += 2) {
;             const bool last = (t == nt - 2);
;             const char* a1 = PG8_KP(cA, t + 1, rot, nt);
;             const char* a2 = last ? nAr : PG8_KP(cA, t + 2, rot, nt); const char* b2 = last ? nBr : PG8_KP(cB, t + 2, rot, nt);
;             const char* a3 = a2 + kstep; const char* b3 = b2 + kstep;
;             if (last && has_next) S.a_ready(nxt);
;             if constexpr (SP2) {
;             PG8_LDB(B0, 0, 0); PG8_LDB(B1, 0, 1); PG8_SCHED; PG8_LDA(At, 0, 0); PG8_STAGE(PG8_SA(1, 1), a1 + hstep, voffA);
;             PG8_WAIT_V(8); PG8_WAIT_L(0); PG8_BAR; PG8_MMA(0, 0, At, B0); PG8_MMA(0, 1, At, B1); PG8_BAR; PG8_SCHED;
;             PG8_LDA(At, 0, 1); PG8_STAGEB(PG8_SB(0, 0), b2, voffB); PG8_STAGEB(PG8_SB(0, 1), b2 + hstep, voffB); PG8_STAGE(PG8_SA(0, 0), a2, voffA);
;             PG8_WAIT_V(8); PG8_WAIT_L(0); PG8_BAR; PG8_MMA(1, 0, At, B0); PG8_MMA(1, 1, At, B1); PG8_BAR; PG8_SCHED;
;             PG8_LDB(B0, 1, 0); PG8_LDB(B1, 1, 1); PG8_SCHED; PG8_LDA(At, 1, 0); PG8_STAGE(PG8_SA(0, 1), a2 + hstep, voffA);
;             PG8_WAIT_V(8); PG8_WAIT_L(0); PG8_BAR; PG8_MMA(0, 0, At, B0); PG8_MMA(0, 1, At, B1); PG8_BAR; PG8_SCHED;
;             PG8_LDA(At, 1, 1); PG8_STAGEB(PG8_SB(1, 0), b3, voffB); PG8_STAGEB(PG8_SB(1, 1), b3 + hstep, voffB); PG8_STAGE(PG8_SA(1, 0), a3, voffA);
;             PG8_WAIT_V(8); PG8_WAIT_L(0); PG8_BAR; PG8_MMA(1, 0, At, B0); PG8_MMA(1, 1, At, B1); PG8_BAR; PG8_SCHED;
	v_mfma_f32_16x16x32_bf16 v[66:69], v[160:163], v[236:239], v[66:69]
	v_mfma_f32_16x16x32_bf16 v[66:69], v[164:167], v[240:243], v[66:69]
	s_setprio 0
	s_mov_b32 m0, s0
	v_lshl_add_u64 v[168:169], v[244:245], 0, s[76:77]
	ds_read_b128 v[192:195], v222 offset:49152
	ds_read_b128 v[196:199], v222 offset:50176
	ds_read_b128 v[200:203], v222 offset:51200
	ds_read_b128 v[224:227], v222 offset:52224
	ds_read_b128 v[228:231], v222 offset:53248
	ds_read_b128 v[232:235], v222 offset:54272
	ds_read_b128 v[236:239], v222 offset:55296
	ds_read_b128 v[240:243], v222 offset:56320
	global_load_lds_dwordx4 v[168:169], off
	v_lshl_add_u64 v[168:169], v[246:247], 0, s[76:77]
	s_mov_b32 m0, s89
	s_nop 0
	global_load_lds_dwordx4 v[168:169], off
	v_lshl_add_u64 v[168:169], s[42:43], 0, v[184:185]
	s_mov_b32 m0, s46
	s_nop 0
	global_load_lds_dwordx4 v[168:169], off
	v_lshl_add_u64 v[168:169], s[42:43], 0, v[180:181]
	s_mov_b32 m0, s92
	s_nop 0
	global_load_lds_dwordx4 v[168:169], off
	v_lshl_add_u64 v[168:169], v[212:213], 0, s[76:77]
	s_mov_b32 m0, s90
	s_nop 0
	global_load_lds_dwordx4 v[168:169], off
	v_lshl_add_u64 v[168:169], v[172:173], 0, s[76:77]
	s_mov_b32 m0, s91
	s_nop 0
	global_load_lds_dwordx4 v[168:169], off
	s_waitcnt vmcnt(8)
	s_waitcnt lgkmcnt(0)
	s_setprio 1
	s_barrier
	v_mfma_f32_16x16x32_bf16 v[62:65], v[136:139], v[192:195], v[62:65]
	v_mfma_f32_16x16x32_bf16 v[62:65], v[140:143], v[196:199], v[62:65]
	v_mfma_f32_16x16x32_bf16 v[58:61], v[144:147], v[192:195], v[58:61]
	v_mfma_f32_16x16x32_bf16 v[58:61], v[148:151], v[196:199], v[58:61]
	v_mfma_f32_16x16x32_bf16 v[46:49], v[136:139], v[200:203], v[46:49]
	v_mfma_f32_16x16x32_bf16 v[46:49], v[140:143], v[224:227], v[46:49]
	v_mfma_f32_16x16x32_bf16 v[42:45], v[144:147], v[200:203], v[42:45]
	v_mfma_f32_16x16x32_bf16 v[42:45], v[148:151], v[224:227], v[42:45]
	v_mfma_f32_16x16x32_bf16 v[30:33], v[136:139], v[228:231], v[30:33]
	v_mfma_f32_16x16x32_bf16 v[30:33], v[140:143], v[232:235], v[30:33]
	v_mfma_f32_16x16x32_bf16 v[26:29], v[144:147], v[228:231], v[26:29]
	v_mfma_f32_16x16x32_bf16 v[26:29], v[148:151], v[232:235], v[26:29]
	v_mfma_f32_16x16x32_bf16 v[14:17], v[136:139], v[236:239], v[14:17]
	v_mfma_f32_16x16x32_bf16 v[14:17], v[140:143], v[240:243], v[14:17]
	v_mfma_f32_16x16x32_bf16 v[10:13], v[144:147], v[236:239], v[10:13]
	v_mfma_f32_16x16x32_bf16 v[10:13], v[148:151], v[240:243], v[10:13]
	s_setprio 0
	s_setprio 1
	v_mfma_f32_16x16x32_bf16 v[54:57], v[152:155], v[192:195], v[54:57]
	v_mfma_f32_16x16x32_bf16 v[54:57], v[156:159], v[196:199], v[54:57]
	v_mfma_f32_16x16x32_bf16 v[50:53], v[160:163], v[192:195], v[50:53]
	v_mfma_f32_16x16x32_bf16 v[50:53], v[164:167], v[196:199], v[50:53]
	v_mfma_f32_16x16x32_bf16 v[38:41], v[152:155], v[200:203], v[38:41]
	v_mfma_f32_16x16x32_bf16 v[38:41], v[156:159], v[224:227], v[38:41]
	v_mfma_f32_16x16x32_bf16 v[34:37], v[160:163], v[200:203], v[34:37]
	v_mfma_f32_16x16x32_bf16 v[34:37], v[164:167], v[224:227], v[34:37]
	v_mfma_f32_16x16x32_bf16 v[22:25], v[152:155], v[228:231], v[22:25]
	v_mfma_f32_16x16x32_bf16 v[22:25], v[156:159], v[232:235], v[22:25]
	v_mfma_f32_16x16x32_bf16 v[18:21], v[160:163], v[228:231], v[18:21]
	v_mfma_f32_16x16x32_bf16 v[18:21], v[164:167], v[232:235], v[18:21]
	v_mfma_f32_16x16x32_bf16 v[6:9], v[152:155], v[236:239], v[6:9]
	v_mfma_f32_16x16x32_bf16 v[6:9], v[156:159], v[240:243], v[6:9]
	s_setprio 2
	s_cbranch_scc1 .Lq4x_270p
	s_barrier

; #define PG8_STAGE(bufoff, gbase, voff) do { _Pragma("unroll") for (int _i = 0; _i < 2; ++_i) \
;         __builtin_amdgcn_global_load_lds((const unsigned*)((const char*)(gbase) + (voff)[_i]), (PG8_LAS unsigned*)(lds + (bufoff) + ldsw + _i * 8192), 16, 0, AUX_A); } while (0)
; #define PG8_STAGEB(bufoff, gbase, voff) do { _Pragma("unroll") for (int _i = 0; _i < 2; ++_i) \
;         __builtin_amdgcn_global_load_lds((const unsigned*)((const char*)(gbase) + (voff)[_i]), (PG8_LAS unsigned*)(lds + (bufoff) + ldsw + _i * 8192), 16, 0, AUX_B); } while (0)
; #define PG8_WAIT_V(n) asm volatile("s_waitcnt vmcnt(" #n ")" ::: "memory")
; #define PG8_WAIT_L(n) asm volatile("s_waitcnt lgkmcnt(" #n ")" ::: "memory")
; template <class Epi, class Sched, bool ALIGN_EPI = false, bool SP2 = false>
; __device__ __forceinline__ void gemm_phase(PG8_LAS unsigned char* lds, const Gemm g, const Sched& S, const Epi& E) {
;     ...
;         for (int t = 0; t < nt; t += 2) {
;             const bool last = (t == nt - 2);
;             const char* a1 = PG8_KP(cA, t + 1, rot, nt);
;             const char* a2 = last ? nAr : PG8_KP(cA, t + 2, rot, nt); const char* b2 = last ? nBr : PG8_KP(cB, t + 2, rot, nt);
;             const char* a3 = a2 + kstep; const char* b3 = b2 + kstep;
;             if (last && has_next) S.a_ready(nxt);
;             if constexpr (SP2) {
;             PG8_LDB(B0, 0, 0); PG8_LDB(B1, 0, 1); PG8_SCHED; PG8_LDA(At, 0, 0); PG8_STAGE(PG8_SA(1, 1), a1 + hstep, voffA);
;             PG8_WAIT_V(8); PG8_WAIT_L(0); PG8_BAR; PG8_MMA(0, 0, At, B0); PG8_MMA(0, 1, At, B1); PG8_BAR; PG8_SCHED;
;             PG8_LDA(At, 0, 1); PG8_STAGEB(PG8_SB(0, 0), b2, voffB); PG8_STAGEB(PG8_SB(0, 1), b2 + hstep, voffB); PG8_STAGE(PG8_SA(0, 0), a2, voffA);
;             PG8_WAIT_V(8); PG8_WAIT_L(0); PG8_BAR; PG8_MMA(1, 0, At, B0); PG8_MMA(1, 1, At, B1); PG8_BAR; PG8_SCHED;
;             PG8_LDB(B0, 1, 0); PG8_LDB(B1, 1, 1); PG8_SCHED; PG8_LDA(At, 1, 0); PG8_STAGE(PG8_SA(0, 1), a2 + hstep, voffA);
;             PG8_WAIT_V(8); PG8_WAIT_L(0); PG8_BAR; PG8_MMA(0, 0, At, B0); PG8_MMA(0, 1, At, B1); PG8_BAR; PG8_SCHED;
;             PG8_LDA(At, 1, 1); PG8_STAGEB(PG8_SB(1, 0), b3, voffB); PG8_STAGEB(PG8_SB(1, 1), b3 + hstep, voffB); PG8_STAGE(PG8_SA(1, 0), a3, voffA);
;             PG8_WAIT_V(8); PG8_WAIT_L(0); PG8_BAR; PG8_MMA(1, 0, At, B0); PG8_MMA(1, 1, At, B1); PG8_BAR; PG8_SCHED;
.LBB0_270:
	s_add_i32 s81, s29, 2
	s_cmp_lt_u32 s29, 30
	s_cselect_b32 s0, 0, 0xffffffe0
	s_add_i32 s0, s81, s0
	s_ashr_i32 s1, s0, 31
	s_lshl_b64 s[0:1], s[0:1], 7
	s_add_u32 s42, s40, s0
	s_addc_u32 s43, s41, s1
	s_add_u32 s0, s38, s0
	s_addc_u32 s1, s39, s1
	s_cmp_eq_u32 s29, 30
	s_cselect_b32 s59, s49, s43
	s_cselect_b32 s58, s51, s42
	s_cselect_b32 s61, vcc_lo, s1
	s_cselect_b32 s60, vcc_hi, s0
	s_add_i32 s43, 0, 0x10000
	s_add_i32 s97, s43, s70
	s_add_i32 s46, 0, 0x14000
	s_add_i32 m0, s96, 0xc000
	s_add_i32 s69, s96, 0xe000
	s_add_i32 s84, s97, 0x2000
	s_add_u32 s62, s60, 0x80000
	s_addc_u32 s63, s61, 0
	s_add_i32 s4, s46, s70
	v_add_u32_e32 v148, s43, v221
	v_add_u32_e32 v164, s46, v221
	s_add_i32 s5, s4, 0x2000
	s_add_i32 s1, 0, 0x18000
	s_add_i32 s47, 0, 0x1c000
	ds_read_b128 v[136:139], v148
	ds_read_b128 v[140:143], v148 offset:1024
	ds_read_b128 v[144:147], v148 offset:2048
	ds_read_b128 v[148:151], v148 offset:3072
	ds_read_b128 v[152:155], v164
	ds_read_b128 v[156:159], v164 offset:1024
	ds_read_b128 v[160:163], v164 offset:2048
	ds_read_b128 v[164:167], v164 offset:3072
	s_add_u32 s56, s58, 0x80000
	s_addc_u32 s57, s59, 0
	s_add_i32 s0, s1, s70
	s_add_i32 s89, s0, 0x2000
	s_add_u32 s42, s60, 0x80080
	s_addc_u32 s43, s61, 0
	s_add_i32 s46, s47, s70
	s_add_i32 s92, s46, 0x2000
	s_cmp_gt_u32 s29, 29
	ds_read_b128 v[192:195], v222
	ds_read_b128 v[196:199], v222 offset:1024
	ds_read_b128 v[200:203], v222 offset:2048
	ds_read_b128 v[224:227], v222 offset:3072
	ds_read_b128 v[228:231], v222 offset:4096
	ds_read_b128 v[232:235], v222 offset:5120
	ds_read_b128 v[236:239], v222 offset:6144
	ds_read_b128 v[240:243], v222 offset:7168
	global_load_lds_dwordx4 v[134:135], off
	s_mov_b32 m0, s69
	s_nop 0
	global_load_lds_dwordx4 v[132:133], off
	s_waitcnt vmcnt(8)
	s_waitcnt lgkmcnt(0)
	s_setprio 1
	s_barrier
	v_mfma_f32_16x16x32_bf16 v[128:131], v[136:139], v[192:195], v[128:131]
	v_mfma_f32_16x16x32_bf16 v[128:131], v[140:143], v[196:199], v[128:131]
	v_mfma_f32_16x16x32_bf16 v[124:127], v[144:147], v[192:195], v[124:127]
	v_mfma_f32_16x16x32_bf16 v[124:127], v[148:151], v[196:199], v[124:127]
	v_mfma_f32_16x16x32_bf16 v[112:115], v[136:139], v[200:203], v[112:115]
	v_mfma_f32_16x16x32_bf16 v[112:115], v[140:143], v[224:227], v[112:115]
	v_mfma_f32_16x16x32_bf16 v[108:111], v[144:147], v[200:203], v[108:111]
	v_mfma_f32_16x16x32_bf16 v[108:111], v[148:151], v[224:227], v[108:111]
	v_mfma_f32_16x16x32_bf16 v[94:97], v[136:139], v[228:231], v[94:97]
	v_mfma_f32_16x16x32_bf16 v[94:97], v[140:143], v[232:235], v[94:97]
	v_mfma_f32_16x16x32_bf16 v[90:93], v[144:147], v[228:231], v[90:93]
	v_mfma_f32_16x16x32_bf16 v[90:93], v[148:151], v[232:235], v[90:93]
	v_mfma_f32_16x16x32_bf16 v[78:81], v[136:139], v[236:239], v[78:81]
	v_mfma_f32_16x16x32_bf16 v[78:81], v[140:143], v[240:243], v[78:81]
	v_mfma_f32_16x16x32_bf16 v[74:77], v[144:147], v[236:239], v[74:77]
	v_mfma_f32_16x16x32_bf16 v[74:77], v[148:151], v[240:243], v[74:77]
	s_setprio 0
	s_setprio 1
	v_mfma_f32_16x16x32_bf16 v[120:123], v[152:155], v[192:195], v[120:123]
	v_mfma_f32_16x16x32_bf16 v[120:123], v[156:159], v[196:199], v[120:123]
	v_mfma_f32_16x16x32_bf16 v[116:119], v[160:163], v[192:195], v[116:119]
	v_mfma_f32_16x16x32_bf16 v[116:119], v[164:167], v[196:199], v[116:119]
	v_mfma_f32_16x16x32_bf16 v[104:107], v[152:155], v[200:203], v[104:107]
	v_mfma_f32_16x16x32_bf16 v[104:107], v[156:159], v[224:227], v[104:107]
	v_mfma_f32_16x16x32_bf16 v[100:103], v[160:163], v[200:203], v[100:103]
	v_mfma_f32_16x16x32_bf16 v[100:103], v[164:167], v[224:227], v[100:103]
	v_mfma_f32_16x16x32_bf16 v[86:89], v[152:155], v[228:231], v[86:89]
	v_mfma_f32_16x16x32_bf16 v[86:89], v[156:159], v[232:235], v[86:89]
	v_mfma_f32_16x16x32_bf16 v[82:85], v[160:163], v[228:231], v[82:85]
	v_mfma_f32_16x16x32_bf16 v[82:85], v[164:167], v[232:235], v[82:85]
	v_mfma_f32_16x16x32_bf16 v[70:73], v[152:155], v[236:239], v[70:73]
	v_mfma_f32_16x16x32_bf16 v[70:73], v[156:159], v[240:243], v[70:73]
	s_setprio 2
	s_barrier
	v_mfma_f32_16x16x32_bf16 v[66:69], v[160:163], v[236:239], v[66:69]
	v_mfma_f32_16x16x32_bf16 v[66:69], v[164:167], v[240:243], v[66:69]
	s_setprio 0
	s_mov_b32 m0, s97
	v_lshl_add_u64 v[244:245], s[60:61], 0, v[184:185]
	ds_read_b128 v[192:195], v222 offset:16384
	ds_read_b128 v[196:199], v222 offset:17408
	ds_read_b128 v[200:203], v222 offset:18432
	ds_read_b128 v[224:227], v222 offset:19456
	ds_read_b128 v[228:231], v222 offset:20480
	ds_read_b128 v[232:235], v222 offset:21504
	ds_read_b128 v[236:239], v222 offset:22528
	ds_read_b128 v[240:243], v222 offset:23552
	global_load_lds_dwordx4 v[244:245], off
	v_lshl_add_u64 v[246:247], s[60:61], 0, v[180:181]
	s_mov_b32 m0, s84
	v_lshl_add_u64 v[212:213], s[62:63], 0, v[184:185]
	global_load_lds_dwordx4 v[246:247], off
	s_mov_b32 m0, s4
	v_lshl_add_u64 v[172:173], s[58:59], 0, v[182:183]
	global_load_lds_dwordx4 v[212:213], off
	v_lshl_add_u64 v[212:213], s[62:63], 0, v[180:181]
	s_mov_b32 m0, s5
	s_nop 0
	global_load_lds_dwordx4 v[212:213], off
	v_lshl_add_u64 v[212:213], s[58:59], 0, v[186:187]
	s_mov_b32 m0, s96
	s_nop 0
	global_load_lds_dwordx4 v[212:213], off
	s_mov_b32 m0, s71
	s_nop 0
	global_load_lds_dwordx4 v[172:173], off
	s_waitcnt vmcnt(8)
	s_waitcnt lgkmcnt(0)
	s_setprio 1
	s_barrier
; #define PG8_STAGE(bufoff, gbase, voff) do { _Pragma("unroll") for (int _i = 0; _i < 2; ++_i) \
;         __builtin_amdgcn_global_load_lds((const unsigned*)((const char*)(gbase) + (voff)[_i]), (PG8_LAS unsigned*)(lds + (bufoff) + ldsw + _i * 8192), 16, 0, AUX_A); } while (0)
; #define PG8_STAGEB(bufoff, gbase, voff) do { _Pragma("unroll") for (int _i = 0; _i < 2; ++_i) \
;         __builtin_amdgcn_global_load_lds((const unsigned*)((const char*)(gbase) + (voff)[_i]), (PG8_LAS unsigned*)(lds + (bufoff) + ldsw + _i * 8192), 16, 0, AUX_B); } while (0)
; #define PG8_WAIT_V(n) asm volatile("s_waitcnt vmcnt(" #n ")" ::: "memory")
; #define PG8_WAIT_L(n) asm volatile("s_waitcnt lgkmcnt(" #n ")" ::: "memory")
; template <class Epi, class Sched, bool ALIGN_EPI = false, bool SP2 = false>
; __device__ __forceinline__ void gemm_phase(PG8_LAS unsigned char* lds, const Gemm g, const Sched& S, const Epi& E) {
;     ...
;         for (int t = 0; t < nt; t += 2) {
;             const bool last = (t == nt - 2);
;             const char* a1 = PG8_KP(cA, t + 1, rot, nt);
;             const char* a2 = last ? nAr : PG8_KP(cA, t + 2, rot, nt); const char* b2 = last ? nBr : PG8_KP(cB, t + 2, rot, nt);
;             const char* a3 = a2 + kstep; const char* b3 = b2 + kstep;
;             if (last && has_next) S.a_ready(nxt);
;             if constexpr (SP2) {
;             PG8_LDB(B0, 0, 0); PG8_LDB(B1, 0, 1); PG8_SCHED; PG8_LDA(At, 0, 0); PG8_STAGE(PG8_SA(1, 1), a1 + hstep, voffA);
;             PG8_WAIT_V(8); PG8_WAIT_L(0); PG8_BAR; PG8_MMA(0, 0, At, B0); PG8_MMA(0, 1, At, B1); PG8_BAR; PG8_SCHED;
;             PG8_LDA(At, 0, 1); PG8_STAGEB(PG8_SB(0, 0), b2, voffB); PG8_STAGEB(PG8_SB(0, 1), b2 + hstep, voffB); PG8_STAGE(PG8_SA(0, 0), a2, voffA);
;             PG8_WAIT_V(8); PG8_WAIT_L(0); PG8_BAR; PG8_MMA(1, 0, At, B0); PG8_MMA(1, 1, At, B1); PG8_BAR; PG8_SCHED;
;             PG8_LDB(B0, 1, 0); PG8_LDB(B1, 1, 1); PG8_SCHED; PG8_LDA(At, 1, 0); PG8_STAGE(PG8_SA(0, 1), a2 + hstep, voffA);
;             PG8_WAIT_V(8); PG8_WAIT_L(0); PG8_BAR; PG8_MMA(0, 0, At, B0); PG8_MMA(0, 1, At, B1); PG8_BAR; PG8_SCHED;
;             PG8_LDA(At, 1, 1); PG8_STAGEB(PG8_SB(1, 0), b3, voffB); PG8_STAGEB(PG8_SB(1, 1), b3 + hstep, voffB); PG8_STAGE(PG8_SA(1, 0), a3, voffA);
;             PG8_WAIT_V(8); PG8_WAIT_L(0); PG8_BAR; PG8_MMA(1, 0, At, B0); PG8_MMA(1, 1, At, B1); PG8_BAR; PG8_SCHED;
	v_mfma_f32_16x16x32_bf16 v[62:65], v[136:139], v[192:195], v[62:65]
	v_mfma_f32_16x16x32_bf16 v[62:65], v[140:143], v[196:199], v[62:65]
	v_mfma_f32_16x16x32_bf16 v[58:61], v[144:147], v[192:195], v[58:61]
	v_mfma_f32_16x16x32_bf16 v[58:61], v[148:151], v[196:199], v[58:61]
	v_mfma_f32_16x16x32_bf16 v[46:49], v[136:139], v[200:203], v[46:49]
	v_mfma_f32_16x16x32_bf16 v[46:49], v[140:143], v[224:227], v[46:49]
	v_mfma_f32_16x16x32_bf16 v[42:45], v[144:147], v[200:203], v[42:45]
	v_mfma_f32_16x16x32_bf16 v[42:45], v[148:151], v[224:227], v[42:45]
	v_mfma_f32_16x16x32_bf16 v[30:33], v[136:139], v[228:231], v[30:33]
	v_mfma_f32_16x16x32_bf16 v[30:33], v[140:143], v[232:235], v[30:33]
	v_mfma_f32_16x16x32_bf16 v[26:29], v[144:147], v[228:231], v[26:29]
	v_mfma_f32_16x16x32_bf16 v[26:29], v[148:151], v[232:235], v[26:29]
	v_mfma_f32_16x16x32_bf16 v[14:17], v[136:139], v[236:239], v[14:17]
	v_mfma_f32_16x16x32_bf16 v[14:17], v[140:143], v[240:243], v[14:17]
	v_mfma_f32_16x16x32_bf16 v[10:13], v[144:147], v[236:239], v[10:13]
	v_mfma_f32_16x16x32_bf16 v[10:13], v[148:151], v[240:243], v[10:13]
	s_setprio 0
	s_setprio 1
	v_mfma_f32_16x16x32_bf16 v[54:57], v[152:155], v[192:195], v[54:57]
	v_mfma_f32_16x16x32_bf16 v[54:57], v[156:159], v[196:199], v[54:57]
	v_mfma_f32_16x16x32_bf16 v[50:53], v[160:163], v[192:195], v[50:53]
	v_mfma_f32_16x16x32_bf16 v[50:53], v[164:167], v[196:199], v[50:53]
	v_mfma_f32_16x16x32_bf16 v[38:41], v[152:155], v[200:203], v[38:41]
	v_mfma_f32_16x16x32_bf16 v[38:41], v[156:159], v[224:227], v[38:41]
	v_mfma_f32_16x16x32_bf16 v[34:37], v[160:163], v[200:203], v[34:37]
	v_mfma_f32_16x16x32_bf16 v[34:37], v[164:167], v[224:227], v[34:37]
	v_mfma_f32_16x16x32_bf16 v[22:25], v[152:155], v[228:231], v[22:25]
	v_mfma_f32_16x16x32_bf16 v[22:25], v[156:159], v[232:235], v[22:25]
	v_mfma_f32_16x16x32_bf16 v[18:21], v[160:163], v[228:231], v[18:21]
	v_mfma_f32_16x16x32_bf16 v[18:21], v[164:167], v[232:235], v[18:21]
	v_mfma_f32_16x16x32_bf16 v[6:9], v[152:155], v[236:239], v[6:9]
	v_mfma_f32_16x16x32_bf16 v[6:9], v[156:159], v[240:243], v[6:9]
	s_setprio 2
	s_barrier
	v_mfma_f32_16x16x32_bf16 v[2:5], v[160:163], v[236:239], v[2:5]
	v_mfma_f32_16x16x32_bf16 v[2:5], v[164:167], v[240:243], v[2:5]
	s_setprio 0
	v_add_u32_e32 v148, s1, v221
	v_add_u32_e32 v164, s47, v221
	ds_read_b128 v[136:139], v148
	ds_read_b128 v[140:143], v148 offset:1024
	ds_read_b128 v[144:147], v148 offset:2048
	ds_read_b128 v[148:151], v148 offset:3072
	ds_read_b128 v[152:155], v164
	ds_read_b128 v[156:159], v164 offset:1024
	ds_read_b128 v[160:163], v164 offset:2048
	ds_read_b128 v[164:167], v164 offset:3072
	s_mov_b32 m0, s33
	v_lshl_add_u64 v[168:169], s[56:57], 0, v[186:187]
	ds_read_b128 v[192:195], v222 offset:32768
	ds_read_b128 v[196:199], v222 offset:33792
	ds_read_b128 v[200:203], v222 offset:34816
	ds_read_b128 v[224:227], v222 offset:35840
	ds_read_b128 v[228:231], v222 offset:36864
	ds_read_b128 v[232:235], v222 offset:37888
	ds_read_b128 v[236:239], v222 offset:38912
	ds_read_b128 v[240:243], v222 offset:39936
	global_load_lds_dwordx4 v[168:169], off
	v_lshl_add_u64 v[168:169], s[56:57], 0, v[182:183]
	s_mov_b32 m0, s30
	s_nop 0
	global_load_lds_dwordx4 v[168:169], off
	s_waitcnt vmcnt(8)
	s_waitcnt lgkmcnt(0)
	s_setprio 1
	s_barrier
	v_mfma_f32_16x16x32_bf16 v[128:131], v[136:139], v[192:195], v[128:131]
	v_mfma_f32_16x16x32_bf16 v[128:131], v[140:143], v[196:199], v[128:131]
	v_mfma_f32_16x16x32_bf16 v[124:127], v[144:147], v[192:195], v[124:127]
	v_mfma_f32_16x16x32_bf16 v[124:127], v[148:151], v[196:199], v[124:127]
	v_mfma_f32_16x16x32_bf16 v[112:115], v[136:139], v[200:203], v[112:115]
	v_mfma_f32_16x16x32_bf16 v[112:115], v[140:143], v[224:227], v[112:115]
	v_mfma_f32_16x16x32_bf16 v[108:111], v[144:147], v[200:203], v[108:111]
	v_mfma_f32_16x16x32_bf16 v[108:111], v[148:151], v[224:227], v[108:111]
	v_mfma_f32_16x16x32_bf16 v[94:97], v[136:139], v[228:231], v[94:97]
	v_mfma_f32_16x16x32_bf16 v[94:97], v[140:143], v[232:235], v[94:97]
	v_mfma_f32_16x16x32_bf16 v[90:93], v[144:147], v[228:231], v[90:93]
	v_mfma_f32_16x16x32_bf16 v[90:93], v[148:151], v[232:235], v[90:93]
	v_mfma_f32_16x16x32_bf16 v[78:81], v[136:139], v[236:239], v[78:81]
	v_mfma_f32_16x16x32_bf16 v[78:81], v[140:143], v[240:243], v[78:81]
	v_mfma_f32_16x16x32_bf16 v[74:77], v[144:147], v[236:239], v[74:77]
	v_mfma_f32_16x16x32_bf16 v[74:77], v[148:151], v[240:243], v[74:77]
	s_setprio 0
	s_setprio 1
	v_mfma_f32_16x16x32_bf16 v[120:123], v[152:155], v[192:195], v[120:123]
	v_mfma_f32_16x16x32_bf16 v[120:123], v[156:159], v[196:199], v[120:123]
	v_mfma_f32_16x16x32_bf16 v[116:119], v[160:163], v[192:195], v[116:119]
	v_mfma_f32_16x16x32_bf16 v[116:119], v[164:167], v[196:199], v[116:119]
	v_mfma_f32_16x16x32_bf16 v[104:107], v[152:155], v[200:203], v[104:107]
	v_mfma_f32_16x16x32_bf16 v[104:107], v[156:159], v[224:227], v[104:107]
	v_mfma_f32_16x16x32_bf16 v[100:103], v[160:163], v[200:203], v[100:103]
	v_mfma_f32_16x16x32_bf16 v[100:103], v[164:167], v[224:227], v[100:103]
	v_mfma_f32_16x16x32_bf16 v[86:89], v[152:155], v[228:231], v[86:89]
	v_mfma_f32_16x16x32_bf16 v[86:89], v[156:159], v[232:235], v[86:89]
	v_mfma_f32_16x16x32_bf16 v[82:85], v[160:163], v[228:231], v[82:85]
	v_mfma_f32_16x16x32_bf16 v[82:85], v[164:167], v[232:235], v[82:85]
	v_mfma_f32_16x16x32_bf16 v[70:73], v[152:155], v[236:239], v[70:73]
	v_mfma_f32_16x16x32_bf16 v[70:73], v[156:159], v[240:243], v[70:73]
	s_setprio 2
	s_barrier
; #define PG8_STAGE(bufoff, gbase, voff) do { _Pragma("unroll") for (int _i = 0; _i < 2; ++_i) \
;         __builtin_amdgcn_global_load_lds((const unsigned*)((const char*)(gbase) + (voff)[_i]), (PG8_LAS unsigned*)(lds + (bufoff) + ldsw + _i * 8192), 16, 0, AUX_A); } while (0)
; #define PG8_STAGEB(bufoff, gbase, voff) do { _Pragma("unroll") for (int _i = 0; _i < 2; ++_i) \
;         __builtin_amdgcn_global_load_lds((const unsigned*)((const char*)(gbase) + (voff)[_i]), (PG8_LAS unsigned*)(lds + (bufoff) + ldsw + _i * 8192), 16, 0, AUX_B); } while (0)
; #define PG8_WAIT_V(n) asm volatile("s_waitcnt vmcnt(" #n ")" ::: "memory")
; #define PG8_WAIT_L(n) asm volatile("s_waitcnt lgkmcnt(" #n ")" ::: "memory")
; template <class Epi, class Sched, bool ALIGN_EPI = false, bool SP2 = false>
; __device__ __forceinline__ void gemm_phase(PG8_LAS unsigned char* lds, const Gemm g, const Sched& S, const Epi& E) {
;     ...
;         for (int t = 0; t < nt; t += 2) {
;             const bool last = (t == nt - 2);
;             const char* a1 = PG8_KP(cA, t + 1, rot, nt);
;             const char* a2 = last ? nAr : PG8_KP(cA, t + 2, rot, nt); const char* b2 = last ? nBr : PG8_KP(cB, t + 2, rot, nt);
;             const char* a3 = a2 + kstep; const char* b3 = b2 + kstep;
;             if (last && has_next) S.a_ready(nxt);
;             if constexpr (SP2) {
;             PG8_LDB(B0, 0, 0); PG8_LDB(B1, 0, 1); PG8_SCHED; PG8_LDA(At, 0, 0); PG8_STAGE(PG8_SA(1, 1), a1 + hstep, voffA);
;             PG8_WAIT_V(8); PG8_WAIT_L(0); PG8_BAR; PG8_MMA(0, 0, At, B0); PG8_MMA(0, 1, At, B1); PG8_BAR; PG8_SCHED;
;             PG8_LDA(At, 0, 1); PG8_STAGEB(PG8_SB(0, 0), b2, voffB); PG8_STAGEB(PG8_SB(0, 1), b2 + hstep, voffB); PG8_STAGE(PG8_SA(0, 0), a2, voffA);
;             PG8_WAIT_V(8); PG8_WAIT_L(0); PG8_BAR; PG8_MMA(1, 0, At, B0); PG8_MMA(1, 1, At, B1); PG8_BAR; PG8_SCHED;
;             PG8_LDB(B0, 1, 0); PG8_LDB(B1, 1, 1); PG8_SCHED; PG8_LDA(At, 1, 0); PG8_STAGE(PG8_SA(0, 1), a2 + hstep, voffA);
;             PG8_WAIT_V(8); PG8_WAIT_L(0); PG8_BAR; PG8_MMA(0, 0, At, B0); PG8_MMA(0, 1, At, B1); PG8_BAR; PG8_SCHED;
;             PG8_LDA(At, 1, 1); PG8_STAGEB(PG8_SB(1, 0), b3, voffB); PG8_STAGEB(PG8_SB(1, 1), b3 + hstep, voffB); PG8_STAGE(PG8_SA(1, 0), a3, voffA);
;             PG8_WAIT_V(8); PG8_WAIT_L(0); PG8_BAR; PG8_MMA(1, 0, At, B0); PG8_MMA(1, 1, At, B1); PG8_BAR; PG8_SCHED;
	v_mfma_f32_16x16x32_bf16 v[66:69], v[160:163], v[236:239], v[66:69]
	v_mfma_f32_16x16x32_bf16 v[66:69], v[164:167], v[240:243], v[66:69]
	s_setprio 0
	s_mov_b32 m0, s0
	v_lshl_add_u64 v[168:169], v[244:245], 0, s[76:77]
	ds_read_b128 v[192:195], v222 offset:49152
	ds_read_b128 v[196:199], v222 offset:50176
	ds_read_b128 v[200:203], v222 offset:51200
	ds_read_b128 v[224:227], v222 offset:52224
	ds_read_b128 v[228:231], v222 offset:53248
	ds_read_b128 v[232:235], v222 offset:54272
	ds_read_b128 v[236:239], v222 offset:55296
	ds_read_b128 v[240:243], v222 offset:56320
	global_load_lds_dwordx4 v[168:169], off
	v_lshl_add_u64 v[168:169], v[246:247], 0, s[76:77]
	s_mov_b32 m0, s89
	s_nop 0
	global_load_lds_dwordx4 v[168:169], off
	v_lshl_add_u64 v[168:169], s[42:43], 0, v[184:185]
	s_mov_b32 m0, s46
	s_nop 0
	global_load_lds_dwordx4 v[168:169], off
	v_lshl_add_u64 v[168:169], s[42:43], 0, v[180:181]
	s_mov_b32 m0, s92
	s_nop 0
	global_load_lds_dwordx4 v[168:169], off
	v_lshl_add_u64 v[168:169], v[212:213], 0, s[76:77]
	s_mov_b32 m0, s90
	s_nop 0
	global_load_lds_dwordx4 v[168:169], off
	v_lshl_add_u64 v[168:169], v[172:173], 0, s[76:77]
	s_mov_b32 m0, s91
	s_nop 0
	global_load_lds_dwordx4 v[168:169], off
	s_waitcnt vmcnt(8)
	s_waitcnt lgkmcnt(0)
	s_setprio 1
	s_barrier
	v_mfma_f32_16x16x32_bf16 v[62:65], v[136:139], v[192:195], v[62:65]
	v_mfma_f32_16x16x32_bf16 v[62:65], v[140:143], v[196:199], v[62:65]
	v_mfma_f32_16x16x32_bf16 v[58:61], v[144:147], v[192:195], v[58:61]
	v_mfma_f32_16x16x32_bf16 v[58:61], v[148:151], v[196:199], v[58:61]
	v_mfma_f32_16x16x32_bf16 v[46:49], v[136:139], v[200:203], v[46:49]
	v_mfma_f32_16x16x32_bf16 v[46:49], v[140:143], v[224:227], v[46:49]
	v_mfma_f32_16x16x32_bf16 v[42:45], v[144:147], v[200:203], v[42:45]
	v_mfma_f32_16x16x32_bf16 v[42:45], v[148:151], v[224:227], v[42:45]
	v_mfma_f32_16x16x32_bf16 v[30:33], v[136:139], v[228:231], v[30:33]
	v_mfma_f32_16x16x32_bf16 v[30:33], v[140:143], v[232:235], v[30:33]
	v_mfma_f32_16x16x32_bf16 v[26:29], v[144:147], v[228:231], v[26:29]
	v_mfma_f32_16x16x32_bf16 v[26:29], v[148:151], v[232:235], v[26:29]
	v_mfma_f32_16x16x32_bf16 v[14:17], v[136:139], v[236:239], v[14:17]
	v_mfma_f32_16x16x32_bf16 v[14:17], v[140:143], v[240:243], v[14:17]
	v_mfma_f32_16x16x32_bf16 v[10:13], v[144:147], v[236:239], v[10:13]
	v_mfma_f32_16x16x32_bf16 v[10:13], v[148:151], v[240:243], v[10:13]
	s_setprio 0
	s_setprio 1
	v_mfma_f32_16x16x32_bf16 v[54:57], v[152:155], v[192:195], v[54:57]
	v_mfma_f32_16x16x32_bf16 v[54:57], v[156:159], v[196:199], v[54:57]
	v_mfma_f32_16x16x32_bf16 v[50:53], v[160:163], v[192:195], v[50:53]
	v_mfma_f32_16x16x32_bf16 v[50:53], v[164:167], v[196:199], v[50:53]
	v_mfma_f32_16x16x32_bf16 v[38:41], v[152:155], v[200:203], v[38:41]
	v_mfma_f32_16x16x32_bf16 v[38:41], v[156:159], v[224:227], v[38:41]
	v_mfma_f32_16x16x32_bf16 v[34:37], v[160:163], v[200:203], v[34:37]
	v_mfma_f32_16x16x32_bf16 v[34:37], v[164:167], v[224:227], v[34:37]
	v_mfma_f32_16x16x32_bf16 v[22:25], v[152:155], v[228:231], v[22:25]
	v_mfma_f32_16x16x32_bf16 v[22:25], v[156:159], v[232:235], v[22:25]
	v_mfma_f32_16x16x32_bf16 v[18:21], v[160:163], v[228:231], v[18:21]
	v_mfma_f32_16x16x32_bf16 v[18:21], v[164:167], v[232:235], v[18:21]
	v_mfma_f32_16x16x32_bf16 v[6:9], v[152:155], v[236:239], v[6:9]
	v_mfma_f32_16x16x32_bf16 v[6:9], v[156:159], v[240:243], v[6:9]
	s_setprio 2
	s_cbranch_scc1 .Lq4x_270l
	s_barrier
.Lq4r_270l:
	v_mfma_f32_16x16x32_bf16 v[2:5], v[160:163], v[236:239], v[2:5]
	v_mfma_f32_16x16x32_bf16 v[2:5], v[164:167], v[240:243], v[2:5]
	s_setprio 0
	v_lshl_add_u64 v[132:133], v[132:133], 0, s[86:87]
	v_lshl_add_u64 v[134:135], v[134:135], 0, s[86:87]
	s_mov_b32 s29, s81
	s_cbranch_scc0 .LBB0_270
	s_branch .Lpx_270
.Lq4x_270l:
	v_cmp_ne_u32_e64 vcc, s10, 0
	s_cbranch_vccz .Lq4r_270l
	s_barrier
	s_branch .Lq4r_270l

; #define PG8_STAGE(bufoff, gbase, voff) do { _Pragma("unroll") for (int _i = 0; _i < 2; ++_i) \
;         __builtin_amdgcn_global_load_lds((const unsigned*)((const char*)(gbase) + (voff)[_i]), (PG8_LAS unsigned*)(lds + (bufoff) + ldsw + _i * 8192), 16, 0, AUX_A); } while (0)
; #define PG8_STAGEB(bufoff, gbase, voff) do { _Pragma("unroll") for (int _i = 0; _i < 2; ++_i) \
;         __builtin_amdgcn_global_load_lds((const unsigned*)((const char*)(gbase) + (voff)[_i]), (PG8_LAS unsigned*)(lds + (bufoff) + ldsw + _i * 8192), 16, 0, AUX_B); } while (0)
; #define PG8_WAIT_V(n) asm volatile("s_waitcnt vmcnt(" #n ")" ::: "memory")
; #define PG8_WAIT_L(n) asm volatile("s_waitcnt lgkmcnt(" #n ")" ::: "memory")
; template <class Epi, class Sched, bool ALIGN_EPI = false, bool SP2 = false>
; __device__ __forceinline__ void gemm_phase(PG8_LAS unsigned char* lds, const Gemm g, const Sched& S, const Epi& E) {
;     ...
;         for (int t = 0; t < nt; t += 2) {
;             const bool last = (t == nt - 2);
;             const char* a1 = PG8_KP(cA, t + 1, rot, nt);
;             const char* a2 = last ? nAr : PG8_KP(cA, t + 2, rot, nt); const char* b2 = last ? nBr : PG8_KP(cB, t + 2, rot, nt);
;             const char* a3 = a2 + kstep; const char* b3 = b2 + kstep;
;             if (last && has_next) S.a_ready(nxt);
;             if constexpr (SP2) {
;             PG8_LDB(B0, 0, 0); PG8_LDB(B1, 0, 1); PG8_SCHED; PG8_LDA(At, 0, 0); PG8_STAGE(PG8_SA(1, 1), a1 + hstep, voffA);
;             PG8_WAIT_V(8); PG8_WAIT_L(0); PG8_BAR; PG8_MMA(0, 0, At, B0); PG8_MMA(0, 1, At, B1); PG8_BAR; PG8_SCHED;
;             PG8_LDA(At, 0, 1); PG8_STAGEB(PG8_SB(0, 0), b2, voffB); PG8_STAGEB(PG8_SB(0, 1), b2 + hstep, voffB); PG8_STAGE(PG8_SA(0, 0), a2, voffA);
;             PG8_WAIT_V(8); PG8_WAIT_L(0); PG8_BAR; PG8_MMA(1, 0, At, B0); PG8_MMA(1, 1, At, B1); PG8_BAR; PG8_SCHED;
;             PG8_LDB(B0, 1, 0); PG8_LDB(B1, 1, 1); PG8_SCHED; PG8_LDA(At, 1, 0); PG8_STAGE(PG8_SA(0, 1), a2 + hstep, voffA);
;             PG8_WAIT_V(8); PG8_WAIT_L(0); PG8_BAR; PG8_MMA(0, 0, At, B0); PG8_MMA(0, 1, At, B1); PG8_BAR; PG8_SCHED;
;             PG8_LDA(At, 1, 1); PG8_STAGEB(PG8_SB(1, 0), b3, voffB); PG8_STAGEB(PG8_SB(1, 1), b3 + hstep, voffB); PG8_STAGE(PG8_SA(1, 0), a3, voffA);
;             PG8_WAIT_V(8); PG8_WAIT_L(0); PG8_BAR; PG8_MMA(1, 0, At, B0); PG8_MMA(1, 1, At, B1); PG8_BAR; PG8_SCHED;
.Lpk_936:
	s_add_i32 s81, s29, 2
	s_cmp_lt_u32 s29, 14
	s_cselect_b32 s0, 0, -16
	s_add_i32 s0, s81, s0
	s_ashr_i32 s1, s0, 31
	s_lshl_b64 s[0:1], s[0:1], 7
	s_add_u32 s2, s64, s0
	s_addc_u32 s46, s65, s1
	s_add_u32 s0, s26, s0
	s_addc_u32 s1, s27, s1
	s_cmp_eq_u32 s29, 14
	s_cselect_b32 s57, s15, s46
	s_cselect_b32 s56, s17, s2
	s_cselect_b32 s59, s43, s1
	s_cselect_b32 s58, s78, s0
	s_add_i32 s2, 0, 0x10000
	s_add_i32 s83, s2, s33
	s_add_i32 s46, 0, 0x14000
	s_add_i32 m0, s25, 0xc000
	s_add_i32 s82, s25, 0xe000
	s_add_i32 s84, s83, 0x2000
	s_add_u32 s60, s58, 0x40000
	s_addc_u32 s61, s59, 0
	s_add_i32 s88, s46, s33
	v_add_u32_e32 v160, s2, v99
	v_add_u32_e32 v166, s46, v99
	s_add_i32 s89, s88, 0x2000
	s_add_i32 s90, 0, 0x18000
	s_add_i32 s91, 0, 0x1c000
	ds_read_b128 v[22:25], v160
	ds_read_b128 v[34:37], v160 offset:1024
	ds_read_b128 v[38:41], v160 offset:2048
	ds_read_b128 v[160:163], v160 offset:3072
	ds_read_b128 v[180:183], v166
	ds_read_b128 v[184:187], v166 offset:1024
	ds_read_b128 v[188:191], v166 offset:2048
	ds_read_b128 v[192:195], v166 offset:3072
	s_add_u32 s54, s56, 0x40000
	s_addc_u32 s55, s57, 0
	s_add_i32 s1, s90, s33
	s_add_i32 s0, s1, 0x2000
	s_add_u32 s52, s58, 0x40080
	s_addc_u32 s53, s59, 0
	s_add_i32 s47, s91, s33
	s_add_i32 s46, s47, 0x2000
	s_cmp_gt_u32 s29, 13
	ds_read_b128 v[196:199], v165
	ds_read_b128 v[200:203], v165 offset:1024
	ds_read_b128 v[222:225], v165 offset:2048
	ds_read_b128 v[226:229], v165 offset:3072
	ds_read_b128 v[230:233], v165 offset:4096
	ds_read_b128 v[234:237], v165 offset:5120
	ds_read_b128 v[238:241], v165 offset:6144
	ds_read_b128 v[242:245], v165 offset:7168
	global_load_lds_dwordx4 v[16:17], off
	s_mov_b32 m0, s82
	s_nop 0
	global_load_lds_dwordx4 v[14:15], off
	s_waitcnt vmcnt(8)
	s_waitcnt lgkmcnt(0)
	s_setprio 1
	s_barrier
	v_mfma_f32_16x16x32_bf16 v[144:147], v[22:25], v[196:199], 0
	v_mfma_f32_16x16x32_bf16 v[144:147], v[34:37], v[200:203], v[144:147]
	v_mfma_f32_16x16x32_bf16 v[140:143], v[38:41], v[196:199], 0
	v_mfma_f32_16x16x32_bf16 v[140:143], v[160:163], v[200:203], v[140:143]
	v_mfma_f32_16x16x32_bf16 v[128:131], v[22:25], v[222:225], 0
	v_mfma_f32_16x16x32_bf16 v[128:131], v[34:37], v[226:229], v[128:131]
	v_mfma_f32_16x16x32_bf16 v[124:127], v[38:41], v[222:225], 0
	v_mfma_f32_16x16x32_bf16 v[124:127], v[160:163], v[226:229], v[124:127]
	v_mfma_f32_16x16x32_bf16 v[112:115], v[22:25], v[230:233], 0
	v_mfma_f32_16x16x32_bf16 v[112:115], v[34:37], v[234:237], v[112:115]
	v_mfma_f32_16x16x32_bf16 v[108:111], v[38:41], v[230:233], 0
	v_mfma_f32_16x16x32_bf16 v[108:111], v[160:163], v[234:237], v[108:111]
	v_mfma_f32_16x16x32_bf16 v[94:97], v[22:25], v[238:241], 0
	v_mfma_f32_16x16x32_bf16 v[94:97], v[34:37], v[242:245], v[94:97]
	v_mfma_f32_16x16x32_bf16 v[90:93], v[38:41], v[238:241], 0
	v_mfma_f32_16x16x32_bf16 v[90:93], v[160:163], v[242:245], v[90:93]
	s_setprio 0
	s_setprio 1
	v_mfma_f32_16x16x32_bf16 v[136:139], v[180:183], v[196:199], 0
	v_mfma_f32_16x16x32_bf16 v[136:139], v[184:187], v[200:203], v[136:139]
	v_mfma_f32_16x16x32_bf16 v[132:135], v[188:191], v[196:199], 0
	v_mfma_f32_16x16x32_bf16 v[132:135], v[192:195], v[200:203], v[132:135]
	v_mfma_f32_16x16x32_bf16 v[120:123], v[180:183], v[222:225], 0
	v_mfma_f32_16x16x32_bf16 v[120:123], v[184:187], v[226:229], v[120:123]
	v_mfma_f32_16x16x32_bf16 v[116:119], v[188:191], v[222:225], 0
	v_mfma_f32_16x16x32_bf16 v[116:119], v[192:195], v[226:229], v[116:119]
	v_mfma_f32_16x16x32_bf16 v[104:107], v[180:183], v[230:233], 0
	v_mfma_f32_16x16x32_bf16 v[104:107], v[184:187], v[234:237], v[104:107]
	v_mfma_f32_16x16x32_bf16 v[100:103], v[188:191], v[230:233], 0
	v_mfma_f32_16x16x32_bf16 v[100:103], v[192:195], v[234:237], v[100:103]
	v_mfma_f32_16x16x32_bf16 v[86:89], v[180:183], v[238:241], 0
	v_mfma_f32_16x16x32_bf16 v[86:89], v[184:187], v[242:245], v[86:89]
	s_setprio 2
	s_barrier
	v_mfma_f32_16x16x32_bf16 v[82:85], v[188:191], v[238:241], 0
	v_mfma_f32_16x16x32_bf16 v[82:85], v[192:195], v[242:245], v[82:85]
	s_setprio 0
	s_mov_b32 m0, s83
	v_lshl_add_u64 v[166:167], s[58:59], 0, v[150:151]
	ds_read_b128 v[196:199], v165 offset:16384
	ds_read_b128 v[200:203], v165 offset:17408
	ds_read_b128 v[222:225], v165 offset:18432
	ds_read_b128 v[226:229], v165 offset:19456
	ds_read_b128 v[230:233], v165 offset:20480
	ds_read_b128 v[234:237], v165 offset:21504
	ds_read_b128 v[238:241], v165 offset:22528
	ds_read_b128 v[242:245], v165 offset:23552
	global_load_lds_dwordx4 v[166:167], off
	v_lshl_add_u64 v[168:169], s[58:59], 0, v[154:155]
	s_mov_b32 m0, s84
	v_lshl_add_u64 v[172:173], s[60:61], 0, v[150:151]
	global_load_lds_dwordx4 v[168:169], off
	s_mov_b32 m0, s88
	v_lshl_add_u64 v[212:213], s[56:57], 0, v[152:153]
	global_load_lds_dwordx4 v[172:173], off
	v_lshl_add_u64 v[172:173], s[60:61], 0, v[154:155]
	s_mov_b32 m0, s89
	s_nop 0
	global_load_lds_dwordx4 v[172:173], off
	v_lshl_add_u64 v[172:173], s[56:57], 0, v[148:149]
	s_mov_b32 m0, s25
	s_nop 0
	global_load_lds_dwordx4 v[172:173], off
	s_mov_b32 m0, s62
	s_nop 0
	global_load_lds_dwordx4 v[212:213], off
	s_waitcnt vmcnt(8)
	s_waitcnt lgkmcnt(0)
	s_setprio 1
	s_barrier
; #define PG8_STAGE(bufoff, gbase, voff) do { _Pragma("unroll") for (int _i = 0; _i < 2; ++_i) \
;         __builtin_amdgcn_global_load_lds((const unsigned*)((const char*)(gbase) + (voff)[_i]), (PG8_LAS unsigned*)(lds + (bufoff) + ldsw + _i * 8192), 16, 0, AUX_A); } while (0)
; #define PG8_STAGEB(bufoff, gbase, voff) do { _Pragma("unroll") for (int _i = 0; _i < 2; ++_i) \
;         __builtin_amdgcn_global_load_lds((const unsigned*)((const char*)(gbase) + (voff)[_i]), (PG8_LAS unsigned*)(lds + (bufoff) + ldsw + _i * 8192), 16, 0, AUX_B); } while (0)
; #define PG8_WAIT_V(n) asm volatile("s_waitcnt vmcnt(" #n ")" ::: "memory")
; #define PG8_WAIT_L(n) asm volatile("s_waitcnt lgkmcnt(" #n ")" ::: "memory")
; template <class Epi, class Sched, bool ALIGN_EPI = false, bool SP2 = false>
; __device__ __forceinline__ void gemm_phase(PG8_LAS unsigned char* lds, const Gemm g, const Sched& S, const Epi& E) {
;     ...
;         for (int t = 0; t < nt; t += 2) {
;             const bool last = (t == nt - 2);
;             const char* a1 = PG8_KP(cA, t + 1, rot, nt);
;             const char* a2 = last ? nAr : PG8_KP(cA, t + 2, rot, nt); const char* b2 = last ? nBr : PG8_KP(cB, t + 2, rot, nt);
;             const char* a3 = a2 + kstep; const char* b3 = b2 + kstep;
;             if (last && has_next) S.a_ready(nxt);
;             if constexpr (SP2) {
;             PG8_LDB(B0, 0, 0); PG8_LDB(B1, 0, 1); PG8_SCHED; PG8_LDA(At, 0, 0); PG8_STAGE(PG8_SA(1, 1), a1 + hstep, voffA);
;             PG8_WAIT_V(8); PG8_WAIT_L(0); PG8_BAR; PG8_MMA(0, 0, At, B0); PG8_MMA(0, 1, At, B1); PG8_BAR; PG8_SCHED;
;             PG8_LDA(At, 0, 1); PG8_STAGEB(PG8_SB(0, 0), b2, voffB); PG8_STAGEB(PG8_SB(0, 1), b2 + hstep, voffB); PG8_STAGE(PG8_SA(0, 0), a2, voffA);
;             PG8_WAIT_V(8); PG8_WAIT_L(0); PG8_BAR; PG8_MMA(1, 0, At, B0); PG8_MMA(1, 1, At, B1); PG8_BAR; PG8_SCHED;
;             PG8_LDB(B0, 1, 0); PG8_LDB(B1, 1, 1); PG8_SCHED; PG8_LDA(At, 1, 0); PG8_STAGE(PG8_SA(0, 1), a2 + hstep, voffA);
;             PG8_WAIT_V(8); PG8_WAIT_L(0); PG8_BAR; PG8_MMA(0, 0, At, B0); PG8_MMA(0, 1, At, B1); PG8_BAR; PG8_SCHED;
;             PG8_LDA(At, 1, 1); PG8_STAGEB(PG8_SB(1, 0), b3, voffB); PG8_STAGEB(PG8_SB(1, 1), b3 + hstep, voffB); PG8_STAGE(PG8_SA(1, 0), a3, voffA);
;             PG8_WAIT_V(8); PG8_WAIT_L(0); PG8_BAR; PG8_MMA(1, 0, At, B0); PG8_MMA(1, 1, At, B1); PG8_BAR; PG8_SCHED;
	v_mfma_f32_16x16x32_bf16 v[78:81], v[22:25], v[196:199], 0
	v_mfma_f32_16x16x32_bf16 v[78:81], v[34:37], v[200:203], v[78:81]
	v_mfma_f32_16x16x32_bf16 v[74:77], v[38:41], v[196:199], 0
	v_mfma_f32_16x16x32_bf16 v[74:77], v[160:163], v[200:203], v[74:77]
	v_mfma_f32_16x16x32_bf16 v[62:65], v[22:25], v[222:225], 0
	v_mfma_f32_16x16x32_bf16 v[62:65], v[34:37], v[226:229], v[62:65]
	v_mfma_f32_16x16x32_bf16 v[58:61], v[38:41], v[222:225], 0
	v_mfma_f32_16x16x32_bf16 v[58:61], v[160:163], v[226:229], v[58:61]
	v_mfma_f32_16x16x32_bf16 v[46:49], v[22:25], v[230:233], 0
	v_mfma_f32_16x16x32_bf16 v[46:49], v[34:37], v[234:237], v[46:49]
	v_mfma_f32_16x16x32_bf16 v[42:45], v[38:41], v[230:233], 0
	v_mfma_f32_16x16x32_bf16 v[42:45], v[160:163], v[234:237], v[42:45]
	v_mfma_f32_16x16x32_bf16 v[18:21], v[22:25], v[238:241], 0
	v_mfma_f32_16x16x32_bf16 v[18:21], v[34:37], v[242:245], v[18:21]
	v_mfma_f32_16x16x32_bf16 v[10:13], v[38:41], v[238:241], 0
	v_mfma_f32_16x16x32_bf16 v[10:13], v[160:163], v[242:245], v[10:13]
	s_setprio 0
	s_setprio 1
	v_mfma_f32_16x16x32_bf16 v[50:53], v[188:191], v[222:225], 0
	v_mfma_f32_16x16x32_bf16 v[30:33], v[180:183], v[230:233], 0
	v_mfma_f32_16x16x32_bf16 v[26:29], v[188:191], v[230:233], 0
	v_mfma_f32_16x16x32_bf16 v[6:9], v[180:183], v[238:241], 0
	v_mfma_f32_16x16x32_bf16 v[2:5], v[188:191], v[238:241], 0
	v_mfma_f32_16x16x32_bf16 v[22:25], v[180:183], v[196:199], 0
	v_mfma_f32_16x16x32_bf16 v[34:37], v[188:191], v[196:199], 0
	v_mfma_f32_16x16x32_bf16 v[38:41], v[180:183], v[222:225], 0
	v_mfma_f32_16x16x32_bf16 v[50:53], v[192:195], v[226:229], v[50:53]
	v_mfma_f32_16x16x32_bf16 v[30:33], v[184:187], v[234:237], v[30:33]
	v_mfma_f32_16x16x32_bf16 v[26:29], v[192:195], v[234:237], v[26:29]
	v_mfma_f32_16x16x32_bf16 v[6:9], v[184:187], v[242:245], v[6:9]
	v_mfma_f32_16x16x32_bf16 v[2:5], v[192:195], v[242:245], v[2:5]
	v_mfma_f32_16x16x32_bf16 v[22:25], v[184:187], v[200:203], v[22:25]
	s_setprio 2
	s_barrier
	v_mfma_f32_16x16x32_bf16 v[34:37], v[192:195], v[200:203], v[34:37]
	v_mfma_f32_16x16x32_bf16 v[38:41], v[184:187], v[226:229], v[38:41]
	s_setprio 0
	v_add_u32_e32 v160, s90, v99
	v_add_u32_e32 v192, s91, v99
	ds_read_b128 v[54:57], v160
	ds_read_b128 v[66:69], v160 offset:1024
	ds_read_b128 v[70:73], v160 offset:2048
	ds_read_b128 v[160:163], v160 offset:3072
	ds_read_b128 v[180:183], v192
	ds_read_b128 v[184:187], v192 offset:1024
	ds_read_b128 v[188:191], v192 offset:2048
	ds_read_b128 v[192:195], v192 offset:3072
	s_mov_b32 m0, s63
	v_lshl_add_u64 v[246:247], s[54:55], 0, v[148:149]
	ds_read_b128 v[196:199], v165 offset:32768
	ds_read_b128 v[200:203], v165 offset:33792
	ds_read_b128 v[222:225], v165 offset:34816
	ds_read_b128 v[226:229], v165 offset:35840
	ds_read_b128 v[230:233], v165 offset:36864
	ds_read_b128 v[234:237], v165 offset:37888
	ds_read_b128 v[238:241], v165 offset:38912
	ds_read_b128 v[242:245], v165 offset:39936
	global_load_lds_dwordx4 v[246:247], off
	v_lshl_add_u64 v[246:247], s[54:55], 0, v[152:153]
	s_mov_b32 m0, s69
	s_nop 0
	global_load_lds_dwordx4 v[246:247], off
	s_waitcnt vmcnt(8)
	s_waitcnt lgkmcnt(0)
	s_setprio 1
	s_barrier
	v_mfma_f32_16x16x32_bf16 v[144:147], v[54:57], v[196:199], v[144:147]
	v_mfma_f32_16x16x32_bf16 v[144:147], v[66:69], v[200:203], v[144:147]
	v_mfma_f32_16x16x32_bf16 v[140:143], v[70:73], v[196:199], v[140:143]
	v_mfma_f32_16x16x32_bf16 v[140:143], v[160:163], v[200:203], v[140:143]
	v_mfma_f32_16x16x32_bf16 v[128:131], v[54:57], v[222:225], v[128:131]
	v_mfma_f32_16x16x32_bf16 v[128:131], v[66:69], v[226:229], v[128:131]
	v_mfma_f32_16x16x32_bf16 v[124:127], v[70:73], v[222:225], v[124:127]
	v_mfma_f32_16x16x32_bf16 v[124:127], v[160:163], v[226:229], v[124:127]
	v_mfma_f32_16x16x32_bf16 v[112:115], v[54:57], v[230:233], v[112:115]
	v_mfma_f32_16x16x32_bf16 v[112:115], v[66:69], v[234:237], v[112:115]
	v_mfma_f32_16x16x32_bf16 v[108:111], v[70:73], v[230:233], v[108:111]
	v_mfma_f32_16x16x32_bf16 v[108:111], v[160:163], v[234:237], v[108:111]
	v_mfma_f32_16x16x32_bf16 v[94:97], v[54:57], v[238:241], v[94:97]
	v_mfma_f32_16x16x32_bf16 v[94:97], v[66:69], v[242:245], v[94:97]
	v_mfma_f32_16x16x32_bf16 v[90:93], v[70:73], v[238:241], v[90:93]
	v_mfma_f32_16x16x32_bf16 v[90:93], v[160:163], v[242:245], v[90:93]
	s_setprio 0
	s_setprio 1
	v_mfma_f32_16x16x32_bf16 v[136:139], v[180:183], v[196:199], v[136:139]
	v_mfma_f32_16x16x32_bf16 v[136:139], v[184:187], v[200:203], v[136:139]
	v_mfma_f32_16x16x32_bf16 v[132:135], v[188:191], v[196:199], v[132:135]
	v_mfma_f32_16x16x32_bf16 v[132:135], v[192:195], v[200:203], v[132:135]
	v_mfma_f32_16x16x32_bf16 v[120:123], v[180:183], v[222:225], v[120:123]
	v_mfma_f32_16x16x32_bf16 v[120:123], v[184:187], v[226:229], v[120:123]
	v_mfma_f32_16x16x32_bf16 v[116:119], v[188:191], v[222:225], v[116:119]
	v_mfma_f32_16x16x32_bf16 v[116:119], v[192:195], v[226:229], v[116:119]
	v_mfma_f32_16x16x32_bf16 v[104:107], v[180:183], v[230:233], v[104:107]
	v_mfma_f32_16x16x32_bf16 v[104:107], v[184:187], v[234:237], v[104:107]
	v_mfma_f32_16x16x32_bf16 v[100:103], v[188:191], v[230:233], v[100:103]
	v_mfma_f32_16x16x32_bf16 v[100:103], v[192:195], v[234:237], v[100:103]
	v_mfma_f32_16x16x32_bf16 v[86:89], v[180:183], v[238:241], v[86:89]
	v_mfma_f32_16x16x32_bf16 v[86:89], v[184:187], v[242:245], v[86:89]
	s_setprio 2
	s_barrier
; #define PG8_STAGE(bufoff, gbase, voff) do { _Pragma("unroll") for (int _i = 0; _i < 2; ++_i) \
;         __builtin_amdgcn_global_load_lds((const unsigned*)((const char*)(gbase) + (voff)[_i]), (PG8_LAS unsigned*)(lds + (bufoff) + ldsw + _i * 8192), 16, 0, AUX_A); } while (0)
; #define PG8_STAGEB(bufoff, gbase, voff) do { _Pragma("unroll") for (int _i = 0; _i < 2; ++_i) \
;         __builtin_amdgcn_global_load_lds((const unsigned*)((const char*)(gbase) + (voff)[_i]), (PG8_LAS unsigned*)(lds + (bufoff) + ldsw + _i * 8192), 16, 0, AUX_B); } while (0)
; #define PG8_WAIT_V(n) asm volatile("s_waitcnt vmcnt(" #n ")" ::: "memory")
; #define PG8_WAIT_L(n) asm volatile("s_waitcnt lgkmcnt(" #n ")" ::: "memory")
; template <class Epi, class Sched, bool ALIGN_EPI = false, bool SP2 = false>
; __device__ __forceinline__ void gemm_phase(PG8_LAS unsigned char* lds, const Gemm g, const Sched& S, const Epi& E) {
;     ...
;         for (int t = 0; t < nt; t += 2) {
;             const bool last = (t == nt - 2);
;             const char* a1 = PG8_KP(cA, t + 1, rot, nt);
;             const char* a2 = last ? nAr : PG8_KP(cA, t + 2, rot, nt); const char* b2 = last ? nBr : PG8_KP(cB, t + 2, rot, nt);
;             const char* a3 = a2 + kstep; const char* b3 = b2 + kstep;
;             if (last && has_next) S.a_ready(nxt);
;             if constexpr (SP2) {
;             PG8_LDB(B0, 0, 0); PG8_LDB(B1, 0, 1); PG8_SCHED; PG8_LDA(At, 0, 0); PG8_STAGE(PG8_SA(1, 1), a1 + hstep, voffA);
;             PG8_WAIT_V(8); PG8_WAIT_L(0); PG8_BAR; PG8_MMA(0, 0, At, B0); PG8_MMA(0, 1, At, B1); PG8_BAR; PG8_SCHED;
;             PG8_LDA(At, 0, 1); PG8_STAGEB(PG8_SB(0, 0), b2, voffB); PG8_STAGEB(PG8_SB(0, 1), b2 + hstep, voffB); PG8_STAGE(PG8_SA(0, 0), a2, voffA);
;             PG8_WAIT_V(8); PG8_WAIT_L(0); PG8_BAR; PG8_MMA(1, 0, At, B0); PG8_MMA(1, 1, At, B1); PG8_BAR; PG8_SCHED;
;             PG8_LDB(B0, 1, 0); PG8_LDB(B1, 1, 1); PG8_SCHED; PG8_LDA(At, 1, 0); PG8_STAGE(PG8_SA(0, 1), a2 + hstep, voffA);
;             PG8_WAIT_V(8); PG8_WAIT_L(0); PG8_BAR; PG8_MMA(0, 0, At, B0); PG8_MMA(0, 1, At, B1); PG8_BAR; PG8_SCHED;
;             PG8_LDA(At, 1, 1); PG8_STAGEB(PG8_SB(1, 0), b3, voffB); PG8_STAGEB(PG8_SB(1, 1), b3 + hstep, voffB); PG8_STAGE(PG8_SA(1, 0), a3, voffA);
;             PG8_WAIT_V(8); PG8_WAIT_L(0); PG8_BAR; PG8_MMA(1, 0, At, B0); PG8_MMA(1, 1, At, B1); PG8_BAR; PG8_SCHED;
	v_mfma_f32_16x16x32_bf16 v[82:85], v[188:191], v[238:241], v[82:85]
	v_mfma_f32_16x16x32_bf16 v[82:85], v[192:195], v[242:245], v[82:85]
	s_setprio 0
	s_mov_b32 m0, s1
	v_lshl_add_u64 v[166:167], v[166:167], 0, s[76:77]
	ds_read_b128 v[196:199], v165 offset:49152
	ds_read_b128 v[200:203], v165 offset:50176
	ds_read_b128 v[222:225], v165 offset:51200
	ds_read_b128 v[226:229], v165 offset:52224
	ds_read_b128 v[230:233], v165 offset:53248
	ds_read_b128 v[234:237], v165 offset:54272
	ds_read_b128 v[238:241], v165 offset:55296
	ds_read_b128 v[242:245], v165 offset:56320
	global_load_lds_dwordx4 v[166:167], off
	v_lshl_add_u64 v[166:167], v[168:169], 0, s[76:77]
	s_mov_b32 m0, s0
	s_nop 0
	global_load_lds_dwordx4 v[166:167], off
	v_lshl_add_u64 v[166:167], s[52:53], 0, v[150:151]
	s_mov_b32 m0, s47
	s_nop 0
	global_load_lds_dwordx4 v[166:167], off
	v_lshl_add_u64 v[166:167], s[52:53], 0, v[154:155]
	s_mov_b32 m0, s46
	s_nop 0
	global_load_lds_dwordx4 v[166:167], off
	v_lshl_add_u64 v[166:167], v[172:173], 0, s[76:77]
	s_mov_b32 m0, s70
	s_nop 0
	global_load_lds_dwordx4 v[166:167], off
	v_lshl_add_u64 v[166:167], v[212:213], 0, s[76:77]
	s_mov_b32 m0, s71
	s_nop 0
	global_load_lds_dwordx4 v[166:167], off
	s_waitcnt vmcnt(8)
	s_waitcnt lgkmcnt(0)
	s_setprio 1
	s_barrier
	v_mfma_f32_16x16x32_bf16 v[78:81], v[54:57], v[196:199], v[78:81]
	v_mfma_f32_16x16x32_bf16 v[78:81], v[66:69], v[200:203], v[78:81]
	v_mfma_f32_16x16x32_bf16 v[74:77], v[70:73], v[196:199], v[74:77]
	v_mfma_f32_16x16x32_bf16 v[74:77], v[160:163], v[200:203], v[74:77]
	v_mfma_f32_16x16x32_bf16 v[62:65], v[54:57], v[222:225], v[62:65]
	v_mfma_f32_16x16x32_bf16 v[62:65], v[66:69], v[226:229], v[62:65]
	v_mfma_f32_16x16x32_bf16 v[58:61], v[70:73], v[222:225], v[58:61]
	v_mfma_f32_16x16x32_bf16 v[58:61], v[160:163], v[226:229], v[58:61]
	v_mfma_f32_16x16x32_bf16 v[46:49], v[54:57], v[230:233], v[46:49]
	v_mfma_f32_16x16x32_bf16 v[46:49], v[66:69], v[234:237], v[46:49]
	v_mfma_f32_16x16x32_bf16 v[42:45], v[70:73], v[230:233], v[42:45]
	v_mfma_f32_16x16x32_bf16 v[42:45], v[160:163], v[234:237], v[42:45]
	v_mfma_f32_16x16x32_bf16 v[18:21], v[54:57], v[238:241], v[18:21]
	v_mfma_f32_16x16x32_bf16 v[18:21], v[66:69], v[242:245], v[18:21]
	v_mfma_f32_16x16x32_bf16 v[10:13], v[70:73], v[238:241], v[10:13]
	v_mfma_f32_16x16x32_bf16 v[10:13], v[160:163], v[242:245], v[10:13]
	s_setprio 0
	s_setprio 1
	v_mfma_f32_16x16x32_bf16 v[22:25], v[180:183], v[196:199], v[22:25]
	v_mfma_f32_16x16x32_bf16 v[70:73], v[184:187], v[200:203], v[22:25]
	v_mfma_f32_16x16x32_bf16 v[22:25], v[188:191], v[196:199], v[34:37]
	v_mfma_f32_16x16x32_bf16 v[66:69], v[192:195], v[200:203], v[22:25]
	v_mfma_f32_16x16x32_bf16 v[22:25], v[180:183], v[222:225], v[38:41]
	v_mfma_f32_16x16x32_bf16 v[54:57], v[184:187], v[226:229], v[22:25]
	v_mfma_f32_16x16x32_bf16 v[22:25], v[188:191], v[222:225], v[50:53]
	v_mfma_f32_16x16x32_bf16 v[50:53], v[192:195], v[226:229], v[22:25]
	v_mfma_f32_16x16x32_bf16 v[22:25], v[180:183], v[230:233], v[30:33]
	v_mfma_f32_16x16x32_bf16 v[30:33], v[184:187], v[234:237], v[22:25]
	v_mfma_f32_16x16x32_bf16 v[22:25], v[188:191], v[230:233], v[26:29]
	v_mfma_f32_16x16x32_bf16 v[6:9], v[180:183], v[238:241], v[6:9]
	v_mfma_f32_16x16x32_bf16 v[2:5], v[188:191], v[238:241], v[2:5]
	v_mfma_f32_16x16x32_bf16 v[26:29], v[192:195], v[234:237], v[22:25]
	s_setprio 2
	s_cbranch_scc1 .Lq4x_936p
	s_barrier

; #define PG8_STAGE(bufoff, gbase, voff) do { _Pragma("unroll") for (int _i = 0; _i < 2; ++_i) \
;         __builtin_amdgcn_global_load_lds((const unsigned*)((const char*)(gbase) + (voff)[_i]), (PG8_LAS unsigned*)(lds + (bufoff) + ldsw + _i * 8192), 16, 0, AUX_A); } while (0)
; #define PG8_STAGEB(bufoff, gbase, voff) do { _Pragma("unroll") for (int _i = 0; _i < 2; ++_i) \
;         __builtin_amdgcn_global_load_lds((const unsigned*)((const char*)(gbase) + (voff)[_i]), (PG8_LAS unsigned*)(lds + (bufoff) + ldsw + _i * 8192), 16, 0, AUX_B); } while (0)
; #define PG8_WAIT_V(n) asm volatile("s_waitcnt vmcnt(" #n ")" ::: "memory")
; #define PG8_WAIT_L(n) asm volatile("s_waitcnt lgkmcnt(" #n ")" ::: "memory")
; template <class Epi, class Sched, bool ALIGN_EPI = false, bool SP2 = false>
; __device__ __forceinline__ void gemm_phase(PG8_LAS unsigned char* lds, const Gemm g, const Sched& S, const Epi& E) {
;     ...
;         for (int t = 0; t < nt; t += 2) {
;             const bool last = (t == nt - 2);
;             const char* a1 = PG8_KP(cA, t + 1, rot, nt);
;             const char* a2 = last ? nAr : PG8_KP(cA, t + 2, rot, nt); const char* b2 = last ? nBr : PG8_KP(cB, t + 2, rot, nt);
;             const char* a3 = a2 + kstep; const char* b3 = b2 + kstep;
;             if (last && has_next) S.a_ready(nxt);
;             if constexpr (SP2) {
;             PG8_LDB(B0, 0, 0); PG8_LDB(B1, 0, 1); PG8_SCHED; PG8_LDA(At, 0, 0); PG8_STAGE(PG8_SA(1, 1), a1 + hstep, voffA);
;             PG8_WAIT_V(8); PG8_WAIT_L(0); PG8_BAR; PG8_MMA(0, 0, At, B0); PG8_MMA(0, 1, At, B1); PG8_BAR; PG8_SCHED;
;             PG8_LDA(At, 0, 1); PG8_STAGEB(PG8_SB(0, 0), b2, voffB); PG8_STAGEB(PG8_SB(0, 1), b2 + hstep, voffB); PG8_STAGE(PG8_SA(0, 0), a2, voffA);
;             PG8_WAIT_V(8); PG8_WAIT_L(0); PG8_BAR; PG8_MMA(1, 0, At, B0); PG8_MMA(1, 1, At, B1); PG8_BAR; PG8_SCHED;
;             PG8_LDB(B0, 1, 0); PG8_LDB(B1, 1, 1); PG8_SCHED; PG8_LDA(At, 1, 0); PG8_STAGE(PG8_SA(0, 1), a2 + hstep, voffA);
;             PG8_WAIT_V(8); PG8_WAIT_L(0); PG8_BAR; PG8_MMA(0, 0, At, B0); PG8_MMA(0, 1, At, B1); PG8_BAR; PG8_SCHED;
;             PG8_LDA(At, 1, 1); PG8_STAGEB(PG8_SB(1, 0), b3, voffB); PG8_STAGEB(PG8_SB(1, 1), b3 + hstep, voffB); PG8_STAGE(PG8_SA(1, 0), a3, voffA);
;             PG8_WAIT_V(8); PG8_WAIT_L(0); PG8_BAR; PG8_MMA(1, 0, At, B0); PG8_MMA(1, 1, At, B1); PG8_BAR; PG8_SCHED;
.LBB0_936:
	s_add_i32 s81, s29, 2
	s_cmp_lt_u32 s29, 14
	s_cselect_b32 s0, 0, -16
	s_add_i32 s0, s81, s0
	s_ashr_i32 s1, s0, 31
	s_lshl_b64 s[0:1], s[0:1], 7
	s_add_u32 s2, s64, s0
	s_addc_u32 s46, s65, s1
	s_add_u32 s0, s26, s0
	s_addc_u32 s1, s27, s1
	s_cmp_eq_u32 s29, 14
	s_cselect_b32 s57, s15, s46
	s_cselect_b32 s56, s17, s2
	s_cselect_b32 s59, s43, s1
	s_cselect_b32 s58, s78, s0
	s_add_i32 s2, 0, 0x10000
	s_add_i32 s83, s2, s33
	s_add_i32 s46, 0, 0x14000
	s_add_i32 m0, s25, 0xc000
	s_add_i32 s82, s25, 0xe000
	s_add_i32 s84, s83, 0x2000
	s_add_u32 s60, s58, 0x40000
	s_addc_u32 s61, s59, 0
	s_add_i32 s88, s46, s33
	v_add_u32_e32 v160, s2, v99
	v_add_u32_e32 v166, s46, v99
	s_add_i32 s89, s88, 0x2000
	s_add_i32 s90, 0, 0x18000
	s_add_i32 s91, 0, 0x1c000
	ds_read_b128 v[22:25], v160
	ds_read_b128 v[34:37], v160 offset:1024
	ds_read_b128 v[38:41], v160 offset:2048
	ds_read_b128 v[160:163], v160 offset:3072
	ds_read_b128 v[180:183], v166
	ds_read_b128 v[184:187], v166 offset:1024
	ds_read_b128 v[188:191], v166 offset:2048
	ds_read_b128 v[192:195], v166 offset:3072
	s_add_u32 s54, s56, 0x40000
	s_addc_u32 s55, s57, 0
	s_add_i32 s1, s90, s33
	s_add_i32 s0, s1, 0x2000
	s_add_u32 s52, s58, 0x40080
	s_addc_u32 s53, s59, 0
	s_add_i32 s47, s91, s33
	s_add_i32 s46, s47, 0x2000
	s_cmp_gt_u32 s29, 13
	ds_read_b128 v[196:199], v165
	ds_read_b128 v[200:203], v165 offset:1024
	ds_read_b128 v[222:225], v165 offset:2048
	ds_read_b128 v[226:229], v165 offset:3072
	ds_read_b128 v[230:233], v165 offset:4096
	ds_read_b128 v[234:237], v165 offset:5120
	ds_read_b128 v[238:241], v165 offset:6144
	ds_read_b128 v[242:245], v165 offset:7168
	global_load_lds_dwordx4 v[16:17], off
	s_mov_b32 m0, s82
	s_nop 0
	global_load_lds_dwordx4 v[14:15], off
	s_waitcnt vmcnt(8)
	s_waitcnt lgkmcnt(0)
	s_setprio 1
	s_barrier
	v_mfma_f32_16x16x32_bf16 v[144:147], v[22:25], v[196:199], v[144:147]
	v_mfma_f32_16x16x32_bf16 v[144:147], v[34:37], v[200:203], v[144:147]
	v_mfma_f32_16x16x32_bf16 v[140:143], v[38:41], v[196:199], v[140:143]
	v_mfma_f32_16x16x32_bf16 v[140:143], v[160:163], v[200:203], v[140:143]
	v_mfma_f32_16x16x32_bf16 v[128:131], v[22:25], v[222:225], v[128:131]
	v_mfma_f32_16x16x32_bf16 v[128:131], v[34:37], v[226:229], v[128:131]
	v_mfma_f32_16x16x32_bf16 v[124:127], v[38:41], v[222:225], v[124:127]
	v_mfma_f32_16x16x32_bf16 v[124:127], v[160:163], v[226:229], v[124:127]
	v_mfma_f32_16x16x32_bf16 v[112:115], v[22:25], v[230:233], v[112:115]
	v_mfma_f32_16x16x32_bf16 v[112:115], v[34:37], v[234:237], v[112:115]
	v_mfma_f32_16x16x32_bf16 v[108:111], v[38:41], v[230:233], v[108:111]
	v_mfma_f32_16x16x32_bf16 v[108:111], v[160:163], v[234:237], v[108:111]
	v_mfma_f32_16x16x32_bf16 v[94:97], v[22:25], v[238:241], v[94:97]
	v_mfma_f32_16x16x32_bf16 v[94:97], v[34:37], v[242:245], v[94:97]
	v_mfma_f32_16x16x32_bf16 v[90:93], v[38:41], v[238:241], v[90:93]
	v_mfma_f32_16x16x32_bf16 v[90:93], v[160:163], v[242:245], v[90:93]
	s_setprio 0
	s_setprio 1
	v_mfma_f32_16x16x32_bf16 v[136:139], v[180:183], v[196:199], v[136:139]
	v_mfma_f32_16x16x32_bf16 v[136:139], v[184:187], v[200:203], v[136:139]
	v_mfma_f32_16x16x32_bf16 v[132:135], v[188:191], v[196:199], v[132:135]
	v_mfma_f32_16x16x32_bf16 v[132:135], v[192:195], v[200:203], v[132:135]
	v_mfma_f32_16x16x32_bf16 v[120:123], v[180:183], v[222:225], v[120:123]
	v_mfma_f32_16x16x32_bf16 v[120:123], v[184:187], v[226:229], v[120:123]
	v_mfma_f32_16x16x32_bf16 v[116:119], v[188:191], v[222:225], v[116:119]
	v_mfma_f32_16x16x32_bf16 v[116:119], v[192:195], v[226:229], v[116:119]
	v_mfma_f32_16x16x32_bf16 v[104:107], v[180:183], v[230:233], v[104:107]
	v_mfma_f32_16x16x32_bf16 v[104:107], v[184:187], v[234:237], v[104:107]
	v_mfma_f32_16x16x32_bf16 v[100:103], v[188:191], v[230:233], v[100:103]
	v_mfma_f32_16x16x32_bf16 v[100:103], v[192:195], v[234:237], v[100:103]
	v_mfma_f32_16x16x32_bf16 v[86:89], v[180:183], v[238:241], v[86:89]
	v_mfma_f32_16x16x32_bf16 v[86:89], v[184:187], v[242:245], v[86:89]
	s_setprio 2
	s_barrier
	v_mfma_f32_16x16x32_bf16 v[82:85], v[188:191], v[238:241], v[82:85]
	v_mfma_f32_16x16x32_bf16 v[82:85], v[192:195], v[242:245], v[82:85]
	s_setprio 0
	s_mov_b32 m0, s83
	v_lshl_add_u64 v[166:167], s[58:59], 0, v[150:151]
	ds_read_b128 v[196:199], v165 offset:16384
	ds_read_b128 v[200:203], v165 offset:17408
	ds_read_b128 v[222:225], v165 offset:18432
	ds_read_b128 v[226:229], v165 offset:19456
	ds_read_b128 v[230:233], v165 offset:20480
	ds_read_b128 v[234:237], v165 offset:21504
	ds_read_b128 v[238:241], v165 offset:22528
	ds_read_b128 v[242:245], v165 offset:23552
	global_load_lds_dwordx4 v[166:167], off
	v_lshl_add_u64 v[168:169], s[58:59], 0, v[154:155]
	s_mov_b32 m0, s84
	v_lshl_add_u64 v[172:173], s[60:61], 0, v[150:151]
	global_load_lds_dwordx4 v[168:169], off
	s_mov_b32 m0, s88
	v_lshl_add_u64 v[212:213], s[56:57], 0, v[152:153]
	global_load_lds_dwordx4 v[172:173], off
	v_lshl_add_u64 v[172:173], s[60:61], 0, v[154:155]
	s_mov_b32 m0, s89
	s_nop 0
	global_load_lds_dwordx4 v[172:173], off
	v_lshl_add_u64 v[172:173], s[56:57], 0, v[148:149]
	s_mov_b32 m0, s25
	s_nop 0
	global_load_lds_dwordx4 v[172:173], off
	s_mov_b32 m0, s62
	s_nop 0
	global_load_lds_dwordx4 v[212:213], off
	s_waitcnt vmcnt(8)
	s_waitcnt lgkmcnt(0)
	s_setprio 1
	s_barrier
; #define PG8_STAGE(bufoff, gbase, voff) do { _Pragma("unroll") for (int _i = 0; _i < 2; ++_i) \
;         __builtin_amdgcn_global_load_lds((const unsigned*)((const char*)(gbase) + (voff)[_i]), (PG8_LAS unsigned*)(lds + (bufoff) + ldsw + _i * 8192), 16, 0, AUX_A); } while (0)
; #define PG8_STAGEB(bufoff, gbase, voff) do { _Pragma("unroll") for (int _i = 0; _i < 2; ++_i) \
;         __builtin_amdgcn_global_load_lds((const unsigned*)((const char*)(gbase) + (voff)[_i]), (PG8_LAS unsigned*)(lds + (bufoff) + ldsw + _i * 8192), 16, 0, AUX_B); } while (0)
; #define PG8_WAIT_V(n) asm volatile("s_waitcnt vmcnt(" #n ")" ::: "memory")
; #define PG8_WAIT_L(n) asm volatile("s_waitcnt lgkmcnt(" #n ")" ::: "memory")
; template <class Epi, class Sched, bool ALIGN_EPI = false, bool SP2 = false>
; __device__ __forceinline__ void gemm_phase(PG8_LAS unsigned char* lds, const Gemm g, const Sched& S, const Epi& E) {
;     ...
;         for (int t = 0; t < nt; t += 2) {
;             const bool last = (t == nt - 2);
;             const char* a1 = PG8_KP(cA, t + 1, rot, nt);
;             const char* a2 = last ? nAr : PG8_KP(cA, t + 2, rot, nt); const char* b2 = last ? nBr : PG8_KP(cB, t + 2, rot, nt);
;             const char* a3 = a2 + kstep; const char* b3 = b2 + kstep;
;             if (last && has_next) S.a_ready(nxt);
;             if constexpr (SP2) {
;             PG8_LDB(B0, 0, 0); PG8_LDB(B1, 0, 1); PG8_SCHED; PG8_LDA(At, 0, 0); PG8_STAGE(PG8_SA(1, 1), a1 + hstep, voffA);
;             PG8_WAIT_V(8); PG8_WAIT_L(0); PG8_BAR; PG8_MMA(0, 0, At, B0); PG8_MMA(0, 1, At, B1); PG8_BAR; PG8_SCHED;
;             PG8_LDA(At, 0, 1); PG8_STAGEB(PG8_SB(0, 0), b2, voffB); PG8_STAGEB(PG8_SB(0, 1), b2 + hstep, voffB); PG8_STAGE(PG8_SA(0, 0), a2, voffA);
;             PG8_WAIT_V(8); PG8_WAIT_L(0); PG8_BAR; PG8_MMA(1, 0, At, B0); PG8_MMA(1, 1, At, B1); PG8_BAR; PG8_SCHED;
;             PG8_LDB(B0, 1, 0); PG8_LDB(B1, 1, 1); PG8_SCHED; PG8_LDA(At, 1, 0); PG8_STAGE(PG8_SA(0, 1), a2 + hstep, voffA);
;             PG8_WAIT_V(8); PG8_WAIT_L(0); PG8_BAR; PG8_MMA(0, 0, At, B0); PG8_MMA(0, 1, At, B1); PG8_BAR; PG8_SCHED;
;             PG8_LDA(At, 1, 1); PG8_STAGEB(PG8_SB(1, 0), b3, voffB); PG8_STAGEB(PG8_SB(1, 1), b3 + hstep, voffB); PG8_STAGE(PG8_SA(1, 0), a3, voffA);
;             PG8_WAIT_V(8); PG8_WAIT_L(0); PG8_BAR; PG8_MMA(1, 0, At, B0); PG8_MMA(1, 1, At, B1); PG8_BAR; PG8_SCHED;
	v_mfma_f32_16x16x32_bf16 v[78:81], v[22:25], v[196:199], v[78:81]
	v_mfma_f32_16x16x32_bf16 v[78:81], v[34:37], v[200:203], v[78:81]
	v_mfma_f32_16x16x32_bf16 v[74:77], v[38:41], v[196:199], v[74:77]
	v_mfma_f32_16x16x32_bf16 v[74:77], v[160:163], v[200:203], v[74:77]
	v_mfma_f32_16x16x32_bf16 v[62:65], v[22:25], v[222:225], v[62:65]
	v_mfma_f32_16x16x32_bf16 v[62:65], v[34:37], v[226:229], v[62:65]
	v_mfma_f32_16x16x32_bf16 v[58:61], v[38:41], v[222:225], v[58:61]
	v_mfma_f32_16x16x32_bf16 v[58:61], v[160:163], v[226:229], v[58:61]
	v_mfma_f32_16x16x32_bf16 v[46:49], v[22:25], v[230:233], v[46:49]
	v_mfma_f32_16x16x32_bf16 v[46:49], v[34:37], v[234:237], v[46:49]
	v_mfma_f32_16x16x32_bf16 v[42:45], v[38:41], v[230:233], v[42:45]
	v_mfma_f32_16x16x32_bf16 v[42:45], v[160:163], v[234:237], v[42:45]
	v_mfma_f32_16x16x32_bf16 v[18:21], v[22:25], v[238:241], v[18:21]
	v_mfma_f32_16x16x32_bf16 v[18:21], v[34:37], v[242:245], v[18:21]
	v_mfma_f32_16x16x32_bf16 v[10:13], v[38:41], v[238:241], v[10:13]
	v_mfma_f32_16x16x32_bf16 v[10:13], v[160:163], v[242:245], v[10:13]
	s_setprio 0
	s_setprio 1
	v_mfma_f32_16x16x32_bf16 v[50:53], v[188:191], v[222:225], v[50:53]
	v_mfma_f32_16x16x32_bf16 v[30:33], v[180:183], v[230:233], v[30:33]
	v_mfma_f32_16x16x32_bf16 v[26:29], v[188:191], v[230:233], v[26:29]
	v_mfma_f32_16x16x32_bf16 v[6:9], v[180:183], v[238:241], v[6:9]
	v_mfma_f32_16x16x32_bf16 v[2:5], v[188:191], v[238:241], v[2:5]
	v_mfma_f32_16x16x32_bf16 v[22:25], v[180:183], v[196:199], v[70:73]
	v_mfma_f32_16x16x32_bf16 v[34:37], v[188:191], v[196:199], v[66:69]
	v_mfma_f32_16x16x32_bf16 v[38:41], v[180:183], v[222:225], v[54:57]
	v_mfma_f32_16x16x32_bf16 v[50:53], v[192:195], v[226:229], v[50:53]
	v_mfma_f32_16x16x32_bf16 v[30:33], v[184:187], v[234:237], v[30:33]
	v_mfma_f32_16x16x32_bf16 v[26:29], v[192:195], v[234:237], v[26:29]
	v_mfma_f32_16x16x32_bf16 v[6:9], v[184:187], v[242:245], v[6:9]
	v_mfma_f32_16x16x32_bf16 v[2:5], v[192:195], v[242:245], v[2:5]
	v_mfma_f32_16x16x32_bf16 v[22:25], v[184:187], v[200:203], v[22:25]
	s_setprio 2
	s_barrier
	v_mfma_f32_16x16x32_bf16 v[34:37], v[192:195], v[200:203], v[34:37]
	v_mfma_f32_16x16x32_bf16 v[38:41], v[184:187], v[226:229], v[38:41]
	s_setprio 0
	v_add_u32_e32 v160, s90, v99
	v_add_u32_e32 v192, s91, v99
	ds_read_b128 v[54:57], v160
	ds_read_b128 v[66:69], v160 offset:1024
	ds_read_b128 v[70:73], v160 offset:2048
	ds_read_b128 v[160:163], v160 offset:3072
	ds_read_b128 v[180:183], v192
	ds_read_b128 v[184:187], v192 offset:1024
	ds_read_b128 v[188:191], v192 offset:2048
	ds_read_b128 v[192:195], v192 offset:3072
	s_mov_b32 m0, s63
	v_lshl_add_u64 v[246:247], s[54:55], 0, v[148:149]
	ds_read_b128 v[196:199], v165 offset:32768
	ds_read_b128 v[200:203], v165 offset:33792
	ds_read_b128 v[222:225], v165 offset:34816
	ds_read_b128 v[226:229], v165 offset:35840
	ds_read_b128 v[230:233], v165 offset:36864
	ds_read_b128 v[234:237], v165 offset:37888
	ds_read_b128 v[238:241], v165 offset:38912
	ds_read_b128 v[242:245], v165 offset:39936
	global_load_lds_dwordx4 v[246:247], off
	v_lshl_add_u64 v[246:247], s[54:55], 0, v[152:153]
	s_mov_b32 m0, s69
	s_nop 0
	global_load_lds_dwordx4 v[246:247], off
	s_waitcnt vmcnt(8)
	s_waitcnt lgkmcnt(0)
	s_setprio 1
	s_barrier
	v_mfma_f32_16x16x32_bf16 v[144:147], v[54:57], v[196:199], v[144:147]
	v_mfma_f32_16x16x32_bf16 v[144:147], v[66:69], v[200:203], v[144:147]
	v_mfma_f32_16x16x32_bf16 v[140:143], v[70:73], v[196:199], v[140:143]
	v_mfma_f32_16x16x32_bf16 v[140:143], v[160:163], v[200:203], v[140:143]
	v_mfma_f32_16x16x32_bf16 v[128:131], v[54:57], v[222:225], v[128:131]
	v_mfma_f32_16x16x32_bf16 v[128:131], v[66:69], v[226:229], v[128:131]
	v_mfma_f32_16x16x32_bf16 v[124:127], v[70:73], v[222:225], v[124:127]
	v_mfma_f32_16x16x32_bf16 v[124:127], v[160:163], v[226:229], v[124:127]
	v_mfma_f32_16x16x32_bf16 v[112:115], v[54:57], v[230:233], v[112:115]
	v_mfma_f32_16x16x32_bf16 v[112:115], v[66:69], v[234:237], v[112:115]
	v_mfma_f32_16x16x32_bf16 v[108:111], v[70:73], v[230:233], v[108:111]
	v_mfma_f32_16x16x32_bf16 v[108:111], v[160:163], v[234:237], v[108:111]
	v_mfma_f32_16x16x32_bf16 v[94:97], v[54:57], v[238:241], v[94:97]
	v_mfma_f32_16x16x32_bf16 v[94:97], v[66:69], v[242:245], v[94:97]
	v_mfma_f32_16x16x32_bf16 v[90:93], v[70:73], v[238:241], v[90:93]
	v_mfma_f32_16x16x32_bf16 v[90:93], v[160:163], v[242:245], v[90:93]
	s_setprio 0
	s_setprio 1
	v_mfma_f32_16x16x32_bf16 v[136:139], v[180:183], v[196:199], v[136:139]
	v_mfma_f32_16x16x32_bf16 v[136:139], v[184:187], v[200:203], v[136:139]
	v_mfma_f32_16x16x32_bf16 v[132:135], v[188:191], v[196:199], v[132:135]
	v_mfma_f32_16x16x32_bf16 v[132:135], v[192:195], v[200:203], v[132:135]
	v_mfma_f32_16x16x32_bf16 v[120:123], v[180:183], v[222:225], v[120:123]
	v_mfma_f32_16x16x32_bf16 v[120:123], v[184:187], v[226:229], v[120:123]
	v_mfma_f32_16x16x32_bf16 v[116:119], v[188:191], v[222:225], v[116:119]
	v_mfma_f32_16x16x32_bf16 v[116:119], v[192:195], v[226:229], v[116:119]
	v_mfma_f32_16x16x32_bf16 v[104:107], v[180:183], v[230:233], v[104:107]
	v_mfma_f32_16x16x32_bf16 v[104:107], v[184:187], v[234:237], v[104:107]
	v_mfma_f32_16x16x32_bf16 v[100:103], v[188:191], v[230:233], v[100:103]
	v_mfma_f32_16x16x32_bf16 v[100:103], v[192:195], v[234:237], v[100:103]
	v_mfma_f32_16x16x32_bf16 v[86:89], v[180:183], v[238:241], v[86:89]
	v_mfma_f32_16x16x32_bf16 v[86:89], v[184:187], v[242:245], v[86:89]
	s_setprio 2
	s_barrier
; #define PG8_STAGE(bufoff, gbase, voff) do { _Pragma("unroll") for (int _i = 0; _i < 2; ++_i) \
;         __builtin_amdgcn_global_load_lds((const unsigned*)((const char*)(gbase) + (voff)[_i]), (PG8_LAS unsigned*)(lds + (bufoff) + ldsw + _i * 8192), 16, 0, AUX_A); } while (0)
; #define PG8_STAGEB(bufoff, gbase, voff) do { _Pragma("unroll") for (int _i = 0; _i < 2; ++_i) \
;         __builtin_amdgcn_global_load_lds((const unsigned*)((const char*)(gbase) + (voff)[_i]), (PG8_LAS unsigned*)(lds + (bufoff) + ldsw + _i * 8192), 16, 0, AUX_B); } while (0)
; #define PG8_WAIT_V(n) asm volatile("s_waitcnt vmcnt(" #n ")" ::: "memory")
; #define PG8_WAIT_L(n) asm volatile("s_waitcnt lgkmcnt(" #n ")" ::: "memory")
; template <class Epi, class Sched, bool ALIGN_EPI = false, bool SP2 = false>
; __device__ __forceinline__ void gemm_phase(PG8_LAS unsigned char* lds, const Gemm g, const Sched& S, const Epi& E) {
;     ...
;         for (int t = 0; t < nt; t += 2) {
;             const bool last = (t == nt - 2);
;             const char* a1 = PG8_KP(cA, t + 1, rot, nt);
;             const char* a2 = last ? nAr : PG8_KP(cA, t + 2, rot, nt); const char* b2 = last ? nBr : PG8_KP(cB, t + 2, rot, nt);
;             const char* a3 = a2 + kstep; const char* b3 = b2 + kstep;
;             if (last && has_next) S.a_ready(nxt);
;             if constexpr (SP2) {
;             PG8_LDB(B0, 0, 0); PG8_LDB(B1, 0, 1); PG8_SCHED; PG8_LDA(At, 0, 0); PG8_STAGE(PG8_SA(1, 1), a1 + hstep, voffA);
;             PG8_WAIT_V(8); PG8_WAIT_L(0); PG8_BAR; PG8_MMA(0, 0, At, B0); PG8_MMA(0, 1, At, B1); PG8_BAR; PG8_SCHED;
;             PG8_LDA(At, 0, 1); PG8_STAGEB(PG8_SB(0, 0), b2, voffB); PG8_STAGEB(PG8_SB(0, 1), b2 + hstep, voffB); PG8_STAGE(PG8_SA(0, 0), a2, voffA);
;             PG8_WAIT_V(8); PG8_WAIT_L(0); PG8_BAR; PG8_MMA(1, 0, At, B0); PG8_MMA(1, 1, At, B1); PG8_BAR; PG8_SCHED;
;             PG8_LDB(B0, 1, 0); PG8_LDB(B1, 1, 1); PG8_SCHED; PG8_LDA(At, 1, 0); PG8_STAGE(PG8_SA(0, 1), a2 + hstep, voffA);
;             PG8_WAIT_V(8); PG8_WAIT_L(0); PG8_BAR; PG8_MMA(0, 0, At, B0); PG8_MMA(0, 1, At, B1); PG8_BAR; PG8_SCHED;
;             PG8_LDA(At, 1, 1); PG8_STAGEB(PG8_SB(1, 0), b3, voffB); PG8_STAGEB(PG8_SB(1, 1), b3 + hstep, voffB); PG8_STAGE(PG8_SA(1, 0), a3, voffA);
;             PG8_WAIT_V(8); PG8_WAIT_L(0); PG8_BAR; PG8_MMA(1, 0, At, B0); PG8_MMA(1, 1, At, B1); PG8_BAR; PG8_SCHED;
	v_mfma_f32_16x16x32_bf16 v[82:85], v[188:191], v[238:241], v[82:85]
	v_mfma_f32_16x16x32_bf16 v[82:85], v[192:195], v[242:245], v[82:85]
	s_setprio 0
	s_mov_b32 m0, s1
	v_lshl_add_u64 v[166:167], v[166:167], 0, s[76:77]
	ds_read_b128 v[196:199], v165 offset:49152
	ds_read_b128 v[200:203], v165 offset:50176
	ds_read_b128 v[222:225], v165 offset:51200
	ds_read_b128 v[226:229], v165 offset:52224
	ds_read_b128 v[230:233], v165 offset:53248
	ds_read_b128 v[234:237], v165 offset:54272
	ds_read_b128 v[238:241], v165 offset:55296
	ds_read_b128 v[242:245], v165 offset:56320
	global_load_lds_dwordx4 v[166:167], off
	v_lshl_add_u64 v[166:167], v[168:169], 0, s[76:77]
	s_mov_b32 m0, s0
	s_nop 0
	global_load_lds_dwordx4 v[166:167], off
	v_lshl_add_u64 v[166:167], s[52:53], 0, v[150:151]
	s_mov_b32 m0, s47
	s_nop 0
	global_load_lds_dwordx4 v[166:167], off
	v_lshl_add_u64 v[166:167], s[52:53], 0, v[154:155]
	s_mov_b32 m0, s46
	s_nop 0
	global_load_lds_dwordx4 v[166:167], off
	v_lshl_add_u64 v[166:167], v[172:173], 0, s[76:77]
	s_mov_b32 m0, s70
	s_nop 0
	global_load_lds_dwordx4 v[166:167], off
	v_lshl_add_u64 v[166:167], v[212:213], 0, s[76:77]
	s_mov_b32 m0, s71
	s_nop 0
	global_load_lds_dwordx4 v[166:167], off
	s_waitcnt vmcnt(8)
	s_waitcnt lgkmcnt(0)
	s_setprio 1
	s_barrier
	v_mfma_f32_16x16x32_bf16 v[78:81], v[54:57], v[196:199], v[78:81]
	v_mfma_f32_16x16x32_bf16 v[78:81], v[66:69], v[200:203], v[78:81]
	v_mfma_f32_16x16x32_bf16 v[74:77], v[70:73], v[196:199], v[74:77]
	v_mfma_f32_16x16x32_bf16 v[74:77], v[160:163], v[200:203], v[74:77]
	v_mfma_f32_16x16x32_bf16 v[62:65], v[54:57], v[222:225], v[62:65]
	v_mfma_f32_16x16x32_bf16 v[62:65], v[66:69], v[226:229], v[62:65]
	v_mfma_f32_16x16x32_bf16 v[58:61], v[70:73], v[222:225], v[58:61]
	v_mfma_f32_16x16x32_bf16 v[58:61], v[160:163], v[226:229], v[58:61]
	v_mfma_f32_16x16x32_bf16 v[46:49], v[54:57], v[230:233], v[46:49]
	v_mfma_f32_16x16x32_bf16 v[46:49], v[66:69], v[234:237], v[46:49]
	v_mfma_f32_16x16x32_bf16 v[42:45], v[70:73], v[230:233], v[42:45]
	v_mfma_f32_16x16x32_bf16 v[42:45], v[160:163], v[234:237], v[42:45]
	v_mfma_f32_16x16x32_bf16 v[18:21], v[54:57], v[238:241], v[18:21]
	v_mfma_f32_16x16x32_bf16 v[18:21], v[66:69], v[242:245], v[18:21]
	v_mfma_f32_16x16x32_bf16 v[10:13], v[70:73], v[238:241], v[10:13]
	v_mfma_f32_16x16x32_bf16 v[10:13], v[160:163], v[242:245], v[10:13]
	s_setprio 0
	s_setprio 1
	v_mfma_f32_16x16x32_bf16 v[22:25], v[180:183], v[196:199], v[22:25]
	v_mfma_f32_16x16x32_bf16 v[70:73], v[184:187], v[200:203], v[22:25]
	v_mfma_f32_16x16x32_bf16 v[22:25], v[188:191], v[196:199], v[34:37]
	v_mfma_f32_16x16x32_bf16 v[66:69], v[192:195], v[200:203], v[22:25]
	v_mfma_f32_16x16x32_bf16 v[22:25], v[180:183], v[222:225], v[38:41]
	v_mfma_f32_16x16x32_bf16 v[54:57], v[184:187], v[226:229], v[22:25]
	v_mfma_f32_16x16x32_bf16 v[22:25], v[188:191], v[222:225], v[50:53]
	v_mfma_f32_16x16x32_bf16 v[50:53], v[192:195], v[226:229], v[22:25]
	v_mfma_f32_16x16x32_bf16 v[22:25], v[180:183], v[230:233], v[30:33]
	v_mfma_f32_16x16x32_bf16 v[30:33], v[184:187], v[234:237], v[22:25]
	v_mfma_f32_16x16x32_bf16 v[22:25], v[188:191], v[230:233], v[26:29]
	v_mfma_f32_16x16x32_bf16 v[6:9], v[180:183], v[238:241], v[6:9]
	v_mfma_f32_16x16x32_bf16 v[2:5], v[188:191], v[238:241], v[2:5]
	v_mfma_f32_16x16x32_bf16 v[26:29], v[192:195], v[234:237], v[22:25]
	s_setprio 2
	s_cbranch_scc1 .Lq4x_936l
	s_barrier
.Lq4r_936l:
	v_mfma_f32_16x16x32_bf16 v[6:9], v[184:187], v[242:245], v[6:9]
	v_mfma_f32_16x16x32_bf16 v[2:5], v[192:195], v[242:245], v[2:5]
	s_setprio 0
	v_lshl_add_u64 v[14:15], v[14:15], 0, s[86:87]
	v_lshl_add_u64 v[16:17], v[16:17], 0, s[86:87]
	s_mov_b32 s29, s81
	s_cbranch_scc0 .LBB0_936
	s_branch .Lpx_936
.Lq4x_936l:
	v_cmp_ne_u32_e64 vcc, s12, 0
	s_cbranch_vccz .Lq4r_936l
	s_barrier
	s_branch .Lq4r_936l

; #define GAS __attribute__((address_space(1)))
; __device__ __forceinline__ u32x4 pack8(f32x4 v0, f32x4 v1) { u32x4 w; w.x = cvt_pk_bf16(v0[0], v0[1]); w.y = cvt_pk_bf16(v0[2], v0[3]); w.z = cvt_pk_bf16(v1[0], v1[1]); w.w = cvt_pk_bf16(v1[2], v1[3]); return w; }
; __device__ __forceinline__ void unpack8(u32x4 w, f32x4& v0, f32x4& v1) { v0 = (f32x4){bflo(w.x), bfhi(w.x), bflo(w.y), bfhi(w.y)}; v1 = (f32x4){bflo(w.z), bfhi(w.z), bflo(w.w), bfhi(w.w)}; }
; #define PG8_BAR __builtin_amdgcn_s_barrier()
; #define GAS __attribute__((address_space(1)))
;     __device__ __forceinline__ void operator()(const f32x4 (&acc)[2][2][4][2], const Unit& u, int wr, int wc, int fr, int fq) const {
;         const int row0 = u.pm * BM + wr * 64 + fr, col0 = u.pn * BM + wc * 32 + 8 * fq;
;         f32x4 bv[2][2];
; #pragma unroll
;         for (int bj = 0; bj < 2; ++bj)
; #pragma unroll
;             for (int n = 0; n < 2; ++n) bv[bj][n] = *(const f32x4*)(bglu + col0 + bj * HALF + 4 * n);
;         const bf16_t* const zb = Z + (size_t)row0 * 1024 + col0; bf16_t* const sob = SO + (size_t)row0 * 1024 + col0;
; #pragma unroll
;         for (int ai = 0; ai < 2; ++ai)
; #pragma unroll
;             for (int m = 0; m < 4; ++m) { const size_t off = (size_t)(ai * HALF + m * 16) * 1024;
; #pragma unroll
;                 for (int bj = 0; bj < 2; ++bj) { f32x4 z0, z1; unpack8(*(const GAS u32x4*)(zb + off + bj * HALF), z0, z1);
;                     const f32x4 v0 = z0 * sigmoid4(acc[ai][bj][m][0] + bv[bj][0]), v1 = z1 * sigmoid4(acc[ai][bj][m][1] + bv[bj][1]);
;                     *(GAS u32x4*)(sob + off + bj * HALF) = pack8(v0, v1); } }
; template <class Epi, class Sched, bool ALIGN_EPI = false, bool SP2 = false>
; __device__ __forceinline__ void gemm_phase(PG8_LAS unsigned char* lds, const Gemm g, const Sched& S, const Epi& E) {
;     ...
;         if constexpr (ALIGN_EPI) { if (wr == 0) PG8_BAR; }
;     ...
;         if constexpr (!Epi::AFTER_DRAIN) { E(acc, cur, wr, wc, fr, fq); if (PROBE_EPI && Epi::IDEMPOTENT) { asm volatile("" ::: "memory"); E(acc, cur, wr, wc, fr, fq); } S.done(cur); }
.Lpx_936:
	s_and_b64 vcc, exec, s[12:13]
	s_cbranch_vccz .LBB0_939
.LBB0_939:
	v_lshl_or_b32 v160, s24, 8, v164
	v_ashrrev_i32_e32 v161, 31, v160
	v_lshl_add_u64 v[22:23], v[160:161], 2, s[8:9]
	global_load_dwordx4 v[34:37], v[22:23], off offset:16
	global_load_dwordx4 v[38:41], v[22:23], off
	global_load_dwordx4 v[14:17], v[22:23], off offset:528
	s_nop 0
	global_load_dwordx4 v[22:25], v[22:23], off offset:512
	v_lshl_add_u32 v162, s42, 8, v1
	v_ashrrev_i32_e32 v163, 31, v162
	v_lshlrev_b64 v[166:167], 11, v[162:163]
	v_lshl_add_u64 v[162:163], s[4:5], 0, v[166:167]
	v_lshlrev_b64 v[160:161], 1, v[160:161]
	v_lshl_add_u64 v[162:163], v[162:163], 0, v[160:161]
	global_load_dwordx4 v[184:187], v[162:163], off
	global_load_dwordx4 v[188:191], v[162:163], off offset:256
	v_add_co_u32_e32 v242, vcc, s94, v162
	v_addc_co_u32_e32 v243, vcc, 0, v163, vcc
	global_load_dwordx4 v[192:195], v[242:243], off
	global_load_dwordx4 v[196:199], v[242:243], off offset:256
	v_add_co_u32_e32 v242, vcc, s73, v162
	v_addc_co_u32_e32 v243, vcc, 0, v163, vcc
	global_load_dwordx4 v[200:203], v[242:243], off
	global_load_dwordx4 v[222:225], v[242:243], off offset:256
	v_add_co_u32_e32 v242, vcc, s93, v162
	v_addc_co_u32_e32 v243, vcc, 0, v163, vcc
	global_load_dwordx4 v[226:229], v[242:243], off
	global_load_dwordx4 v[230:233], v[242:243], off offset:256
	v_add_co_u32_e32 v242, vcc, s49, v162
	v_addc_co_u32_e32 v243, vcc, 0, v163, vcc
	global_load_dwordx4 v[234:237], v[242:243], off
	global_load_dwordx4 v[238:241], v[242:243], off offset:256
	v_lshl_add_u64 v[166:167], s[10:11], 0, v[166:167]
	v_lshl_add_u64 v[160:161], v[166:167], 0, v[160:161]
	v_readlane_b32 s90, v254, 50
	s_mov_b64 s[42:43], -1
	v_readlane_b32 s91, v254, 51
	s_waitcnt vmcnt(9)
	v_mov_b32_e32 v180, v184
	v_mov_b32_e32 v181, v185
	v_mov_b32_e32 v182, v186
	v_mov_b32_e32 v183, v187
	v_add_co_u32_e32 v242, vcc, s50, v162
	v_addc_co_u32_e32 v243, vcc, 0, v163, vcc
	global_load_dwordx4 v[184:187], v[242:243], off
	v_pk_add_f32 v[142:143], v[142:143], v[36:37]
	v_pk_add_f32 v[146:147], v[146:147], v[40:41]
	v_pk_add_f32 v[144:145], v[144:145], v[38:39]
	v_pk_add_f32 v[140:141], v[140:141], v[34:35]
	v_pk_mul_f32 v[144:145], v[144:145], s[74:75] op_sel_hi:[1,0]
	v_pk_mul_f32 v[146:147], v[146:147], s[74:75] op_sel_hi:[1,0]
	v_pk_mul_f32 v[140:141], v[140:141], s[74:75] op_sel_hi:[1,0]
	v_pk_mul_f32 v[142:143], v[142:143], s[74:75] op_sel_hi:[1,0]
	v_exp_f32_e32 v144, v144
	v_exp_f32_e32 v145, v145
	v_exp_f32_e32 v146, v146
	v_exp_f32_e32 v147, v147
	v_exp_f32_e32 v140, v140
	v_exp_f32_e32 v141, v141
	v_exp_f32_e32 v142, v142
	v_exp_f32_e32 v143, v143
	v_pk_add_f32 v[144:145], v[144:145], 1.0 op_sel_hi:[1,0]
	v_pk_add_f32 v[146:147], v[146:147], 1.0 op_sel_hi:[1,0]
	v_pk_add_f32 v[140:141], v[140:141], 1.0 op_sel_hi:[1,0]
	v_pk_add_f32 v[142:143], v[142:143], 1.0 op_sel_hi:[1,0]
	v_rcp_f32_e32 v144, v144
	v_rcp_f32_e32 v145, v145
	v_rcp_f32_e32 v146, v146
	v_rcp_f32_e32 v147, v147
	v_rcp_f32_e32 v140, v140
	v_rcp_f32_e32 v141, v141
	v_rcp_f32_e32 v142, v142
	v_rcp_f32_e32 v143, v143
	v_lshlrev_b32_e32 v166, 16, v180
	v_and_b32_e32 v167, 0xffff0000, v180
	v_lshlrev_b32_e32 v168, 16, v181
	v_and_b32_e32 v169, 0xffff0000, v181
	v_lshlrev_b32_e32 v172, 16, v182
	v_and_b32_e32 v173, 0xffff0000, v182
	v_lshlrev_b32_e32 v180, 16, v183
	v_and_b32_e32 v181, 0xffff0000, v183
	v_pk_mul_f32 v[146:147], v[146:147], v[168:169]
	v_pk_mul_f32 v[144:145], v[144:145], v[166:167]
	v_pk_mul_f32 v[166:167], v[142:143], v[180:181]
	v_pk_mul_f32 v[142:143], v[140:141], v[172:173]
	v_cvt_pk_bf16_f32 v140, v144, v145
	v_cvt_pk_bf16_f32 v141, v146, v147
	v_cvt_pk_bf16_f32 v142, v142, v143
	v_cvt_pk_bf16_f32 v143, v166, v167
	global_store_dwordx4 v[160:161], v[140:143], off
	v_pk_add_f32 v[138:139], v[138:139], v[24:25]
	v_pk_add_f32 v[136:137], v[136:137], v[22:23]
	v_pk_add_f32 v[134:135], v[134:135], v[16:17]
	v_pk_add_f32 v[132:133], v[132:133], v[14:15]
	v_pk_mul_f32 v[136:137], v[136:137], s[74:75] op_sel_hi:[1,0]
	v_pk_mul_f32 v[138:139], v[138:139], s[74:75] op_sel_hi:[1,0]
	v_pk_mul_f32 v[132:133], v[132:133], s[74:75] op_sel_hi:[1,0]
	v_pk_mul_f32 v[134:135], v[134:135], s[74:75] op_sel_hi:[1,0]
	v_exp_f32_e32 v136, v136
	v_exp_f32_e32 v137, v137
	v_exp_f32_e32 v138, v138
	v_exp_f32_e32 v139, v139
	v_exp_f32_e32 v132, v132
	v_exp_f32_e32 v133, v133
	v_exp_f32_e32 v134, v134
	v_exp_f32_e32 v135, v135
	v_pk_add_f32 v[136:137], v[136:137], 1.0 op_sel_hi:[1,0]
	v_pk_add_f32 v[138:139], v[138:139], 1.0 op_sel_hi:[1,0]
	v_pk_add_f32 v[132:133], v[132:133], 1.0 op_sel_hi:[1,0]
	v_pk_add_f32 v[134:135], v[134:135], 1.0 op_sel_hi:[1,0]
	v_rcp_f32_e32 v136, v136
	v_rcp_f32_e32 v137, v137
	v_rcp_f32_e32 v138, v138
	v_rcp_f32_e32 v139, v139
	v_rcp_f32_e32 v132, v132
	v_rcp_f32_e32 v133, v133
	v_rcp_f32_e32 v134, v134
	v_rcp_f32_e32 v135, v135
	v_pk_add_f32 v[128:129], v[128:129], v[38:39]
	v_pk_add_f32 v[124:125], v[124:125], v[34:35]
	v_pk_add_f32 v[130:131], v[130:131], v[40:41]
	v_pk_mul_f32 v[128:129], v[128:129], s[74:75] op_sel_hi:[1,0]
	v_pk_add_f32 v[126:127], v[126:127], v[36:37]
	v_pk_mul_f32 v[124:125], v[124:125], s[74:75] op_sel_hi:[1,0]
	v_pk_mul_f32 v[130:131], v[130:131], s[74:75] op_sel_hi:[1,0]
	v_exp_f32_e32 v128, v128
	v_exp_f32_e32 v129, v129
	v_pk_mul_f32 v[126:127], v[126:127], s[74:75] op_sel_hi:[1,0]
	v_exp_f32_e32 v124, v124
	v_exp_f32_e32 v125, v125
	v_exp_f32_e32 v130, v130
	v_exp_f32_e32 v131, v131
	v_exp_f32_e32 v126, v126
	v_exp_f32_e32 v127, v127
	v_pk_add_f32 v[128:129], v[128:129], 1.0 op_sel_hi:[1,0]
	v_pk_add_f32 v[124:125], v[124:125], 1.0 op_sel_hi:[1,0]
	v_pk_add_f32 v[130:131], v[130:131], 1.0 op_sel_hi:[1,0]
	v_rcp_f32_e32 v128, v128
	v_rcp_f32_e32 v129, v129
	v_pk_add_f32 v[126:127], v[126:127], 1.0 op_sel_hi:[1,0]
	v_rcp_f32_e32 v124, v124
	v_rcp_f32_e32 v125, v125
	v_rcp_f32_e32 v130, v130
	v_rcp_f32_e32 v131, v131
	v_rcp_f32_e32 v126, v126
	v_rcp_f32_e32 v127, v127
	v_pk_add_f32 v[122:123], v[122:123], v[24:25]
	v_pk_add_f32 v[120:121], v[120:121], v[22:23]
	v_pk_add_f32 v[118:119], v[118:119], v[16:17]
	v_pk_add_f32 v[116:117], v[116:117], v[14:15]
	v_pk_mul_f32 v[120:121], v[120:121], s[74:75] op_sel_hi:[1,0]
	v_pk_mul_f32 v[122:123], v[122:123], s[74:75] op_sel_hi:[1,0]
	v_pk_mul_f32 v[116:117], v[116:117], s[74:75] op_sel_hi:[1,0]
	v_pk_mul_f32 v[118:119], v[118:119], s[74:75] op_sel_hi:[1,0]
	v_exp_f32_e32 v120, v120
	v_exp_f32_e32 v121, v121
	v_exp_f32_e32 v122, v122
	v_exp_f32_e32 v123, v123
	v_exp_f32_e32 v116, v116
	v_exp_f32_e32 v117, v117
	v_exp_f32_e32 v118, v118
	v_exp_f32_e32 v119, v119
	v_pk_add_f32 v[120:121], v[120:121], 1.0 op_sel_hi:[1,0]
	v_pk_add_f32 v[122:123], v[122:123], 1.0 op_sel_hi:[1,0]
	v_pk_add_f32 v[116:117], v[116:117], 1.0 op_sel_hi:[1,0]
	v_pk_add_f32 v[118:119], v[118:119], 1.0 op_sel_hi:[1,0]
	v_rcp_f32_e32 v120, v120
	v_rcp_f32_e32 v121, v121
	v_rcp_f32_e32 v122, v122
	s_waitcnt vmcnt(10)
; #define GAS __attribute__((address_space(1)))
; __device__ __forceinline__ u32x4 pack8(f32x4 v0, f32x4 v1) { u32x4 w; w.x = cvt_pk_bf16(v0[0], v0[1]); w.y = cvt_pk_bf16(v0[2], v0[3]); w.z = cvt_pk_bf16(v1[0], v1[1]); w.w = cvt_pk_bf16(v1[2], v1[3]); return w; }
; __device__ __forceinline__ void unpack8(u32x4 w, f32x4& v0, f32x4& v1) { v0 = (f32x4){bflo(w.x), bfhi(w.x), bflo(w.y), bfhi(w.y)}; v1 = (f32x4){bflo(w.z), bfhi(w.z), bflo(w.w), bfhi(w.w)}; }
; #define GAS __attribute__((address_space(1)))
; __device__ __forceinline__ f32x4 sigmoid4(f32x4 v) {
;     const f32x2 t0 = (f32x2){v[0], v[1]} * -1.4426950408889634f, t1 = (f32x2){v[2], v[3]} * -1.4426950408889634f;
;     const f32x2 d0 = (f32x2){__builtin_amdgcn_exp2f(t0.x), __builtin_amdgcn_exp2f(t0.y)} + 1.0f, d1 = (f32x2){__builtin_amdgcn_exp2f(t1.x), __builtin_amdgcn_exp2f(t1.y)} + 1.0f;
;     return (f32x4){__builtin_amdgcn_rcpf(d0.x), __builtin_amdgcn_rcpf(d0.y), __builtin_amdgcn_rcpf(d1.x), __builtin_amdgcn_rcpf(d1.y)}; }
;     __device__ __forceinline__ void operator()(const f32x4 (&acc)[2][2][4][2], const Unit& u, int wr, int wc, int fr, int fq) const {
;     ...
; #pragma unroll
;         for (int ai = 0; ai < 2; ++ai)
; #pragma unroll
;             for (int m = 0; m < 4; ++m) { const size_t off = (size_t)(ai * HALF + m * 16) * 1024;
; #pragma unroll
;                 for (int bj = 0; bj < 2; ++bj) { f32x4 z0, z1; unpack8(*(const GAS u32x4*)(zb + off + bj * HALF), z0, z1);
;                     const f32x4 v0 = z0 * sigmoid4(acc[ai][bj][m][0] + bv[bj][0]), v1 = z1 * sigmoid4(acc[ai][bj][m][1] + bv[bj][1]);
;                     *(GAS u32x4*)(sob + off + bj * HALF) = pack8(v0, v1); } }
	v_mov_b32_e32 v140, v188
	v_mov_b32_e32 v141, v189
	v_mov_b32_e32 v142, v190
	v_mov_b32_e32 v143, v191
	global_load_dwordx4 v[188:191], v[242:243], off offset:256
	v_lshlrev_b32_e32 v144, 16, v140
	v_and_b32_e32 v145, 0xffff0000, v140
	v_lshlrev_b32_e32 v140, 16, v141
	v_and_b32_e32 v141, 0xffff0000, v141
	v_lshlrev_b32_e32 v146, 16, v142
	v_and_b32_e32 v147, 0xffff0000, v142
	v_lshlrev_b32_e32 v142, 16, v143
	v_and_b32_e32 v143, 0xffff0000, v143
	v_pk_mul_f32 v[138:139], v[138:139], v[140:141]
	v_pk_mul_f32 v[136:137], v[136:137], v[144:145]
	v_pk_mul_f32 v[140:141], v[134:135], v[142:143]
	v_pk_mul_f32 v[134:135], v[132:133], v[146:147]
	v_cvt_pk_bf16_f32 v132, v136, v137
	v_cvt_pk_bf16_f32 v133, v138, v139
	v_cvt_pk_bf16_f32 v134, v134, v135
	v_cvt_pk_bf16_f32 v135, v140, v141
	global_store_dwordx4 v[160:161], v[132:135], off offset:256
	v_rcp_f32_e32 v123, v123
	v_rcp_f32_e32 v116, v116
	v_add_co_u32_e32 v132, vcc, s94, v162
	v_rcp_f32_e32 v117, v117
	s_nop 0
	v_addc_co_u32_e32 v133, vcc, 0, v163, vcc
	v_rcp_f32_e32 v118, v118
	v_rcp_f32_e32 v119, v119
	v_pk_add_f32 v[112:113], v[112:113], v[38:39]
	v_pk_add_f32 v[108:109], v[108:109], v[34:35]
	v_pk_add_f32 v[114:115], v[114:115], v[40:41]
	v_pk_mul_f32 v[112:113], v[112:113], s[74:75] op_sel_hi:[1,0]
	v_pk_add_f32 v[110:111], v[110:111], v[36:37]
	v_pk_mul_f32 v[108:109], v[108:109], s[74:75] op_sel_hi:[1,0]
	v_pk_mul_f32 v[114:115], v[114:115], s[74:75] op_sel_hi:[1,0]
	v_exp_f32_e32 v112, v112
	v_exp_f32_e32 v113, v113
	v_pk_mul_f32 v[110:111], v[110:111], s[74:75] op_sel_hi:[1,0]
	v_exp_f32_e32 v108, v108
	v_exp_f32_e32 v109, v109
	v_exp_f32_e32 v114, v114
	v_exp_f32_e32 v115, v115
	v_exp_f32_e32 v110, v110
	v_exp_f32_e32 v111, v111
	v_pk_add_f32 v[112:113], v[112:113], 1.0 op_sel_hi:[1,0]
	v_pk_add_f32 v[108:109], v[108:109], 1.0 op_sel_hi:[1,0]
	v_pk_add_f32 v[114:115], v[114:115], 1.0 op_sel_hi:[1,0]
	v_rcp_f32_e32 v112, v112
	v_rcp_f32_e32 v113, v113
	v_pk_add_f32 v[110:111], v[110:111], 1.0 op_sel_hi:[1,0]
	v_rcp_f32_e32 v108, v108
	v_rcp_f32_e32 v109, v109
	v_rcp_f32_e32 v114, v114
	v_rcp_f32_e32 v115, v115
	v_rcp_f32_e32 v110, v110
	v_rcp_f32_e32 v111, v111
	v_pk_add_f32 v[106:107], v[106:107], v[24:25]
	v_pk_add_f32 v[104:105], v[104:105], v[22:23]
	v_pk_add_f32 v[102:103], v[102:103], v[16:17]
	v_pk_add_f32 v[100:101], v[100:101], v[14:15]
	v_pk_mul_f32 v[104:105], v[104:105], s[74:75] op_sel_hi:[1,0]
	v_pk_mul_f32 v[106:107], v[106:107], s[74:75] op_sel_hi:[1,0]
	v_pk_mul_f32 v[100:101], v[100:101], s[74:75] op_sel_hi:[1,0]
	v_pk_mul_f32 v[102:103], v[102:103], s[74:75] op_sel_hi:[1,0]
	v_exp_f32_e32 v104, v104
	v_exp_f32_e32 v105, v105
	v_exp_f32_e32 v106, v106
	v_exp_f32_e32 v107, v107
	v_exp_f32_e32 v100, v100
	v_exp_f32_e32 v101, v101
	v_exp_f32_e32 v102, v102
	v_exp_f32_e32 v103, v103
	v_pk_add_f32 v[104:105], v[104:105], 1.0 op_sel_hi:[1,0]
	v_pk_add_f32 v[106:107], v[106:107], 1.0 op_sel_hi:[1,0]
	v_pk_add_f32 v[100:101], v[100:101], 1.0 op_sel_hi:[1,0]
	v_pk_add_f32 v[102:103], v[102:103], 1.0 op_sel_hi:[1,0]
	v_rcp_f32_e32 v104, v104
	v_rcp_f32_e32 v105, v105
	v_rcp_f32_e32 v106, v106
	v_rcp_f32_e32 v107, v107
	v_rcp_f32_e32 v100, v100
	v_rcp_f32_e32 v101, v101
	v_rcp_f32_e32 v102, v102
	v_rcp_f32_e32 v103, v103
	v_pk_add_f32 v[94:95], v[94:95], v[38:39]
	v_pk_add_f32 v[90:91], v[90:91], v[34:35]
	v_pk_add_f32 v[96:97], v[96:97], v[40:41]
	v_pk_mul_f32 v[94:95], v[94:95], s[74:75] op_sel_hi:[1,0]
	v_pk_add_f32 v[92:93], v[92:93], v[36:37]
	v_pk_mul_f32 v[90:91], v[90:91], s[74:75] op_sel_hi:[1,0]
	v_pk_mul_f32 v[96:97], v[96:97], s[74:75] op_sel_hi:[1,0]
	v_exp_f32_e32 v94, v94
	v_exp_f32_e32 v95, v95
	v_pk_mul_f32 v[92:93], v[92:93], s[74:75] op_sel_hi:[1,0]
	v_exp_f32_e32 v90, v90
	v_exp_f32_e32 v91, v91
	v_exp_f32_e32 v96, v96
	v_exp_f32_e32 v97, v97
	v_exp_f32_e32 v92, v92
	v_exp_f32_e32 v93, v93
	v_pk_add_f32 v[94:95], v[94:95], 1.0 op_sel_hi:[1,0]
	v_pk_add_f32 v[90:91], v[90:91], 1.0 op_sel_hi:[1,0]
	v_pk_add_f32 v[96:97], v[96:97], 1.0 op_sel_hi:[1,0]
	v_rcp_f32_e32 v94, v94
	v_rcp_f32_e32 v95, v95
	s_waitcnt vmcnt(11)
	v_mov_b32_e32 v134, v192
	v_mov_b32_e32 v135, v193
	v_mov_b32_e32 v136, v194
	v_mov_b32_e32 v137, v195
	v_add_co_u32_e32 v242, vcc, s51, v162
	v_addc_co_u32_e32 v243, vcc, 0, v163, vcc
	global_load_dwordx4 v[192:195], v[242:243], off
	v_lshlrev_b32_e32 v138, 16, v134
	v_and_b32_e32 v139, 0xffff0000, v134
	v_lshlrev_b32_e32 v140, 16, v136
	v_and_b32_e32 v141, 0xffff0000, v136
	v_lshlrev_b32_e32 v134, 16, v135
	v_and_b32_e32 v135, 0xffff0000, v135
	v_lshlrev_b32_e32 v136, 16, v137
	v_and_b32_e32 v137, 0xffff0000, v137
	v_pk_mul_f32 v[128:129], v[128:129], v[138:139]
	v_pk_mul_f32 v[124:125], v[124:125], v[140:141]
	v_pk_mul_f32 v[130:131], v[130:131], v[134:135]
	v_pk_mul_f32 v[134:135], v[126:127], v[136:137]
	v_cvt_pk_bf16_f32 v126, v128, v129
	v_cvt_pk_bf16_f32 v128, v124, v125
	v_add_co_u32_e32 v124, vcc, s94, v160
	v_cvt_pk_bf16_f32 v127, v130, v131
	v_cvt_pk_bf16_f32 v129, v134, v135
	v_addc_co_u32_e32 v125, vcc, 0, v161, vcc
	global_store_dwordx4 v[124:125], v[126:129], off
	v_pk_add_f32 v[92:93], v[92:93], 1.0 op_sel_hi:[1,0]
	v_rcp_f32_e32 v90, v90
	v_rcp_f32_e32 v91, v91
	v_rcp_f32_e32 v96, v96
	v_rcp_f32_e32 v97, v97
	v_rcp_f32_e32 v92, v92
	v_rcp_f32_e32 v93, v93
	v_pk_add_f32 v[88:89], v[88:89], v[24:25]
	v_pk_add_f32 v[86:87], v[86:87], v[22:23]
	v_pk_add_f32 v[84:85], v[84:85], v[16:17]
	v_pk_add_f32 v[82:83], v[82:83], v[14:15]
	v_pk_mul_f32 v[86:87], v[86:87], s[74:75] op_sel_hi:[1,0]
	v_pk_mul_f32 v[88:89], v[88:89], s[74:75] op_sel_hi:[1,0]
	v_pk_mul_f32 v[82:83], v[82:83], s[74:75] op_sel_hi:[1,0]
; #define GAS __attribute__((address_space(1)))
; __device__ __forceinline__ u32x4 pack8(f32x4 v0, f32x4 v1) { u32x4 w; w.x = cvt_pk_bf16(v0[0], v0[1]); w.y = cvt_pk_bf16(v0[2], v0[3]); w.z = cvt_pk_bf16(v1[0], v1[1]); w.w = cvt_pk_bf16(v1[2], v1[3]); return w; }
; __device__ __forceinline__ void unpack8(u32x4 w, f32x4& v0, f32x4& v1) { v0 = (f32x4){bflo(w.x), bfhi(w.x), bflo(w.y), bfhi(w.y)}; v1 = (f32x4){bflo(w.z), bfhi(w.z), bflo(w.w), bfhi(w.w)}; }
; #define GAS __attribute__((address_space(1)))
; __device__ __forceinline__ f32x4 sigmoid4(f32x4 v) {
;     const f32x2 t0 = (f32x2){v[0], v[1]} * -1.4426950408889634f, t1 = (f32x2){v[2], v[3]} * -1.4426950408889634f;
;     const f32x2 d0 = (f32x2){__builtin_amdgcn_exp2f(t0.x), __builtin_amdgcn_exp2f(t0.y)} + 1.0f, d1 = (f32x2){__builtin_amdgcn_exp2f(t1.x), __builtin_amdgcn_exp2f(t1.y)} + 1.0f;
;     return (f32x4){__builtin_amdgcn_rcpf(d0.x), __builtin_amdgcn_rcpf(d0.y), __builtin_amdgcn_rcpf(d1.x), __builtin_amdgcn_rcpf(d1.y)}; }
;     __device__ __forceinline__ void operator()(const f32x4 (&acc)[2][2][4][2], const Unit& u, int wr, int wc, int fr, int fq) const {
;     ...
; #pragma unroll
;         for (int ai = 0; ai < 2; ++ai)
; #pragma unroll
;             for (int m = 0; m < 4; ++m) { const size_t off = (size_t)(ai * HALF + m * 16) * 1024;
; #pragma unroll
;                 for (int bj = 0; bj < 2; ++bj) { f32x4 z0, z1; unpack8(*(const GAS u32x4*)(zb + off + bj * HALF), z0, z1);
;                     const f32x4 v0 = z0 * sigmoid4(acc[ai][bj][m][0] + bv[bj][0]), v1 = z1 * sigmoid4(acc[ai][bj][m][1] + bv[bj][1]);
;                     *(GAS u32x4*)(sob + off + bj * HALF) = pack8(v0, v1); } }
	v_pk_mul_f32 v[84:85], v[84:85], s[74:75] op_sel_hi:[1,0]
	v_exp_f32_e32 v86, v86
	v_exp_f32_e32 v87, v87
	v_exp_f32_e32 v88, v88
	v_exp_f32_e32 v89, v89
	v_exp_f32_e32 v82, v82
	v_exp_f32_e32 v83, v83
	v_exp_f32_e32 v84, v84
	v_exp_f32_e32 v85, v85
	v_pk_add_f32 v[86:87], v[86:87], 1.0 op_sel_hi:[1,0]
	v_pk_add_f32 v[88:89], v[88:89], 1.0 op_sel_hi:[1,0]
	v_pk_add_f32 v[82:83], v[82:83], 1.0 op_sel_hi:[1,0]
	v_pk_add_f32 v[84:85], v[84:85], 1.0 op_sel_hi:[1,0]
	v_rcp_f32_e32 v86, v86
	v_rcp_f32_e32 v87, v87
	v_rcp_f32_e32 v88, v88
	v_rcp_f32_e32 v89, v89
	v_rcp_f32_e32 v82, v82
	v_rcp_f32_e32 v83, v83
	v_rcp_f32_e32 v84, v84
	v_rcp_f32_e32 v85, v85
	v_pk_add_f32 v[78:79], v[78:79], v[38:39]
	v_pk_add_f32 v[74:75], v[74:75], v[34:35]
	v_pk_add_f32 v[80:81], v[80:81], v[40:41]
	v_pk_mul_f32 v[78:79], v[78:79], s[74:75] op_sel_hi:[1,0]
	v_pk_add_f32 v[76:77], v[76:77], v[36:37]
	v_pk_mul_f32 v[74:75], v[74:75], s[74:75] op_sel_hi:[1,0]
	v_pk_mul_f32 v[80:81], v[80:81], s[74:75] op_sel_hi:[1,0]
	v_exp_f32_e32 v78, v78
	v_exp_f32_e32 v79, v79
	v_pk_mul_f32 v[76:77], v[76:77], s[74:75] op_sel_hi:[1,0]
	v_exp_f32_e32 v74, v74
	v_exp_f32_e32 v75, v75
	v_exp_f32_e32 v80, v80
	v_exp_f32_e32 v81, v81
	v_exp_f32_e32 v76, v76
	v_exp_f32_e32 v77, v77
	v_pk_add_f32 v[78:79], v[78:79], 1.0 op_sel_hi:[1,0]
	v_pk_add_f32 v[74:75], v[74:75], 1.0 op_sel_hi:[1,0]
	v_pk_add_f32 v[80:81], v[80:81], 1.0 op_sel_hi:[1,0]
	v_rcp_f32_e32 v78, v78
	v_rcp_f32_e32 v79, v79
	v_pk_add_f32 v[76:77], v[76:77], 1.0 op_sel_hi:[1,0]
	v_rcp_f32_e32 v74, v74
	v_rcp_f32_e32 v75, v75
	v_rcp_f32_e32 v80, v80
	v_rcp_f32_e32 v81, v81
	v_rcp_f32_e32 v76, v76
	v_rcp_f32_e32 v77, v77
	v_pk_add_f32 v[72:73], v[72:73], v[24:25]
	v_pk_add_f32 v[70:71], v[70:71], v[22:23]
	v_pk_add_f32 v[68:69], v[68:69], v[16:17]
	v_pk_add_f32 v[66:67], v[66:67], v[14:15]
	v_pk_mul_f32 v[70:71], v[70:71], s[74:75] op_sel_hi:[1,0]
	v_pk_mul_f32 v[72:73], v[72:73], s[74:75] op_sel_hi:[1,0]
	v_pk_mul_f32 v[66:67], v[66:67], s[74:75] op_sel_hi:[1,0]
	v_pk_mul_f32 v[68:69], v[68:69], s[74:75] op_sel_hi:[1,0]
	v_exp_f32_e32 v70, v70
	v_exp_f32_e32 v71, v71
	v_exp_f32_e32 v72, v72
	v_exp_f32_e32 v73, v73
	v_exp_f32_e32 v66, v66
	v_exp_f32_e32 v67, v67
	v_exp_f32_e32 v68, v68
	v_exp_f32_e32 v69, v69
	s_waitcnt vmcnt(12)
	v_mov_b32_e32 v126, v196
	v_mov_b32_e32 v127, v197
	v_mov_b32_e32 v128, v198
	v_mov_b32_e32 v129, v199
	global_load_dwordx4 v[196:199], v[242:243], off offset:256
	v_lshlrev_b32_e32 v130, 16, v126
	v_and_b32_e32 v131, 0xffff0000, v126
	v_lshlrev_b32_e32 v126, 16, v127
	v_and_b32_e32 v127, 0xffff0000, v127
	v_lshlrev_b32_e32 v132, 16, v128
	v_and_b32_e32 v133, 0xffff0000, v128
	v_lshlrev_b32_e32 v128, 16, v129
	v_and_b32_e32 v129, 0xffff0000, v129
	v_pk_mul_f32 v[122:123], v[122:123], v[126:127]
	v_pk_mul_f32 v[120:121], v[120:121], v[130:131]
	v_pk_mul_f32 v[126:127], v[118:119], v[128:129]
	v_pk_mul_f32 v[118:119], v[116:117], v[132:133]
	v_cvt_pk_bf16_f32 v116, v120, v121
	v_cvt_pk_bf16_f32 v117, v122, v123
	v_cvt_pk_bf16_f32 v118, v118, v119
	v_cvt_pk_bf16_f32 v119, v126, v127
	global_store_dwordx4 v[124:125], v[116:119], off offset:256
	v_pk_add_f32 v[70:71], v[70:71], 1.0 op_sel_hi:[1,0]
	v_pk_add_f32 v[72:73], v[72:73], 1.0 op_sel_hi:[1,0]
	v_add_co_u32_e32 v116, vcc, s73, v162
	v_pk_add_f32 v[66:67], v[66:67], 1.0 op_sel_hi:[1,0]
	s_nop 0
	v_addc_co_u32_e32 v117, vcc, 0, v163, vcc
	v_pk_add_f32 v[68:69], v[68:69], 1.0 op_sel_hi:[1,0]
	v_rcp_f32_e32 v70, v70
	v_rcp_f32_e32 v71, v71
	v_rcp_f32_e32 v72, v72
	v_rcp_f32_e32 v73, v73
	v_rcp_f32_e32 v66, v66
	v_rcp_f32_e32 v67, v67
	v_rcp_f32_e32 v68, v68
	v_rcp_f32_e32 v69, v69
	v_pk_add_f32 v[62:63], v[62:63], v[38:39]
	v_pk_add_f32 v[58:59], v[58:59], v[34:35]
	v_pk_add_f32 v[64:65], v[64:65], v[40:41]
	v_pk_mul_f32 v[62:63], v[62:63], s[74:75] op_sel_hi:[1,0]
	v_pk_add_f32 v[60:61], v[60:61], v[36:37]
	v_pk_mul_f32 v[58:59], v[58:59], s[74:75] op_sel_hi:[1,0]
	v_pk_mul_f32 v[64:65], v[64:65], s[74:75] op_sel_hi:[1,0]
	v_exp_f32_e32 v62, v62
	v_exp_f32_e32 v63, v63
	v_pk_mul_f32 v[60:61], v[60:61], s[74:75] op_sel_hi:[1,0]
	v_exp_f32_e32 v58, v58
	v_exp_f32_e32 v59, v59
	v_exp_f32_e32 v64, v64
	v_exp_f32_e32 v65, v65
	v_exp_f32_e32 v60, v60
	v_exp_f32_e32 v61, v61
	v_pk_add_f32 v[62:63], v[62:63], 1.0 op_sel_hi:[1,0]
	v_pk_add_f32 v[58:59], v[58:59], 1.0 op_sel_hi:[1,0]
	v_pk_add_f32 v[64:65], v[64:65], 1.0 op_sel_hi:[1,0]
	v_rcp_f32_e32 v62, v62
	v_rcp_f32_e32 v63, v63
	v_pk_add_f32 v[60:61], v[60:61], 1.0 op_sel_hi:[1,0]
	v_rcp_f32_e32 v58, v58
	v_rcp_f32_e32 v59, v59
	v_rcp_f32_e32 v64, v64
	v_rcp_f32_e32 v65, v65
	v_rcp_f32_e32 v60, v60
	v_rcp_f32_e32 v61, v61
	v_pk_add_f32 v[56:57], v[56:57], v[24:25]
	v_pk_add_f32 v[54:55], v[54:55], v[22:23]
	v_pk_add_f32 v[52:53], v[52:53], v[16:17]
	v_pk_add_f32 v[50:51], v[50:51], v[14:15]
	v_pk_mul_f32 v[54:55], v[54:55], s[74:75] op_sel_hi:[1,0]
	v_pk_mul_f32 v[56:57], v[56:57], s[74:75] op_sel_hi:[1,0]
	v_pk_mul_f32 v[50:51], v[50:51], s[74:75] op_sel_hi:[1,0]
	v_pk_mul_f32 v[52:53], v[52:53], s[74:75] op_sel_hi:[1,0]
	v_exp_f32_e32 v54, v54
	v_exp_f32_e32 v55, v55
	v_exp_f32_e32 v56, v56
	v_exp_f32_e32 v57, v57
	v_exp_f32_e32 v50, v50
	v_exp_f32_e32 v51, v51
	v_exp_f32_e32 v52, v52
	v_exp_f32_e32 v53, v53
	v_pk_add_f32 v[54:55], v[54:55], 1.0 op_sel_hi:[1,0]
	v_pk_add_f32 v[56:57], v[56:57], 1.0 op_sel_hi:[1,0]
	v_pk_add_f32 v[50:51], v[50:51], 1.0 op_sel_hi:[1,0]
	v_pk_add_f32 v[52:53], v[52:53], 1.0 op_sel_hi:[1,0]
	v_rcp_f32_e32 v54, v54
	v_rcp_f32_e32 v55, v55
	v_rcp_f32_e32 v56, v56
	v_rcp_f32_e32 v57, v57
	v_rcp_f32_e32 v50, v50
	v_rcp_f32_e32 v51, v51
	v_rcp_f32_e32 v52, v52
	v_rcp_f32_e32 v53, v53
	v_pk_add_f32 v[46:47], v[46:47], v[38:39]
	v_pk_add_f32 v[42:43], v[42:43], v[34:35]
	v_pk_add_f32 v[48:49], v[48:49], v[40:41]
	v_pk_mul_f32 v[46:47], v[46:47], s[74:75] op_sel_hi:[1,0]
	v_pk_add_f32 v[44:45], v[44:45], v[36:37]
	v_pk_mul_f32 v[42:43], v[42:43], s[74:75] op_sel_hi:[1,0]
	v_pk_mul_f32 v[48:49], v[48:49], s[74:75] op_sel_hi:[1,0]
	v_exp_f32_e32 v46, v46
	v_exp_f32_e32 v47, v47
	v_pk_mul_f32 v[44:45], v[44:45], s[74:75] op_sel_hi:[1,0]
	v_exp_f32_e32 v42, v42
	v_exp_f32_e32 v43, v43
	v_exp_f32_e32 v48, v48
	v_exp_f32_e32 v49, v49
	s_waitcnt vmcnt(13)
; #define GAS __attribute__((address_space(1)))
; __device__ __forceinline__ u32x4 pack8(f32x4 v0, f32x4 v1) { u32x4 w; w.x = cvt_pk_bf16(v0[0], v0[1]); w.y = cvt_pk_bf16(v0[2], v0[3]); w.z = cvt_pk_bf16(v1[0], v1[1]); w.w = cvt_pk_bf16(v1[2], v1[3]); return w; }
; __device__ __forceinline__ void unpack8(u32x4 w, f32x4& v0, f32x4& v1) { v0 = (f32x4){bflo(w.x), bfhi(w.x), bflo(w.y), bfhi(w.y)}; v1 = (f32x4){bflo(w.z), bfhi(w.z), bflo(w.w), bfhi(w.w)}; }
; #define GAS __attribute__((address_space(1)))
; __device__ __forceinline__ f32x4 sigmoid4(f32x4 v) {
;     const f32x2 t0 = (f32x2){v[0], v[1]} * -1.4426950408889634f, t1 = (f32x2){v[2], v[3]} * -1.4426950408889634f;
;     const f32x2 d0 = (f32x2){__builtin_amdgcn_exp2f(t0.x), __builtin_amdgcn_exp2f(t0.y)} + 1.0f, d1 = (f32x2){__builtin_amdgcn_exp2f(t1.x), __builtin_amdgcn_exp2f(t1.y)} + 1.0f;
;     return (f32x4){__builtin_amdgcn_rcpf(d0.x), __builtin_amdgcn_rcpf(d0.y), __builtin_amdgcn_rcpf(d1.x), __builtin_amdgcn_rcpf(d1.y)}; }
;     __device__ __forceinline__ void operator()(const f32x4 (&acc)[2][2][4][2], const Unit& u, int wr, int wc, int fr, int fq) const {
;     ...
; #pragma unroll
;         for (int ai = 0; ai < 2; ++ai)
; #pragma unroll
;             for (int m = 0; m < 4; ++m) { const size_t off = (size_t)(ai * HALF + m * 16) * 1024;
; #pragma unroll
;                 for (int bj = 0; bj < 2; ++bj) { f32x4 z0, z1; unpack8(*(const GAS u32x4*)(zb + off + bj * HALF), z0, z1);
;                     const f32x4 v0 = z0 * sigmoid4(acc[ai][bj][m][0] + bv[bj][0]), v1 = z1 * sigmoid4(acc[ai][bj][m][1] + bv[bj][1]);
;                     *(GAS u32x4*)(sob + off + bj * HALF) = pack8(v0, v1); } }
	v_mov_b32_e32 v118, v200
	v_mov_b32_e32 v119, v201
	v_mov_b32_e32 v120, v202
	v_mov_b32_e32 v121, v203
	v_add_co_u32_e32 v242, vcc, s66, v162
	v_addc_co_u32_e32 v243, vcc, 0, v163, vcc
	global_load_dwordx4 v[200:203], v[242:243], off
	v_lshlrev_b32_e32 v122, 16, v118
	v_and_b32_e32 v123, 0xffff0000, v118
	v_lshlrev_b32_e32 v124, 16, v120
	v_and_b32_e32 v125, 0xffff0000, v120
	v_lshlrev_b32_e32 v118, 16, v119
	v_and_b32_e32 v119, 0xffff0000, v119
	v_lshlrev_b32_e32 v120, 16, v121
	v_and_b32_e32 v121, 0xffff0000, v121
	v_pk_mul_f32 v[112:113], v[112:113], v[122:123]
	v_pk_mul_f32 v[108:109], v[108:109], v[124:125]
	v_pk_mul_f32 v[114:115], v[114:115], v[118:119]
	v_pk_mul_f32 v[118:119], v[110:111], v[120:121]
	v_cvt_pk_bf16_f32 v110, v112, v113
	v_cvt_pk_bf16_f32 v112, v108, v109
	v_add_co_u32_e32 v108, vcc, s73, v160
	v_cvt_pk_bf16_f32 v111, v114, v115
	v_cvt_pk_bf16_f32 v113, v118, v119
	v_addc_co_u32_e32 v109, vcc, 0, v161, vcc
	global_store_dwordx4 v[108:109], v[110:113], off
	v_exp_f32_e32 v44, v44
	v_exp_f32_e32 v45, v45
	v_pk_add_f32 v[46:47], v[46:47], 1.0 op_sel_hi:[1,0]
	v_pk_add_f32 v[42:43], v[42:43], 1.0 op_sel_hi:[1,0]
	v_pk_add_f32 v[48:49], v[48:49], 1.0 op_sel_hi:[1,0]
	v_rcp_f32_e32 v46, v46
	v_rcp_f32_e32 v47, v47
	v_pk_add_f32 v[44:45], v[44:45], 1.0 op_sel_hi:[1,0]
	v_rcp_f32_e32 v42, v42
	v_rcp_f32_e32 v43, v43
	v_rcp_f32_e32 v48, v48
	v_rcp_f32_e32 v49, v49
	v_rcp_f32_e32 v44, v44
	v_rcp_f32_e32 v45, v45
	v_pk_add_f32 v[32:33], v[32:33], v[24:25]
	v_pk_add_f32 v[30:31], v[30:31], v[22:23]
	v_pk_add_f32 v[28:29], v[28:29], v[16:17]
	v_pk_add_f32 v[26:27], v[26:27], v[14:15]
	v_pk_mul_f32 v[30:31], v[30:31], s[74:75] op_sel_hi:[1,0]
	v_pk_mul_f32 v[32:33], v[32:33], s[74:75] op_sel_hi:[1,0]
	v_pk_mul_f32 v[26:27], v[26:27], s[74:75] op_sel_hi:[1,0]
	v_pk_mul_f32 v[28:29], v[28:29], s[74:75] op_sel_hi:[1,0]
	v_exp_f32_e32 v30, v30
	v_exp_f32_e32 v31, v31
	v_exp_f32_e32 v32, v32
	v_exp_f32_e32 v33, v33
	v_exp_f32_e32 v26, v26
	v_exp_f32_e32 v27, v27
	v_exp_f32_e32 v28, v28
	v_exp_f32_e32 v29, v29
	v_pk_add_f32 v[30:31], v[30:31], 1.0 op_sel_hi:[1,0]
	v_pk_add_f32 v[32:33], v[32:33], 1.0 op_sel_hi:[1,0]
	v_pk_add_f32 v[26:27], v[26:27], 1.0 op_sel_hi:[1,0]
	v_pk_add_f32 v[28:29], v[28:29], 1.0 op_sel_hi:[1,0]
	v_rcp_f32_e32 v30, v30
	v_rcp_f32_e32 v31, v31
	v_rcp_f32_e32 v32, v32
	v_rcp_f32_e32 v33, v33
	v_rcp_f32_e32 v26, v26
	v_rcp_f32_e32 v27, v27
	v_rcp_f32_e32 v28, v28
	v_rcp_f32_e32 v29, v29
	v_pk_add_f32 v[18:19], v[18:19], v[38:39]
	v_pk_add_f32 v[20:21], v[20:21], v[40:41]
	v_pk_mul_f32 v[18:19], v[18:19], s[74:75] op_sel_hi:[1,0]
	v_pk_add_f32 v[12:13], v[12:13], v[36:37]
	v_pk_add_f32 v[10:11], v[10:11], v[34:35]
	v_pk_mul_f32 v[20:21], v[20:21], s[74:75] op_sel_hi:[1,0]
	v_exp_f32_e32 v18, v18
	v_exp_f32_e32 v19, v19
	v_pk_mul_f32 v[10:11], v[10:11], s[74:75] op_sel_hi:[1,0]
	v_pk_mul_f32 v[12:13], v[12:13], s[74:75] op_sel_hi:[1,0]
	v_exp_f32_e32 v20, v20
	v_exp_f32_e32 v21, v21
	v_exp_f32_e32 v10, v10
	v_exp_f32_e32 v11, v11
	v_exp_f32_e32 v12, v12
	v_exp_f32_e32 v13, v13
	v_pk_add_f32 v[18:19], v[18:19], 1.0 op_sel_hi:[1,0]
	v_pk_add_f32 v[20:21], v[20:21], 1.0 op_sel_hi:[1,0]
	v_rcp_f32_e32 v18, v18
	v_rcp_f32_e32 v19, v19
	v_pk_add_f32 v[10:11], v[10:11], 1.0 op_sel_hi:[1,0]
	v_pk_add_f32 v[12:13], v[12:13], 1.0 op_sel_hi:[1,0]
	v_rcp_f32_e32 v20, v20
	v_rcp_f32_e32 v21, v21
	v_rcp_f32_e32 v10, v10
	v_rcp_f32_e32 v11, v11
	v_rcp_f32_e32 v12, v12
	v_rcp_f32_e32 v13, v13
	v_pk_add_f32 v[8:9], v[8:9], v[24:25]
	v_pk_add_f32 v[6:7], v[6:7], v[22:23]
	v_pk_add_f32 v[4:5], v[4:5], v[16:17]
	v_pk_add_f32 v[2:3], v[2:3], v[14:15]
	v_pk_mul_f32 v[6:7], v[6:7], s[74:75] op_sel_hi:[1,0]
	v_pk_mul_f32 v[8:9], v[8:9], s[74:75] op_sel_hi:[1,0]
	v_pk_mul_f32 v[2:3], v[2:3], s[74:75] op_sel_hi:[1,0]
	v_pk_mul_f32 v[4:5], v[4:5], s[74:75] op_sel_hi:[1,0]
	v_exp_f32_e32 v6, v6
	s_waitcnt vmcnt(14)
	v_mov_b32_e32 v110, v222
	v_mov_b32_e32 v111, v223
	v_mov_b32_e32 v112, v224
	v_mov_b32_e32 v113, v225
	global_load_dwordx4 v[222:225], v[242:243], off offset:256
	v_lshlrev_b32_e32 v114, 16, v110
	v_and_b32_e32 v115, 0xffff0000, v110
	v_lshlrev_b32_e32 v110, 16, v111
	v_and_b32_e32 v111, 0xffff0000, v111
	v_lshlrev_b32_e32 v116, 16, v112
	v_and_b32_e32 v117, 0xffff0000, v112
	v_lshlrev_b32_e32 v112, 16, v113
	v_and_b32_e32 v113, 0xffff0000, v113
	v_pk_mul_f32 v[106:107], v[106:107], v[110:111]
	v_pk_mul_f32 v[104:105], v[104:105], v[114:115]
	v_pk_mul_f32 v[110:111], v[102:103], v[112:113]
	v_pk_mul_f32 v[102:103], v[100:101], v[116:117]
	v_cvt_pk_bf16_f32 v100, v104, v105
	v_cvt_pk_bf16_f32 v101, v106, v107
	v_cvt_pk_bf16_f32 v102, v102, v103
	v_cvt_pk_bf16_f32 v103, v110, v111
	global_store_dwordx4 v[108:109], v[100:103], off offset:256
	v_exp_f32_e32 v7, v7
	v_exp_f32_e32 v8, v8
	v_add_co_u32_e32 v100, vcc, s93, v162
	v_exp_f32_e32 v9, v9
	s_nop 0
	v_addc_co_u32_e32 v101, vcc, 0, v163, vcc
	v_exp_f32_e32 v2, v2
	v_exp_f32_e32 v3, v3
	v_exp_f32_e32 v4, v4
	v_exp_f32_e32 v5, v5
	v_pk_add_f32 v[6:7], v[6:7], 1.0 op_sel_hi:[1,0]
	v_pk_add_f32 v[8:9], v[8:9], 1.0 op_sel_hi:[1,0]
	v_pk_add_f32 v[2:3], v[2:3], 1.0 op_sel_hi:[1,0]
	v_pk_add_f32 v[4:5], v[4:5], 1.0 op_sel_hi:[1,0]
	v_rcp_f32_e32 v6, v6
	v_rcp_f32_e32 v7, v7
	v_rcp_f32_e32 v8, v8
	v_rcp_f32_e32 v9, v9
	v_rcp_f32_e32 v2, v2
	v_rcp_f32_e32 v3, v3
	v_rcp_f32_e32 v4, v4
	v_rcp_f32_e32 v5, v5
	s_waitcnt vmcnt(15)
; #define GAS __attribute__((address_space(1)))
; __device__ __forceinline__ u32x4 pack8(f32x4 v0, f32x4 v1) { u32x4 w; w.x = cvt_pk_bf16(v0[0], v0[1]); w.y = cvt_pk_bf16(v0[2], v0[3]); w.z = cvt_pk_bf16(v1[0], v1[1]); w.w = cvt_pk_bf16(v1[2], v1[3]); return w; }
; __device__ __forceinline__ void unpack8(u32x4 w, f32x4& v0, f32x4& v1) { v0 = (f32x4){bflo(w.x), bfhi(w.x), bflo(w.y), bfhi(w.y)}; v1 = (f32x4){bflo(w.z), bfhi(w.z), bflo(w.w), bfhi(w.w)}; }
; #define GAS __attribute__((address_space(1)))
;     __device__ __forceinline__ void operator()(const f32x4 (&acc)[2][2][4][2], const Unit& u, int wr, int wc, int fr, int fq) const {
;     ...
;             for (int m = 0; m < 4; ++m) { const size_t off = (size_t)(ai * HALF + m * 16) * 1024;
; #pragma unroll
;                 for (int bj = 0; bj < 2; ++bj) { f32x4 z0, z1; unpack8(*(const GAS u32x4*)(zb + off + bj * HALF), z0, z1);
;                     const f32x4 v0 = z0 * sigmoid4(acc[ai][bj][m][0] + bv[bj][0]), v1 = z1 * sigmoid4(acc[ai][bj][m][1] + bv[bj][1]);
;                     *(GAS u32x4*)(sob + off + bj * HALF) = pack8(v0, v1); } }
	v_mov_b32_e32 v102, v226
	v_mov_b32_e32 v103, v227
	v_mov_b32_e32 v104, v228
	v_mov_b32_e32 v105, v229
	v_lshlrev_b32_e32 v106, 16, v102
	v_and_b32_e32 v107, 0xffff0000, v102
	v_lshlrev_b32_e32 v108, 16, v104
	v_and_b32_e32 v109, 0xffff0000, v104
	v_lshlrev_b32_e32 v102, 16, v103
	v_and_b32_e32 v103, 0xffff0000, v103
	v_lshlrev_b32_e32 v104, 16, v105
	v_and_b32_e32 v105, 0xffff0000, v105
	v_pk_mul_f32 v[94:95], v[94:95], v[106:107]
	v_pk_mul_f32 v[90:91], v[90:91], v[108:109]
	v_pk_mul_f32 v[96:97], v[96:97], v[102:103]
	v_pk_mul_f32 v[102:103], v[92:93], v[104:105]
	v_cvt_pk_bf16_f32 v92, v94, v95
	v_cvt_pk_bf16_f32 v94, v90, v91
	v_add_co_u32_e32 v90, vcc, s93, v160
	v_cvt_pk_bf16_f32 v93, v96, v97
	v_cvt_pk_bf16_f32 v95, v102, v103
	v_addc_co_u32_e32 v91, vcc, 0, v161, vcc
	global_store_dwordx4 v[90:91], v[92:95], off
	s_waitcnt vmcnt(15)
	v_mov_b32_e32 v92, v230
	v_mov_b32_e32 v93, v231
	v_mov_b32_e32 v94, v232
	v_mov_b32_e32 v95, v233
	v_lshlrev_b32_e32 v96, 16, v92
	v_and_b32_e32 v97, 0xffff0000, v92
	v_lshlrev_b32_e32 v92, 16, v93
	v_and_b32_e32 v93, 0xffff0000, v93
	v_lshlrev_b32_e32 v100, 16, v94
	v_and_b32_e32 v101, 0xffff0000, v94
	v_lshlrev_b32_e32 v94, 16, v95
	v_and_b32_e32 v95, 0xffff0000, v95
	v_pk_mul_f32 v[88:89], v[88:89], v[92:93]
	v_pk_mul_f32 v[86:87], v[86:87], v[96:97]
	v_pk_mul_f32 v[92:93], v[84:85], v[94:95]
	v_pk_mul_f32 v[84:85], v[82:83], v[100:101]
	v_cvt_pk_bf16_f32 v82, v86, v87
	v_cvt_pk_bf16_f32 v83, v88, v89
	v_cvt_pk_bf16_f32 v84, v84, v85
	v_cvt_pk_bf16_f32 v85, v92, v93
	global_store_dwordx4 v[90:91], v[82:85], off offset:256
	s_nop 1
	v_add_co_u32_e32 v82, vcc, s49, v162
	s_nop 1
	v_addc_co_u32_e32 v83, vcc, 0, v163, vcc
	s_waitcnt vmcnt(15)
	v_mov_b32_e32 v84, v234
	v_mov_b32_e32 v85, v235
	v_mov_b32_e32 v86, v236
	v_mov_b32_e32 v87, v237
	v_lshlrev_b32_e32 v88, 16, v84
	v_and_b32_e32 v89, 0xffff0000, v84
	v_lshlrev_b32_e32 v90, 16, v86
	v_and_b32_e32 v91, 0xffff0000, v86
	v_lshlrev_b32_e32 v84, 16, v85
	v_and_b32_e32 v85, 0xffff0000, v85
	v_lshlrev_b32_e32 v86, 16, v87
	v_and_b32_e32 v87, 0xffff0000, v87
	v_pk_mul_f32 v[78:79], v[78:79], v[88:89]
	v_pk_mul_f32 v[74:75], v[74:75], v[90:91]
	v_pk_mul_f32 v[80:81], v[80:81], v[84:85]
	v_pk_mul_f32 v[84:85], v[76:77], v[86:87]
	v_cvt_pk_bf16_f32 v76, v78, v79
	v_cvt_pk_bf16_f32 v78, v74, v75
	v_add_co_u32_e32 v74, vcc, s49, v160
	v_cvt_pk_bf16_f32 v77, v80, v81
	v_cvt_pk_bf16_f32 v79, v84, v85
	v_addc_co_u32_e32 v75, vcc, 0, v161, vcc
	global_store_dwordx4 v[74:75], v[76:79], off
	s_waitcnt vmcnt(15)
	v_mov_b32_e32 v76, v238
	v_mov_b32_e32 v77, v239
	v_mov_b32_e32 v78, v240
	v_mov_b32_e32 v79, v241
	v_lshlrev_b32_e32 v80, 16, v76
	v_and_b32_e32 v81, 0xffff0000, v76
	v_lshlrev_b32_e32 v76, 16, v77
	v_and_b32_e32 v77, 0xffff0000, v77
	v_lshlrev_b32_e32 v82, 16, v78
	v_and_b32_e32 v83, 0xffff0000, v78
	v_lshlrev_b32_e32 v78, 16, v79
	v_and_b32_e32 v79, 0xffff0000, v79
	v_pk_mul_f32 v[72:73], v[72:73], v[76:77]
	v_pk_mul_f32 v[70:71], v[70:71], v[80:81]
	v_pk_mul_f32 v[76:77], v[68:69], v[78:79]
	v_pk_mul_f32 v[68:69], v[66:67], v[82:83]
	v_cvt_pk_bf16_f32 v66, v70, v71
	v_cvt_pk_bf16_f32 v67, v72, v73
	v_cvt_pk_bf16_f32 v68, v68, v69
	v_cvt_pk_bf16_f32 v69, v76, v77
	global_store_dwordx4 v[74:75], v[66:69], off offset:256
	s_nop 1
	v_add_co_u32_e32 v66, vcc, s50, v162
	s_nop 1
	v_addc_co_u32_e32 v67, vcc, 0, v163, vcc
	s_waitcnt vmcnt(15)
	v_mov_b32_e32 v68, v184
	v_mov_b32_e32 v69, v185
	v_mov_b32_e32 v70, v186
	v_mov_b32_e32 v71, v187
	v_lshlrev_b32_e32 v72, 16, v68
	v_and_b32_e32 v73, 0xffff0000, v68
	v_lshlrev_b32_e32 v74, 16, v70
	v_and_b32_e32 v75, 0xffff0000, v70
	v_lshlrev_b32_e32 v68, 16, v69
	v_and_b32_e32 v69, 0xffff0000, v69
	v_lshlrev_b32_e32 v70, 16, v71
	v_and_b32_e32 v71, 0xffff0000, v71
	v_pk_mul_f32 v[62:63], v[62:63], v[72:73]
	v_pk_mul_f32 v[58:59], v[58:59], v[74:75]
	v_pk_mul_f32 v[64:65], v[64:65], v[68:69]
	v_pk_mul_f32 v[68:69], v[60:61], v[70:71]
	v_cvt_pk_bf16_f32 v60, v62, v63
	v_cvt_pk_bf16_f32 v62, v58, v59
	v_add_co_u32_e32 v58, vcc, s50, v160
	v_cvt_pk_bf16_f32 v61, v64, v65
	v_cvt_pk_bf16_f32 v63, v68, v69
	v_addc_co_u32_e32 v59, vcc, 0, v161, vcc
	global_store_dwordx4 v[58:59], v[60:63], off
	s_waitcnt vmcnt(14)
; #define GAS __attribute__((address_space(1)))
; __device__ __forceinline__ u32x4 pack8(f32x4 v0, f32x4 v1) { u32x4 w; w.x = cvt_pk_bf16(v0[0], v0[1]); w.y = cvt_pk_bf16(v0[2], v0[3]); w.z = cvt_pk_bf16(v1[0], v1[1]); w.w = cvt_pk_bf16(v1[2], v1[3]); return w; }
; __device__ __forceinline__ void unpack8(u32x4 w, f32x4& v0, f32x4& v1) { v0 = (f32x4){bflo(w.x), bfhi(w.x), bflo(w.y), bfhi(w.y)}; v1 = (f32x4){bflo(w.z), bfhi(w.z), bflo(w.w), bfhi(w.w)}; }
; #define PG8_BAR __builtin_amdgcn_s_barrier()
; #define GAS __attribute__((address_space(1)))
;     __device__ __forceinline__ void operator()(const f32x4 (&acc)[2][2][4][2], const Unit& u, int wr, int wc, int fr, int fq) const {
;     ...
;             for (int m = 0; m < 4; ++m) { const size_t off = (size_t)(ai * HALF + m * 16) * 1024;
; #pragma unroll
;                 for (int bj = 0; bj < 2; ++bj) { f32x4 z0, z1; unpack8(*(const GAS u32x4*)(zb + off + bj * HALF), z0, z1);
;                     const f32x4 v0 = z0 * sigmoid4(acc[ai][bj][m][0] + bv[bj][0]), v1 = z1 * sigmoid4(acc[ai][bj][m][1] + bv[bj][1]);
;                     *(GAS u32x4*)(sob + off + bj * HALF) = pack8(v0, v1); } }
; template <class Epi, class Sched, bool ALIGN_EPI = false, bool SP2 = false>
; __device__ __forceinline__ void gemm_phase(PG8_LAS unsigned char* lds, const Gemm g, const Sched& S, const Epi& E) {
;     ...
;         if (!has_next) break;
; #pragma unroll
;         for (int a = 0; a < 2; ++a)
; #pragma unroll
;             for (int b = 0; b < 2; ++b)
; #pragma unroll
;                 for (int m = 0; m < 4; ++m)
; #pragma unroll
;                     for (int n = 0; n < 2; ++n) acc[a][b][m][n] = (f32x4){0.f, 0.f, 0.f, 0.f};
;         cur = nxt; cA = nA; cB = nB; ++ui;
;         if constexpr (ALIGN_EPI) { if (wr == 1) PG8_BAR; }
	v_mov_b32_e32 v60, v188
	v_mov_b32_e32 v61, v189
	v_mov_b32_e32 v62, v190
	v_mov_b32_e32 v63, v191
	v_lshlrev_b32_e32 v64, 16, v60
	v_and_b32_e32 v65, 0xffff0000, v60
	v_lshlrev_b32_e32 v60, 16, v61
	v_and_b32_e32 v61, 0xffff0000, v61
	v_lshlrev_b32_e32 v66, 16, v62
	v_and_b32_e32 v67, 0xffff0000, v62
	v_lshlrev_b32_e32 v62, 16, v63
	v_and_b32_e32 v63, 0xffff0000, v63
	v_pk_mul_f32 v[56:57], v[56:57], v[60:61]
	v_pk_mul_f32 v[54:55], v[54:55], v[64:65]
	v_pk_mul_f32 v[60:61], v[52:53], v[62:63]
	v_pk_mul_f32 v[52:53], v[50:51], v[66:67]
	v_cvt_pk_bf16_f32 v50, v54, v55
	v_cvt_pk_bf16_f32 v51, v56, v57
	v_cvt_pk_bf16_f32 v52, v52, v53
	v_cvt_pk_bf16_f32 v53, v60, v61
	global_store_dwordx4 v[58:59], v[50:53], off offset:256
	s_nop 1
	v_add_co_u32_e32 v50, vcc, s51, v162
	s_nop 1
	v_addc_co_u32_e32 v51, vcc, 0, v163, vcc
	s_waitcnt vmcnt(13)
	v_mov_b32_e32 v52, v192
	v_mov_b32_e32 v53, v193
	v_mov_b32_e32 v54, v194
	v_mov_b32_e32 v55, v195
	v_lshlrev_b32_e32 v56, 16, v52
	v_and_b32_e32 v57, 0xffff0000, v52
	v_lshlrev_b32_e32 v58, 16, v54
	v_and_b32_e32 v59, 0xffff0000, v54
	v_lshlrev_b32_e32 v52, 16, v53
	v_and_b32_e32 v53, 0xffff0000, v53
	v_lshlrev_b32_e32 v54, 16, v55
	v_and_b32_e32 v55, 0xffff0000, v55
	v_pk_mul_f32 v[46:47], v[46:47], v[56:57]
	v_pk_mul_f32 v[42:43], v[42:43], v[58:59]
	v_pk_mul_f32 v[48:49], v[48:49], v[52:53]
	v_pk_mul_f32 v[52:53], v[44:45], v[54:55]
	v_cvt_pk_bf16_f32 v44, v46, v47
	v_cvt_pk_bf16_f32 v46, v42, v43
	v_add_co_u32_e32 v42, vcc, s51, v160
	v_cvt_pk_bf16_f32 v45, v48, v49
	v_cvt_pk_bf16_f32 v47, v52, v53
	v_addc_co_u32_e32 v43, vcc, 0, v161, vcc
	global_store_dwordx4 v[42:43], v[44:47], off
	s_waitcnt vmcnt(12)
	v_mov_b32_e32 v44, v196
	v_mov_b32_e32 v45, v197
	v_mov_b32_e32 v46, v198
	v_mov_b32_e32 v47, v199
	v_lshlrev_b32_e32 v48, 16, v44
	v_and_b32_e32 v49, 0xffff0000, v44
	v_lshlrev_b32_e32 v44, 16, v45
	v_and_b32_e32 v45, 0xffff0000, v45
	v_lshlrev_b32_e32 v50, 16, v46
	v_and_b32_e32 v51, 0xffff0000, v46
	v_lshlrev_b32_e32 v46, 16, v47
	v_and_b32_e32 v47, 0xffff0000, v47
	v_pk_mul_f32 v[32:33], v[32:33], v[44:45]
	v_pk_mul_f32 v[30:31], v[30:31], v[48:49]
	v_pk_mul_f32 v[44:45], v[28:29], v[46:47]
	v_pk_mul_f32 v[28:29], v[26:27], v[50:51]
	v_cvt_pk_bf16_f32 v26, v30, v31
	v_cvt_pk_bf16_f32 v27, v32, v33
	v_cvt_pk_bf16_f32 v28, v28, v29
	v_cvt_pk_bf16_f32 v29, v44, v45
	global_store_dwordx4 v[42:43], v[26:29], off offset:256
	s_nop 1
	v_add_co_u32_e32 v26, vcc, s66, v162
	s_nop 1
	v_addc_co_u32_e32 v27, vcc, 0, v163, vcc
	s_waitcnt vmcnt(11)
	v_mov_b32_e32 v28, v200
	v_mov_b32_e32 v29, v201
	v_mov_b32_e32 v30, v202
	v_mov_b32_e32 v31, v203
	v_lshlrev_b32_e32 v32, 16, v28
	v_and_b32_e32 v33, 0xffff0000, v28
	v_lshlrev_b32_e32 v28, 16, v29
	v_and_b32_e32 v29, 0xffff0000, v29
	v_lshlrev_b32_e32 v42, 16, v30
	v_and_b32_e32 v43, 0xffff0000, v30
	v_lshlrev_b32_e32 v30, 16, v31
	v_and_b32_e32 v31, 0xffff0000, v31
	v_pk_mul_f32 v[18:19], v[18:19], v[32:33]
	v_pk_mul_f32 v[20:21], v[20:21], v[28:29]
	v_pk_mul_f32 v[28:29], v[12:13], v[30:31]
	v_pk_mul_f32 v[12:13], v[10:11], v[42:43]
	v_cvt_pk_bf16_f32 v10, v18, v19
	v_add_co_u32_e32 v18, vcc, s66, v160
	v_cvt_pk_bf16_f32 v11, v20, v21
	v_cvt_pk_bf16_f32 v12, v12, v13
	v_cvt_pk_bf16_f32 v13, v28, v29
	v_addc_co_u32_e32 v19, vcc, 0, v161, vcc
	global_store_dwordx4 v[18:19], v[10:13], off
	s_andn2_b64 vcc, exec, s[18:19]
	s_waitcnt vmcnt(10)
	v_mov_b32_e32 v10, v222
	v_mov_b32_e32 v11, v223
	v_mov_b32_e32 v12, v224
	v_mov_b32_e32 v13, v225
	v_lshlrev_b32_e32 v20, 16, v10
	v_and_b32_e32 v21, 0xffff0000, v10
	v_lshlrev_b32_e32 v10, 16, v11
	v_and_b32_e32 v11, 0xffff0000, v11
	v_lshlrev_b32_e32 v26, 16, v12
	v_and_b32_e32 v27, 0xffff0000, v12
	v_lshlrev_b32_e32 v12, 16, v13
	v_and_b32_e32 v13, 0xffff0000, v13
	v_pk_mul_f32 v[8:9], v[8:9], v[10:11]
	v_pk_mul_f32 v[6:7], v[6:7], v[20:21]
	v_pk_mul_f32 v[10:11], v[4:5], v[12:13]
	v_pk_mul_f32 v[4:5], v[2:3], v[26:27]
	v_cvt_pk_bf16_f32 v2, v6, v7
	v_cvt_pk_bf16_f32 v3, v8, v9
	v_cvt_pk_bf16_f32 v4, v4, v5
	v_cvt_pk_bf16_f32 v5, v10, v11
	global_store_dwordx4 v[18:19], v[2:5], off offset:256
	s_cbranch_vccnz .LBB0_923
	s_andn2_b64 vcc, exec, s[6:7]
	s_cbranch_vccnz .LBB0_922
	s_barrier
	s_branch .LBB0_922

; #define PG8_STAGE(bufoff, gbase, voff) do { _Pragma("unroll") for (int _i = 0; _i < 2; ++_i) \
;         __builtin_amdgcn_global_load_lds((const unsigned*)((const char*)(gbase) + (voff)[_i]), (PG8_LAS unsigned*)(lds + (bufoff) + ldsw + _i * 8192), 16, 0, AUX_A); } while (0)
; #define PG8_STAGEB(bufoff, gbase, voff) do { _Pragma("unroll") for (int _i = 0; _i < 2; ++_i) \
;         __builtin_amdgcn_global_load_lds((const unsigned*)((const char*)(gbase) + (voff)[_i]), (PG8_LAS unsigned*)(lds + (bufoff) + ldsw + _i * 8192), 16, 0, AUX_B); } while (0)
; #define PG8_LDA(dst, b, h) do { _Pragma("unroll") for (int m = 0; m < 4; ++m) _Pragma("unroll") for (int k = 0; k < 2; ++k) dst[m][k] = *(const PG8_LAS bf16x8*)(lds + PG8_SA(b, h) + aoff + m * 2048 + k * 1024); } while (0)
; #define PG8_LDB(dst, b, h) do { _Pragma("unroll") for (int n = 0; n < 2; ++n) _Pragma("unroll") for (int k = 0; k < 2; ++k) dst[n][k] = *(const PG8_LAS bf16x8*)(lds + PG8_SB(b, h) + boff + n * 2048 + k * 1024); } while (0)
; #define PG8_WAIT_V(n) asm volatile("s_waitcnt vmcnt(" #n ")" ::: "memory")
; #define PG8_WAIT_L(n) asm volatile("s_waitcnt lgkmcnt(" #n ")" ::: "memory")
; #define PG8_BAR __builtin_amdgcn_s_barrier()
; template <class Epi, class Sched, bool ALIGN_EPI = false, bool SP2 = false>
; __device__ __forceinline__ void gemm_phase(PG8_LAS unsigned char* lds, const Gemm g, const Sched& S, const Epi& E) {
;     ...
;         for (int t = 0; t < nt; t += 2) {
;             const bool last = (t == nt - 2);
;             const char* a1 = PG8_KP(cA, t + 1, rot, nt);
;             const char* a2 = last ? nAr : PG8_KP(cA, t + 2, rot, nt); const char* b2 = last ? nBr : PG8_KP(cB, t + 2, rot, nt);
;             const char* a3 = a2 + kstep; const char* b3 = b2 + kstep;
;             if (last && has_next) S.a_ready(nxt);
;             if constexpr (SP2) {
;             PG8_LDB(B0, 0, 0); PG8_LDB(B1, 0, 1); PG8_SCHED; PG8_LDA(At, 0, 0); PG8_STAGE(PG8_SA(1, 1), a1 + hstep, voffA);
;             PG8_WAIT_V(8); PG8_WAIT_L(0); PG8_BAR; PG8_MMA(0, 0, At, B0); PG8_MMA(0, 1, At, B1); PG8_BAR; PG8_SCHED;
;             PG8_LDA(At, 0, 1); PG8_STAGEB(PG8_SB(0, 0), b2, voffB); PG8_STAGEB(PG8_SB(0, 1), b2 + hstep, voffB); PG8_STAGE(PG8_SA(0, 0), a2, voffA);
;             PG8_WAIT_V(8); PG8_WAIT_L(0); PG8_BAR; PG8_MMA(1, 0, At, B0); PG8_MMA(1, 1, At, B1); PG8_BAR; PG8_SCHED;
.Lpk_1067:
	s_add_i32 s81, s29, 2
	s_cmp_lt_u32 s29, 14
	s_cselect_b32 s0, 0, -16
	s_add_i32 s0, s81, s0
	s_ashr_i32 s1, s0, 31
	s_lshl_b64 s[0:1], s[0:1], 7
	s_add_u32 s2, s52, s0
	s_addc_u32 s46, s53, s1
	s_add_u32 s0, s42, s0
	s_addc_u32 s1, s43, s1
	s_cmp_eq_u32 s29, 14
	s_cselect_b32 s59, s15, s46
	s_cselect_b32 s58, s17, s2
	s_cselect_b32 s61, s92, s1
	s_cselect_b32 s60, s93, s0
	s_add_i32 s2, 0, 0x10000
	s_add_i32 s94, s2, s70
	s_add_i32 s46, 0, 0x14000
	s_add_i32 m0, s71, 0xc000
	s_add_i32 s84, s71, 0xe000
	s_add_i32 s95, s94, 0x2000
	s_add_u32 s62, s60, 0x40000
	v_add_u32_e32 v148, s2, v99
	s_addc_u32 s63, s61, 0
	s_add_i32 s96, s46, s70
	ds_read_b128 v[152:155], v148
	ds_read_b128 v[156:159], v148 offset:1024
	ds_read_b128 v[160:163], v148 offset:2048
	ds_read_b128 v[164:167], v148 offset:3072
	v_add_u32_e32 v148, s46, v99
	s_add_i32 s97, s96, 0x2000
	s_add_i32 vcc_lo, 0, 0x18000
	s_add_i32 vcc_hi, 0, 0x1c000
	ds_read_b128 v[180:183], v148
	ds_read_b128 v[184:187], v148 offset:1024
	ds_read_b128 v[188:191], v148 offset:2048
	ds_read_b128 v[192:195], v148 offset:3072
	s_add_u32 s56, s58, 0x40000
	s_addc_u32 s57, s59, 0
	s_add_i32 s1, vcc_lo, s70
	s_add_i32 s0, s1, 0x2000
	s_add_u32 s54, s60, 0x40080
	s_addc_u32 s55, s61, 0
	s_add_i32 s47, vcc_hi, s70
	s_add_i32 s46, s47, 0x2000
	s_cmp_gt_u32 s29, 13
	ds_read_b128 v[196:199], v151
	ds_read_b128 v[200:203], v151 offset:1024
	ds_read_b128 v[222:225], v151 offset:2048
	ds_read_b128 v[226:229], v151 offset:3072
	ds_read_b128 v[230:233], v151 offset:4096
	ds_read_b128 v[234:237], v151 offset:5120
	ds_read_b128 v[238:241], v151 offset:6144
	ds_read_b128 v[242:245], v151 offset:7168
	global_load_lds_dwordx4 v[146:147], off
	s_mov_b32 m0, s84
	s_nop 0
	global_load_lds_dwordx4 v[144:145], off
	s_waitcnt vmcnt(8)
	s_waitcnt lgkmcnt(0)
	s_setprio 1
	s_barrier
	v_mfma_f32_16x16x32_bf16 v[128:131], v[152:155], v[196:199], 0
	v_mfma_f32_16x16x32_bf16 v[128:131], v[156:159], v[200:203], v[128:131]
	v_mfma_f32_16x16x32_bf16 v[124:127], v[160:163], v[196:199], 0
	v_mfma_f32_16x16x32_bf16 v[124:127], v[164:167], v[200:203], v[124:127]
	v_mfma_f32_16x16x32_bf16 v[112:115], v[152:155], v[222:225], 0
	v_mfma_f32_16x16x32_bf16 v[112:115], v[156:159], v[226:229], v[112:115]
	v_mfma_f32_16x16x32_bf16 v[108:111], v[160:163], v[222:225], 0
	v_mfma_f32_16x16x32_bf16 v[108:111], v[164:167], v[226:229], v[108:111]
	v_mfma_f32_16x16x32_bf16 v[94:97], v[152:155], v[230:233], 0
	v_mfma_f32_16x16x32_bf16 v[94:97], v[156:159], v[234:237], v[94:97]
	v_mfma_f32_16x16x32_bf16 v[90:93], v[160:163], v[230:233], 0
	v_mfma_f32_16x16x32_bf16 v[90:93], v[164:167], v[234:237], v[90:93]
	v_mfma_f32_16x16x32_bf16 v[78:81], v[152:155], v[238:241], 0
	v_mfma_f32_16x16x32_bf16 v[78:81], v[156:159], v[242:245], v[78:81]
	v_mfma_f32_16x16x32_bf16 v[74:77], v[160:163], v[238:241], 0
	v_mfma_f32_16x16x32_bf16 v[74:77], v[164:167], v[242:245], v[74:77]
	s_setprio 0
	s_setprio 1
	v_mfma_f32_16x16x32_bf16 v[120:123], v[180:183], v[196:199], 0
	v_mfma_f32_16x16x32_bf16 v[120:123], v[184:187], v[200:203], v[120:123]
	v_mfma_f32_16x16x32_bf16 v[116:119], v[188:191], v[196:199], 0
	v_mfma_f32_16x16x32_bf16 v[116:119], v[192:195], v[200:203], v[116:119]
	v_mfma_f32_16x16x32_bf16 v[104:107], v[180:183], v[222:225], 0
	v_mfma_f32_16x16x32_bf16 v[104:107], v[184:187], v[226:229], v[104:107]
	v_mfma_f32_16x16x32_bf16 v[100:103], v[188:191], v[222:225], 0
	v_mfma_f32_16x16x32_bf16 v[100:103], v[192:195], v[226:229], v[100:103]
	v_mfma_f32_16x16x32_bf16 v[86:89], v[180:183], v[230:233], 0
	v_mfma_f32_16x16x32_bf16 v[86:89], v[184:187], v[234:237], v[86:89]
	v_mfma_f32_16x16x32_bf16 v[82:85], v[188:191], v[230:233], 0
	v_mfma_f32_16x16x32_bf16 v[82:85], v[192:195], v[234:237], v[82:85]
	v_mfma_f32_16x16x32_bf16 v[70:73], v[180:183], v[238:241], 0
	v_mfma_f32_16x16x32_bf16 v[70:73], v[184:187], v[242:245], v[70:73]
	s_setprio 2
	s_barrier
	v_mfma_f32_16x16x32_bf16 v[66:69], v[188:191], v[238:241], 0
	v_mfma_f32_16x16x32_bf16 v[66:69], v[192:195], v[242:245], v[66:69]
	s_setprio 0
	s_mov_b32 m0, s94
	v_lshl_add_u64 v[148:149], s[60:61], 0, v[136:137]
	ds_read_b128 v[196:199], v151 offset:16384
	ds_read_b128 v[200:203], v151 offset:17408
	ds_read_b128 v[222:225], v151 offset:18432
	ds_read_b128 v[226:229], v151 offset:19456
	ds_read_b128 v[230:233], v151 offset:20480
	ds_read_b128 v[234:237], v151 offset:21504
	ds_read_b128 v[238:241], v151 offset:22528
	ds_read_b128 v[242:245], v151 offset:23552
	global_load_lds_dwordx4 v[148:149], off
	v_lshl_add_u64 v[168:169], s[60:61], 0, v[132:133]
	s_mov_b32 m0, s95
	v_lshl_add_u64 v[172:173], s[62:63], 0, v[136:137]
	global_load_lds_dwordx4 v[168:169], off
	s_mov_b32 m0, s96
	v_lshl_add_u64 v[212:213], s[58:59], 0, v[134:135]
	global_load_lds_dwordx4 v[172:173], off
	v_lshl_add_u64 v[172:173], s[62:63], 0, v[132:133]
	s_mov_b32 m0, s97
	s_nop 0
	global_load_lds_dwordx4 v[172:173], off
	v_lshl_add_u64 v[172:173], s[58:59], 0, v[138:139]
	s_mov_b32 m0, s71
	s_nop 0
	global_load_lds_dwordx4 v[172:173], off
	s_mov_b32 m0, s75
	s_nop 0
	global_load_lds_dwordx4 v[212:213], off
	s_waitcnt vmcnt(8)
	s_waitcnt lgkmcnt(0)
	s_setprio 1
	s_barrier
; #define PG8_STAGE(bufoff, gbase, voff) do { _Pragma("unroll") for (int _i = 0; _i < 2; ++_i) \
;         __builtin_amdgcn_global_load_lds((const unsigned*)((const char*)(gbase) + (voff)[_i]), (PG8_LAS unsigned*)(lds + (bufoff) + ldsw + _i * 8192), 16, 0, AUX_A); } while (0)
; #define PG8_STAGEB(bufoff, gbase, voff) do { _Pragma("unroll") for (int _i = 0; _i < 2; ++_i) \
;         __builtin_amdgcn_global_load_lds((const unsigned*)((const char*)(gbase) + (voff)[_i]), (PG8_LAS unsigned*)(lds + (bufoff) + ldsw + _i * 8192), 16, 0, AUX_B); } while (0)
; #define PG8_LDA(dst, b, h) do { _Pragma("unroll") for (int m = 0; m < 4; ++m) _Pragma("unroll") for (int k = 0; k < 2; ++k) dst[m][k] = *(const PG8_LAS bf16x8*)(lds + PG8_SA(b, h) + aoff + m * 2048 + k * 1024); } while (0)
; #define PG8_LDB(dst, b, h) do { _Pragma("unroll") for (int n = 0; n < 2; ++n) _Pragma("unroll") for (int k = 0; k < 2; ++k) dst[n][k] = *(const PG8_LAS bf16x8*)(lds + PG8_SB(b, h) + boff + n * 2048 + k * 1024); } while (0)
; #define PG8_MMA(ai, bj, At, Bt) do { __builtin_amdgcn_s_setprio(1); _Pragma("unroll") for (int m = 0; m < 4; ++m) _Pragma("unroll") for (int n = 0; n < 2; ++n) _Pragma("unroll") for (int k = 0; k < 2; ++k) \
;         acc[ai][bj][m][n] = __builtin_amdgcn_mfma_f32_16x16x32_bf16(Bt[n][k], At[m][k], acc[ai][bj][m][n], 0, 0, 0); __builtin_amdgcn_s_setprio(0); } while (0)
; template <class Epi, class Sched, bool ALIGN_EPI = false, bool SP2 = false>
; __device__ __forceinline__ void gemm_phase(PG8_LAS unsigned char* lds, const Gemm g, const Sched& S, const Epi& E) {
;     ...
;             if constexpr (SP2) {
;             PG8_LDB(B0, 0, 0); PG8_LDB(B1, 0, 1); PG8_SCHED; PG8_LDA(At, 0, 0); PG8_STAGE(PG8_SA(1, 1), a1 + hstep, voffA);
;             PG8_WAIT_V(8); PG8_WAIT_L(0); PG8_BAR; PG8_MMA(0, 0, At, B0); PG8_MMA(0, 1, At, B1); PG8_BAR; PG8_SCHED;
;             PG8_LDA(At, 0, 1); PG8_STAGEB(PG8_SB(0, 0), b2, voffB); PG8_STAGEB(PG8_SB(0, 1), b2 + hstep, voffB); PG8_STAGE(PG8_SA(0, 0), a2, voffA);
;             PG8_WAIT_V(8); PG8_WAIT_L(0); PG8_BAR; PG8_MMA(1, 0, At, B0); PG8_MMA(1, 1, At, B1); PG8_BAR; PG8_SCHED;
;             PG8_LDB(B0, 1, 0); PG8_LDB(B1, 1, 1); PG8_SCHED; PG8_LDA(At, 1, 0); PG8_STAGE(PG8_SA(0, 1), a2 + hstep, voffA);
;             PG8_WAIT_V(8); PG8_WAIT_L(0); PG8_BAR; PG8_MMA(0, 0, At, B0); PG8_MMA(0, 1, At, B1); PG8_BAR; PG8_SCHED;
	v_mfma_f32_16x16x32_bf16 v[62:65], v[152:155], v[196:199], 0
	v_mfma_f32_16x16x32_bf16 v[62:65], v[156:159], v[200:203], v[62:65]
	v_mfma_f32_16x16x32_bf16 v[58:61], v[160:163], v[196:199], 0
	v_mfma_f32_16x16x32_bf16 v[58:61], v[164:167], v[200:203], v[58:61]
	v_mfma_f32_16x16x32_bf16 v[46:49], v[152:155], v[222:225], 0
	v_mfma_f32_16x16x32_bf16 v[46:49], v[156:159], v[226:229], v[46:49]
	v_mfma_f32_16x16x32_bf16 v[42:45], v[160:163], v[222:225], 0
	v_mfma_f32_16x16x32_bf16 v[42:45], v[164:167], v[226:229], v[42:45]
	v_mfma_f32_16x16x32_bf16 v[30:33], v[152:155], v[230:233], 0
	v_mfma_f32_16x16x32_bf16 v[30:33], v[156:159], v[234:237], v[30:33]
	v_mfma_f32_16x16x32_bf16 v[26:29], v[160:163], v[230:233], 0
	v_mfma_f32_16x16x32_bf16 v[26:29], v[164:167], v[234:237], v[26:29]
	v_mfma_f32_16x16x32_bf16 v[14:17], v[152:155], v[238:241], 0
	v_mfma_f32_16x16x32_bf16 v[14:17], v[156:159], v[242:245], v[14:17]
	v_mfma_f32_16x16x32_bf16 v[10:13], v[160:163], v[238:241], 0
	v_mfma_f32_16x16x32_bf16 v[10:13], v[164:167], v[242:245], v[10:13]
	s_setprio 0
	s_setprio 1
	v_mfma_f32_16x16x32_bf16 v[54:57], v[180:183], v[196:199], 0
	v_mfma_f32_16x16x32_bf16 v[54:57], v[184:187], v[200:203], v[54:57]
	v_mfma_f32_16x16x32_bf16 v[50:53], v[188:191], v[196:199], 0
	v_mfma_f32_16x16x32_bf16 v[50:53], v[192:195], v[200:203], v[50:53]
	v_mfma_f32_16x16x32_bf16 v[38:41], v[180:183], v[222:225], 0
	v_mfma_f32_16x16x32_bf16 v[38:41], v[184:187], v[226:229], v[38:41]
	v_mfma_f32_16x16x32_bf16 v[34:37], v[188:191], v[222:225], 0
	v_mfma_f32_16x16x32_bf16 v[34:37], v[192:195], v[226:229], v[34:37]
	v_mfma_f32_16x16x32_bf16 v[22:25], v[180:183], v[230:233], 0
	v_mfma_f32_16x16x32_bf16 v[22:25], v[184:187], v[234:237], v[22:25]
	v_mfma_f32_16x16x32_bf16 v[18:21], v[188:191], v[230:233], 0
	v_mfma_f32_16x16x32_bf16 v[18:21], v[192:195], v[234:237], v[18:21]
	v_mfma_f32_16x16x32_bf16 v[6:9], v[180:183], v[238:241], 0
	v_mfma_f32_16x16x32_bf16 v[6:9], v[184:187], v[242:245], v[6:9]
	s_setprio 2
	s_barrier
	v_mfma_f32_16x16x32_bf16 v[2:5], v[188:191], v[238:241], 0
	v_mfma_f32_16x16x32_bf16 v[2:5], v[192:195], v[242:245], v[2:5]
	s_setprio 0
	v_add_u32_e32 v164, vcc_lo, v99
	v_add_u32_e32 v192, vcc_hi, v99
	ds_read_b128 v[152:155], v164
	ds_read_b128 v[156:159], v164 offset:1024
	ds_read_b128 v[160:163], v164 offset:2048
	ds_read_b128 v[164:167], v164 offset:3072
	ds_read_b128 v[180:183], v192
	ds_read_b128 v[184:187], v192 offset:1024
	ds_read_b128 v[188:191], v192 offset:2048
	ds_read_b128 v[192:195], v192 offset:3072
	s_mov_b32 m0, s78
	v_lshl_add_u64 v[246:247], s[56:57], 0, v[138:139]
	ds_read_b128 v[196:199], v151 offset:32768
	ds_read_b128 v[200:203], v151 offset:33792
	ds_read_b128 v[222:225], v151 offset:34816
	ds_read_b128 v[226:229], v151 offset:35840
	ds_read_b128 v[230:233], v151 offset:36864
	ds_read_b128 v[234:237], v151 offset:37888
	ds_read_b128 v[238:241], v151 offset:38912
	ds_read_b128 v[242:245], v151 offset:39936
	global_load_lds_dwordx4 v[246:247], off
	v_lshl_add_u64 v[246:247], s[56:57], 0, v[134:135]
	s_mov_b32 m0, s82
	s_nop 0
	global_load_lds_dwordx4 v[246:247], off
	s_waitcnt vmcnt(8)
	s_waitcnt lgkmcnt(0)
	s_setprio 1
	s_barrier
	v_mfma_f32_16x16x32_bf16 v[128:131], v[152:155], v[196:199], v[128:131]
	v_mfma_f32_16x16x32_bf16 v[128:131], v[156:159], v[200:203], v[128:131]
	v_mfma_f32_16x16x32_bf16 v[124:127], v[160:163], v[196:199], v[124:127]
	v_mfma_f32_16x16x32_bf16 v[124:127], v[164:167], v[200:203], v[124:127]
	v_mfma_f32_16x16x32_bf16 v[112:115], v[152:155], v[222:225], v[112:115]
	v_mfma_f32_16x16x32_bf16 v[112:115], v[156:159], v[226:229], v[112:115]
	v_mfma_f32_16x16x32_bf16 v[108:111], v[160:163], v[222:225], v[108:111]
	v_mfma_f32_16x16x32_bf16 v[108:111], v[164:167], v[226:229], v[108:111]
	v_mfma_f32_16x16x32_bf16 v[94:97], v[152:155], v[230:233], v[94:97]
	v_mfma_f32_16x16x32_bf16 v[94:97], v[156:159], v[234:237], v[94:97]
	v_mfma_f32_16x16x32_bf16 v[90:93], v[160:163], v[230:233], v[90:93]
	v_mfma_f32_16x16x32_bf16 v[90:93], v[164:167], v[234:237], v[90:93]
	v_mfma_f32_16x16x32_bf16 v[78:81], v[152:155], v[238:241], v[78:81]
	v_mfma_f32_16x16x32_bf16 v[78:81], v[156:159], v[242:245], v[78:81]
	v_mfma_f32_16x16x32_bf16 v[74:77], v[160:163], v[238:241], v[74:77]
	v_mfma_f32_16x16x32_bf16 v[74:77], v[164:167], v[242:245], v[74:77]
	s_setprio 0
	s_setprio 1
	v_mfma_f32_16x16x32_bf16 v[120:123], v[180:183], v[196:199], v[120:123]
	v_mfma_f32_16x16x32_bf16 v[120:123], v[184:187], v[200:203], v[120:123]
	v_mfma_f32_16x16x32_bf16 v[116:119], v[188:191], v[196:199], v[116:119]
	v_mfma_f32_16x16x32_bf16 v[116:119], v[192:195], v[200:203], v[116:119]
	v_mfma_f32_16x16x32_bf16 v[104:107], v[180:183], v[222:225], v[104:107]
	v_mfma_f32_16x16x32_bf16 v[104:107], v[184:187], v[226:229], v[104:107]
	v_mfma_f32_16x16x32_bf16 v[100:103], v[188:191], v[222:225], v[100:103]
	v_mfma_f32_16x16x32_bf16 v[100:103], v[192:195], v[226:229], v[100:103]
	v_mfma_f32_16x16x32_bf16 v[86:89], v[180:183], v[230:233], v[86:89]
	v_mfma_f32_16x16x32_bf16 v[86:89], v[184:187], v[234:237], v[86:89]
	v_mfma_f32_16x16x32_bf16 v[82:85], v[188:191], v[230:233], v[82:85]
	v_mfma_f32_16x16x32_bf16 v[82:85], v[192:195], v[234:237], v[82:85]
	v_mfma_f32_16x16x32_bf16 v[70:73], v[180:183], v[238:241], v[70:73]
	v_mfma_f32_16x16x32_bf16 v[70:73], v[184:187], v[242:245], v[70:73]
	s_setprio 2
	s_barrier
; #define PG8_STAGE(bufoff, gbase, voff) do { _Pragma("unroll") for (int _i = 0; _i < 2; ++_i) \
;         __builtin_amdgcn_global_load_lds((const unsigned*)((const char*)(gbase) + (voff)[_i]), (PG8_LAS unsigned*)(lds + (bufoff) + ldsw + _i * 8192), 16, 0, AUX_A); } while (0)
; #define PG8_STAGEB(bufoff, gbase, voff) do { _Pragma("unroll") for (int _i = 0; _i < 2; ++_i) \
;         __builtin_amdgcn_global_load_lds((const unsigned*)((const char*)(gbase) + (voff)[_i]), (PG8_LAS unsigned*)(lds + (bufoff) + ldsw + _i * 8192), 16, 0, AUX_B); } while (0)
; #define PG8_LDA(dst, b, h) do { _Pragma("unroll") for (int m = 0; m < 4; ++m) _Pragma("unroll") for (int k = 0; k < 2; ++k) dst[m][k] = *(const PG8_LAS bf16x8*)(lds + PG8_SA(b, h) + aoff + m * 2048 + k * 1024); } while (0)
; #define PG8_LDB(dst, b, h) do { _Pragma("unroll") for (int n = 0; n < 2; ++n) _Pragma("unroll") for (int k = 0; k < 2; ++k) dst[n][k] = *(const PG8_LAS bf16x8*)(lds + PG8_SB(b, h) + boff + n * 2048 + k * 1024); } while (0)
; #define PG8_MMA(ai, bj, At, Bt) do { __builtin_amdgcn_s_setprio(1); _Pragma("unroll") for (int m = 0; m < 4; ++m) _Pragma("unroll") for (int n = 0; n < 2; ++n) _Pragma("unroll") for (int k = 0; k < 2; ++k) \
;         acc[ai][bj][m][n] = __builtin_amdgcn_mfma_f32_16x16x32_bf16(Bt[n][k], At[m][k], acc[ai][bj][m][n], 0, 0, 0); __builtin_amdgcn_s_setprio(0); } while (0)
; #define PG8_WAIT_V(n) asm volatile("s_waitcnt vmcnt(" #n ")" ::: "memory")
; #define PG8_WAIT_L(n) asm volatile("s_waitcnt lgkmcnt(" #n ")" ::: "memory")
; #define PG8_BAR __builtin_amdgcn_s_barrier()
; #define PG8_SCHED __builtin_amdgcn_sched_barrier(0)
; template <class Epi, class Sched, bool ALIGN_EPI = false, bool SP2 = false>
; __device__ __forceinline__ void gemm_phase(PG8_LAS unsigned char* lds, const Gemm g, const Sched& S, const Epi& E) {
;     ...
;             PG8_LDB(B0, 1, 0); PG8_LDB(B1, 1, 1); PG8_SCHED; PG8_LDA(At, 1, 0); PG8_STAGE(PG8_SA(0, 1), a2 + hstep, voffA);
;             PG8_WAIT_V(8); PG8_WAIT_L(0); PG8_BAR; PG8_MMA(0, 0, At, B0); PG8_MMA(0, 1, At, B1); PG8_BAR; PG8_SCHED;
;             PG8_LDA(At, 1, 1); PG8_STAGEB(PG8_SB(1, 0), b3, voffB); PG8_STAGEB(PG8_SB(1, 1), b3 + hstep, voffB); PG8_STAGE(PG8_SA(1, 0), a3, voffA);
;             PG8_WAIT_V(8); PG8_WAIT_L(0); PG8_BAR; PG8_MMA(1, 0, At, B0); PG8_MMA(1, 1, At, B1); PG8_BAR; PG8_SCHED;
	v_mfma_f32_16x16x32_bf16 v[66:69], v[188:191], v[238:241], v[66:69]
	v_mfma_f32_16x16x32_bf16 v[66:69], v[192:195], v[242:245], v[66:69]
	s_setprio 0
	s_mov_b32 m0, s1
	v_lshl_add_u64 v[148:149], v[148:149], 0, s[76:77]
	ds_read_b128 v[196:199], v151 offset:49152
	ds_read_b128 v[200:203], v151 offset:50176
	ds_read_b128 v[222:225], v151 offset:51200
	ds_read_b128 v[226:229], v151 offset:52224
	ds_read_b128 v[230:233], v151 offset:53248
	ds_read_b128 v[234:237], v151 offset:54272
	ds_read_b128 v[238:241], v151 offset:55296
	ds_read_b128 v[242:245], v151 offset:56320
	global_load_lds_dwordx4 v[148:149], off
	v_lshl_add_u64 v[148:149], v[168:169], 0, s[76:77]
	s_mov_b32 m0, s0
	s_nop 0
	global_load_lds_dwordx4 v[148:149], off
	v_lshl_add_u64 v[148:149], s[54:55], 0, v[136:137]
	s_mov_b32 m0, s47
	s_nop 0
	global_load_lds_dwordx4 v[148:149], off
	v_lshl_add_u64 v[148:149], s[54:55], 0, v[132:133]
	s_mov_b32 m0, s46
	s_nop 0
	global_load_lds_dwordx4 v[148:149], off
	v_lshl_add_u64 v[148:149], v[172:173], 0, s[76:77]
	s_mov_b32 m0, s83
	s_nop 0
	global_load_lds_dwordx4 v[148:149], off
	v_lshl_add_u64 v[148:149], v[212:213], 0, s[76:77]
	s_mov_b32 m0, s88
	s_nop 0
	global_load_lds_dwordx4 v[148:149], off
	s_waitcnt vmcnt(8)
	s_waitcnt lgkmcnt(0)
	s_setprio 1
	s_barrier
	v_mfma_f32_16x16x32_bf16 v[62:65], v[152:155], v[196:199], v[62:65]
	v_mfma_f32_16x16x32_bf16 v[62:65], v[156:159], v[200:203], v[62:65]
	v_mfma_f32_16x16x32_bf16 v[58:61], v[160:163], v[196:199], v[58:61]
	v_mfma_f32_16x16x32_bf16 v[58:61], v[164:167], v[200:203], v[58:61]
	v_mfma_f32_16x16x32_bf16 v[46:49], v[152:155], v[222:225], v[46:49]
	v_mfma_f32_16x16x32_bf16 v[46:49], v[156:159], v[226:229], v[46:49]
	v_mfma_f32_16x16x32_bf16 v[42:45], v[160:163], v[222:225], v[42:45]
	v_mfma_f32_16x16x32_bf16 v[42:45], v[164:167], v[226:229], v[42:45]
	v_mfma_f32_16x16x32_bf16 v[30:33], v[152:155], v[230:233], v[30:33]
	v_mfma_f32_16x16x32_bf16 v[30:33], v[156:159], v[234:237], v[30:33]
	v_mfma_f32_16x16x32_bf16 v[26:29], v[160:163], v[230:233], v[26:29]
	v_mfma_f32_16x16x32_bf16 v[26:29], v[164:167], v[234:237], v[26:29]
	v_mfma_f32_16x16x32_bf16 v[14:17], v[152:155], v[238:241], v[14:17]
	v_mfma_f32_16x16x32_bf16 v[14:17], v[156:159], v[242:245], v[14:17]
	v_mfma_f32_16x16x32_bf16 v[10:13], v[160:163], v[238:241], v[10:13]
	v_mfma_f32_16x16x32_bf16 v[10:13], v[164:167], v[242:245], v[10:13]
	s_setprio 0
	s_setprio 1
	v_mfma_f32_16x16x32_bf16 v[54:57], v[180:183], v[196:199], v[54:57]
	v_mfma_f32_16x16x32_bf16 v[54:57], v[184:187], v[200:203], v[54:57]
	v_mfma_f32_16x16x32_bf16 v[50:53], v[188:191], v[196:199], v[50:53]
	v_mfma_f32_16x16x32_bf16 v[50:53], v[192:195], v[200:203], v[50:53]
	v_mfma_f32_16x16x32_bf16 v[38:41], v[180:183], v[222:225], v[38:41]
	v_mfma_f32_16x16x32_bf16 v[38:41], v[184:187], v[226:229], v[38:41]
	v_mfma_f32_16x16x32_bf16 v[34:37], v[188:191], v[222:225], v[34:37]
	v_mfma_f32_16x16x32_bf16 v[34:37], v[192:195], v[226:229], v[34:37]
	v_mfma_f32_16x16x32_bf16 v[22:25], v[180:183], v[230:233], v[22:25]
	v_mfma_f32_16x16x32_bf16 v[22:25], v[184:187], v[234:237], v[22:25]
	v_mfma_f32_16x16x32_bf16 v[18:21], v[188:191], v[230:233], v[18:21]
	v_mfma_f32_16x16x32_bf16 v[18:21], v[192:195], v[234:237], v[18:21]
	v_mfma_f32_16x16x32_bf16 v[6:9], v[180:183], v[238:241], v[6:9]
	v_mfma_f32_16x16x32_bf16 v[6:9], v[184:187], v[242:245], v[6:9]
	s_setprio 2
	s_cbranch_scc1 .Lq4x_1067p
	s_barrier

; #define PG8_STAGE(bufoff, gbase, voff) do { _Pragma("unroll") for (int _i = 0; _i < 2; ++_i) \
;         __builtin_amdgcn_global_load_lds((const unsigned*)((const char*)(gbase) + (voff)[_i]), (PG8_LAS unsigned*)(lds + (bufoff) + ldsw + _i * 8192), 16, 0, AUX_A); } while (0)
; #define PG8_STAGEB(bufoff, gbase, voff) do { _Pragma("unroll") for (int _i = 0; _i < 2; ++_i) \
;         __builtin_amdgcn_global_load_lds((const unsigned*)((const char*)(gbase) + (voff)[_i]), (PG8_LAS unsigned*)(lds + (bufoff) + ldsw + _i * 8192), 16, 0, AUX_B); } while (0)
; #define PG8_LDA(dst, b, h) do { _Pragma("unroll") for (int m = 0; m < 4; ++m) _Pragma("unroll") for (int k = 0; k < 2; ++k) dst[m][k] = *(const PG8_LAS bf16x8*)(lds + PG8_SA(b, h) + aoff + m * 2048 + k * 1024); } while (0)
; #define PG8_LDB(dst, b, h) do { _Pragma("unroll") for (int n = 0; n < 2; ++n) _Pragma("unroll") for (int k = 0; k < 2; ++k) dst[n][k] = *(const PG8_LAS bf16x8*)(lds + PG8_SB(b, h) + boff + n * 2048 + k * 1024); } while (0)
; #define PG8_WAIT_V(n) asm volatile("s_waitcnt vmcnt(" #n ")" ::: "memory")
; #define PG8_WAIT_L(n) asm volatile("s_waitcnt lgkmcnt(" #n ")" ::: "memory")
; #define PG8_BAR __builtin_amdgcn_s_barrier()
; template <class Epi, class Sched, bool ALIGN_EPI = false, bool SP2 = false>
; __device__ __forceinline__ void gemm_phase(PG8_LAS unsigned char* lds, const Gemm g, const Sched& S, const Epi& E) {
;     ...
;         for (int t = 0; t < nt; t += 2) {
;             const bool last = (t == nt - 2);
;             const char* a1 = PG8_KP(cA, t + 1, rot, nt);
;             const char* a2 = last ? nAr : PG8_KP(cA, t + 2, rot, nt); const char* b2 = last ? nBr : PG8_KP(cB, t + 2, rot, nt);
;             const char* a3 = a2 + kstep; const char* b3 = b2 + kstep;
;             if (last && has_next) S.a_ready(nxt);
;             if constexpr (SP2) {
;             PG8_LDB(B0, 0, 0); PG8_LDB(B1, 0, 1); PG8_SCHED; PG8_LDA(At, 0, 0); PG8_STAGE(PG8_SA(1, 1), a1 + hstep, voffA);
;             PG8_WAIT_V(8); PG8_WAIT_L(0); PG8_BAR; PG8_MMA(0, 0, At, B0); PG8_MMA(0, 1, At, B1); PG8_BAR; PG8_SCHED;
;             PG8_LDA(At, 0, 1); PG8_STAGEB(PG8_SB(0, 0), b2, voffB); PG8_STAGEB(PG8_SB(0, 1), b2 + hstep, voffB); PG8_STAGE(PG8_SA(0, 0), a2, voffA);
;             PG8_WAIT_V(8); PG8_WAIT_L(0); PG8_BAR; PG8_MMA(1, 0, At, B0); PG8_MMA(1, 1, At, B1); PG8_BAR; PG8_SCHED;
.LBB0_1067:
	s_add_i32 s81, s29, 2
	s_cmp_lt_u32 s29, 14
	s_cselect_b32 s0, 0, -16
	s_add_i32 s0, s81, s0
	s_ashr_i32 s1, s0, 31
	s_lshl_b64 s[0:1], s[0:1], 7
	s_add_u32 s2, s52, s0
	s_addc_u32 s46, s53, s1
	s_add_u32 s0, s42, s0
	s_addc_u32 s1, s43, s1
	s_cmp_eq_u32 s29, 14
	s_cselect_b32 s59, s15, s46
	s_cselect_b32 s58, s17, s2
	s_cselect_b32 s61, s92, s1
	s_cselect_b32 s60, s93, s0
	s_add_i32 s2, 0, 0x10000
	s_add_i32 s94, s2, s70
	s_add_i32 s46, 0, 0x14000
	s_add_i32 m0, s71, 0xc000
	s_add_i32 s84, s71, 0xe000
	s_add_i32 s95, s94, 0x2000
	s_add_u32 s62, s60, 0x40000
	v_add_u32_e32 v148, s2, v99
	s_addc_u32 s63, s61, 0
	s_add_i32 s96, s46, s70
	ds_read_b128 v[152:155], v148
	ds_read_b128 v[156:159], v148 offset:1024
	ds_read_b128 v[160:163], v148 offset:2048
	ds_read_b128 v[164:167], v148 offset:3072
	v_add_u32_e32 v148, s46, v99
	s_add_i32 s97, s96, 0x2000
	s_add_i32 vcc_lo, 0, 0x18000
	s_add_i32 vcc_hi, 0, 0x1c000
	ds_read_b128 v[180:183], v148
	ds_read_b128 v[184:187], v148 offset:1024
	ds_read_b128 v[188:191], v148 offset:2048
	ds_read_b128 v[192:195], v148 offset:3072
	s_add_u32 s56, s58, 0x40000
	s_addc_u32 s57, s59, 0
	s_add_i32 s1, vcc_lo, s70
	s_add_i32 s0, s1, 0x2000
	s_add_u32 s54, s60, 0x40080
	s_addc_u32 s55, s61, 0
	s_add_i32 s47, vcc_hi, s70
	s_add_i32 s46, s47, 0x2000
	s_cmp_gt_u32 s29, 13
	ds_read_b128 v[196:199], v151
	ds_read_b128 v[200:203], v151 offset:1024
	ds_read_b128 v[222:225], v151 offset:2048
	ds_read_b128 v[226:229], v151 offset:3072
	ds_read_b128 v[230:233], v151 offset:4096
	ds_read_b128 v[234:237], v151 offset:5120
	ds_read_b128 v[238:241], v151 offset:6144
	ds_read_b128 v[242:245], v151 offset:7168
	global_load_lds_dwordx4 v[146:147], off
	s_mov_b32 m0, s84
	s_nop 0
	global_load_lds_dwordx4 v[144:145], off
	s_waitcnt vmcnt(8)
	s_waitcnt lgkmcnt(0)
	s_setprio 1
	s_barrier
	v_mfma_f32_16x16x32_bf16 v[128:131], v[152:155], v[196:199], v[128:131]
	v_mfma_f32_16x16x32_bf16 v[128:131], v[156:159], v[200:203], v[128:131]
	v_mfma_f32_16x16x32_bf16 v[124:127], v[160:163], v[196:199], v[124:127]
	v_mfma_f32_16x16x32_bf16 v[124:127], v[164:167], v[200:203], v[124:127]
	v_mfma_f32_16x16x32_bf16 v[112:115], v[152:155], v[222:225], v[112:115]
	v_mfma_f32_16x16x32_bf16 v[112:115], v[156:159], v[226:229], v[112:115]
	v_mfma_f32_16x16x32_bf16 v[108:111], v[160:163], v[222:225], v[108:111]
	v_mfma_f32_16x16x32_bf16 v[108:111], v[164:167], v[226:229], v[108:111]
	v_mfma_f32_16x16x32_bf16 v[94:97], v[152:155], v[230:233], v[94:97]
	v_mfma_f32_16x16x32_bf16 v[94:97], v[156:159], v[234:237], v[94:97]
	v_mfma_f32_16x16x32_bf16 v[90:93], v[160:163], v[230:233], v[90:93]
	v_mfma_f32_16x16x32_bf16 v[90:93], v[164:167], v[234:237], v[90:93]
	v_mfma_f32_16x16x32_bf16 v[78:81], v[152:155], v[238:241], v[78:81]
	v_mfma_f32_16x16x32_bf16 v[78:81], v[156:159], v[242:245], v[78:81]
	v_mfma_f32_16x16x32_bf16 v[74:77], v[160:163], v[238:241], v[74:77]
	v_mfma_f32_16x16x32_bf16 v[74:77], v[164:167], v[242:245], v[74:77]
	s_setprio 0
	s_setprio 1
	v_mfma_f32_16x16x32_bf16 v[120:123], v[180:183], v[196:199], v[120:123]
	v_mfma_f32_16x16x32_bf16 v[120:123], v[184:187], v[200:203], v[120:123]
	v_mfma_f32_16x16x32_bf16 v[116:119], v[188:191], v[196:199], v[116:119]
	v_mfma_f32_16x16x32_bf16 v[116:119], v[192:195], v[200:203], v[116:119]
	v_mfma_f32_16x16x32_bf16 v[104:107], v[180:183], v[222:225], v[104:107]
	v_mfma_f32_16x16x32_bf16 v[104:107], v[184:187], v[226:229], v[104:107]
	v_mfma_f32_16x16x32_bf16 v[100:103], v[188:191], v[222:225], v[100:103]
	v_mfma_f32_16x16x32_bf16 v[100:103], v[192:195], v[226:229], v[100:103]
	v_mfma_f32_16x16x32_bf16 v[86:89], v[180:183], v[230:233], v[86:89]
	v_mfma_f32_16x16x32_bf16 v[86:89], v[184:187], v[234:237], v[86:89]
	v_mfma_f32_16x16x32_bf16 v[82:85], v[188:191], v[230:233], v[82:85]
	v_mfma_f32_16x16x32_bf16 v[82:85], v[192:195], v[234:237], v[82:85]
	v_mfma_f32_16x16x32_bf16 v[70:73], v[180:183], v[238:241], v[70:73]
	v_mfma_f32_16x16x32_bf16 v[70:73], v[184:187], v[242:245], v[70:73]
	s_setprio 2
	s_barrier
	v_mfma_f32_16x16x32_bf16 v[66:69], v[188:191], v[238:241], v[66:69]
	v_mfma_f32_16x16x32_bf16 v[66:69], v[192:195], v[242:245], v[66:69]
	s_setprio 0
	s_mov_b32 m0, s94
	v_lshl_add_u64 v[148:149], s[60:61], 0, v[136:137]
	ds_read_b128 v[196:199], v151 offset:16384
	ds_read_b128 v[200:203], v151 offset:17408
	ds_read_b128 v[222:225], v151 offset:18432
	ds_read_b128 v[226:229], v151 offset:19456
	ds_read_b128 v[230:233], v151 offset:20480
	ds_read_b128 v[234:237], v151 offset:21504
	ds_read_b128 v[238:241], v151 offset:22528
	ds_read_b128 v[242:245], v151 offset:23552
	global_load_lds_dwordx4 v[148:149], off
	v_lshl_add_u64 v[168:169], s[60:61], 0, v[132:133]
	s_mov_b32 m0, s95
	v_lshl_add_u64 v[172:173], s[62:63], 0, v[136:137]
	global_load_lds_dwordx4 v[168:169], off
	s_mov_b32 m0, s96
	v_lshl_add_u64 v[212:213], s[58:59], 0, v[134:135]
	global_load_lds_dwordx4 v[172:173], off
	v_lshl_add_u64 v[172:173], s[62:63], 0, v[132:133]
	s_mov_b32 m0, s97
	s_nop 0
	global_load_lds_dwordx4 v[172:173], off
	v_lshl_add_u64 v[172:173], s[58:59], 0, v[138:139]
	s_mov_b32 m0, s71
	s_nop 0
	global_load_lds_dwordx4 v[172:173], off
	s_mov_b32 m0, s75
	s_nop 0
	global_load_lds_dwordx4 v[212:213], off
	s_waitcnt vmcnt(8)
	s_waitcnt lgkmcnt(0)
	s_setprio 1
	s_barrier
; #define PG8_STAGE(bufoff, gbase, voff) do { _Pragma("unroll") for (int _i = 0; _i < 2; ++_i) \
;         __builtin_amdgcn_global_load_lds((const unsigned*)((const char*)(gbase) + (voff)[_i]), (PG8_LAS unsigned*)(lds + (bufoff) + ldsw + _i * 8192), 16, 0, AUX_A); } while (0)
; #define PG8_STAGEB(bufoff, gbase, voff) do { _Pragma("unroll") for (int _i = 0; _i < 2; ++_i) \
;         __builtin_amdgcn_global_load_lds((const unsigned*)((const char*)(gbase) + (voff)[_i]), (PG8_LAS unsigned*)(lds + (bufoff) + ldsw + _i * 8192), 16, 0, AUX_B); } while (0)
; #define PG8_LDA(dst, b, h) do { _Pragma("unroll") for (int m = 0; m < 4; ++m) _Pragma("unroll") for (int k = 0; k < 2; ++k) dst[m][k] = *(const PG8_LAS bf16x8*)(lds + PG8_SA(b, h) + aoff + m * 2048 + k * 1024); } while (0)
; #define PG8_LDB(dst, b, h) do { _Pragma("unroll") for (int n = 0; n < 2; ++n) _Pragma("unroll") for (int k = 0; k < 2; ++k) dst[n][k] = *(const PG8_LAS bf16x8*)(lds + PG8_SB(b, h) + boff + n * 2048 + k * 1024); } while (0)
; #define PG8_MMA(ai, bj, At, Bt) do { __builtin_amdgcn_s_setprio(1); _Pragma("unroll") for (int m = 0; m < 4; ++m) _Pragma("unroll") for (int n = 0; n < 2; ++n) _Pragma("unroll") for (int k = 0; k < 2; ++k) \
;         acc[ai][bj][m][n] = __builtin_amdgcn_mfma_f32_16x16x32_bf16(Bt[n][k], At[m][k], acc[ai][bj][m][n], 0, 0, 0); __builtin_amdgcn_s_setprio(0); } while (0)
; template <class Epi, class Sched, bool ALIGN_EPI = false, bool SP2 = false>
; __device__ __forceinline__ void gemm_phase(PG8_LAS unsigned char* lds, const Gemm g, const Sched& S, const Epi& E) {
;     ...
;             if constexpr (SP2) {
;             PG8_LDB(B0, 0, 0); PG8_LDB(B1, 0, 1); PG8_SCHED; PG8_LDA(At, 0, 0); PG8_STAGE(PG8_SA(1, 1), a1 + hstep, voffA);
;             PG8_WAIT_V(8); PG8_WAIT_L(0); PG8_BAR; PG8_MMA(0, 0, At, B0); PG8_MMA(0, 1, At, B1); PG8_BAR; PG8_SCHED;
;             PG8_LDA(At, 0, 1); PG8_STAGEB(PG8_SB(0, 0), b2, voffB); PG8_STAGEB(PG8_SB(0, 1), b2 + hstep, voffB); PG8_STAGE(PG8_SA(0, 0), a2, voffA);
;             PG8_WAIT_V(8); PG8_WAIT_L(0); PG8_BAR; PG8_MMA(1, 0, At, B0); PG8_MMA(1, 1, At, B1); PG8_BAR; PG8_SCHED;
;             PG8_LDB(B0, 1, 0); PG8_LDB(B1, 1, 1); PG8_SCHED; PG8_LDA(At, 1, 0); PG8_STAGE(PG8_SA(0, 1), a2 + hstep, voffA);
;             PG8_WAIT_V(8); PG8_WAIT_L(0); PG8_BAR; PG8_MMA(0, 0, At, B0); PG8_MMA(0, 1, At, B1); PG8_BAR; PG8_SCHED;
	v_mfma_f32_16x16x32_bf16 v[62:65], v[152:155], v[196:199], v[62:65]
	v_mfma_f32_16x16x32_bf16 v[62:65], v[156:159], v[200:203], v[62:65]
	v_mfma_f32_16x16x32_bf16 v[58:61], v[160:163], v[196:199], v[58:61]
	v_mfma_f32_16x16x32_bf16 v[58:61], v[164:167], v[200:203], v[58:61]
	v_mfma_f32_16x16x32_bf16 v[46:49], v[152:155], v[222:225], v[46:49]
	v_mfma_f32_16x16x32_bf16 v[46:49], v[156:159], v[226:229], v[46:49]
	v_mfma_f32_16x16x32_bf16 v[42:45], v[160:163], v[222:225], v[42:45]
	v_mfma_f32_16x16x32_bf16 v[42:45], v[164:167], v[226:229], v[42:45]
	v_mfma_f32_16x16x32_bf16 v[30:33], v[152:155], v[230:233], v[30:33]
	v_mfma_f32_16x16x32_bf16 v[30:33], v[156:159], v[234:237], v[30:33]
	v_mfma_f32_16x16x32_bf16 v[26:29], v[160:163], v[230:233], v[26:29]
	v_mfma_f32_16x16x32_bf16 v[26:29], v[164:167], v[234:237], v[26:29]
	v_mfma_f32_16x16x32_bf16 v[14:17], v[152:155], v[238:241], v[14:17]
	v_mfma_f32_16x16x32_bf16 v[14:17], v[156:159], v[242:245], v[14:17]
	v_mfma_f32_16x16x32_bf16 v[10:13], v[160:163], v[238:241], v[10:13]
	v_mfma_f32_16x16x32_bf16 v[10:13], v[164:167], v[242:245], v[10:13]
	s_setprio 0
	s_setprio 1
	v_mfma_f32_16x16x32_bf16 v[54:57], v[180:183], v[196:199], v[54:57]
	v_mfma_f32_16x16x32_bf16 v[54:57], v[184:187], v[200:203], v[54:57]
	v_mfma_f32_16x16x32_bf16 v[50:53], v[188:191], v[196:199], v[50:53]
	v_mfma_f32_16x16x32_bf16 v[50:53], v[192:195], v[200:203], v[50:53]
	v_mfma_f32_16x16x32_bf16 v[38:41], v[180:183], v[222:225], v[38:41]
	v_mfma_f32_16x16x32_bf16 v[38:41], v[184:187], v[226:229], v[38:41]
	v_mfma_f32_16x16x32_bf16 v[34:37], v[188:191], v[222:225], v[34:37]
	v_mfma_f32_16x16x32_bf16 v[34:37], v[192:195], v[226:229], v[34:37]
	v_mfma_f32_16x16x32_bf16 v[22:25], v[180:183], v[230:233], v[22:25]
	v_mfma_f32_16x16x32_bf16 v[22:25], v[184:187], v[234:237], v[22:25]
	v_mfma_f32_16x16x32_bf16 v[18:21], v[188:191], v[230:233], v[18:21]
	v_mfma_f32_16x16x32_bf16 v[18:21], v[192:195], v[234:237], v[18:21]
	v_mfma_f32_16x16x32_bf16 v[6:9], v[180:183], v[238:241], v[6:9]
	v_mfma_f32_16x16x32_bf16 v[6:9], v[184:187], v[242:245], v[6:9]
	s_setprio 2
	s_barrier
	v_mfma_f32_16x16x32_bf16 v[2:5], v[188:191], v[238:241], v[2:5]
	v_mfma_f32_16x16x32_bf16 v[2:5], v[192:195], v[242:245], v[2:5]
	s_setprio 0
	v_add_u32_e32 v164, vcc_lo, v99
	v_add_u32_e32 v192, vcc_hi, v99
	ds_read_b128 v[152:155], v164
	ds_read_b128 v[156:159], v164 offset:1024
	ds_read_b128 v[160:163], v164 offset:2048
	ds_read_b128 v[164:167], v164 offset:3072
	ds_read_b128 v[180:183], v192
	ds_read_b128 v[184:187], v192 offset:1024
	ds_read_b128 v[188:191], v192 offset:2048
	ds_read_b128 v[192:195], v192 offset:3072
	s_mov_b32 m0, s78
	v_lshl_add_u64 v[246:247], s[56:57], 0, v[138:139]
	ds_read_b128 v[196:199], v151 offset:32768
	ds_read_b128 v[200:203], v151 offset:33792
	ds_read_b128 v[222:225], v151 offset:34816
	ds_read_b128 v[226:229], v151 offset:35840
	ds_read_b128 v[230:233], v151 offset:36864
	ds_read_b128 v[234:237], v151 offset:37888
	ds_read_b128 v[238:241], v151 offset:38912
	ds_read_b128 v[242:245], v151 offset:39936
	global_load_lds_dwordx4 v[246:247], off
	v_lshl_add_u64 v[246:247], s[56:57], 0, v[134:135]
	s_mov_b32 m0, s82
	s_nop 0
	global_load_lds_dwordx4 v[246:247], off
	s_waitcnt vmcnt(8)
	s_waitcnt lgkmcnt(0)
	s_setprio 1
	s_barrier
	v_mfma_f32_16x16x32_bf16 v[128:131], v[152:155], v[196:199], v[128:131]
	v_mfma_f32_16x16x32_bf16 v[128:131], v[156:159], v[200:203], v[128:131]
	v_mfma_f32_16x16x32_bf16 v[124:127], v[160:163], v[196:199], v[124:127]
	v_mfma_f32_16x16x32_bf16 v[124:127], v[164:167], v[200:203], v[124:127]
	v_mfma_f32_16x16x32_bf16 v[112:115], v[152:155], v[222:225], v[112:115]
	v_mfma_f32_16x16x32_bf16 v[112:115], v[156:159], v[226:229], v[112:115]
	v_mfma_f32_16x16x32_bf16 v[108:111], v[160:163], v[222:225], v[108:111]
	v_mfma_f32_16x16x32_bf16 v[108:111], v[164:167], v[226:229], v[108:111]
	v_mfma_f32_16x16x32_bf16 v[94:97], v[152:155], v[230:233], v[94:97]
	v_mfma_f32_16x16x32_bf16 v[94:97], v[156:159], v[234:237], v[94:97]
	v_mfma_f32_16x16x32_bf16 v[90:93], v[160:163], v[230:233], v[90:93]
	v_mfma_f32_16x16x32_bf16 v[90:93], v[164:167], v[234:237], v[90:93]
	v_mfma_f32_16x16x32_bf16 v[78:81], v[152:155], v[238:241], v[78:81]
	v_mfma_f32_16x16x32_bf16 v[78:81], v[156:159], v[242:245], v[78:81]
	v_mfma_f32_16x16x32_bf16 v[74:77], v[160:163], v[238:241], v[74:77]
	v_mfma_f32_16x16x32_bf16 v[74:77], v[164:167], v[242:245], v[74:77]
	s_setprio 0
	s_setprio 1
	v_mfma_f32_16x16x32_bf16 v[120:123], v[180:183], v[196:199], v[120:123]
	v_mfma_f32_16x16x32_bf16 v[120:123], v[184:187], v[200:203], v[120:123]
	v_mfma_f32_16x16x32_bf16 v[116:119], v[188:191], v[196:199], v[116:119]
	v_mfma_f32_16x16x32_bf16 v[116:119], v[192:195], v[200:203], v[116:119]
	v_mfma_f32_16x16x32_bf16 v[104:107], v[180:183], v[222:225], v[104:107]
	v_mfma_f32_16x16x32_bf16 v[104:107], v[184:187], v[226:229], v[104:107]
	v_mfma_f32_16x16x32_bf16 v[100:103], v[188:191], v[222:225], v[100:103]
	v_mfma_f32_16x16x32_bf16 v[100:103], v[192:195], v[226:229], v[100:103]
	v_mfma_f32_16x16x32_bf16 v[86:89], v[180:183], v[230:233], v[86:89]
	v_mfma_f32_16x16x32_bf16 v[86:89], v[184:187], v[234:237], v[86:89]
	v_mfma_f32_16x16x32_bf16 v[82:85], v[188:191], v[230:233], v[82:85]
	v_mfma_f32_16x16x32_bf16 v[82:85], v[192:195], v[234:237], v[82:85]
	v_mfma_f32_16x16x32_bf16 v[70:73], v[180:183], v[238:241], v[70:73]
	v_mfma_f32_16x16x32_bf16 v[70:73], v[184:187], v[242:245], v[70:73]
	s_setprio 2
	s_barrier
; #define PG8_STAGE(bufoff, gbase, voff) do { _Pragma("unroll") for (int _i = 0; _i < 2; ++_i) \
;         __builtin_amdgcn_global_load_lds((const unsigned*)((const char*)(gbase) + (voff)[_i]), (PG8_LAS unsigned*)(lds + (bufoff) + ldsw + _i * 8192), 16, 0, AUX_A); } while (0)
; #define PG8_STAGEB(bufoff, gbase, voff) do { _Pragma("unroll") for (int _i = 0; _i < 2; ++_i) \
;         __builtin_amdgcn_global_load_lds((const unsigned*)((const char*)(gbase) + (voff)[_i]), (PG8_LAS unsigned*)(lds + (bufoff) + ldsw + _i * 8192), 16, 0, AUX_B); } while (0)
; #define PG8_LDA(dst, b, h) do { _Pragma("unroll") for (int m = 0; m < 4; ++m) _Pragma("unroll") for (int k = 0; k < 2; ++k) dst[m][k] = *(const PG8_LAS bf16x8*)(lds + PG8_SA(b, h) + aoff + m * 2048 + k * 1024); } while (0)
; #define PG8_LDB(dst, b, h) do { _Pragma("unroll") for (int n = 0; n < 2; ++n) _Pragma("unroll") for (int k = 0; k < 2; ++k) dst[n][k] = *(const PG8_LAS bf16x8*)(lds + PG8_SB(b, h) + boff + n * 2048 + k * 1024); } while (0)
; #define PG8_MMA(ai, bj, At, Bt) do { __builtin_amdgcn_s_setprio(1); _Pragma("unroll") for (int m = 0; m < 4; ++m) _Pragma("unroll") for (int n = 0; n < 2; ++n) _Pragma("unroll") for (int k = 0; k < 2; ++k) \
;         acc[ai][bj][m][n] = __builtin_amdgcn_mfma_f32_16x16x32_bf16(Bt[n][k], At[m][k], acc[ai][bj][m][n], 0, 0, 0); __builtin_amdgcn_s_setprio(0); } while (0)
; #define PG8_WAIT_V(n) asm volatile("s_waitcnt vmcnt(" #n ")" ::: "memory")
; #define PG8_WAIT_L(n) asm volatile("s_waitcnt lgkmcnt(" #n ")" ::: "memory")
; #define PG8_BAR __builtin_amdgcn_s_barrier()
; #define PG8_SCHED __builtin_amdgcn_sched_barrier(0)
; template <class Epi, class Sched, bool ALIGN_EPI = false, bool SP2 = false>
; __device__ __forceinline__ void gemm_phase(PG8_LAS unsigned char* lds, const Gemm g, const Sched& S, const Epi& E) {
;     ...
;             PG8_LDB(B0, 1, 0); PG8_LDB(B1, 1, 1); PG8_SCHED; PG8_LDA(At, 1, 0); PG8_STAGE(PG8_SA(0, 1), a2 + hstep, voffA);
;             PG8_WAIT_V(8); PG8_WAIT_L(0); PG8_BAR; PG8_MMA(0, 0, At, B0); PG8_MMA(0, 1, At, B1); PG8_BAR; PG8_SCHED;
;             PG8_LDA(At, 1, 1); PG8_STAGEB(PG8_SB(1, 0), b3, voffB); PG8_STAGEB(PG8_SB(1, 1), b3 + hstep, voffB); PG8_STAGE(PG8_SA(1, 0), a3, voffA);
;             PG8_WAIT_V(8); PG8_WAIT_L(0); PG8_BAR; PG8_MMA(1, 0, At, B0); PG8_MMA(1, 1, At, B1); PG8_BAR; PG8_SCHED;
	v_mfma_f32_16x16x32_bf16 v[66:69], v[188:191], v[238:241], v[66:69]
	v_mfma_f32_16x16x32_bf16 v[66:69], v[192:195], v[242:245], v[66:69]
	s_setprio 0
	s_mov_b32 m0, s1
	v_lshl_add_u64 v[148:149], v[148:149], 0, s[76:77]
	ds_read_b128 v[196:199], v151 offset:49152
	ds_read_b128 v[200:203], v151 offset:50176
	ds_read_b128 v[222:225], v151 offset:51200
	ds_read_b128 v[226:229], v151 offset:52224
	ds_read_b128 v[230:233], v151 offset:53248
	ds_read_b128 v[234:237], v151 offset:54272
	ds_read_b128 v[238:241], v151 offset:55296
	ds_read_b128 v[242:245], v151 offset:56320
	global_load_lds_dwordx4 v[148:149], off
	v_lshl_add_u64 v[148:149], v[168:169], 0, s[76:77]
	s_mov_b32 m0, s0
	s_nop 0
	global_load_lds_dwordx4 v[148:149], off
	v_lshl_add_u64 v[148:149], s[54:55], 0, v[136:137]
	s_mov_b32 m0, s47
	s_nop 0
	global_load_lds_dwordx4 v[148:149], off
	v_lshl_add_u64 v[148:149], s[54:55], 0, v[132:133]
	s_mov_b32 m0, s46
	s_nop 0
	global_load_lds_dwordx4 v[148:149], off
	v_lshl_add_u64 v[148:149], v[172:173], 0, s[76:77]
	s_mov_b32 m0, s83
	s_nop 0
	global_load_lds_dwordx4 v[148:149], off
	v_lshl_add_u64 v[148:149], v[212:213], 0, s[76:77]
	s_mov_b32 m0, s88
	s_nop 0
	global_load_lds_dwordx4 v[148:149], off
	s_waitcnt vmcnt(8)
	s_waitcnt lgkmcnt(0)
	s_setprio 1
	s_barrier
	v_mfma_f32_16x16x32_bf16 v[62:65], v[152:155], v[196:199], v[62:65]
	v_mfma_f32_16x16x32_bf16 v[62:65], v[156:159], v[200:203], v[62:65]
	v_mfma_f32_16x16x32_bf16 v[58:61], v[160:163], v[196:199], v[58:61]
	v_mfma_f32_16x16x32_bf16 v[58:61], v[164:167], v[200:203], v[58:61]
	v_mfma_f32_16x16x32_bf16 v[46:49], v[152:155], v[222:225], v[46:49]
	v_mfma_f32_16x16x32_bf16 v[46:49], v[156:159], v[226:229], v[46:49]
	v_mfma_f32_16x16x32_bf16 v[42:45], v[160:163], v[222:225], v[42:45]
	v_mfma_f32_16x16x32_bf16 v[42:45], v[164:167], v[226:229], v[42:45]
	v_mfma_f32_16x16x32_bf16 v[30:33], v[152:155], v[230:233], v[30:33]
	v_mfma_f32_16x16x32_bf16 v[30:33], v[156:159], v[234:237], v[30:33]
	v_mfma_f32_16x16x32_bf16 v[26:29], v[160:163], v[230:233], v[26:29]
	v_mfma_f32_16x16x32_bf16 v[26:29], v[164:167], v[234:237], v[26:29]
	v_mfma_f32_16x16x32_bf16 v[14:17], v[152:155], v[238:241], v[14:17]
	v_mfma_f32_16x16x32_bf16 v[14:17], v[156:159], v[242:245], v[14:17]
	v_mfma_f32_16x16x32_bf16 v[10:13], v[160:163], v[238:241], v[10:13]
	v_mfma_f32_16x16x32_bf16 v[10:13], v[164:167], v[242:245], v[10:13]
	s_setprio 0
	s_setprio 1
	v_mfma_f32_16x16x32_bf16 v[54:57], v[180:183], v[196:199], v[54:57]
	v_mfma_f32_16x16x32_bf16 v[54:57], v[184:187], v[200:203], v[54:57]
	v_mfma_f32_16x16x32_bf16 v[50:53], v[188:191], v[196:199], v[50:53]
	v_mfma_f32_16x16x32_bf16 v[50:53], v[192:195], v[200:203], v[50:53]
	v_mfma_f32_16x16x32_bf16 v[38:41], v[180:183], v[222:225], v[38:41]
	v_mfma_f32_16x16x32_bf16 v[38:41], v[184:187], v[226:229], v[38:41]
	v_mfma_f32_16x16x32_bf16 v[34:37], v[188:191], v[222:225], v[34:37]
	v_mfma_f32_16x16x32_bf16 v[34:37], v[192:195], v[226:229], v[34:37]
	v_mfma_f32_16x16x32_bf16 v[22:25], v[180:183], v[230:233], v[22:25]
	v_mfma_f32_16x16x32_bf16 v[22:25], v[184:187], v[234:237], v[22:25]
	v_mfma_f32_16x16x32_bf16 v[18:21], v[188:191], v[230:233], v[18:21]
	v_mfma_f32_16x16x32_bf16 v[18:21], v[192:195], v[234:237], v[18:21]
	v_mfma_f32_16x16x32_bf16 v[6:9], v[180:183], v[238:241], v[6:9]
	v_mfma_f32_16x16x32_bf16 v[6:9], v[184:187], v[242:245], v[6:9]
	s_setprio 2
	s_cbranch_scc1 .Lq4x_1067l
	s_barrier
.Lq4r_1067l:
	v_mfma_f32_16x16x32_bf16 v[2:5], v[188:191], v[238:241], v[2:5]
	v_mfma_f32_16x16x32_bf16 v[2:5], v[192:195], v[242:245], v[2:5]
	s_setprio 0
	v_lshl_add_u64 v[144:145], v[144:145], 0, s[86:87]
	v_lshl_add_u64 v[146:147], v[146:147], 0, s[86:87]
	s_mov_b32 s29, s81
	s_cbranch_scc0 .LBB0_1067
	s_branch .Lpx_1067

; #define PG8_STAGE(bufoff, gbase, voff) do { _Pragma("unroll") for (int _i = 0; _i < 2; ++_i) \
;         __builtin_amdgcn_global_load_lds((const unsigned*)((const char*)(gbase) + (voff)[_i]), (PG8_LAS unsigned*)(lds + (bufoff) + ldsw + _i * 8192), 16, 0, AUX_A); } while (0)
; #define PG8_STAGEB(bufoff, gbase, voff) do { _Pragma("unroll") for (int _i = 0; _i < 2; ++_i) \
;         __builtin_amdgcn_global_load_lds((const unsigned*)((const char*)(gbase) + (voff)[_i]), (PG8_LAS unsigned*)(lds + (bufoff) + ldsw + _i * 8192), 16, 0, AUX_B); } while (0)
; #define PG8_LDA(dst, b, h) do { _Pragma("unroll") for (int m = 0; m < 4; ++m) _Pragma("unroll") for (int k = 0; k < 2; ++k) dst[m][k] = *(const PG8_LAS bf16x8*)(lds + PG8_SA(b, h) + aoff + m * 2048 + k * 1024); } while (0)
; #define PG8_LDB(dst, b, h) do { _Pragma("unroll") for (int n = 0; n < 2; ++n) _Pragma("unroll") for (int k = 0; k < 2; ++k) dst[n][k] = *(const PG8_LAS bf16x8*)(lds + PG8_SB(b, h) + boff + n * 2048 + k * 1024); } while (0)
; #define PG8_WAIT_V(n) asm volatile("s_waitcnt vmcnt(" #n ")" ::: "memory")
; #define PG8_WAIT_L(n) asm volatile("s_waitcnt lgkmcnt(" #n ")" ::: "memory")
; #define PG8_BAR __builtin_amdgcn_s_barrier()
; template <class Epi, class Sched, bool ALIGN_EPI = false, bool SP2 = false>
; __device__ __forceinline__ void gemm_phase(PG8_LAS unsigned char* lds, const Gemm g, const Sched& S, const Epi& E) {
;     ...
;         for (int t = 0; t < nt; t += 2) {
;             const bool last = (t == nt - 2);
;             const char* a1 = PG8_KP(cA, t + 1, rot, nt);
;             const char* a2 = last ? nAr : PG8_KP(cA, t + 2, rot, nt); const char* b2 = last ? nBr : PG8_KP(cB, t + 2, rot, nt);
;             const char* a3 = a2 + kstep; const char* b3 = b2 + kstep;
;             if (last && has_next) S.a_ready(nxt);
;             if constexpr (SP2) {
;             PG8_LDB(B0, 0, 0); PG8_LDB(B1, 0, 1); PG8_SCHED; PG8_LDA(At, 0, 0); PG8_STAGE(PG8_SA(1, 1), a1 + hstep, voffA);
;             PG8_WAIT_V(8); PG8_WAIT_L(0); PG8_BAR; PG8_MMA(0, 0, At, B0); PG8_MMA(0, 1, At, B1); PG8_BAR; PG8_SCHED;
;             PG8_LDA(At, 0, 1); PG8_STAGEB(PG8_SB(0, 0), b2, voffB); PG8_STAGEB(PG8_SB(0, 1), b2 + hstep, voffB); PG8_STAGE(PG8_SA(0, 0), a2, voffA);
;             PG8_WAIT_V(8); PG8_WAIT_L(0); PG8_BAR; PG8_MMA(1, 0, At, B0); PG8_MMA(1, 1, At, B1); PG8_BAR; PG8_SCHED;
.Lpk_1157:
	s_add_i32 s81, s29, 2
	s_cmp_lt_u32 s29, 14
	s_cselect_b32 s0, 0, -16
	s_add_i32 s0, s81, s0
	s_ashr_i32 s1, s0, 31
	s_lshl_b64 s[0:1], s[0:1], 7
	s_add_u32 s2, s52, s0
	s_addc_u32 s46, s53, s1
	s_add_u32 s0, s50, s0
	s_addc_u32 s1, s51, s1
	s_cmp_eq_u32 s29, 14
	s_cselect_b32 s59, s19, s46
	s_cselect_b32 s58, s39, s2
	s_cselect_b32 s61, s92, s1
	s_cselect_b32 s60, s93, s0
	s_add_i32 s2, 0, 0x10000
	s_add_i32 s94, s2, s70
	s_add_i32 s46, 0, 0x14000
	s_add_i32 m0, s71, 0xc000
	s_add_i32 s84, s71, 0xe000
	s_add_i32 s95, s94, 0x2000
	s_add_u32 s62, s60, 0x40000
	s_addc_u32 s63, s61, 0
	s_add_i32 s96, s46, s70
	v_add_u32_e32 v162, s2, v99
	v_add_u32_e32 v166, s46, v99
	s_add_i32 s97, s96, 0x2000
	s_add_i32 vcc_lo, 0, 0x18000
	s_add_i32 vcc_hi, 0, 0x1c000
	ds_read_b128 v[148:151], v162
	ds_read_b128 v[154:157], v162 offset:1024
	ds_read_b128 v[158:161], v162 offset:2048
	ds_read_b128 v[162:165], v162 offset:3072
	ds_read_b128 v[180:183], v166
	ds_read_b128 v[184:187], v166 offset:1024
	ds_read_b128 v[188:191], v166 offset:2048
	ds_read_b128 v[192:195], v166 offset:3072
	s_add_u32 s56, s58, 0x40000
	s_addc_u32 s57, s59, 0
	s_add_i32 s1, vcc_lo, s70
	s_add_i32 s0, s1, 0x2000
	s_add_u32 s54, s60, 0x40080
	s_addc_u32 s55, s61, 0
	s_add_i32 s47, vcc_hi, s70
	s_add_i32 s46, s47, 0x2000
	s_cmp_gt_u32 s29, 13
	ds_read_b128 v[196:199], v153
	ds_read_b128 v[200:203], v153 offset:1024
	ds_read_b128 v[222:225], v153 offset:2048
	ds_read_b128 v[226:229], v153 offset:3072
	ds_read_b128 v[230:233], v153 offset:4096
	ds_read_b128 v[234:237], v153 offset:5120
	ds_read_b128 v[238:241], v153 offset:6144
	ds_read_b128 v[242:245], v153 offset:7168
	global_load_lds_dwordx4 v[146:147], off
	s_mov_b32 m0, s84
	s_nop 0
	global_load_lds_dwordx4 v[144:145], off
	s_waitcnt vmcnt(8)
	s_waitcnt lgkmcnt(0)
	s_setprio 1
	s_barrier
	v_mfma_f32_16x16x32_bf16 v[128:131], v[148:151], v[196:199], 0
	v_mfma_f32_16x16x32_bf16 v[128:131], v[154:157], v[200:203], v[128:131]
	v_mfma_f32_16x16x32_bf16 v[124:127], v[158:161], v[196:199], 0
	v_mfma_f32_16x16x32_bf16 v[124:127], v[162:165], v[200:203], v[124:127]
	v_mfma_f32_16x16x32_bf16 v[112:115], v[148:151], v[222:225], 0
	v_mfma_f32_16x16x32_bf16 v[112:115], v[154:157], v[226:229], v[112:115]
	v_mfma_f32_16x16x32_bf16 v[108:111], v[158:161], v[222:225], 0
	v_mfma_f32_16x16x32_bf16 v[108:111], v[162:165], v[226:229], v[108:111]
	v_mfma_f32_16x16x32_bf16 v[94:97], v[148:151], v[230:233], 0
	v_mfma_f32_16x16x32_bf16 v[94:97], v[154:157], v[234:237], v[94:97]
	v_mfma_f32_16x16x32_bf16 v[90:93], v[158:161], v[230:233], 0
	v_mfma_f32_16x16x32_bf16 v[90:93], v[162:165], v[234:237], v[90:93]
	v_mfma_f32_16x16x32_bf16 v[78:81], v[148:151], v[238:241], 0
	v_mfma_f32_16x16x32_bf16 v[78:81], v[154:157], v[242:245], v[78:81]
	v_mfma_f32_16x16x32_bf16 v[74:77], v[158:161], v[238:241], 0
	v_mfma_f32_16x16x32_bf16 v[74:77], v[162:165], v[242:245], v[74:77]
	s_setprio 0
	s_setprio 1
	v_mfma_f32_16x16x32_bf16 v[120:123], v[180:183], v[196:199], 0
	v_mfma_f32_16x16x32_bf16 v[120:123], v[184:187], v[200:203], v[120:123]
	v_mfma_f32_16x16x32_bf16 v[116:119], v[188:191], v[196:199], 0
	v_mfma_f32_16x16x32_bf16 v[116:119], v[192:195], v[200:203], v[116:119]
	v_mfma_f32_16x16x32_bf16 v[104:107], v[180:183], v[222:225], 0
	v_mfma_f32_16x16x32_bf16 v[104:107], v[184:187], v[226:229], v[104:107]
	v_mfma_f32_16x16x32_bf16 v[100:103], v[188:191], v[222:225], 0
	v_mfma_f32_16x16x32_bf16 v[100:103], v[192:195], v[226:229], v[100:103]
	v_mfma_f32_16x16x32_bf16 v[86:89], v[180:183], v[230:233], 0
	v_mfma_f32_16x16x32_bf16 v[86:89], v[184:187], v[234:237], v[86:89]
	v_mfma_f32_16x16x32_bf16 v[82:85], v[188:191], v[230:233], 0
	v_mfma_f32_16x16x32_bf16 v[82:85], v[192:195], v[234:237], v[82:85]
	v_mfma_f32_16x16x32_bf16 v[70:73], v[180:183], v[238:241], 0
	v_mfma_f32_16x16x32_bf16 v[70:73], v[184:187], v[242:245], v[70:73]
	s_setprio 2
	s_barrier
	v_mfma_f32_16x16x32_bf16 v[66:69], v[188:191], v[238:241], 0
	v_mfma_f32_16x16x32_bf16 v[66:69], v[192:195], v[242:245], v[66:69]
	s_setprio 0
	s_mov_b32 m0, s94
	v_lshl_add_u64 v[166:167], s[60:61], 0, v[136:137]
	ds_read_b128 v[196:199], v153 offset:16384
	ds_read_b128 v[200:203], v153 offset:17408
	ds_read_b128 v[222:225], v153 offset:18432
	ds_read_b128 v[226:229], v153 offset:19456
	ds_read_b128 v[230:233], v153 offset:20480
	ds_read_b128 v[234:237], v153 offset:21504
	ds_read_b128 v[238:241], v153 offset:22528
	ds_read_b128 v[242:245], v153 offset:23552
	global_load_lds_dwordx4 v[166:167], off
	v_lshl_add_u64 v[168:169], s[60:61], 0, v[132:133]
	s_mov_b32 m0, s95
	v_lshl_add_u64 v[172:173], s[62:63], 0, v[136:137]
	global_load_lds_dwordx4 v[168:169], off
	s_mov_b32 m0, s96
	v_lshl_add_u64 v[212:213], s[58:59], 0, v[134:135]
	global_load_lds_dwordx4 v[172:173], off
	v_lshl_add_u64 v[172:173], s[62:63], 0, v[132:133]
	s_mov_b32 m0, s97
	s_nop 0
	global_load_lds_dwordx4 v[172:173], off
	v_lshl_add_u64 v[172:173], s[58:59], 0, v[138:139]
	s_mov_b32 m0, s71
	s_nop 0
	global_load_lds_dwordx4 v[172:173], off
	s_mov_b32 m0, s75
	s_nop 0
	global_load_lds_dwordx4 v[212:213], off
	s_waitcnt vmcnt(8)
	s_waitcnt lgkmcnt(0)
	s_setprio 1
	s_barrier
; #define PG8_STAGE(bufoff, gbase, voff) do { _Pragma("unroll") for (int _i = 0; _i < 2; ++_i) \
;         __builtin_amdgcn_global_load_lds((const unsigned*)((const char*)(gbase) + (voff)[_i]), (PG8_LAS unsigned*)(lds + (bufoff) + ldsw + _i * 8192), 16, 0, AUX_A); } while (0)
; #define PG8_STAGEB(bufoff, gbase, voff) do { _Pragma("unroll") for (int _i = 0; _i < 2; ++_i) \
;         __builtin_amdgcn_global_load_lds((const unsigned*)((const char*)(gbase) + (voff)[_i]), (PG8_LAS unsigned*)(lds + (bufoff) + ldsw + _i * 8192), 16, 0, AUX_B); } while (0)
; #define PG8_LDA(dst, b, h) do { _Pragma("unroll") for (int m = 0; m < 4; ++m) _Pragma("unroll") for (int k = 0; k < 2; ++k) dst[m][k] = *(const PG8_LAS bf16x8*)(lds + PG8_SA(b, h) + aoff + m * 2048 + k * 1024); } while (0)
; #define PG8_LDB(dst, b, h) do { _Pragma("unroll") for (int n = 0; n < 2; ++n) _Pragma("unroll") for (int k = 0; k < 2; ++k) dst[n][k] = *(const PG8_LAS bf16x8*)(lds + PG8_SB(b, h) + boff + n * 2048 + k * 1024); } while (0)
; #define PG8_MMA(ai, bj, At, Bt) do { __builtin_amdgcn_s_setprio(1); _Pragma("unroll") for (int m = 0; m < 4; ++m) _Pragma("unroll") for (int n = 0; n < 2; ++n) _Pragma("unroll") for (int k = 0; k < 2; ++k) \
;         acc[ai][bj][m][n] = __builtin_amdgcn_mfma_f32_16x16x32_bf16(Bt[n][k], At[m][k], acc[ai][bj][m][n], 0, 0, 0); __builtin_amdgcn_s_setprio(0); } while (0)
; template <class Epi, class Sched, bool ALIGN_EPI = false, bool SP2 = false>
; __device__ __forceinline__ void gemm_phase(PG8_LAS unsigned char* lds, const Gemm g, const Sched& S, const Epi& E) {
;     ...
;             if constexpr (SP2) {
;             PG8_LDB(B0, 0, 0); PG8_LDB(B1, 0, 1); PG8_SCHED; PG8_LDA(At, 0, 0); PG8_STAGE(PG8_SA(1, 1), a1 + hstep, voffA);
;             PG8_WAIT_V(8); PG8_WAIT_L(0); PG8_BAR; PG8_MMA(0, 0, At, B0); PG8_MMA(0, 1, At, B1); PG8_BAR; PG8_SCHED;
;             PG8_LDA(At, 0, 1); PG8_STAGEB(PG8_SB(0, 0), b2, voffB); PG8_STAGEB(PG8_SB(0, 1), b2 + hstep, voffB); PG8_STAGE(PG8_SA(0, 0), a2, voffA);
;             PG8_WAIT_V(8); PG8_WAIT_L(0); PG8_BAR; PG8_MMA(1, 0, At, B0); PG8_MMA(1, 1, At, B1); PG8_BAR; PG8_SCHED;
;             PG8_LDB(B0, 1, 0); PG8_LDB(B1, 1, 1); PG8_SCHED; PG8_LDA(At, 1, 0); PG8_STAGE(PG8_SA(0, 1), a2 + hstep, voffA);
;             PG8_WAIT_V(8); PG8_WAIT_L(0); PG8_BAR; PG8_MMA(0, 0, At, B0); PG8_MMA(0, 1, At, B1); PG8_BAR; PG8_SCHED;
	v_mfma_f32_16x16x32_bf16 v[62:65], v[148:151], v[196:199], 0
	v_mfma_f32_16x16x32_bf16 v[62:65], v[154:157], v[200:203], v[62:65]
	v_mfma_f32_16x16x32_bf16 v[58:61], v[158:161], v[196:199], 0
	v_mfma_f32_16x16x32_bf16 v[58:61], v[162:165], v[200:203], v[58:61]
	v_mfma_f32_16x16x32_bf16 v[46:49], v[148:151], v[222:225], 0
	v_mfma_f32_16x16x32_bf16 v[46:49], v[154:157], v[226:229], v[46:49]
	v_mfma_f32_16x16x32_bf16 v[42:45], v[158:161], v[222:225], 0
	v_mfma_f32_16x16x32_bf16 v[42:45], v[162:165], v[226:229], v[42:45]
	v_mfma_f32_16x16x32_bf16 v[30:33], v[148:151], v[230:233], 0
	v_mfma_f32_16x16x32_bf16 v[30:33], v[154:157], v[234:237], v[30:33]
	v_mfma_f32_16x16x32_bf16 v[26:29], v[158:161], v[230:233], 0
	v_mfma_f32_16x16x32_bf16 v[26:29], v[162:165], v[234:237], v[26:29]
	v_mfma_f32_16x16x32_bf16 v[14:17], v[148:151], v[238:241], 0
	v_mfma_f32_16x16x32_bf16 v[14:17], v[154:157], v[242:245], v[14:17]
	v_mfma_f32_16x16x32_bf16 v[10:13], v[158:161], v[238:241], 0
	v_mfma_f32_16x16x32_bf16 v[10:13], v[162:165], v[242:245], v[10:13]
	s_setprio 0
	s_setprio 1
	v_mfma_f32_16x16x32_bf16 v[54:57], v[180:183], v[196:199], 0
	v_mfma_f32_16x16x32_bf16 v[54:57], v[184:187], v[200:203], v[54:57]
	v_mfma_f32_16x16x32_bf16 v[50:53], v[188:191], v[196:199], 0
	v_mfma_f32_16x16x32_bf16 v[50:53], v[192:195], v[200:203], v[50:53]
	v_mfma_f32_16x16x32_bf16 v[38:41], v[180:183], v[222:225], 0
	v_mfma_f32_16x16x32_bf16 v[38:41], v[184:187], v[226:229], v[38:41]
	v_mfma_f32_16x16x32_bf16 v[34:37], v[188:191], v[222:225], 0
	v_mfma_f32_16x16x32_bf16 v[34:37], v[192:195], v[226:229], v[34:37]
	v_mfma_f32_16x16x32_bf16 v[22:25], v[180:183], v[230:233], 0
	v_mfma_f32_16x16x32_bf16 v[22:25], v[184:187], v[234:237], v[22:25]
	v_mfma_f32_16x16x32_bf16 v[18:21], v[188:191], v[230:233], 0
	v_mfma_f32_16x16x32_bf16 v[18:21], v[192:195], v[234:237], v[18:21]
	v_mfma_f32_16x16x32_bf16 v[6:9], v[180:183], v[238:241], 0
	v_mfma_f32_16x16x32_bf16 v[6:9], v[184:187], v[242:245], v[6:9]
	s_setprio 2
	s_barrier
	v_mfma_f32_16x16x32_bf16 v[2:5], v[188:191], v[238:241], 0
	v_mfma_f32_16x16x32_bf16 v[2:5], v[192:195], v[242:245], v[2:5]
	s_setprio 0
	v_add_u32_e32 v162, vcc_lo, v99
	v_add_u32_e32 v192, vcc_hi, v99
	ds_read_b128 v[148:151], v162
	ds_read_b128 v[154:157], v162 offset:1024
	ds_read_b128 v[158:161], v162 offset:2048
	ds_read_b128 v[162:165], v162 offset:3072
	ds_read_b128 v[180:183], v192
	ds_read_b128 v[184:187], v192 offset:1024
	ds_read_b128 v[188:191], v192 offset:2048
	ds_read_b128 v[192:195], v192 offset:3072
	s_mov_b32 m0, s78
	v_lshl_add_u64 v[246:247], s[56:57], 0, v[138:139]
	ds_read_b128 v[196:199], v153 offset:32768
	ds_read_b128 v[200:203], v153 offset:33792
	ds_read_b128 v[222:225], v153 offset:34816
	ds_read_b128 v[226:229], v153 offset:35840
	ds_read_b128 v[230:233], v153 offset:36864
	ds_read_b128 v[234:237], v153 offset:37888
	ds_read_b128 v[238:241], v153 offset:38912
	ds_read_b128 v[242:245], v153 offset:39936
	global_load_lds_dwordx4 v[246:247], off
	v_lshl_add_u64 v[246:247], s[56:57], 0, v[134:135]
	s_mov_b32 m0, s82
	s_nop 0
	global_load_lds_dwordx4 v[246:247], off
	s_waitcnt vmcnt(8)
	s_waitcnt lgkmcnt(0)
	s_setprio 1
	s_barrier
	v_mfma_f32_16x16x32_bf16 v[128:131], v[148:151], v[196:199], v[128:131]
	v_mfma_f32_16x16x32_bf16 v[128:131], v[154:157], v[200:203], v[128:131]
	v_mfma_f32_16x16x32_bf16 v[124:127], v[158:161], v[196:199], v[124:127]
	v_mfma_f32_16x16x32_bf16 v[124:127], v[162:165], v[200:203], v[124:127]
	v_mfma_f32_16x16x32_bf16 v[112:115], v[148:151], v[222:225], v[112:115]
	v_mfma_f32_16x16x32_bf16 v[112:115], v[154:157], v[226:229], v[112:115]
	v_mfma_f32_16x16x32_bf16 v[108:111], v[158:161], v[222:225], v[108:111]
	v_mfma_f32_16x16x32_bf16 v[108:111], v[162:165], v[226:229], v[108:111]
	v_mfma_f32_16x16x32_bf16 v[94:97], v[148:151], v[230:233], v[94:97]
	v_mfma_f32_16x16x32_bf16 v[94:97], v[154:157], v[234:237], v[94:97]
	v_mfma_f32_16x16x32_bf16 v[90:93], v[158:161], v[230:233], v[90:93]
	v_mfma_f32_16x16x32_bf16 v[90:93], v[162:165], v[234:237], v[90:93]
	v_mfma_f32_16x16x32_bf16 v[78:81], v[148:151], v[238:241], v[78:81]
	v_mfma_f32_16x16x32_bf16 v[78:81], v[154:157], v[242:245], v[78:81]
	v_mfma_f32_16x16x32_bf16 v[74:77], v[158:161], v[238:241], v[74:77]
	v_mfma_f32_16x16x32_bf16 v[74:77], v[162:165], v[242:245], v[74:77]
	s_setprio 0
	s_setprio 1
	v_mfma_f32_16x16x32_bf16 v[120:123], v[180:183], v[196:199], v[120:123]
	v_mfma_f32_16x16x32_bf16 v[120:123], v[184:187], v[200:203], v[120:123]
	v_mfma_f32_16x16x32_bf16 v[116:119], v[188:191], v[196:199], v[116:119]
	v_mfma_f32_16x16x32_bf16 v[116:119], v[192:195], v[200:203], v[116:119]
	v_mfma_f32_16x16x32_bf16 v[104:107], v[180:183], v[222:225], v[104:107]
	v_mfma_f32_16x16x32_bf16 v[104:107], v[184:187], v[226:229], v[104:107]
	v_mfma_f32_16x16x32_bf16 v[100:103], v[188:191], v[222:225], v[100:103]
	v_mfma_f32_16x16x32_bf16 v[100:103], v[192:195], v[226:229], v[100:103]
	v_mfma_f32_16x16x32_bf16 v[86:89], v[180:183], v[230:233], v[86:89]
	v_mfma_f32_16x16x32_bf16 v[86:89], v[184:187], v[234:237], v[86:89]
	v_mfma_f32_16x16x32_bf16 v[82:85], v[188:191], v[230:233], v[82:85]
	v_mfma_f32_16x16x32_bf16 v[82:85], v[192:195], v[234:237], v[82:85]
	v_mfma_f32_16x16x32_bf16 v[70:73], v[180:183], v[238:241], v[70:73]
	v_mfma_f32_16x16x32_bf16 v[70:73], v[184:187], v[242:245], v[70:73]
	s_setprio 2
	s_barrier
; #define PG8_STAGE(bufoff, gbase, voff) do { _Pragma("unroll") for (int _i = 0; _i < 2; ++_i) \
;         __builtin_amdgcn_global_load_lds((const unsigned*)((const char*)(gbase) + (voff)[_i]), (PG8_LAS unsigned*)(lds + (bufoff) + ldsw + _i * 8192), 16, 0, AUX_A); } while (0)
; #define PG8_STAGEB(bufoff, gbase, voff) do { _Pragma("unroll") for (int _i = 0; _i < 2; ++_i) \
;         __builtin_amdgcn_global_load_lds((const unsigned*)((const char*)(gbase) + (voff)[_i]), (PG8_LAS unsigned*)(lds + (bufoff) + ldsw + _i * 8192), 16, 0, AUX_B); } while (0)
; #define PG8_LDA(dst, b, h) do { _Pragma("unroll") for (int m = 0; m < 4; ++m) _Pragma("unroll") for (int k = 0; k < 2; ++k) dst[m][k] = *(const PG8_LAS bf16x8*)(lds + PG8_SA(b, h) + aoff + m * 2048 + k * 1024); } while (0)
; #define PG8_LDB(dst, b, h) do { _Pragma("unroll") for (int n = 0; n < 2; ++n) _Pragma("unroll") for (int k = 0; k < 2; ++k) dst[n][k] = *(const PG8_LAS bf16x8*)(lds + PG8_SB(b, h) + boff + n * 2048 + k * 1024); } while (0)
; #define PG8_MMA(ai, bj, At, Bt) do { __builtin_amdgcn_s_setprio(1); _Pragma("unroll") for (int m = 0; m < 4; ++m) _Pragma("unroll") for (int n = 0; n < 2; ++n) _Pragma("unroll") for (int k = 0; k < 2; ++k) \
;         acc[ai][bj][m][n] = __builtin_amdgcn_mfma_f32_16x16x32_bf16(Bt[n][k], At[m][k], acc[ai][bj][m][n], 0, 0, 0); __builtin_amdgcn_s_setprio(0); } while (0)
; #define PG8_WAIT_V(n) asm volatile("s_waitcnt vmcnt(" #n ")" ::: "memory")
; #define PG8_WAIT_L(n) asm volatile("s_waitcnt lgkmcnt(" #n ")" ::: "memory")
; #define PG8_BAR __builtin_amdgcn_s_barrier()
; #define PG8_SCHED __builtin_amdgcn_sched_barrier(0)
; template <class Epi, class Sched, bool ALIGN_EPI = false, bool SP2 = false>
; __device__ __forceinline__ void gemm_phase(PG8_LAS unsigned char* lds, const Gemm g, const Sched& S, const Epi& E) {
;     ...
;             PG8_LDB(B0, 1, 0); PG8_LDB(B1, 1, 1); PG8_SCHED; PG8_LDA(At, 1, 0); PG8_STAGE(PG8_SA(0, 1), a2 + hstep, voffA);
;             PG8_WAIT_V(8); PG8_WAIT_L(0); PG8_BAR; PG8_MMA(0, 0, At, B0); PG8_MMA(0, 1, At, B1); PG8_BAR; PG8_SCHED;
;             PG8_LDA(At, 1, 1); PG8_STAGEB(PG8_SB(1, 0), b3, voffB); PG8_STAGEB(PG8_SB(1, 1), b3 + hstep, voffB); PG8_STAGE(PG8_SA(1, 0), a3, voffA);
;             PG8_WAIT_V(8); PG8_WAIT_L(0); PG8_BAR; PG8_MMA(1, 0, At, B0); PG8_MMA(1, 1, At, B1); PG8_BAR; PG8_SCHED;
	v_mfma_f32_16x16x32_bf16 v[66:69], v[188:191], v[238:241], v[66:69]
	v_mfma_f32_16x16x32_bf16 v[66:69], v[192:195], v[242:245], v[66:69]
	s_setprio 0
	s_mov_b32 m0, s1
	v_lshl_add_u64 v[166:167], v[166:167], 0, s[76:77]
	ds_read_b128 v[196:199], v153 offset:49152
	ds_read_b128 v[200:203], v153 offset:50176
	ds_read_b128 v[222:225], v153 offset:51200
	ds_read_b128 v[226:229], v153 offset:52224
	ds_read_b128 v[230:233], v153 offset:53248
	ds_read_b128 v[234:237], v153 offset:54272
	ds_read_b128 v[238:241], v153 offset:55296
	ds_read_b128 v[242:245], v153 offset:56320
	global_load_lds_dwordx4 v[166:167], off
	v_lshl_add_u64 v[166:167], v[168:169], 0, s[76:77]
	s_mov_b32 m0, s0
	s_nop 0
	global_load_lds_dwordx4 v[166:167], off
	v_lshl_add_u64 v[166:167], s[54:55], 0, v[136:137]
	s_mov_b32 m0, s47
	s_nop 0
	global_load_lds_dwordx4 v[166:167], off
	v_lshl_add_u64 v[166:167], s[54:55], 0, v[132:133]
	s_mov_b32 m0, s46
	s_nop 0
	global_load_lds_dwordx4 v[166:167], off
	v_lshl_add_u64 v[166:167], v[172:173], 0, s[76:77]
	s_mov_b32 m0, s83
	s_nop 0
	global_load_lds_dwordx4 v[166:167], off
	v_lshl_add_u64 v[166:167], v[212:213], 0, s[76:77]
	s_mov_b32 m0, s88
	s_nop 0
	global_load_lds_dwordx4 v[166:167], off
	s_waitcnt vmcnt(8)
	s_waitcnt lgkmcnt(0)
	s_setprio 1
	s_barrier
	v_mfma_f32_16x16x32_bf16 v[62:65], v[148:151], v[196:199], v[62:65]
	v_mfma_f32_16x16x32_bf16 v[62:65], v[154:157], v[200:203], v[62:65]
	v_mfma_f32_16x16x32_bf16 v[58:61], v[158:161], v[196:199], v[58:61]
	v_mfma_f32_16x16x32_bf16 v[58:61], v[162:165], v[200:203], v[58:61]
	v_mfma_f32_16x16x32_bf16 v[46:49], v[148:151], v[222:225], v[46:49]
	v_mfma_f32_16x16x32_bf16 v[46:49], v[154:157], v[226:229], v[46:49]
	v_mfma_f32_16x16x32_bf16 v[42:45], v[158:161], v[222:225], v[42:45]
	v_mfma_f32_16x16x32_bf16 v[42:45], v[162:165], v[226:229], v[42:45]
	v_mfma_f32_16x16x32_bf16 v[30:33], v[148:151], v[230:233], v[30:33]
	v_mfma_f32_16x16x32_bf16 v[30:33], v[154:157], v[234:237], v[30:33]
	v_mfma_f32_16x16x32_bf16 v[26:29], v[158:161], v[230:233], v[26:29]
	v_mfma_f32_16x16x32_bf16 v[26:29], v[162:165], v[234:237], v[26:29]
	v_mfma_f32_16x16x32_bf16 v[14:17], v[148:151], v[238:241], v[14:17]
	v_mfma_f32_16x16x32_bf16 v[14:17], v[154:157], v[242:245], v[14:17]
	v_mfma_f32_16x16x32_bf16 v[10:13], v[158:161], v[238:241], v[10:13]
	v_mfma_f32_16x16x32_bf16 v[10:13], v[162:165], v[242:245], v[10:13]
	s_setprio 0
	s_setprio 1
	v_mfma_f32_16x16x32_bf16 v[54:57], v[180:183], v[196:199], v[54:57]
	v_mfma_f32_16x16x32_bf16 v[54:57], v[184:187], v[200:203], v[54:57]
	v_mfma_f32_16x16x32_bf16 v[50:53], v[188:191], v[196:199], v[50:53]
	v_mfma_f32_16x16x32_bf16 v[50:53], v[192:195], v[200:203], v[50:53]
	v_mfma_f32_16x16x32_bf16 v[38:41], v[180:183], v[222:225], v[38:41]
	v_mfma_f32_16x16x32_bf16 v[38:41], v[184:187], v[226:229], v[38:41]
	v_mfma_f32_16x16x32_bf16 v[34:37], v[188:191], v[222:225], v[34:37]
	v_mfma_f32_16x16x32_bf16 v[34:37], v[192:195], v[226:229], v[34:37]
	v_mfma_f32_16x16x32_bf16 v[22:25], v[180:183], v[230:233], v[22:25]
	v_mfma_f32_16x16x32_bf16 v[22:25], v[184:187], v[234:237], v[22:25]
	v_mfma_f32_16x16x32_bf16 v[18:21], v[188:191], v[230:233], v[18:21]
	v_mfma_f32_16x16x32_bf16 v[18:21], v[192:195], v[234:237], v[18:21]
	v_mfma_f32_16x16x32_bf16 v[6:9], v[180:183], v[238:241], v[6:9]
	v_mfma_f32_16x16x32_bf16 v[6:9], v[184:187], v[242:245], v[6:9]
	s_setprio 2
	s_cbranch_scc1 .Lq4x_1157p
	s_barrier

; #define PG8_STAGE(bufoff, gbase, voff) do { _Pragma("unroll") for (int _i = 0; _i < 2; ++_i) \
;         __builtin_amdgcn_global_load_lds((const unsigned*)((const char*)(gbase) + (voff)[_i]), (PG8_LAS unsigned*)(lds + (bufoff) + ldsw + _i * 8192), 16, 0, AUX_A); } while (0)
; #define PG8_STAGEB(bufoff, gbase, voff) do { _Pragma("unroll") for (int _i = 0; _i < 2; ++_i) \
;         __builtin_amdgcn_global_load_lds((const unsigned*)((const char*)(gbase) + (voff)[_i]), (PG8_LAS unsigned*)(lds + (bufoff) + ldsw + _i * 8192), 16, 0, AUX_B); } while (0)
; #define PG8_LDA(dst, b, h) do { _Pragma("unroll") for (int m = 0; m < 4; ++m) _Pragma("unroll") for (int k = 0; k < 2; ++k) dst[m][k] = *(const PG8_LAS bf16x8*)(lds + PG8_SA(b, h) + aoff + m * 2048 + k * 1024); } while (0)
; #define PG8_LDB(dst, b, h) do { _Pragma("unroll") for (int n = 0; n < 2; ++n) _Pragma("unroll") for (int k = 0; k < 2; ++k) dst[n][k] = *(const PG8_LAS bf16x8*)(lds + PG8_SB(b, h) + boff + n * 2048 + k * 1024); } while (0)
; #define PG8_WAIT_V(n) asm volatile("s_waitcnt vmcnt(" #n ")" ::: "memory")
; #define PG8_WAIT_L(n) asm volatile("s_waitcnt lgkmcnt(" #n ")" ::: "memory")
; #define PG8_BAR __builtin_amdgcn_s_barrier()
; template <class Epi, class Sched, bool ALIGN_EPI = false, bool SP2 = false>
; __device__ __forceinline__ void gemm_phase(PG8_LAS unsigned char* lds, const Gemm g, const Sched& S, const Epi& E) {
;     ...
;         for (int t = 0; t < nt; t += 2) {
;             const bool last = (t == nt - 2);
;             const char* a1 = PG8_KP(cA, t + 1, rot, nt);
;             const char* a2 = last ? nAr : PG8_KP(cA, t + 2, rot, nt); const char* b2 = last ? nBr : PG8_KP(cB, t + 2, rot, nt);
;             const char* a3 = a2 + kstep; const char* b3 = b2 + kstep;
;             if (last && has_next) S.a_ready(nxt);
;             if constexpr (SP2) {
;             PG8_LDB(B0, 0, 0); PG8_LDB(B1, 0, 1); PG8_SCHED; PG8_LDA(At, 0, 0); PG8_STAGE(PG8_SA(1, 1), a1 + hstep, voffA);
;             PG8_WAIT_V(8); PG8_WAIT_L(0); PG8_BAR; PG8_MMA(0, 0, At, B0); PG8_MMA(0, 1, At, B1); PG8_BAR; PG8_SCHED;
;             PG8_LDA(At, 0, 1); PG8_STAGEB(PG8_SB(0, 0), b2, voffB); PG8_STAGEB(PG8_SB(0, 1), b2 + hstep, voffB); PG8_STAGE(PG8_SA(0, 0), a2, voffA);
;             PG8_WAIT_V(8); PG8_WAIT_L(0); PG8_BAR; PG8_MMA(1, 0, At, B0); PG8_MMA(1, 1, At, B1); PG8_BAR; PG8_SCHED;
.LBB0_1157:
	s_add_i32 s81, s29, 2
	s_cmp_lt_u32 s29, 14
	s_cselect_b32 s0, 0, -16
	s_add_i32 s0, s81, s0
	s_ashr_i32 s1, s0, 31
	s_lshl_b64 s[0:1], s[0:1], 7
	s_add_u32 s2, s52, s0
	s_addc_u32 s46, s53, s1
	s_add_u32 s0, s50, s0
	s_addc_u32 s1, s51, s1
	s_cmp_eq_u32 s29, 14
	s_cselect_b32 s59, s19, s46
	s_cselect_b32 s58, s39, s2
	s_cselect_b32 s61, s92, s1
	s_cselect_b32 s60, s93, s0
	s_add_i32 s2, 0, 0x10000
	s_add_i32 s94, s2, s70
	s_add_i32 s46, 0, 0x14000
	s_add_i32 m0, s71, 0xc000
	s_add_i32 s84, s71, 0xe000
	s_add_i32 s95, s94, 0x2000
	s_add_u32 s62, s60, 0x40000
	s_addc_u32 s63, s61, 0
	s_add_i32 s96, s46, s70
	v_add_u32_e32 v162, s2, v99
	v_add_u32_e32 v166, s46, v99
	s_add_i32 s97, s96, 0x2000
	s_add_i32 vcc_lo, 0, 0x18000
	s_add_i32 vcc_hi, 0, 0x1c000
	ds_read_b128 v[148:151], v162
	ds_read_b128 v[154:157], v162 offset:1024
	ds_read_b128 v[158:161], v162 offset:2048
	ds_read_b128 v[162:165], v162 offset:3072
	ds_read_b128 v[180:183], v166
	ds_read_b128 v[184:187], v166 offset:1024
	ds_read_b128 v[188:191], v166 offset:2048
	ds_read_b128 v[192:195], v166 offset:3072
	s_add_u32 s56, s58, 0x40000
	s_addc_u32 s57, s59, 0
	s_add_i32 s1, vcc_lo, s70
	s_add_i32 s0, s1, 0x2000
	s_add_u32 s54, s60, 0x40080
	s_addc_u32 s55, s61, 0
	s_add_i32 s47, vcc_hi, s70
	s_add_i32 s46, s47, 0x2000
	s_cmp_gt_u32 s29, 13
	ds_read_b128 v[196:199], v153
	ds_read_b128 v[200:203], v153 offset:1024
	ds_read_b128 v[222:225], v153 offset:2048
	ds_read_b128 v[226:229], v153 offset:3072
	ds_read_b128 v[230:233], v153 offset:4096
	ds_read_b128 v[234:237], v153 offset:5120
	ds_read_b128 v[238:241], v153 offset:6144
	ds_read_b128 v[242:245], v153 offset:7168
	global_load_lds_dwordx4 v[146:147], off
	s_mov_b32 m0, s84
	s_nop 0
	global_load_lds_dwordx4 v[144:145], off
	s_waitcnt vmcnt(8)
	s_waitcnt lgkmcnt(0)
	s_setprio 1
	s_barrier
	v_mfma_f32_16x16x32_bf16 v[128:131], v[148:151], v[196:199], v[128:131]
	v_mfma_f32_16x16x32_bf16 v[128:131], v[154:157], v[200:203], v[128:131]
	v_mfma_f32_16x16x32_bf16 v[124:127], v[158:161], v[196:199], v[124:127]
	v_mfma_f32_16x16x32_bf16 v[124:127], v[162:165], v[200:203], v[124:127]
	v_mfma_f32_16x16x32_bf16 v[112:115], v[148:151], v[222:225], v[112:115]
	v_mfma_f32_16x16x32_bf16 v[112:115], v[154:157], v[226:229], v[112:115]
	v_mfma_f32_16x16x32_bf16 v[108:111], v[158:161], v[222:225], v[108:111]
	v_mfma_f32_16x16x32_bf16 v[108:111], v[162:165], v[226:229], v[108:111]
	v_mfma_f32_16x16x32_bf16 v[94:97], v[148:151], v[230:233], v[94:97]
	v_mfma_f32_16x16x32_bf16 v[94:97], v[154:157], v[234:237], v[94:97]
	v_mfma_f32_16x16x32_bf16 v[90:93], v[158:161], v[230:233], v[90:93]
	v_mfma_f32_16x16x32_bf16 v[90:93], v[162:165], v[234:237], v[90:93]
	v_mfma_f32_16x16x32_bf16 v[78:81], v[148:151], v[238:241], v[78:81]
	v_mfma_f32_16x16x32_bf16 v[78:81], v[154:157], v[242:245], v[78:81]
	v_mfma_f32_16x16x32_bf16 v[74:77], v[158:161], v[238:241], v[74:77]
	v_mfma_f32_16x16x32_bf16 v[74:77], v[162:165], v[242:245], v[74:77]
	s_setprio 0
	s_setprio 1
	v_mfma_f32_16x16x32_bf16 v[120:123], v[180:183], v[196:199], v[120:123]
	v_mfma_f32_16x16x32_bf16 v[120:123], v[184:187], v[200:203], v[120:123]
	v_mfma_f32_16x16x32_bf16 v[116:119], v[188:191], v[196:199], v[116:119]
	v_mfma_f32_16x16x32_bf16 v[116:119], v[192:195], v[200:203], v[116:119]
	v_mfma_f32_16x16x32_bf16 v[104:107], v[180:183], v[222:225], v[104:107]
	v_mfma_f32_16x16x32_bf16 v[104:107], v[184:187], v[226:229], v[104:107]
	v_mfma_f32_16x16x32_bf16 v[100:103], v[188:191], v[222:225], v[100:103]
	v_mfma_f32_16x16x32_bf16 v[100:103], v[192:195], v[226:229], v[100:103]
	v_mfma_f32_16x16x32_bf16 v[86:89], v[180:183], v[230:233], v[86:89]
	v_mfma_f32_16x16x32_bf16 v[86:89], v[184:187], v[234:237], v[86:89]
	v_mfma_f32_16x16x32_bf16 v[82:85], v[188:191], v[230:233], v[82:85]
	v_mfma_f32_16x16x32_bf16 v[82:85], v[192:195], v[234:237], v[82:85]
	v_mfma_f32_16x16x32_bf16 v[70:73], v[180:183], v[238:241], v[70:73]
	v_mfma_f32_16x16x32_bf16 v[70:73], v[184:187], v[242:245], v[70:73]
	s_setprio 2
	s_barrier
	v_mfma_f32_16x16x32_bf16 v[66:69], v[188:191], v[238:241], v[66:69]
	v_mfma_f32_16x16x32_bf16 v[66:69], v[192:195], v[242:245], v[66:69]
	s_setprio 0
	s_mov_b32 m0, s94
	v_lshl_add_u64 v[166:167], s[60:61], 0, v[136:137]
	ds_read_b128 v[196:199], v153 offset:16384
	ds_read_b128 v[200:203], v153 offset:17408
	ds_read_b128 v[222:225], v153 offset:18432
	ds_read_b128 v[226:229], v153 offset:19456
	ds_read_b128 v[230:233], v153 offset:20480
	ds_read_b128 v[234:237], v153 offset:21504
	ds_read_b128 v[238:241], v153 offset:22528
	ds_read_b128 v[242:245], v153 offset:23552
	global_load_lds_dwordx4 v[166:167], off
	v_lshl_add_u64 v[168:169], s[60:61], 0, v[132:133]
	s_mov_b32 m0, s95
	v_lshl_add_u64 v[172:173], s[62:63], 0, v[136:137]
	global_load_lds_dwordx4 v[168:169], off
	s_mov_b32 m0, s96
	v_lshl_add_u64 v[212:213], s[58:59], 0, v[134:135]
	global_load_lds_dwordx4 v[172:173], off
	v_lshl_add_u64 v[172:173], s[62:63], 0, v[132:133]
	s_mov_b32 m0, s97
	s_nop 0
	global_load_lds_dwordx4 v[172:173], off
	v_lshl_add_u64 v[172:173], s[58:59], 0, v[138:139]
	s_mov_b32 m0, s71
	s_nop 0
	global_load_lds_dwordx4 v[172:173], off
	s_mov_b32 m0, s75
	s_nop 0
	global_load_lds_dwordx4 v[212:213], off
	s_waitcnt vmcnt(8)
	s_waitcnt lgkmcnt(0)
	s_setprio 1
	s_barrier
; #define PG8_STAGE(bufoff, gbase, voff) do { _Pragma("unroll") for (int _i = 0; _i < 2; ++_i) \
;         __builtin_amdgcn_global_load_lds((const unsigned*)((const char*)(gbase) + (voff)[_i]), (PG8_LAS unsigned*)(lds + (bufoff) + ldsw + _i * 8192), 16, 0, AUX_A); } while (0)
; #define PG8_STAGEB(bufoff, gbase, voff) do { _Pragma("unroll") for (int _i = 0; _i < 2; ++_i) \
;         __builtin_amdgcn_global_load_lds((const unsigned*)((const char*)(gbase) + (voff)[_i]), (PG8_LAS unsigned*)(lds + (bufoff) + ldsw + _i * 8192), 16, 0, AUX_B); } while (0)
; #define PG8_LDA(dst, b, h) do { _Pragma("unroll") for (int m = 0; m < 4; ++m) _Pragma("unroll") for (int k = 0; k < 2; ++k) dst[m][k] = *(const PG8_LAS bf16x8*)(lds + PG8_SA(b, h) + aoff + m * 2048 + k * 1024); } while (0)
; #define PG8_LDB(dst, b, h) do { _Pragma("unroll") for (int n = 0; n < 2; ++n) _Pragma("unroll") for (int k = 0; k < 2; ++k) dst[n][k] = *(const PG8_LAS bf16x8*)(lds + PG8_SB(b, h) + boff + n * 2048 + k * 1024); } while (0)
; #define PG8_MMA(ai, bj, At, Bt) do { __builtin_amdgcn_s_setprio(1); _Pragma("unroll") for (int m = 0; m < 4; ++m) _Pragma("unroll") for (int n = 0; n < 2; ++n) _Pragma("unroll") for (int k = 0; k < 2; ++k) \
;         acc[ai][bj][m][n] = __builtin_amdgcn_mfma_f32_16x16x32_bf16(Bt[n][k], At[m][k], acc[ai][bj][m][n], 0, 0, 0); __builtin_amdgcn_s_setprio(0); } while (0)
; template <class Epi, class Sched, bool ALIGN_EPI = false, bool SP2 = false>
; __device__ __forceinline__ void gemm_phase(PG8_LAS unsigned char* lds, const Gemm g, const Sched& S, const Epi& E) {
;     ...
;             if constexpr (SP2) {
;             PG8_LDB(B0, 0, 0); PG8_LDB(B1, 0, 1); PG8_SCHED; PG8_LDA(At, 0, 0); PG8_STAGE(PG8_SA(1, 1), a1 + hstep, voffA);
;             PG8_WAIT_V(8); PG8_WAIT_L(0); PG8_BAR; PG8_MMA(0, 0, At, B0); PG8_MMA(0, 1, At, B1); PG8_BAR; PG8_SCHED;
;             PG8_LDA(At, 0, 1); PG8_STAGEB(PG8_SB(0, 0), b2, voffB); PG8_STAGEB(PG8_SB(0, 1), b2 + hstep, voffB); PG8_STAGE(PG8_SA(0, 0), a2, voffA);
;             PG8_WAIT_V(8); PG8_WAIT_L(0); PG8_BAR; PG8_MMA(1, 0, At, B0); PG8_MMA(1, 1, At, B1); PG8_BAR; PG8_SCHED;
;             PG8_LDB(B0, 1, 0); PG8_LDB(B1, 1, 1); PG8_SCHED; PG8_LDA(At, 1, 0); PG8_STAGE(PG8_SA(0, 1), a2 + hstep, voffA);
;             PG8_WAIT_V(8); PG8_WAIT_L(0); PG8_BAR; PG8_MMA(0, 0, At, B0); PG8_MMA(0, 1, At, B1); PG8_BAR; PG8_SCHED;
	v_mfma_f32_16x16x32_bf16 v[62:65], v[148:151], v[196:199], v[62:65]
	v_mfma_f32_16x16x32_bf16 v[62:65], v[154:157], v[200:203], v[62:65]
	v_mfma_f32_16x16x32_bf16 v[58:61], v[158:161], v[196:199], v[58:61]
	v_mfma_f32_16x16x32_bf16 v[58:61], v[162:165], v[200:203], v[58:61]
	v_mfma_f32_16x16x32_bf16 v[46:49], v[148:151], v[222:225], v[46:49]
	v_mfma_f32_16x16x32_bf16 v[46:49], v[154:157], v[226:229], v[46:49]
	v_mfma_f32_16x16x32_bf16 v[42:45], v[158:161], v[222:225], v[42:45]
	v_mfma_f32_16x16x32_bf16 v[42:45], v[162:165], v[226:229], v[42:45]
	v_mfma_f32_16x16x32_bf16 v[30:33], v[148:151], v[230:233], v[30:33]
	v_mfma_f32_16x16x32_bf16 v[30:33], v[154:157], v[234:237], v[30:33]
	v_mfma_f32_16x16x32_bf16 v[26:29], v[158:161], v[230:233], v[26:29]
	v_mfma_f32_16x16x32_bf16 v[26:29], v[162:165], v[234:237], v[26:29]
	v_mfma_f32_16x16x32_bf16 v[14:17], v[148:151], v[238:241], v[14:17]
	v_mfma_f32_16x16x32_bf16 v[14:17], v[154:157], v[242:245], v[14:17]
	v_mfma_f32_16x16x32_bf16 v[10:13], v[158:161], v[238:241], v[10:13]
	v_mfma_f32_16x16x32_bf16 v[10:13], v[162:165], v[242:245], v[10:13]
	s_setprio 0
	s_setprio 1
	v_mfma_f32_16x16x32_bf16 v[54:57], v[180:183], v[196:199], v[54:57]
	v_mfma_f32_16x16x32_bf16 v[54:57], v[184:187], v[200:203], v[54:57]
	v_mfma_f32_16x16x32_bf16 v[50:53], v[188:191], v[196:199], v[50:53]
	v_mfma_f32_16x16x32_bf16 v[50:53], v[192:195], v[200:203], v[50:53]
	v_mfma_f32_16x16x32_bf16 v[38:41], v[180:183], v[222:225], v[38:41]
	v_mfma_f32_16x16x32_bf16 v[38:41], v[184:187], v[226:229], v[38:41]
	v_mfma_f32_16x16x32_bf16 v[34:37], v[188:191], v[222:225], v[34:37]
	v_mfma_f32_16x16x32_bf16 v[34:37], v[192:195], v[226:229], v[34:37]
	v_mfma_f32_16x16x32_bf16 v[22:25], v[180:183], v[230:233], v[22:25]
	v_mfma_f32_16x16x32_bf16 v[22:25], v[184:187], v[234:237], v[22:25]
	v_mfma_f32_16x16x32_bf16 v[18:21], v[188:191], v[230:233], v[18:21]
	v_mfma_f32_16x16x32_bf16 v[18:21], v[192:195], v[234:237], v[18:21]
	v_mfma_f32_16x16x32_bf16 v[6:9], v[180:183], v[238:241], v[6:9]
	v_mfma_f32_16x16x32_bf16 v[6:9], v[184:187], v[242:245], v[6:9]
	s_setprio 2
	s_barrier
	v_mfma_f32_16x16x32_bf16 v[2:5], v[188:191], v[238:241], v[2:5]
	v_mfma_f32_16x16x32_bf16 v[2:5], v[192:195], v[242:245], v[2:5]
	s_setprio 0
	v_add_u32_e32 v162, vcc_lo, v99
	v_add_u32_e32 v192, vcc_hi, v99
	ds_read_b128 v[148:151], v162
	ds_read_b128 v[154:157], v162 offset:1024
	ds_read_b128 v[158:161], v162 offset:2048
	ds_read_b128 v[162:165], v162 offset:3072
	ds_read_b128 v[180:183], v192
	ds_read_b128 v[184:187], v192 offset:1024
	ds_read_b128 v[188:191], v192 offset:2048
	ds_read_b128 v[192:195], v192 offset:3072
	s_mov_b32 m0, s78
	v_lshl_add_u64 v[246:247], s[56:57], 0, v[138:139]
	ds_read_b128 v[196:199], v153 offset:32768
	ds_read_b128 v[200:203], v153 offset:33792
	ds_read_b128 v[222:225], v153 offset:34816
	ds_read_b128 v[226:229], v153 offset:35840
	ds_read_b128 v[230:233], v153 offset:36864
	ds_read_b128 v[234:237], v153 offset:37888
	ds_read_b128 v[238:241], v153 offset:38912
	ds_read_b128 v[242:245], v153 offset:39936
	global_load_lds_dwordx4 v[246:247], off
	v_lshl_add_u64 v[246:247], s[56:57], 0, v[134:135]
	s_mov_b32 m0, s82
	s_nop 0
	global_load_lds_dwordx4 v[246:247], off
	s_waitcnt vmcnt(8)
	s_waitcnt lgkmcnt(0)
	s_setprio 1
	s_barrier
	v_mfma_f32_16x16x32_bf16 v[128:131], v[148:151], v[196:199], v[128:131]
	v_mfma_f32_16x16x32_bf16 v[128:131], v[154:157], v[200:203], v[128:131]
	v_mfma_f32_16x16x32_bf16 v[124:127], v[158:161], v[196:199], v[124:127]
	v_mfma_f32_16x16x32_bf16 v[124:127], v[162:165], v[200:203], v[124:127]
	v_mfma_f32_16x16x32_bf16 v[112:115], v[148:151], v[222:225], v[112:115]
	v_mfma_f32_16x16x32_bf16 v[112:115], v[154:157], v[226:229], v[112:115]
	v_mfma_f32_16x16x32_bf16 v[108:111], v[158:161], v[222:225], v[108:111]
	v_mfma_f32_16x16x32_bf16 v[108:111], v[162:165], v[226:229], v[108:111]
	v_mfma_f32_16x16x32_bf16 v[94:97], v[148:151], v[230:233], v[94:97]
	v_mfma_f32_16x16x32_bf16 v[94:97], v[154:157], v[234:237], v[94:97]
	v_mfma_f32_16x16x32_bf16 v[90:93], v[158:161], v[230:233], v[90:93]
	v_mfma_f32_16x16x32_bf16 v[90:93], v[162:165], v[234:237], v[90:93]
	v_mfma_f32_16x16x32_bf16 v[78:81], v[148:151], v[238:241], v[78:81]
	v_mfma_f32_16x16x32_bf16 v[78:81], v[154:157], v[242:245], v[78:81]
	v_mfma_f32_16x16x32_bf16 v[74:77], v[158:161], v[238:241], v[74:77]
	v_mfma_f32_16x16x32_bf16 v[74:77], v[162:165], v[242:245], v[74:77]
	s_setprio 0
	s_setprio 1
	v_mfma_f32_16x16x32_bf16 v[120:123], v[180:183], v[196:199], v[120:123]
	v_mfma_f32_16x16x32_bf16 v[120:123], v[184:187], v[200:203], v[120:123]
	v_mfma_f32_16x16x32_bf16 v[116:119], v[188:191], v[196:199], v[116:119]
	v_mfma_f32_16x16x32_bf16 v[116:119], v[192:195], v[200:203], v[116:119]
	v_mfma_f32_16x16x32_bf16 v[104:107], v[180:183], v[222:225], v[104:107]
	v_mfma_f32_16x16x32_bf16 v[104:107], v[184:187], v[226:229], v[104:107]
	v_mfma_f32_16x16x32_bf16 v[100:103], v[188:191], v[222:225], v[100:103]
	v_mfma_f32_16x16x32_bf16 v[100:103], v[192:195], v[226:229], v[100:103]
	v_mfma_f32_16x16x32_bf16 v[86:89], v[180:183], v[230:233], v[86:89]
	v_mfma_f32_16x16x32_bf16 v[86:89], v[184:187], v[234:237], v[86:89]
	v_mfma_f32_16x16x32_bf16 v[82:85], v[188:191], v[230:233], v[82:85]
	v_mfma_f32_16x16x32_bf16 v[82:85], v[192:195], v[234:237], v[82:85]
	v_mfma_f32_16x16x32_bf16 v[70:73], v[180:183], v[238:241], v[70:73]
	v_mfma_f32_16x16x32_bf16 v[70:73], v[184:187], v[242:245], v[70:73]
	s_setprio 2
	s_barrier
; #define PG8_STAGE(bufoff, gbase, voff) do { _Pragma("unroll") for (int _i = 0; _i < 2; ++_i) \
;         __builtin_amdgcn_global_load_lds((const unsigned*)((const char*)(gbase) + (voff)[_i]), (PG8_LAS unsigned*)(lds + (bufoff) + ldsw + _i * 8192), 16, 0, AUX_A); } while (0)
; #define PG8_STAGEB(bufoff, gbase, voff) do { _Pragma("unroll") for (int _i = 0; _i < 2; ++_i) \
;         __builtin_amdgcn_global_load_lds((const unsigned*)((const char*)(gbase) + (voff)[_i]), (PG8_LAS unsigned*)(lds + (bufoff) + ldsw + _i * 8192), 16, 0, AUX_B); } while (0)
; #define PG8_LDA(dst, b, h) do { _Pragma("unroll") for (int m = 0; m < 4; ++m) _Pragma("unroll") for (int k = 0; k < 2; ++k) dst[m][k] = *(const PG8_LAS bf16x8*)(lds + PG8_SA(b, h) + aoff + m * 2048 + k * 1024); } while (0)
; #define PG8_LDB(dst, b, h) do { _Pragma("unroll") for (int n = 0; n < 2; ++n) _Pragma("unroll") for (int k = 0; k < 2; ++k) dst[n][k] = *(const PG8_LAS bf16x8*)(lds + PG8_SB(b, h) + boff + n * 2048 + k * 1024); } while (0)
; #define PG8_MMA(ai, bj, At, Bt) do { __builtin_amdgcn_s_setprio(1); _Pragma("unroll") for (int m = 0; m < 4; ++m) _Pragma("unroll") for (int n = 0; n < 2; ++n) _Pragma("unroll") for (int k = 0; k < 2; ++k) \
;         acc[ai][bj][m][n] = __builtin_amdgcn_mfma_f32_16x16x32_bf16(Bt[n][k], At[m][k], acc[ai][bj][m][n], 0, 0, 0); __builtin_amdgcn_s_setprio(0); } while (0)
; #define PG8_WAIT_V(n) asm volatile("s_waitcnt vmcnt(" #n ")" ::: "memory")
; #define PG8_WAIT_L(n) asm volatile("s_waitcnt lgkmcnt(" #n ")" ::: "memory")
; #define PG8_BAR __builtin_amdgcn_s_barrier()
; #define PG8_SCHED __builtin_amdgcn_sched_barrier(0)
; template <class Epi, class Sched, bool ALIGN_EPI = false, bool SP2 = false>
; __device__ __forceinline__ void gemm_phase(PG8_LAS unsigned char* lds, const Gemm g, const Sched& S, const Epi& E) {
;     ...
;             PG8_LDB(B0, 1, 0); PG8_LDB(B1, 1, 1); PG8_SCHED; PG8_LDA(At, 1, 0); PG8_STAGE(PG8_SA(0, 1), a2 + hstep, voffA);
;             PG8_WAIT_V(8); PG8_WAIT_L(0); PG8_BAR; PG8_MMA(0, 0, At, B0); PG8_MMA(0, 1, At, B1); PG8_BAR; PG8_SCHED;
;             PG8_LDA(At, 1, 1); PG8_STAGEB(PG8_SB(1, 0), b3, voffB); PG8_STAGEB(PG8_SB(1, 1), b3 + hstep, voffB); PG8_STAGE(PG8_SA(1, 0), a3, voffA);
;             PG8_WAIT_V(8); PG8_WAIT_L(0); PG8_BAR; PG8_MMA(1, 0, At, B0); PG8_MMA(1, 1, At, B1); PG8_BAR; PG8_SCHED;
	v_mfma_f32_16x16x32_bf16 v[66:69], v[188:191], v[238:241], v[66:69]
	v_mfma_f32_16x16x32_bf16 v[66:69], v[192:195], v[242:245], v[66:69]
	s_setprio 0
	s_mov_b32 m0, s1
	v_lshl_add_u64 v[166:167], v[166:167], 0, s[76:77]
	ds_read_b128 v[196:199], v153 offset:49152
	ds_read_b128 v[200:203], v153 offset:50176
	ds_read_b128 v[222:225], v153 offset:51200
	ds_read_b128 v[226:229], v153 offset:52224
	ds_read_b128 v[230:233], v153 offset:53248
	ds_read_b128 v[234:237], v153 offset:54272
	ds_read_b128 v[238:241], v153 offset:55296
	ds_read_b128 v[242:245], v153 offset:56320
	global_load_lds_dwordx4 v[166:167], off
	v_lshl_add_u64 v[166:167], v[168:169], 0, s[76:77]
	s_mov_b32 m0, s0
	s_nop 0
	global_load_lds_dwordx4 v[166:167], off
	v_lshl_add_u64 v[166:167], s[54:55], 0, v[136:137]
	s_mov_b32 m0, s47
	s_nop 0
	global_load_lds_dwordx4 v[166:167], off
	v_lshl_add_u64 v[166:167], s[54:55], 0, v[132:133]
	s_mov_b32 m0, s46
	s_nop 0
	global_load_lds_dwordx4 v[166:167], off
	v_lshl_add_u64 v[166:167], v[172:173], 0, s[76:77]
	s_mov_b32 m0, s83
	s_nop 0
	global_load_lds_dwordx4 v[166:167], off
	v_lshl_add_u64 v[166:167], v[212:213], 0, s[76:77]
	s_mov_b32 m0, s88
	s_nop 0
	global_load_lds_dwordx4 v[166:167], off
	s_waitcnt vmcnt(8)
	s_waitcnt lgkmcnt(0)
	s_setprio 1
	s_barrier
	v_mfma_f32_16x16x32_bf16 v[62:65], v[148:151], v[196:199], v[62:65]
	v_mfma_f32_16x16x32_bf16 v[62:65], v[154:157], v[200:203], v[62:65]
	v_mfma_f32_16x16x32_bf16 v[58:61], v[158:161], v[196:199], v[58:61]
	v_mfma_f32_16x16x32_bf16 v[58:61], v[162:165], v[200:203], v[58:61]
	v_mfma_f32_16x16x32_bf16 v[46:49], v[148:151], v[222:225], v[46:49]
	v_mfma_f32_16x16x32_bf16 v[46:49], v[154:157], v[226:229], v[46:49]
	v_mfma_f32_16x16x32_bf16 v[42:45], v[158:161], v[222:225], v[42:45]
	v_mfma_f32_16x16x32_bf16 v[42:45], v[162:165], v[226:229], v[42:45]
	v_mfma_f32_16x16x32_bf16 v[30:33], v[148:151], v[230:233], v[30:33]
	v_mfma_f32_16x16x32_bf16 v[30:33], v[154:157], v[234:237], v[30:33]
	v_mfma_f32_16x16x32_bf16 v[26:29], v[158:161], v[230:233], v[26:29]
	v_mfma_f32_16x16x32_bf16 v[26:29], v[162:165], v[234:237], v[26:29]
	v_mfma_f32_16x16x32_bf16 v[14:17], v[148:151], v[238:241], v[14:17]
	v_mfma_f32_16x16x32_bf16 v[14:17], v[154:157], v[242:245], v[14:17]
	v_mfma_f32_16x16x32_bf16 v[10:13], v[158:161], v[238:241], v[10:13]
	v_mfma_f32_16x16x32_bf16 v[10:13], v[162:165], v[242:245], v[10:13]
	s_setprio 0
	s_setprio 1
	v_mfma_f32_16x16x32_bf16 v[54:57], v[180:183], v[196:199], v[54:57]
	v_mfma_f32_16x16x32_bf16 v[54:57], v[184:187], v[200:203], v[54:57]
	v_mfma_f32_16x16x32_bf16 v[50:53], v[188:191], v[196:199], v[50:53]
	v_mfma_f32_16x16x32_bf16 v[50:53], v[192:195], v[200:203], v[50:53]
	v_mfma_f32_16x16x32_bf16 v[38:41], v[180:183], v[222:225], v[38:41]
	v_mfma_f32_16x16x32_bf16 v[38:41], v[184:187], v[226:229], v[38:41]
	v_mfma_f32_16x16x32_bf16 v[34:37], v[188:191], v[222:225], v[34:37]
	v_mfma_f32_16x16x32_bf16 v[34:37], v[192:195], v[226:229], v[34:37]
	v_mfma_f32_16x16x32_bf16 v[22:25], v[180:183], v[230:233], v[22:25]
	v_mfma_f32_16x16x32_bf16 v[22:25], v[184:187], v[234:237], v[22:25]
	v_mfma_f32_16x16x32_bf16 v[18:21], v[188:191], v[230:233], v[18:21]
	v_mfma_f32_16x16x32_bf16 v[18:21], v[192:195], v[234:237], v[18:21]
	v_mfma_f32_16x16x32_bf16 v[6:9], v[180:183], v[238:241], v[6:9]
	v_mfma_f32_16x16x32_bf16 v[6:9], v[184:187], v[242:245], v[6:9]
	s_setprio 2
	s_cbranch_scc1 .Lq4x_1157l
	s_barrier

; #define PG8_MMA(ai, bj, At, Bt) do { __builtin_amdgcn_s_setprio(1); _Pragma("unroll") for (int m = 0; m < 4; ++m) _Pragma("unroll") for (int n = 0; n < 2; ++n) _Pragma("unroll") for (int k = 0; k < 2; ++k) \
;         acc[ai][bj][m][n] = __builtin_amdgcn_mfma_f32_16x16x32_bf16(Bt[n][k], At[m][k], acc[ai][bj][m][n], 0, 0, 0); __builtin_amdgcn_s_setprio(0); } while (0)
; #define PG8_WAIT_V(n) asm volatile("s_waitcnt vmcnt(" #n ")" ::: "memory")
; #define PG8_WAIT_L(n) asm volatile("s_waitcnt lgkmcnt(" #n ")" ::: "memory")
; #define PG8_BAR __builtin_amdgcn_s_barrier()
; #define PG8_SCHED __builtin_amdgcn_sched_barrier(0)
; template <class Epi, class Sched, bool ALIGN_EPI = false, bool SP2 = false>
; __device__ __forceinline__ void gemm_phase(PG8_LAS unsigned char* lds, const Gemm g, const Sched& S, const Epi& E) {
;     ...
;             PG8_WAIT_V(8); PG8_WAIT_L(0); PG8_BAR; PG8_MMA(1, 0, At, B0); PG8_MMA(1, 1, At, B1); PG8_BAR; PG8_SCHED;
;     ...
;         if constexpr (ALIGN_EPI) { if (wr == 0) PG8_BAR; }
.Lq4x_1157l:
	v_cmp_ne_u32_e64 vcc, s16, 0
	s_cbranch_vccz .Lq4r_1157l
	s_barrier
	s_branch .Lq4r_1157l

; #define PG8_STAGE(bufoff, gbase, voff) do { _Pragma("unroll") for (int _i = 0; _i < 2; ++_i) \
;         __builtin_amdgcn_global_load_lds((const unsigned*)((const char*)(gbase) + (voff)[_i]), (PG8_LAS unsigned*)(lds + (bufoff) + ldsw + _i * 8192), 16, 0, AUX_A); } while (0)
; #define PG8_STAGEB(bufoff, gbase, voff) do { _Pragma("unroll") for (int _i = 0; _i < 2; ++_i) \
;         __builtin_amdgcn_global_load_lds((const unsigned*)((const char*)(gbase) + (voff)[_i]), (PG8_LAS unsigned*)(lds + (bufoff) + ldsw + _i * 8192), 16, 0, AUX_B); } while (0)
; #define PG8_LDA(dst, b, h) do { _Pragma("unroll") for (int m = 0; m < 4; ++m) _Pragma("unroll") for (int k = 0; k < 2; ++k) dst[m][k] = *(const PG8_LAS bf16x8*)(lds + PG8_SA(b, h) + aoff + m * 2048 + k * 1024); } while (0)
; #define PG8_LDB(dst, b, h) do { _Pragma("unroll") for (int n = 0; n < 2; ++n) _Pragma("unroll") for (int k = 0; k < 2; ++k) dst[n][k] = *(const PG8_LAS bf16x8*)(lds + PG8_SB(b, h) + boff + n * 2048 + k * 1024); } while (0)
; #define PG8_WAIT_V(n) asm volatile("s_waitcnt vmcnt(" #n ")" ::: "memory")
; #define PG8_WAIT_L(n) asm volatile("s_waitcnt lgkmcnt(" #n ")" ::: "memory")
; #define PG8_BAR __builtin_amdgcn_s_barrier()
; template <class Epi, class Sched, bool ALIGN_EPI = false, bool SP2 = false>
; __device__ __forceinline__ void gemm_phase(PG8_LAS unsigned char* lds, const Gemm g, const Sched& S, const Epi& E) {
;     ...
;         for (int t = 0; t < nt; t += 2) {
;             const bool last = (t == nt - 2);
;             const char* a1 = PG8_KP(cA, t + 1, rot, nt);
;             const char* a2 = last ? nAr : PG8_KP(cA, t + 2, rot, nt); const char* b2 = last ? nBr : PG8_KP(cB, t + 2, rot, nt);
;             const char* a3 = a2 + kstep; const char* b3 = b2 + kstep;
;             if (last && has_next) S.a_ready(nxt);
;             if constexpr (SP2) {
;             PG8_LDB(B0, 0, 0); PG8_LDB(B1, 0, 1); PG8_SCHED; PG8_LDA(At, 0, 0); PG8_STAGE(PG8_SA(1, 1), a1 + hstep, voffA);
;             PG8_WAIT_V(8); PG8_WAIT_L(0); PG8_BAR; PG8_MMA(0, 0, At, B0); PG8_MMA(0, 1, At, B1); PG8_BAR; PG8_SCHED;
;             PG8_LDA(At, 0, 1); PG8_STAGEB(PG8_SB(0, 0), b2, voffB); PG8_STAGEB(PG8_SB(0, 1), b2 + hstep, voffB); PG8_STAGE(PG8_SA(0, 0), a2, voffA);
;             PG8_WAIT_V(8); PG8_WAIT_L(0); PG8_BAR; PG8_MMA(1, 0, At, B0); PG8_MMA(1, 1, At, B1); PG8_BAR; PG8_SCHED;
.Lpk_1308:
	s_or_b32 s0, s11, 1
	s_cmp_ge_i32 s0, s71
	s_cselect_b32 s2, s71, 0
	s_add_i32 s11, s11, 2
	s_cmp_ge_i32 s11, s71
	s_cselect_b32 s0, s71, 0
	s_sub_i32 s0, s13, s0
	s_ashr_i32 s1, s0, 31
	s_lshl_b64 s[0:1], s[0:1], 7
	s_add_u32 s15, s40, s0
	s_addc_u32 s29, s41, s1
	s_add_u32 s0, s34, s0
	s_addc_u32 s1, s35, s1
	s_cmp_eq_u32 s71, s13
	s_cselect_b32 s45, s43, s29
	s_cselect_b32 s44, s42, s15
	s_cselect_b32 s37, s19, s1
	s_cselect_b32 s36, s18, s0
	s_add_i32 s15, 0, 0x10000
	s_add_i32 s29, 0, 0x14000
	v_add_u32_e32 v148, s15, v99
	v_add_u32_e32 v168, s29, v99
	ds_read_b128 v[136:139], v148
	ds_read_b128 v[140:143], v148 offset:1024
	ds_read_b128 v[144:147], v148 offset:2048
	ds_read_b128 v[148:151], v148 offset:3072
	ds_read_b128 v[164:167], v168
	ds_read_b128 v[182:185], v168 offset:1024
	ds_read_b128 v[186:189], v168 offset:2048
	ds_read_b128 v[190:193], v168 offset:3072
	v_mad_i64_i32 v[168:169], s[0:1], s2, v220, v[134:135]
	s_add_i32 m0, s50, 0xc000
	ds_read_b128 v[194:197], v181
	ds_read_b128 v[198:201], v181 offset:1024
	ds_read_b128 v[222:225], v181 offset:2048
	ds_read_b128 v[226:229], v181 offset:3072
	ds_read_b128 v[230:233], v181 offset:4096
	ds_read_b128 v[234:237], v181 offset:5120
	ds_read_b128 v[238:241], v181 offset:6144
	ds_read_b128 v[242:245], v181 offset:7168
	global_load_lds_dwordx4 v[168:169], off
	v_mad_i64_i32 v[168:169], s[0:1], s2, v220, v[132:133]
	s_add_i32 m0, s50, 0xe000
	s_nop 0
	global_load_lds_dwordx4 v[168:169], off
	s_waitcnt vmcnt(8)
	s_waitcnt lgkmcnt(0)
	s_setprio 1
	s_barrier
	v_mfma_f32_16x16x32_bf16 v[128:131], v[136:139], v[194:197], 0
	v_mfma_f32_16x16x32_bf16 v[128:131], v[140:143], v[198:201], v[128:131]
	v_mfma_f32_16x16x32_bf16 v[124:127], v[144:147], v[194:197], 0
	v_mfma_f32_16x16x32_bf16 v[124:127], v[148:151], v[198:201], v[124:127]
	v_mfma_f32_16x16x32_bf16 v[120:123], v[136:139], v[222:225], 0
	v_mfma_f32_16x16x32_bf16 v[120:123], v[140:143], v[226:229], v[120:123]
	v_mfma_f32_16x16x32_bf16 v[112:115], v[144:147], v[222:225], 0
	v_mfma_f32_16x16x32_bf16 v[112:115], v[148:151], v[226:229], v[112:115]
	v_mfma_f32_16x16x32_bf16 v[104:107], v[136:139], v[230:233], 0
	v_mfma_f32_16x16x32_bf16 v[104:107], v[140:143], v[234:237], v[104:107]
	v_mfma_f32_16x16x32_bf16 v[94:97], v[144:147], v[230:233], 0
	v_mfma_f32_16x16x32_bf16 v[94:97], v[148:151], v[234:237], v[94:97]
	v_mfma_f32_16x16x32_bf16 v[86:89], v[136:139], v[238:241], 0
	v_mfma_f32_16x16x32_bf16 v[86:89], v[140:143], v[242:245], v[86:89]
	v_mfma_f32_16x16x32_bf16 v[78:81], v[144:147], v[238:241], 0
	v_mfma_f32_16x16x32_bf16 v[78:81], v[148:151], v[242:245], v[78:81]
	s_setprio 0
	s_setprio 1
	v_mfma_f32_16x16x32_bf16 v[116:119], v[164:167], v[194:197], 0
	v_mfma_f32_16x16x32_bf16 v[116:119], v[182:185], v[198:201], v[116:119]
	v_mfma_f32_16x16x32_bf16 v[108:111], v[186:189], v[194:197], 0
	v_mfma_f32_16x16x32_bf16 v[108:111], v[190:193], v[198:201], v[108:111]
	v_mfma_f32_16x16x32_bf16 v[100:103], v[164:167], v[222:225], 0
	v_mfma_f32_16x16x32_bf16 v[100:103], v[182:185], v[226:229], v[100:103]
	v_mfma_f32_16x16x32_bf16 v[90:93], v[186:189], v[222:225], 0
	v_mfma_f32_16x16x32_bf16 v[90:93], v[190:193], v[226:229], v[90:93]
	v_mfma_f32_16x16x32_bf16 v[82:85], v[164:167], v[230:233], 0
	v_mfma_f32_16x16x32_bf16 v[82:85], v[182:185], v[234:237], v[82:85]
	v_mfma_f32_16x16x32_bf16 v[74:77], v[186:189], v[230:233], 0
	v_mfma_f32_16x16x32_bf16 v[74:77], v[190:193], v[234:237], v[74:77]
	v_mfma_f32_16x16x32_bf16 v[70:73], v[164:167], v[238:241], 0
	v_mfma_f32_16x16x32_bf16 v[70:73], v[182:185], v[242:245], v[70:73]
	s_setprio 2
	s_barrier
	v_mfma_f32_16x16x32_bf16 v[66:69], v[186:189], v[238:241], 0
	v_mfma_f32_16x16x32_bf16 v[66:69], v[190:193], v[242:245], v[66:69]
	s_setprio 0
	s_add_i32 s0, s15, s49
	v_lshl_add_u64 v[168:169], s[36:37], 0, v[156:157]
	s_mov_b32 m0, s0
	ds_read_b128 v[194:197], v181 offset:16384
	ds_read_b128 v[198:201], v181 offset:17408
	ds_read_b128 v[222:225], v181 offset:18432
	ds_read_b128 v[226:229], v181 offset:19456
	ds_read_b128 v[230:233], v181 offset:20480
	ds_read_b128 v[234:237], v181 offset:21504
	ds_read_b128 v[238:241], v181 offset:22528
	ds_read_b128 v[242:245], v181 offset:23552
	global_load_lds_dwordx4 v[168:169], off
	s_add_i32 m0, s0, 0x2000
	s_add_u32 s0, s36, 0x80000
	v_lshl_add_u64 v[172:173], s[36:37], 0, v[152:153]
	s_addc_u32 s1, s37, 0
	s_add_i32 s2, s29, s49
	global_load_lds_dwordx4 v[172:173], off
	v_lshl_add_u64 v[202:203], s[0:1], 0, v[156:157]
	s_mov_b32 m0, s2
	v_lshl_add_u64 v[212:213], s[44:45], 0, v[154:155]
	global_load_lds_dwordx4 v[202:203], off
	v_lshl_add_u64 v[202:203], s[0:1], 0, v[152:153]
	s_add_i32 m0, s2, 0x2000
	s_nop 0
	global_load_lds_dwordx4 v[202:203], off
	v_lshl_add_u64 v[202:203], s[44:45], 0, v[158:159]
	s_mov_b32 m0, s50
	s_nop 0
	global_load_lds_dwordx4 v[202:203], off
	s_mov_b32 m0, s51
	s_nop 0
	global_load_lds_dwordx4 v[212:213], off
	s_waitcnt vmcnt(8)
	s_waitcnt lgkmcnt(0)
	s_setprio 1
	s_barrier
; #define PG8_STAGE(bufoff, gbase, voff) do { _Pragma("unroll") for (int _i = 0; _i < 2; ++_i) \
;         __builtin_amdgcn_global_load_lds((const unsigned*)((const char*)(gbase) + (voff)[_i]), (PG8_LAS unsigned*)(lds + (bufoff) + ldsw + _i * 8192), 16, 0, AUX_A); } while (0)
; #define PG8_STAGEB(bufoff, gbase, voff) do { _Pragma("unroll") for (int _i = 0; _i < 2; ++_i) \
;         __builtin_amdgcn_global_load_lds((const unsigned*)((const char*)(gbase) + (voff)[_i]), (PG8_LAS unsigned*)(lds + (bufoff) + ldsw + _i * 8192), 16, 0, AUX_B); } while (0)
; #define PG8_LDA(dst, b, h) do { _Pragma("unroll") for (int m = 0; m < 4; ++m) _Pragma("unroll") for (int k = 0; k < 2; ++k) dst[m][k] = *(const PG8_LAS bf16x8*)(lds + PG8_SA(b, h) + aoff + m * 2048 + k * 1024); } while (0)
; #define PG8_LDB(dst, b, h) do { _Pragma("unroll") for (int n = 0; n < 2; ++n) _Pragma("unroll") for (int k = 0; k < 2; ++k) dst[n][k] = *(const PG8_LAS bf16x8*)(lds + PG8_SB(b, h) + boff + n * 2048 + k * 1024); } while (0)
; #define PG8_MMA(ai, bj, At, Bt) do { __builtin_amdgcn_s_setprio(1); _Pragma("unroll") for (int m = 0; m < 4; ++m) _Pragma("unroll") for (int n = 0; n < 2; ++n) _Pragma("unroll") for (int k = 0; k < 2; ++k) \
;         acc[ai][bj][m][n] = __builtin_amdgcn_mfma_f32_16x16x32_bf16(Bt[n][k], At[m][k], acc[ai][bj][m][n], 0, 0, 0); __builtin_amdgcn_s_setprio(0); } while (0)
; template <class Epi, class Sched, bool ALIGN_EPI = false, bool SP2 = false>
; __device__ __forceinline__ void gemm_phase(PG8_LAS unsigned char* lds, const Gemm g, const Sched& S, const Epi& E) {
;     ...
;             if constexpr (SP2) {
;             PG8_LDB(B0, 0, 0); PG8_LDB(B1, 0, 1); PG8_SCHED; PG8_LDA(At, 0, 0); PG8_STAGE(PG8_SA(1, 1), a1 + hstep, voffA);
;             PG8_WAIT_V(8); PG8_WAIT_L(0); PG8_BAR; PG8_MMA(0, 0, At, B0); PG8_MMA(0, 1, At, B1); PG8_BAR; PG8_SCHED;
;             PG8_LDA(At, 0, 1); PG8_STAGEB(PG8_SB(0, 0), b2, voffB); PG8_STAGEB(PG8_SB(0, 1), b2 + hstep, voffB); PG8_STAGE(PG8_SA(0, 0), a2, voffA);
;             PG8_WAIT_V(8); PG8_WAIT_L(0); PG8_BAR; PG8_MMA(1, 0, At, B0); PG8_MMA(1, 1, At, B1); PG8_BAR; PG8_SCHED;
;             PG8_LDB(B0, 1, 0); PG8_LDB(B1, 1, 1); PG8_SCHED; PG8_LDA(At, 1, 0); PG8_STAGE(PG8_SA(0, 1), a2 + hstep, voffA);
;             PG8_WAIT_V(8); PG8_WAIT_L(0); PG8_BAR; PG8_MMA(0, 0, At, B0); PG8_MMA(0, 1, At, B1); PG8_BAR; PG8_SCHED;
	v_mfma_f32_16x16x32_bf16 v[62:65], v[136:139], v[194:197], 0
	v_mfma_f32_16x16x32_bf16 v[62:65], v[140:143], v[198:201], v[62:65]
	v_mfma_f32_16x16x32_bf16 v[58:61], v[144:147], v[194:197], 0
	v_mfma_f32_16x16x32_bf16 v[58:61], v[148:151], v[198:201], v[58:61]
	v_mfma_f32_16x16x32_bf16 v[54:57], v[136:139], v[222:225], 0
	v_mfma_f32_16x16x32_bf16 v[54:57], v[140:143], v[226:229], v[54:57]
	v_mfma_f32_16x16x32_bf16 v[46:49], v[144:147], v[222:225], 0
	v_mfma_f32_16x16x32_bf16 v[46:49], v[148:151], v[226:229], v[46:49]
	v_mfma_f32_16x16x32_bf16 v[38:41], v[136:139], v[230:233], 0
	v_mfma_f32_16x16x32_bf16 v[38:41], v[140:143], v[234:237], v[38:41]
	v_mfma_f32_16x16x32_bf16 v[30:33], v[144:147], v[230:233], 0
	v_mfma_f32_16x16x32_bf16 v[30:33], v[148:151], v[234:237], v[30:33]
	v_mfma_f32_16x16x32_bf16 v[22:25], v[136:139], v[238:241], 0
	v_mfma_f32_16x16x32_bf16 v[22:25], v[140:143], v[242:245], v[22:25]
	v_mfma_f32_16x16x32_bf16 v[14:17], v[144:147], v[238:241], 0
	v_mfma_f32_16x16x32_bf16 v[14:17], v[148:151], v[242:245], v[14:17]
	s_setprio 0
	s_setprio 1
	v_mfma_f32_16x16x32_bf16 v[50:53], v[164:167], v[194:197], 0
	v_mfma_f32_16x16x32_bf16 v[50:53], v[182:185], v[198:201], v[50:53]
	v_mfma_f32_16x16x32_bf16 v[42:45], v[186:189], v[194:197], 0
	v_mfma_f32_16x16x32_bf16 v[42:45], v[190:193], v[198:201], v[42:45]
	v_mfma_f32_16x16x32_bf16 v[34:37], v[164:167], v[222:225], 0
	v_mfma_f32_16x16x32_bf16 v[34:37], v[182:185], v[226:229], v[34:37]
	v_mfma_f32_16x16x32_bf16 v[26:29], v[186:189], v[222:225], 0
	v_mfma_f32_16x16x32_bf16 v[26:29], v[190:193], v[226:229], v[26:29]
	v_mfma_f32_16x16x32_bf16 v[18:21], v[164:167], v[230:233], 0
	v_mfma_f32_16x16x32_bf16 v[18:21], v[182:185], v[234:237], v[18:21]
	v_mfma_f32_16x16x32_bf16 v[10:13], v[186:189], v[230:233], 0
	v_mfma_f32_16x16x32_bf16 v[10:13], v[190:193], v[234:237], v[10:13]
	v_mfma_f32_16x16x32_bf16 v[6:9], v[164:167], v[238:241], 0
	v_mfma_f32_16x16x32_bf16 v[6:9], v[182:185], v[242:245], v[6:9]
	s_setprio 2
	s_barrier
	v_mfma_f32_16x16x32_bf16 v[2:5], v[186:189], v[238:241], 0
	v_mfma_f32_16x16x32_bf16 v[2:5], v[190:193], v[242:245], v[2:5]
	s_setprio 0
	s_add_i32 s2, 0, 0x18000
	s_add_i32 s15, 0, 0x1c000
	v_add_u32_e32 v148, s2, v99
	v_add_u32_e32 v190, s15, v99
	ds_read_b128 v[136:139], v148
	ds_read_b128 v[140:143], v148 offset:1024
	ds_read_b128 v[144:147], v148 offset:2048
	ds_read_b128 v[148:151], v148 offset:3072
	ds_read_b128 v[164:167], v190
	ds_read_b128 v[182:185], v190 offset:1024
	ds_read_b128 v[186:189], v190 offset:2048
	ds_read_b128 v[190:193], v190 offset:3072
	s_add_u32 s0, s44, 0x80000
	s_addc_u32 s1, s45, 0
	s_mov_b32 m0, s52
	v_lshl_add_u64 v[246:247], s[0:1], 0, v[158:159]
	ds_read_b128 v[194:197], v181 offset:32768
	ds_read_b128 v[198:201], v181 offset:33792
	ds_read_b128 v[222:225], v181 offset:34816
	ds_read_b128 v[226:229], v181 offset:35840
	ds_read_b128 v[230:233], v181 offset:36864
	ds_read_b128 v[234:237], v181 offset:37888
	ds_read_b128 v[238:241], v181 offset:38912
	ds_read_b128 v[242:245], v181 offset:39936
	global_load_lds_dwordx4 v[246:247], off
	v_lshl_add_u64 v[246:247], s[0:1], 0, v[154:155]
	s_mov_b32 m0, s53
	s_nop 0
	global_load_lds_dwordx4 v[246:247], off
	s_waitcnt vmcnt(8)
	s_waitcnt lgkmcnt(0)
	s_setprio 1
	s_barrier
	v_mfma_f32_16x16x32_bf16 v[128:131], v[136:139], v[194:197], v[128:131]
	v_mfma_f32_16x16x32_bf16 v[128:131], v[140:143], v[198:201], v[128:131]
	v_mfma_f32_16x16x32_bf16 v[124:127], v[144:147], v[194:197], v[124:127]
	v_mfma_f32_16x16x32_bf16 v[124:127], v[148:151], v[198:201], v[124:127]
	v_mfma_f32_16x16x32_bf16 v[120:123], v[136:139], v[222:225], v[120:123]
	v_mfma_f32_16x16x32_bf16 v[120:123], v[140:143], v[226:229], v[120:123]
	v_mfma_f32_16x16x32_bf16 v[112:115], v[144:147], v[222:225], v[112:115]
	v_mfma_f32_16x16x32_bf16 v[112:115], v[148:151], v[226:229], v[112:115]
	v_mfma_f32_16x16x32_bf16 v[104:107], v[136:139], v[230:233], v[104:107]
	v_mfma_f32_16x16x32_bf16 v[104:107], v[140:143], v[234:237], v[104:107]
	v_mfma_f32_16x16x32_bf16 v[94:97], v[144:147], v[230:233], v[94:97]
	v_mfma_f32_16x16x32_bf16 v[94:97], v[148:151], v[234:237], v[94:97]
	v_mfma_f32_16x16x32_bf16 v[86:89], v[136:139], v[238:241], v[86:89]
	v_mfma_f32_16x16x32_bf16 v[86:89], v[140:143], v[242:245], v[86:89]
	v_mfma_f32_16x16x32_bf16 v[78:81], v[144:147], v[238:241], v[78:81]
	v_mfma_f32_16x16x32_bf16 v[78:81], v[148:151], v[242:245], v[78:81]
	s_setprio 0
	s_setprio 1
	v_mfma_f32_16x16x32_bf16 v[116:119], v[164:167], v[194:197], v[116:119]
	v_mfma_f32_16x16x32_bf16 v[116:119], v[182:185], v[198:201], v[116:119]
	v_mfma_f32_16x16x32_bf16 v[108:111], v[186:189], v[194:197], v[108:111]
	v_mfma_f32_16x16x32_bf16 v[108:111], v[190:193], v[198:201], v[108:111]
	v_mfma_f32_16x16x32_bf16 v[100:103], v[164:167], v[222:225], v[100:103]
	v_mfma_f32_16x16x32_bf16 v[100:103], v[182:185], v[226:229], v[100:103]
	v_mfma_f32_16x16x32_bf16 v[90:93], v[186:189], v[222:225], v[90:93]
	v_mfma_f32_16x16x32_bf16 v[90:93], v[190:193], v[226:229], v[90:93]
	v_mfma_f32_16x16x32_bf16 v[82:85], v[164:167], v[230:233], v[82:85]
	v_mfma_f32_16x16x32_bf16 v[82:85], v[182:185], v[234:237], v[82:85]
	v_mfma_f32_16x16x32_bf16 v[74:77], v[186:189], v[230:233], v[74:77]
	v_mfma_f32_16x16x32_bf16 v[74:77], v[190:193], v[234:237], v[74:77]
	v_mfma_f32_16x16x32_bf16 v[70:73], v[164:167], v[238:241], v[70:73]
	v_mfma_f32_16x16x32_bf16 v[70:73], v[182:185], v[242:245], v[70:73]
	s_setprio 2
	s_barrier
; #define PG8_STAGE(bufoff, gbase, voff) do { _Pragma("unroll") for (int _i = 0; _i < 2; ++_i) \
;         __builtin_amdgcn_global_load_lds((const unsigned*)((const char*)(gbase) + (voff)[_i]), (PG8_LAS unsigned*)(lds + (bufoff) + ldsw + _i * 8192), 16, 0, AUX_A); } while (0)
; #define PG8_STAGEB(bufoff, gbase, voff) do { _Pragma("unroll") for (int _i = 0; _i < 2; ++_i) \
;         __builtin_amdgcn_global_load_lds((const unsigned*)((const char*)(gbase) + (voff)[_i]), (PG8_LAS unsigned*)(lds + (bufoff) + ldsw + _i * 8192), 16, 0, AUX_B); } while (0)
; #define PG8_LDA(dst, b, h) do { _Pragma("unroll") for (int m = 0; m < 4; ++m) _Pragma("unroll") for (int k = 0; k < 2; ++k) dst[m][k] = *(const PG8_LAS bf16x8*)(lds + PG8_SA(b, h) + aoff + m * 2048 + k * 1024); } while (0)
; #define PG8_LDB(dst, b, h) do { _Pragma("unroll") for (int n = 0; n < 2; ++n) _Pragma("unroll") for (int k = 0; k < 2; ++k) dst[n][k] = *(const PG8_LAS bf16x8*)(lds + PG8_SB(b, h) + boff + n * 2048 + k * 1024); } while (0)
; #define PG8_MMA(ai, bj, At, Bt) do { __builtin_amdgcn_s_setprio(1); _Pragma("unroll") for (int m = 0; m < 4; ++m) _Pragma("unroll") for (int n = 0; n < 2; ++n) _Pragma("unroll") for (int k = 0; k < 2; ++k) \
;         acc[ai][bj][m][n] = __builtin_amdgcn_mfma_f32_16x16x32_bf16(Bt[n][k], At[m][k], acc[ai][bj][m][n], 0, 0, 0); __builtin_amdgcn_s_setprio(0); } while (0)
; #define PG8_WAIT_V(n) asm volatile("s_waitcnt vmcnt(" #n ")" ::: "memory")
; #define PG8_WAIT_L(n) asm volatile("s_waitcnt lgkmcnt(" #n ")" ::: "memory")
; #define PG8_BAR __builtin_amdgcn_s_barrier()
; #define PG8_SCHED __builtin_amdgcn_sched_barrier(0)
; template <class Epi, class Sched, bool ALIGN_EPI = false, bool SP2 = false>
; __device__ __forceinline__ void gemm_phase(PG8_LAS unsigned char* lds, const Gemm g, const Sched& S, const Epi& E) {
;     ...
;             PG8_LDB(B0, 1, 0); PG8_LDB(B1, 1, 1); PG8_SCHED; PG8_LDA(At, 1, 0); PG8_STAGE(PG8_SA(0, 1), a2 + hstep, voffA);
;             PG8_WAIT_V(8); PG8_WAIT_L(0); PG8_BAR; PG8_MMA(0, 0, At, B0); PG8_MMA(0, 1, At, B1); PG8_BAR; PG8_SCHED;
;             PG8_LDA(At, 1, 1); PG8_STAGEB(PG8_SB(1, 0), b3, voffB); PG8_STAGEB(PG8_SB(1, 1), b3 + hstep, voffB); PG8_STAGE(PG8_SA(1, 0), a3, voffA);
;             PG8_WAIT_V(8); PG8_WAIT_L(0); PG8_BAR; PG8_MMA(1, 0, At, B0); PG8_MMA(1, 1, At, B1); PG8_BAR; PG8_SCHED;
	v_mfma_f32_16x16x32_bf16 v[66:69], v[186:189], v[238:241], v[66:69]
	v_mfma_f32_16x16x32_bf16 v[66:69], v[190:193], v[242:245], v[66:69]
	s_setprio 0
	s_add_i32 s0, s2, s49
	v_lshl_add_u64 v[168:169], v[168:169], 0, s[76:77]
	s_mov_b32 m0, s0
	ds_read_b128 v[194:197], v181 offset:49152
	ds_read_b128 v[198:201], v181 offset:50176
	ds_read_b128 v[222:225], v181 offset:51200
	ds_read_b128 v[226:229], v181 offset:52224
	ds_read_b128 v[230:233], v181 offset:53248
	ds_read_b128 v[234:237], v181 offset:54272
	ds_read_b128 v[238:241], v181 offset:55296
	ds_read_b128 v[242:245], v181 offset:56320
	global_load_lds_dwordx4 v[168:169], off
	s_add_i32 m0, s0, 0x2000
	s_add_u32 s0, s36, 0x80080
	v_lshl_add_u64 v[168:169], v[172:173], 0, s[76:77]
	s_addc_u32 s1, s37, 0
	s_add_i32 s2, s15, s49
	global_load_lds_dwordx4 v[168:169], off
	v_lshl_add_u64 v[168:169], s[0:1], 0, v[156:157]
	s_mov_b32 m0, s2
	s_nop 0
	global_load_lds_dwordx4 v[168:169], off
	v_lshl_add_u64 v[168:169], s[0:1], 0, v[152:153]
	s_add_i32 m0, s2, 0x2000
	s_nop 0
	global_load_lds_dwordx4 v[168:169], off
	v_lshl_add_u64 v[168:169], v[202:203], 0, s[76:77]
	s_mov_b32 m0, s59
	s_nop 0
	global_load_lds_dwordx4 v[168:169], off
	v_lshl_add_u64 v[168:169], v[212:213], 0, s[76:77]
	s_mov_b32 m0, s60
	s_nop 0
	global_load_lds_dwordx4 v[168:169], off
	s_waitcnt vmcnt(8)
	s_waitcnt lgkmcnt(0)
	s_setprio 1
	s_barrier
	v_mfma_f32_16x16x32_bf16 v[62:65], v[136:139], v[194:197], v[62:65]
	v_mfma_f32_16x16x32_bf16 v[62:65], v[140:143], v[198:201], v[62:65]
	v_mfma_f32_16x16x32_bf16 v[58:61], v[144:147], v[194:197], v[58:61]
	v_mfma_f32_16x16x32_bf16 v[58:61], v[148:151], v[198:201], v[58:61]
	v_mfma_f32_16x16x32_bf16 v[54:57], v[136:139], v[222:225], v[54:57]
	v_mfma_f32_16x16x32_bf16 v[54:57], v[140:143], v[226:229], v[54:57]
	v_mfma_f32_16x16x32_bf16 v[46:49], v[144:147], v[222:225], v[46:49]
	v_mfma_f32_16x16x32_bf16 v[46:49], v[148:151], v[226:229], v[46:49]
	v_mfma_f32_16x16x32_bf16 v[38:41], v[136:139], v[230:233], v[38:41]
	v_mfma_f32_16x16x32_bf16 v[38:41], v[140:143], v[234:237], v[38:41]
	v_mfma_f32_16x16x32_bf16 v[30:33], v[144:147], v[230:233], v[30:33]
	v_mfma_f32_16x16x32_bf16 v[30:33], v[148:151], v[234:237], v[30:33]
	v_mfma_f32_16x16x32_bf16 v[22:25], v[136:139], v[238:241], v[22:25]
	v_mfma_f32_16x16x32_bf16 v[22:25], v[140:143], v[242:245], v[22:25]
	v_mfma_f32_16x16x32_bf16 v[14:17], v[144:147], v[238:241], v[14:17]
	v_mfma_f32_16x16x32_bf16 v[14:17], v[148:151], v[242:245], v[14:17]
	s_setprio 0
	s_setprio 1
	v_mfma_f32_16x16x32_bf16 v[50:53], v[164:167], v[194:197], v[50:53]
	v_mfma_f32_16x16x32_bf16 v[50:53], v[182:185], v[198:201], v[50:53]
	v_mfma_f32_16x16x32_bf16 v[42:45], v[186:189], v[194:197], v[42:45]
	v_mfma_f32_16x16x32_bf16 v[42:45], v[190:193], v[198:201], v[42:45]
	v_mfma_f32_16x16x32_bf16 v[34:37], v[164:167], v[222:225], v[34:37]
	v_mfma_f32_16x16x32_bf16 v[34:37], v[182:185], v[226:229], v[34:37]
	v_mfma_f32_16x16x32_bf16 v[26:29], v[186:189], v[222:225], v[26:29]
	v_mfma_f32_16x16x32_bf16 v[26:29], v[190:193], v[226:229], v[26:29]
	v_mfma_f32_16x16x32_bf16 v[18:21], v[164:167], v[230:233], v[18:21]
	v_mfma_f32_16x16x32_bf16 v[18:21], v[182:185], v[234:237], v[18:21]
	v_mfma_f32_16x16x32_bf16 v[10:13], v[186:189], v[230:233], v[10:13]
	v_mfma_f32_16x16x32_bf16 v[10:13], v[190:193], v[234:237], v[10:13]
	v_mfma_f32_16x16x32_bf16 v[6:9], v[164:167], v[238:241], v[6:9]
	v_mfma_f32_16x16x32_bf16 v[6:9], v[182:185], v[242:245], v[6:9]
	s_setprio 2
	s_cmp_ge_i32 s13, s71
	s_cbranch_scc1 .Lq4x_1308p
	s_barrier

; #define PG8_STAGE(bufoff, gbase, voff) do { _Pragma("unroll") for (int _i = 0; _i < 2; ++_i) \
;         __builtin_amdgcn_global_load_lds((const unsigned*)((const char*)(gbase) + (voff)[_i]), (PG8_LAS unsigned*)(lds + (bufoff) + ldsw + _i * 8192), 16, 0, AUX_A); } while (0)
; #define PG8_STAGEB(bufoff, gbase, voff) do { _Pragma("unroll") for (int _i = 0; _i < 2; ++_i) \
;         __builtin_amdgcn_global_load_lds((const unsigned*)((const char*)(gbase) + (voff)[_i]), (PG8_LAS unsigned*)(lds + (bufoff) + ldsw + _i * 8192), 16, 0, AUX_B); } while (0)
; #define PG8_LDA(dst, b, h) do { _Pragma("unroll") for (int m = 0; m < 4; ++m) _Pragma("unroll") for (int k = 0; k < 2; ++k) dst[m][k] = *(const PG8_LAS bf16x8*)(lds + PG8_SA(b, h) + aoff + m * 2048 + k * 1024); } while (0)
; #define PG8_LDB(dst, b, h) do { _Pragma("unroll") for (int n = 0; n < 2; ++n) _Pragma("unroll") for (int k = 0; k < 2; ++k) dst[n][k] = *(const PG8_LAS bf16x8*)(lds + PG8_SB(b, h) + boff + n * 2048 + k * 1024); } while (0)
; #define PG8_WAIT_V(n) asm volatile("s_waitcnt vmcnt(" #n ")" ::: "memory")
; #define PG8_WAIT_L(n) asm volatile("s_waitcnt lgkmcnt(" #n ")" ::: "memory")
; #define PG8_BAR __builtin_amdgcn_s_barrier()
; template <class Epi, class Sched, bool ALIGN_EPI = false, bool SP2 = false>
; __device__ __forceinline__ void gemm_phase(PG8_LAS unsigned char* lds, const Gemm g, const Sched& S, const Epi& E) {
;     ...
;         for (int t = 0; t < nt; t += 2) {
;             const bool last = (t == nt - 2);
;             const char* a1 = PG8_KP(cA, t + 1, rot, nt);
;             const char* a2 = last ? nAr : PG8_KP(cA, t + 2, rot, nt); const char* b2 = last ? nBr : PG8_KP(cB, t + 2, rot, nt);
;             const char* a3 = a2 + kstep; const char* b3 = b2 + kstep;
;             if (last && has_next) S.a_ready(nxt);
;             if constexpr (SP2) {
;             PG8_LDB(B0, 0, 0); PG8_LDB(B1, 0, 1); PG8_SCHED; PG8_LDA(At, 0, 0); PG8_STAGE(PG8_SA(1, 1), a1 + hstep, voffA);
;             PG8_WAIT_V(8); PG8_WAIT_L(0); PG8_BAR; PG8_MMA(0, 0, At, B0); PG8_MMA(0, 1, At, B1); PG8_BAR; PG8_SCHED;
;             PG8_LDA(At, 0, 1); PG8_STAGEB(PG8_SB(0, 0), b2, voffB); PG8_STAGEB(PG8_SB(0, 1), b2 + hstep, voffB); PG8_STAGE(PG8_SA(0, 0), a2, voffA);
;             PG8_WAIT_V(8); PG8_WAIT_L(0); PG8_BAR; PG8_MMA(1, 0, At, B0); PG8_MMA(1, 1, At, B1); PG8_BAR; PG8_SCHED;
.LBB0_1308:
	s_or_b32 s0, s11, 1
	s_cmp_ge_i32 s0, s71
	s_cselect_b32 s2, s71, 0
	s_add_i32 s11, s11, 2
	s_cmp_ge_i32 s11, s71
	s_cselect_b32 s0, s71, 0
	s_sub_i32 s0, s13, s0
	s_ashr_i32 s1, s0, 31
	s_lshl_b64 s[0:1], s[0:1], 7
	s_add_u32 s15, s40, s0
	s_addc_u32 s29, s41, s1
	s_add_u32 s0, s34, s0
	s_addc_u32 s1, s35, s1
	s_cmp_eq_u32 s71, s13
	s_cselect_b32 s45, s43, s29
	s_cselect_b32 s44, s42, s15
	s_cselect_b32 s37, s19, s1
	s_cselect_b32 s36, s18, s0
	s_add_i32 s15, 0, 0x10000
	s_add_i32 s29, 0, 0x14000
	v_add_u32_e32 v148, s15, v99
	v_add_u32_e32 v168, s29, v99
	ds_read_b128 v[136:139], v148
	ds_read_b128 v[140:143], v148 offset:1024
	ds_read_b128 v[144:147], v148 offset:2048
	ds_read_b128 v[148:151], v148 offset:3072
	ds_read_b128 v[164:167], v168
	ds_read_b128 v[182:185], v168 offset:1024
	ds_read_b128 v[186:189], v168 offset:2048
	ds_read_b128 v[190:193], v168 offset:3072
	v_mad_i64_i32 v[168:169], s[0:1], s2, v220, v[134:135]
	s_add_i32 m0, s50, 0xc000
	ds_read_b128 v[194:197], v181
	ds_read_b128 v[198:201], v181 offset:1024
	ds_read_b128 v[222:225], v181 offset:2048
	ds_read_b128 v[226:229], v181 offset:3072
	ds_read_b128 v[230:233], v181 offset:4096
	ds_read_b128 v[234:237], v181 offset:5120
	ds_read_b128 v[238:241], v181 offset:6144
	ds_read_b128 v[242:245], v181 offset:7168
	global_load_lds_dwordx4 v[168:169], off
	v_mad_i64_i32 v[168:169], s[0:1], s2, v220, v[132:133]
	s_add_i32 m0, s50, 0xe000
	s_nop 0
	global_load_lds_dwordx4 v[168:169], off
	s_waitcnt vmcnt(8)
	s_waitcnt lgkmcnt(0)
	s_setprio 1
	s_barrier
	v_mfma_f32_16x16x32_bf16 v[128:131], v[136:139], v[194:197], v[128:131]
	v_mfma_f32_16x16x32_bf16 v[128:131], v[140:143], v[198:201], v[128:131]
	v_mfma_f32_16x16x32_bf16 v[124:127], v[144:147], v[194:197], v[124:127]
	v_mfma_f32_16x16x32_bf16 v[124:127], v[148:151], v[198:201], v[124:127]
	v_mfma_f32_16x16x32_bf16 v[120:123], v[136:139], v[222:225], v[120:123]
	v_mfma_f32_16x16x32_bf16 v[120:123], v[140:143], v[226:229], v[120:123]
	v_mfma_f32_16x16x32_bf16 v[112:115], v[144:147], v[222:225], v[112:115]
	v_mfma_f32_16x16x32_bf16 v[112:115], v[148:151], v[226:229], v[112:115]
	v_mfma_f32_16x16x32_bf16 v[104:107], v[136:139], v[230:233], v[104:107]
	v_mfma_f32_16x16x32_bf16 v[104:107], v[140:143], v[234:237], v[104:107]
	v_mfma_f32_16x16x32_bf16 v[94:97], v[144:147], v[230:233], v[94:97]
	v_mfma_f32_16x16x32_bf16 v[94:97], v[148:151], v[234:237], v[94:97]
	v_mfma_f32_16x16x32_bf16 v[86:89], v[136:139], v[238:241], v[86:89]
	v_mfma_f32_16x16x32_bf16 v[86:89], v[140:143], v[242:245], v[86:89]
	v_mfma_f32_16x16x32_bf16 v[78:81], v[144:147], v[238:241], v[78:81]
	v_mfma_f32_16x16x32_bf16 v[78:81], v[148:151], v[242:245], v[78:81]
	s_setprio 0
	s_setprio 1
	v_mfma_f32_16x16x32_bf16 v[116:119], v[164:167], v[194:197], v[116:119]
	v_mfma_f32_16x16x32_bf16 v[116:119], v[182:185], v[198:201], v[116:119]
	v_mfma_f32_16x16x32_bf16 v[108:111], v[186:189], v[194:197], v[108:111]
	v_mfma_f32_16x16x32_bf16 v[108:111], v[190:193], v[198:201], v[108:111]
	v_mfma_f32_16x16x32_bf16 v[100:103], v[164:167], v[222:225], v[100:103]
	v_mfma_f32_16x16x32_bf16 v[100:103], v[182:185], v[226:229], v[100:103]
	v_mfma_f32_16x16x32_bf16 v[90:93], v[186:189], v[222:225], v[90:93]
	v_mfma_f32_16x16x32_bf16 v[90:93], v[190:193], v[226:229], v[90:93]
	v_mfma_f32_16x16x32_bf16 v[82:85], v[164:167], v[230:233], v[82:85]
	v_mfma_f32_16x16x32_bf16 v[82:85], v[182:185], v[234:237], v[82:85]
	v_mfma_f32_16x16x32_bf16 v[74:77], v[186:189], v[230:233], v[74:77]
	v_mfma_f32_16x16x32_bf16 v[74:77], v[190:193], v[234:237], v[74:77]
	v_mfma_f32_16x16x32_bf16 v[70:73], v[164:167], v[238:241], v[70:73]
	v_mfma_f32_16x16x32_bf16 v[70:73], v[182:185], v[242:245], v[70:73]
	s_setprio 2
	s_barrier
	v_mfma_f32_16x16x32_bf16 v[66:69], v[186:189], v[238:241], v[66:69]
	v_mfma_f32_16x16x32_bf16 v[66:69], v[190:193], v[242:245], v[66:69]
	s_setprio 0
	s_add_i32 s0, s15, s49
	v_lshl_add_u64 v[168:169], s[36:37], 0, v[156:157]
	s_mov_b32 m0, s0
	ds_read_b128 v[194:197], v181 offset:16384
	ds_read_b128 v[198:201], v181 offset:17408
	ds_read_b128 v[222:225], v181 offset:18432
	ds_read_b128 v[226:229], v181 offset:19456
	ds_read_b128 v[230:233], v181 offset:20480
	ds_read_b128 v[234:237], v181 offset:21504
	ds_read_b128 v[238:241], v181 offset:22528
	ds_read_b128 v[242:245], v181 offset:23552
	global_load_lds_dwordx4 v[168:169], off
	s_add_i32 m0, s0, 0x2000
	s_add_u32 s0, s36, 0x80000
	v_lshl_add_u64 v[172:173], s[36:37], 0, v[152:153]
	s_addc_u32 s1, s37, 0
	s_add_i32 s2, s29, s49
	global_load_lds_dwordx4 v[172:173], off
	v_lshl_add_u64 v[202:203], s[0:1], 0, v[156:157]
	s_mov_b32 m0, s2
	v_lshl_add_u64 v[212:213], s[44:45], 0, v[154:155]
	global_load_lds_dwordx4 v[202:203], off
	v_lshl_add_u64 v[202:203], s[0:1], 0, v[152:153]
	s_add_i32 m0, s2, 0x2000
	s_nop 0
	global_load_lds_dwordx4 v[202:203], off
	v_lshl_add_u64 v[202:203], s[44:45], 0, v[158:159]
	s_mov_b32 m0, s50
	s_nop 0
	global_load_lds_dwordx4 v[202:203], off
	s_mov_b32 m0, s51
	s_nop 0
	global_load_lds_dwordx4 v[212:213], off
	s_waitcnt vmcnt(8)
	s_waitcnt lgkmcnt(0)
	s_setprio 1
	s_barrier
; #define PG8_STAGE(bufoff, gbase, voff) do { _Pragma("unroll") for (int _i = 0; _i < 2; ++_i) \
;         __builtin_amdgcn_global_load_lds((const unsigned*)((const char*)(gbase) + (voff)[_i]), (PG8_LAS unsigned*)(lds + (bufoff) + ldsw + _i * 8192), 16, 0, AUX_A); } while (0)
; #define PG8_STAGEB(bufoff, gbase, voff) do { _Pragma("unroll") for (int _i = 0; _i < 2; ++_i) \
;         __builtin_amdgcn_global_load_lds((const unsigned*)((const char*)(gbase) + (voff)[_i]), (PG8_LAS unsigned*)(lds + (bufoff) + ldsw + _i * 8192), 16, 0, AUX_B); } while (0)
; #define PG8_LDA(dst, b, h) do { _Pragma("unroll") for (int m = 0; m < 4; ++m) _Pragma("unroll") for (int k = 0; k < 2; ++k) dst[m][k] = *(const PG8_LAS bf16x8*)(lds + PG8_SA(b, h) + aoff + m * 2048 + k * 1024); } while (0)
; #define PG8_LDB(dst, b, h) do { _Pragma("unroll") for (int n = 0; n < 2; ++n) _Pragma("unroll") for (int k = 0; k < 2; ++k) dst[n][k] = *(const PG8_LAS bf16x8*)(lds + PG8_SB(b, h) + boff + n * 2048 + k * 1024); } while (0)
; #define PG8_MMA(ai, bj, At, Bt) do { __builtin_amdgcn_s_setprio(1); _Pragma("unroll") for (int m = 0; m < 4; ++m) _Pragma("unroll") for (int n = 0; n < 2; ++n) _Pragma("unroll") for (int k = 0; k < 2; ++k) \
;         acc[ai][bj][m][n] = __builtin_amdgcn_mfma_f32_16x16x32_bf16(Bt[n][k], At[m][k], acc[ai][bj][m][n], 0, 0, 0); __builtin_amdgcn_s_setprio(0); } while (0)
; template <class Epi, class Sched, bool ALIGN_EPI = false, bool SP2 = false>
; __device__ __forceinline__ void gemm_phase(PG8_LAS unsigned char* lds, const Gemm g, const Sched& S, const Epi& E) {
;     ...
;             if constexpr (SP2) {
;             PG8_LDB(B0, 0, 0); PG8_LDB(B1, 0, 1); PG8_SCHED; PG8_LDA(At, 0, 0); PG8_STAGE(PG8_SA(1, 1), a1 + hstep, voffA);
;             PG8_WAIT_V(8); PG8_WAIT_L(0); PG8_BAR; PG8_MMA(0, 0, At, B0); PG8_MMA(0, 1, At, B1); PG8_BAR; PG8_SCHED;
;             PG8_LDA(At, 0, 1); PG8_STAGEB(PG8_SB(0, 0), b2, voffB); PG8_STAGEB(PG8_SB(0, 1), b2 + hstep, voffB); PG8_STAGE(PG8_SA(0, 0), a2, voffA);
;             PG8_WAIT_V(8); PG8_WAIT_L(0); PG8_BAR; PG8_MMA(1, 0, At, B0); PG8_MMA(1, 1, At, B1); PG8_BAR; PG8_SCHED;
;             PG8_LDB(B0, 1, 0); PG8_LDB(B1, 1, 1); PG8_SCHED; PG8_LDA(At, 1, 0); PG8_STAGE(PG8_SA(0, 1), a2 + hstep, voffA);
;             PG8_WAIT_V(8); PG8_WAIT_L(0); PG8_BAR; PG8_MMA(0, 0, At, B0); PG8_MMA(0, 1, At, B1); PG8_BAR; PG8_SCHED;
	v_mfma_f32_16x16x32_bf16 v[62:65], v[136:139], v[194:197], v[62:65]
	v_mfma_f32_16x16x32_bf16 v[62:65], v[140:143], v[198:201], v[62:65]
	v_mfma_f32_16x16x32_bf16 v[58:61], v[144:147], v[194:197], v[58:61]
	v_mfma_f32_16x16x32_bf16 v[58:61], v[148:151], v[198:201], v[58:61]
	v_mfma_f32_16x16x32_bf16 v[54:57], v[136:139], v[222:225], v[54:57]
	v_mfma_f32_16x16x32_bf16 v[54:57], v[140:143], v[226:229], v[54:57]
	v_mfma_f32_16x16x32_bf16 v[46:49], v[144:147], v[222:225], v[46:49]
	v_mfma_f32_16x16x32_bf16 v[46:49], v[148:151], v[226:229], v[46:49]
	v_mfma_f32_16x16x32_bf16 v[38:41], v[136:139], v[230:233], v[38:41]
	v_mfma_f32_16x16x32_bf16 v[38:41], v[140:143], v[234:237], v[38:41]
	v_mfma_f32_16x16x32_bf16 v[30:33], v[144:147], v[230:233], v[30:33]
	v_mfma_f32_16x16x32_bf16 v[30:33], v[148:151], v[234:237], v[30:33]
	v_mfma_f32_16x16x32_bf16 v[22:25], v[136:139], v[238:241], v[22:25]
	v_mfma_f32_16x16x32_bf16 v[22:25], v[140:143], v[242:245], v[22:25]
	v_mfma_f32_16x16x32_bf16 v[14:17], v[144:147], v[238:241], v[14:17]
	v_mfma_f32_16x16x32_bf16 v[14:17], v[148:151], v[242:245], v[14:17]
	s_setprio 0
	s_setprio 1
	v_mfma_f32_16x16x32_bf16 v[50:53], v[164:167], v[194:197], v[50:53]
	v_mfma_f32_16x16x32_bf16 v[50:53], v[182:185], v[198:201], v[50:53]
	v_mfma_f32_16x16x32_bf16 v[42:45], v[186:189], v[194:197], v[42:45]
	v_mfma_f32_16x16x32_bf16 v[42:45], v[190:193], v[198:201], v[42:45]
	v_mfma_f32_16x16x32_bf16 v[34:37], v[164:167], v[222:225], v[34:37]
	v_mfma_f32_16x16x32_bf16 v[34:37], v[182:185], v[226:229], v[34:37]
	v_mfma_f32_16x16x32_bf16 v[26:29], v[186:189], v[222:225], v[26:29]
	v_mfma_f32_16x16x32_bf16 v[26:29], v[190:193], v[226:229], v[26:29]
	v_mfma_f32_16x16x32_bf16 v[18:21], v[164:167], v[230:233], v[18:21]
	v_mfma_f32_16x16x32_bf16 v[18:21], v[182:185], v[234:237], v[18:21]
	v_mfma_f32_16x16x32_bf16 v[10:13], v[186:189], v[230:233], v[10:13]
	v_mfma_f32_16x16x32_bf16 v[10:13], v[190:193], v[234:237], v[10:13]
	v_mfma_f32_16x16x32_bf16 v[6:9], v[164:167], v[238:241], v[6:9]
	v_mfma_f32_16x16x32_bf16 v[6:9], v[182:185], v[242:245], v[6:9]
	s_setprio 2
	s_barrier
	v_mfma_f32_16x16x32_bf16 v[2:5], v[186:189], v[238:241], v[2:5]
	v_mfma_f32_16x16x32_bf16 v[2:5], v[190:193], v[242:245], v[2:5]
	s_setprio 0
	s_add_i32 s2, 0, 0x18000
	s_add_i32 s15, 0, 0x1c000
	v_add_u32_e32 v148, s2, v99
	v_add_u32_e32 v190, s15, v99
	ds_read_b128 v[136:139], v148
	ds_read_b128 v[140:143], v148 offset:1024
	ds_read_b128 v[144:147], v148 offset:2048
	ds_read_b128 v[148:151], v148 offset:3072
	ds_read_b128 v[164:167], v190
	ds_read_b128 v[182:185], v190 offset:1024
	ds_read_b128 v[186:189], v190 offset:2048
	ds_read_b128 v[190:193], v190 offset:3072
	s_add_u32 s0, s44, 0x80000
	s_addc_u32 s1, s45, 0
	s_mov_b32 m0, s52
	v_lshl_add_u64 v[246:247], s[0:1], 0, v[158:159]
	ds_read_b128 v[194:197], v181 offset:32768
	ds_read_b128 v[198:201], v181 offset:33792
	ds_read_b128 v[222:225], v181 offset:34816
	ds_read_b128 v[226:229], v181 offset:35840
	ds_read_b128 v[230:233], v181 offset:36864
	ds_read_b128 v[234:237], v181 offset:37888
	ds_read_b128 v[238:241], v181 offset:38912
	ds_read_b128 v[242:245], v181 offset:39936
	global_load_lds_dwordx4 v[246:247], off
	v_lshl_add_u64 v[246:247], s[0:1], 0, v[154:155]
	s_mov_b32 m0, s53
	s_nop 0
	global_load_lds_dwordx4 v[246:247], off
	s_waitcnt vmcnt(8)
	s_waitcnt lgkmcnt(0)
	s_setprio 1
	s_barrier
	v_mfma_f32_16x16x32_bf16 v[128:131], v[136:139], v[194:197], v[128:131]
	v_mfma_f32_16x16x32_bf16 v[128:131], v[140:143], v[198:201], v[128:131]
	v_mfma_f32_16x16x32_bf16 v[124:127], v[144:147], v[194:197], v[124:127]
	v_mfma_f32_16x16x32_bf16 v[124:127], v[148:151], v[198:201], v[124:127]
	v_mfma_f32_16x16x32_bf16 v[120:123], v[136:139], v[222:225], v[120:123]
	v_mfma_f32_16x16x32_bf16 v[120:123], v[140:143], v[226:229], v[120:123]
	v_mfma_f32_16x16x32_bf16 v[112:115], v[144:147], v[222:225], v[112:115]
	v_mfma_f32_16x16x32_bf16 v[112:115], v[148:151], v[226:229], v[112:115]
	v_mfma_f32_16x16x32_bf16 v[104:107], v[136:139], v[230:233], v[104:107]
	v_mfma_f32_16x16x32_bf16 v[104:107], v[140:143], v[234:237], v[104:107]
	v_mfma_f32_16x16x32_bf16 v[94:97], v[144:147], v[230:233], v[94:97]
	v_mfma_f32_16x16x32_bf16 v[94:97], v[148:151], v[234:237], v[94:97]
	v_mfma_f32_16x16x32_bf16 v[86:89], v[136:139], v[238:241], v[86:89]
	v_mfma_f32_16x16x32_bf16 v[86:89], v[140:143], v[242:245], v[86:89]
	v_mfma_f32_16x16x32_bf16 v[78:81], v[144:147], v[238:241], v[78:81]
	v_mfma_f32_16x16x32_bf16 v[78:81], v[148:151], v[242:245], v[78:81]
	s_setprio 0
	s_setprio 1
	v_mfma_f32_16x16x32_bf16 v[116:119], v[164:167], v[194:197], v[116:119]
	v_mfma_f32_16x16x32_bf16 v[116:119], v[182:185], v[198:201], v[116:119]
	v_mfma_f32_16x16x32_bf16 v[108:111], v[186:189], v[194:197], v[108:111]
	v_mfma_f32_16x16x32_bf16 v[108:111], v[190:193], v[198:201], v[108:111]
	v_mfma_f32_16x16x32_bf16 v[100:103], v[164:167], v[222:225], v[100:103]
	v_mfma_f32_16x16x32_bf16 v[100:103], v[182:185], v[226:229], v[100:103]
	v_mfma_f32_16x16x32_bf16 v[90:93], v[186:189], v[222:225], v[90:93]
	v_mfma_f32_16x16x32_bf16 v[90:93], v[190:193], v[226:229], v[90:93]
	v_mfma_f32_16x16x32_bf16 v[82:85], v[164:167], v[230:233], v[82:85]
	v_mfma_f32_16x16x32_bf16 v[82:85], v[182:185], v[234:237], v[82:85]
	v_mfma_f32_16x16x32_bf16 v[74:77], v[186:189], v[230:233], v[74:77]
	v_mfma_f32_16x16x32_bf16 v[74:77], v[190:193], v[234:237], v[74:77]
	v_mfma_f32_16x16x32_bf16 v[70:73], v[164:167], v[238:241], v[70:73]
	v_mfma_f32_16x16x32_bf16 v[70:73], v[182:185], v[242:245], v[70:73]
	s_setprio 2
	s_barrier
; #define PG8_STAGE(bufoff, gbase, voff) do { _Pragma("unroll") for (int _i = 0; _i < 2; ++_i) \
;         __builtin_amdgcn_global_load_lds((const unsigned*)((const char*)(gbase) + (voff)[_i]), (PG8_LAS unsigned*)(lds + (bufoff) + ldsw + _i * 8192), 16, 0, AUX_A); } while (0)
; #define PG8_STAGEB(bufoff, gbase, voff) do { _Pragma("unroll") for (int _i = 0; _i < 2; ++_i) \
;         __builtin_amdgcn_global_load_lds((const unsigned*)((const char*)(gbase) + (voff)[_i]), (PG8_LAS unsigned*)(lds + (bufoff) + ldsw + _i * 8192), 16, 0, AUX_B); } while (0)
; #define PG8_LDA(dst, b, h) do { _Pragma("unroll") for (int m = 0; m < 4; ++m) _Pragma("unroll") for (int k = 0; k < 2; ++k) dst[m][k] = *(const PG8_LAS bf16x8*)(lds + PG8_SA(b, h) + aoff + m * 2048 + k * 1024); } while (0)
; #define PG8_LDB(dst, b, h) do { _Pragma("unroll") for (int n = 0; n < 2; ++n) _Pragma("unroll") for (int k = 0; k < 2; ++k) dst[n][k] = *(const PG8_LAS bf16x8*)(lds + PG8_SB(b, h) + boff + n * 2048 + k * 1024); } while (0)
; #define PG8_MMA(ai, bj, At, Bt) do { __builtin_amdgcn_s_setprio(1); _Pragma("unroll") for (int m = 0; m < 4; ++m) _Pragma("unroll") for (int n = 0; n < 2; ++n) _Pragma("unroll") for (int k = 0; k < 2; ++k) \
;         acc[ai][bj][m][n] = __builtin_amdgcn_mfma_f32_16x16x32_bf16(Bt[n][k], At[m][k], acc[ai][bj][m][n], 0, 0, 0); __builtin_amdgcn_s_setprio(0); } while (0)
; #define PG8_WAIT_V(n) asm volatile("s_waitcnt vmcnt(" #n ")" ::: "memory")
; #define PG8_WAIT_L(n) asm volatile("s_waitcnt lgkmcnt(" #n ")" ::: "memory")
; #define PG8_BAR __builtin_amdgcn_s_barrier()
; template <class Epi, class Sched, bool ALIGN_EPI = false, bool SP2 = false>
; __device__ __forceinline__ void gemm_phase(PG8_LAS unsigned char* lds, const Gemm g, const Sched& S, const Epi& E) {
;     ...
;             PG8_LDB(B0, 1, 0); PG8_LDB(B1, 1, 1); PG8_SCHED; PG8_LDA(At, 1, 0); PG8_STAGE(PG8_SA(0, 1), a2 + hstep, voffA);
;             PG8_WAIT_V(8); PG8_WAIT_L(0); PG8_BAR; PG8_MMA(0, 0, At, B0); PG8_MMA(0, 1, At, B1); PG8_BAR; PG8_SCHED;
;             PG8_LDA(At, 1, 1); PG8_STAGEB(PG8_SB(1, 0), b3, voffB); PG8_STAGEB(PG8_SB(1, 1), b3 + hstep, voffB); PG8_STAGE(PG8_SA(1, 0), a3, voffA);
;             PG8_WAIT_V(8); PG8_WAIT_L(0); PG8_BAR; PG8_MMA(1, 0, At, B0); PG8_MMA(1, 1, At, B1); PG8_BAR; PG8_SCHED;
;     ...
;         if constexpr (ALIGN_EPI) { if (wr == 0) PG8_BAR; }
	v_mfma_f32_16x16x32_bf16 v[66:69], v[186:189], v[238:241], v[66:69]
	v_mfma_f32_16x16x32_bf16 v[66:69], v[190:193], v[242:245], v[66:69]
	s_setprio 0
	s_add_i32 s0, s2, s49
	v_lshl_add_u64 v[168:169], v[168:169], 0, s[76:77]
	s_mov_b32 m0, s0
	ds_read_b128 v[194:197], v181 offset:49152
	ds_read_b128 v[198:201], v181 offset:50176
	ds_read_b128 v[222:225], v181 offset:51200
	ds_read_b128 v[226:229], v181 offset:52224
	ds_read_b128 v[230:233], v181 offset:53248
	ds_read_b128 v[234:237], v181 offset:54272
	ds_read_b128 v[238:241], v181 offset:55296
	ds_read_b128 v[242:245], v181 offset:56320
	global_load_lds_dwordx4 v[168:169], off
	s_add_i32 m0, s0, 0x2000
	s_add_u32 s0, s36, 0x80080
	v_lshl_add_u64 v[168:169], v[172:173], 0, s[76:77]
	s_addc_u32 s1, s37, 0
	s_add_i32 s2, s15, s49
	global_load_lds_dwordx4 v[168:169], off
	v_lshl_add_u64 v[168:169], s[0:1], 0, v[156:157]
	s_mov_b32 m0, s2
	s_nop 0
	global_load_lds_dwordx4 v[168:169], off
	v_lshl_add_u64 v[168:169], s[0:1], 0, v[152:153]
	s_add_i32 m0, s2, 0x2000
	s_nop 0
	global_load_lds_dwordx4 v[168:169], off
	v_lshl_add_u64 v[168:169], v[202:203], 0, s[76:77]
	s_mov_b32 m0, s59
	s_nop 0
	global_load_lds_dwordx4 v[168:169], off
	v_lshl_add_u64 v[168:169], v[212:213], 0, s[76:77]
	s_mov_b32 m0, s60
	s_nop 0
	global_load_lds_dwordx4 v[168:169], off
	s_waitcnt vmcnt(8)
	s_waitcnt lgkmcnt(0)
	s_setprio 1
	s_barrier
	v_mfma_f32_16x16x32_bf16 v[62:65], v[136:139], v[194:197], v[62:65]
	v_mfma_f32_16x16x32_bf16 v[62:65], v[140:143], v[198:201], v[62:65]
	v_mfma_f32_16x16x32_bf16 v[58:61], v[144:147], v[194:197], v[58:61]
	v_mfma_f32_16x16x32_bf16 v[58:61], v[148:151], v[198:201], v[58:61]
	v_mfma_f32_16x16x32_bf16 v[54:57], v[136:139], v[222:225], v[54:57]
	v_mfma_f32_16x16x32_bf16 v[54:57], v[140:143], v[226:229], v[54:57]
	v_mfma_f32_16x16x32_bf16 v[46:49], v[144:147], v[222:225], v[46:49]
	v_mfma_f32_16x16x32_bf16 v[46:49], v[148:151], v[226:229], v[46:49]
	v_mfma_f32_16x16x32_bf16 v[38:41], v[136:139], v[230:233], v[38:41]
	v_mfma_f32_16x16x32_bf16 v[38:41], v[140:143], v[234:237], v[38:41]
	v_mfma_f32_16x16x32_bf16 v[30:33], v[144:147], v[230:233], v[30:33]
	v_mfma_f32_16x16x32_bf16 v[30:33], v[148:151], v[234:237], v[30:33]
	v_mfma_f32_16x16x32_bf16 v[22:25], v[136:139], v[238:241], v[22:25]
	v_mfma_f32_16x16x32_bf16 v[22:25], v[140:143], v[242:245], v[22:25]
	v_mfma_f32_16x16x32_bf16 v[14:17], v[144:147], v[238:241], v[14:17]
	v_mfma_f32_16x16x32_bf16 v[14:17], v[148:151], v[242:245], v[14:17]
	s_setprio 0
	s_setprio 1
	v_mfma_f32_16x16x32_bf16 v[50:53], v[164:167], v[194:197], v[50:53]
	v_mfma_f32_16x16x32_bf16 v[50:53], v[182:185], v[198:201], v[50:53]
	v_mfma_f32_16x16x32_bf16 v[42:45], v[186:189], v[194:197], v[42:45]
	v_mfma_f32_16x16x32_bf16 v[42:45], v[190:193], v[198:201], v[42:45]
	v_mfma_f32_16x16x32_bf16 v[34:37], v[164:167], v[222:225], v[34:37]
	v_mfma_f32_16x16x32_bf16 v[34:37], v[182:185], v[226:229], v[34:37]
	v_mfma_f32_16x16x32_bf16 v[26:29], v[186:189], v[222:225], v[26:29]
	v_mfma_f32_16x16x32_bf16 v[26:29], v[190:193], v[226:229], v[26:29]
	v_mfma_f32_16x16x32_bf16 v[18:21], v[164:167], v[230:233], v[18:21]
	v_mfma_f32_16x16x32_bf16 v[18:21], v[182:185], v[234:237], v[18:21]
	v_mfma_f32_16x16x32_bf16 v[10:13], v[186:189], v[230:233], v[10:13]
	v_mfma_f32_16x16x32_bf16 v[10:13], v[190:193], v[234:237], v[10:13]
	v_mfma_f32_16x16x32_bf16 v[6:9], v[164:167], v[238:241], v[6:9]
	v_mfma_f32_16x16x32_bf16 v[6:9], v[182:185], v[242:245], v[6:9]
	s_setprio 2
	s_cmp_ge_i32 s13, s71
	s_cbranch_scc1 .Lq4x_1308l
	s_barrier
.Lq4r_1308l:
	v_mfma_f32_16x16x32_bf16 v[2:5], v[186:189], v[238:241], v[2:5]
	v_mfma_f32_16x16x32_bf16 v[2:5], v[190:193], v[242:245], v[2:5]
	s_setprio 0
	s_add_i32 s0, s13, 2
	v_lshl_add_u64 v[132:133], v[132:133], 0, s[86:87]
	v_lshl_add_u64 v[134:135], v[134:135], 0, s[86:87]
	s_cmp_ge_i32 s13, s71
	s_mov_b32 s13, s0
	s_cbranch_scc0 .LBB0_1308
	s_branch .Lpx_1308
.Lq4x_1308l:
	v_cmp_ne_u32_e64 vcc, s8, 0
	s_cbranch_vccz .Lq4r_1308l
	s_barrier
	s_branch .Lq4r_1308l

; #define PG8_STAGE(bufoff, gbase, voff) do { _Pragma("unroll") for (int _i = 0; _i < 2; ++_i) \
;         __builtin_amdgcn_global_load_lds((const unsigned*)((const char*)(gbase) + (voff)[_i]), (PG8_LAS unsigned*)(lds + (bufoff) + ldsw + _i * 8192), 16, 0, AUX_A); } while (0)
; #define PG8_STAGEB(bufoff, gbase, voff) do { _Pragma("unroll") for (int _i = 0; _i < 2; ++_i) \
;         __builtin_amdgcn_global_load_lds((const unsigned*)((const char*)(gbase) + (voff)[_i]), (PG8_LAS unsigned*)(lds + (bufoff) + ldsw + _i * 8192), 16, 0, AUX_B); } while (0)
; #define PG8_LDA(dst, b, h) do { _Pragma("unroll") for (int m = 0; m < 4; ++m) _Pragma("unroll") for (int k = 0; k < 2; ++k) dst[m][k] = *(const PG8_LAS bf16x8*)(lds + PG8_SA(b, h) + aoff + m * 2048 + k * 1024); } while (0)
; #define PG8_LDB(dst, b, h) do { _Pragma("unroll") for (int n = 0; n < 2; ++n) _Pragma("unroll") for (int k = 0; k < 2; ++k) dst[n][k] = *(const PG8_LAS bf16x8*)(lds + PG8_SB(b, h) + boff + n * 2048 + k * 1024); } while (0)
; #define PG8_WAIT_V(n) asm volatile("s_waitcnt vmcnt(" #n ")" ::: "memory")
; #define PG8_WAIT_L(n) asm volatile("s_waitcnt lgkmcnt(" #n ")" ::: "memory")
; #define PG8_BAR __builtin_amdgcn_s_barrier()
; template <class Epi, class Sched, bool ALIGN_EPI = false, bool SP2 = false>
; __device__ __forceinline__ void gemm_phase(PG8_LAS unsigned char* lds, const Gemm g, const Sched& S, const Epi& E) {
;     ...
;         for (int t = 0; t < nt; t += 2) {
;             const bool last = (t == nt - 2);
;             const char* a1 = PG8_KP(cA, t + 1, rot, nt);
;             const char* a2 = last ? nAr : PG8_KP(cA, t + 2, rot, nt); const char* b2 = last ? nBr : PG8_KP(cB, t + 2, rot, nt);
;             const char* a3 = a2 + kstep; const char* b3 = b2 + kstep;
;             if (last && has_next) S.a_ready(nxt);
;             if constexpr (SP2) {
;             PG8_LDB(B0, 0, 0); PG8_LDB(B1, 0, 1); PG8_SCHED; PG8_LDA(At, 0, 0); PG8_STAGE(PG8_SA(1, 1), a1 + hstep, voffA);
;             PG8_WAIT_V(8); PG8_WAIT_L(0); PG8_BAR; PG8_MMA(0, 0, At, B0); PG8_MMA(0, 1, At, B1); PG8_BAR; PG8_SCHED;
;             PG8_LDA(At, 0, 1); PG8_STAGEB(PG8_SB(0, 0), b2, voffB); PG8_STAGEB(PG8_SB(0, 1), b2 + hstep, voffB); PG8_STAGE(PG8_SA(0, 0), a2, voffA);
;             PG8_WAIT_V(8); PG8_WAIT_L(0); PG8_BAR; PG8_MMA(1, 0, At, B0); PG8_MMA(1, 1, At, B1); PG8_BAR; PG8_SCHED;
.Lpk_1458:
	s_lshl_b32 s100, s29, 7
	s_add_u32 s100, s40, s100
	s_addc_u32 s101, s41, 0
	s_add_u32 s100, s100, 0x80
	s_addc_u32 s101, s101, 0
	s_add_i32 s30, s29, 2
	s_cmp_lt_u32 s29, 30
	s_cselect_b32 s0, 0, 0xffffffe0
	s_add_i32 s0, s30, s0
	s_ashr_i32 s1, s0, 31
	s_lshl_b64 s[0:1], s[0:1], 7
	s_add_u32 s2, s40, s0
	s_addc_u32 s31, s41, s1
	s_add_u32 s0, s34, s0
	s_addc_u32 s1, s35, s1
	s_cmp_eq_u32 s29, 30
	s_cselect_b32 s45, s13, s31
	s_cselect_b32 s44, s15, s2
	s_cselect_b32 s49, s71, s1
	s_cselect_b32 s48, s75, s0
	s_add_i32 s2, 0, 0x10000
	s_add_i32 s78, s2, s56
	s_add_i32 s31, 0, 0x14000
	s_add_i32 s47, s57, 0xe000
	s_add_i32 s81, s78, 0x2000
	s_add_u32 s50, s48, 0x80000
	s_addc_u32 s51, s49, 0
	s_add_i32 s82, s31, s56
	v_add_u32_e32 v162, s2, v99
	v_add_u32_e32 v166, s31, v99
	s_add_i32 s83, s82, 0x2000
	s_add_i32 s84, 0, 0x18000
	s_add_i32 s88, 0, 0x1c000
	ds_read_b128 v[150:153], v162
	ds_read_b128 v[154:157], v162 offset:1024
	ds_read_b128 v[158:161], v162 offset:2048
	ds_read_b128 v[162:165], v162 offset:3072
	ds_read_b128 v[180:183], v166
	ds_read_b128 v[184:187], v166 offset:1024
	ds_read_b128 v[188:191], v166 offset:2048
	ds_read_b128 v[192:195], v166 offset:3072
	s_add_u32 s42, s44, 0x80000
	s_addc_u32 s43, s45, 0
	s_add_i32 s1, s84, s56
	s_add_i32 s0, s1, 0x2000
	s_add_u32 s36, s48, 0x80080
	s_addc_u32 s37, s49, 0
	s_add_i32 s46, s88, s56
	s_add_i32 s31, s46, 0x2000
	ds_read_b128 v[196:199], v149
	ds_read_b128 v[200:203], v149 offset:1024
	ds_read_b128 v[222:225], v149 offset:2048
	ds_read_b128 v[226:229], v149 offset:3072
	ds_read_b128 v[230:233], v149 offset:4096
	ds_read_b128 v[234:237], v149 offset:5120
	ds_read_b128 v[238:241], v149 offset:6144
	ds_read_b128 v[242:245], v149 offset:7168
	v_lshl_add_u64 v[166:167], s[100:101], 0, v[138:139]
	s_mov_b32 m0, s61
	v_lshl_add_u64 v[168:169], s[100:101], 0, v[134:135]
	global_load_lds_dwordx4 v[166:167], off
	s_mov_b32 m0, s62
	s_nop 0
	global_load_lds_dwordx4 v[168:169], off
	s_add_i32 m0, s57, 0xc000
	s_nop 0
	global_load_lds_dwordx4 v[146:147], off
	s_mov_b32 m0, s47
	s_nop 0
	global_load_lds_dwordx4 v[144:145], off
	s_waitcnt vmcnt(8)
	s_waitcnt lgkmcnt(0)
	s_setprio 1
	s_barrier
	v_mfma_f32_16x16x32_bf16 v[128:131], v[150:153], v[196:199], 0
	v_mfma_f32_16x16x32_bf16 v[128:131], v[154:157], v[200:203], v[128:131]
	v_mfma_f32_16x16x32_bf16 v[120:123], v[158:161], v[196:199], 0
	v_mfma_f32_16x16x32_bf16 v[120:123], v[162:165], v[200:203], v[120:123]
	v_mfma_f32_16x16x32_bf16 v[112:115], v[150:153], v[222:225], 0
	v_mfma_f32_16x16x32_bf16 v[112:115], v[154:157], v[226:229], v[112:115]
	v_mfma_f32_16x16x32_bf16 v[104:107], v[158:161], v[222:225], 0
	v_mfma_f32_16x16x32_bf16 v[104:107], v[162:165], v[226:229], v[104:107]
	v_mfma_f32_16x16x32_bf16 v[94:97], v[150:153], v[230:233], 0
	v_mfma_f32_16x16x32_bf16 v[94:97], v[154:157], v[234:237], v[94:97]
	v_mfma_f32_16x16x32_bf16 v[86:89], v[158:161], v[230:233], 0
	v_mfma_f32_16x16x32_bf16 v[86:89], v[162:165], v[234:237], v[86:89]
	v_mfma_f32_16x16x32_bf16 v[78:81], v[150:153], v[238:241], 0
	v_mfma_f32_16x16x32_bf16 v[78:81], v[154:157], v[242:245], v[78:81]
	v_mfma_f32_16x16x32_bf16 v[70:73], v[158:161], v[238:241], 0
	v_mfma_f32_16x16x32_bf16 v[70:73], v[162:165], v[242:245], v[70:73]
	s_setprio 0
	s_setprio 1
	v_mfma_f32_16x16x32_bf16 v[124:127], v[180:183], v[196:199], 0
	v_mfma_f32_16x16x32_bf16 v[124:127], v[184:187], v[200:203], v[124:127]
	v_mfma_f32_16x16x32_bf16 v[116:119], v[188:191], v[196:199], 0
	v_mfma_f32_16x16x32_bf16 v[116:119], v[192:195], v[200:203], v[116:119]
	v_mfma_f32_16x16x32_bf16 v[108:111], v[180:183], v[222:225], 0
	v_mfma_f32_16x16x32_bf16 v[108:111], v[184:187], v[226:229], v[108:111]
	v_mfma_f32_16x16x32_bf16 v[100:103], v[188:191], v[222:225], 0
	v_mfma_f32_16x16x32_bf16 v[100:103], v[192:195], v[226:229], v[100:103]
	v_mfma_f32_16x16x32_bf16 v[90:93], v[180:183], v[230:233], 0
	v_mfma_f32_16x16x32_bf16 v[90:93], v[184:187], v[234:237], v[90:93]
	v_mfma_f32_16x16x32_bf16 v[82:85], v[188:191], v[230:233], 0
	v_mfma_f32_16x16x32_bf16 v[82:85], v[192:195], v[234:237], v[82:85]
	v_mfma_f32_16x16x32_bf16 v[74:77], v[180:183], v[238:241], 0
	v_mfma_f32_16x16x32_bf16 v[74:77], v[184:187], v[242:245], v[74:77]
	s_setprio 2
	s_barrier
	v_mfma_f32_16x16x32_bf16 v[66:69], v[188:191], v[238:241], 0
	v_mfma_f32_16x16x32_bf16 v[66:69], v[192:195], v[242:245], v[66:69]
	s_setprio 0
	s_mov_b32 m0, s78
	v_lshl_add_u64 v[166:167], s[48:49], 0, v[136:137]
	ds_read_b128 v[196:199], v149 offset:16384
	ds_read_b128 v[200:203], v149 offset:17408
	ds_read_b128 v[222:225], v149 offset:18432
	ds_read_b128 v[226:229], v149 offset:19456
	ds_read_b128 v[230:233], v149 offset:20480
	ds_read_b128 v[234:237], v149 offset:21504
	ds_read_b128 v[238:241], v149 offset:22528
	ds_read_b128 v[242:245], v149 offset:23552
	global_load_lds_dwordx4 v[166:167], off
	v_lshl_add_u64 v[168:169], s[48:49], 0, v[132:133]
	s_mov_b32 m0, s81
	v_lshl_add_u64 v[172:173], s[50:51], 0, v[136:137]
	global_load_lds_dwordx4 v[168:169], off
	s_mov_b32 m0, s82
	global_load_lds_dwordx4 v[172:173], off
	v_lshl_add_u64 v[172:173], s[50:51], 0, v[132:133]
	s_mov_b32 m0, s83
	s_nop 0
	global_load_lds_dwordx4 v[172:173], off
	s_waitcnt vmcnt(6)
	s_waitcnt lgkmcnt(0)
	s_setprio 1
	s_barrier
; #define PG8_STAGE(bufoff, gbase, voff) do { _Pragma("unroll") for (int _i = 0; _i < 2; ++_i) \
;         __builtin_amdgcn_global_load_lds((const unsigned*)((const char*)(gbase) + (voff)[_i]), (PG8_LAS unsigned*)(lds + (bufoff) + ldsw + _i * 8192), 16, 0, AUX_A); } while (0)
; #define PG8_STAGEB(bufoff, gbase, voff) do { _Pragma("unroll") for (int _i = 0; _i < 2; ++_i) \
;         __builtin_amdgcn_global_load_lds((const unsigned*)((const char*)(gbase) + (voff)[_i]), (PG8_LAS unsigned*)(lds + (bufoff) + ldsw + _i * 8192), 16, 0, AUX_B); } while (0)
; #define PG8_LDA(dst, b, h) do { _Pragma("unroll") for (int m = 0; m < 4; ++m) _Pragma("unroll") for (int k = 0; k < 2; ++k) dst[m][k] = *(const PG8_LAS bf16x8*)(lds + PG8_SA(b, h) + aoff + m * 2048 + k * 1024); } while (0)
; #define PG8_LDB(dst, b, h) do { _Pragma("unroll") for (int n = 0; n < 2; ++n) _Pragma("unroll") for (int k = 0; k < 2; ++k) dst[n][k] = *(const PG8_LAS bf16x8*)(lds + PG8_SB(b, h) + boff + n * 2048 + k * 1024); } while (0)
; #define PG8_MMA(ai, bj, At, Bt) do { __builtin_amdgcn_s_setprio(1); _Pragma("unroll") for (int m = 0; m < 4; ++m) _Pragma("unroll") for (int n = 0; n < 2; ++n) _Pragma("unroll") for (int k = 0; k < 2; ++k) \
;         acc[ai][bj][m][n] = __builtin_amdgcn_mfma_f32_16x16x32_bf16(Bt[n][k], At[m][k], acc[ai][bj][m][n], 0, 0, 0); __builtin_amdgcn_s_setprio(0); } while (0)
; template <class Epi, class Sched, bool ALIGN_EPI = false, bool SP2 = false>
; __device__ __forceinline__ void gemm_phase(PG8_LAS unsigned char* lds, const Gemm g, const Sched& S, const Epi& E) {
;     ...
;             if constexpr (SP2) {
;             PG8_LDB(B0, 0, 0); PG8_LDB(B1, 0, 1); PG8_SCHED; PG8_LDA(At, 0, 0); PG8_STAGE(PG8_SA(1, 1), a1 + hstep, voffA);
;             PG8_WAIT_V(8); PG8_WAIT_L(0); PG8_BAR; PG8_MMA(0, 0, At, B0); PG8_MMA(0, 1, At, B1); PG8_BAR; PG8_SCHED;
;             PG8_LDA(At, 0, 1); PG8_STAGEB(PG8_SB(0, 0), b2, voffB); PG8_STAGEB(PG8_SB(0, 1), b2 + hstep, voffB); PG8_STAGE(PG8_SA(0, 0), a2, voffA);
;             PG8_WAIT_V(8); PG8_WAIT_L(0); PG8_BAR; PG8_MMA(1, 0, At, B0); PG8_MMA(1, 1, At, B1); PG8_BAR; PG8_SCHED;
;             PG8_LDB(B0, 1, 0); PG8_LDB(B1, 1, 1); PG8_SCHED; PG8_LDA(At, 1, 0); PG8_STAGE(PG8_SA(0, 1), a2 + hstep, voffA);
;             PG8_WAIT_V(8); PG8_WAIT_L(0); PG8_BAR; PG8_MMA(0, 0, At, B0); PG8_MMA(0, 1, At, B1); PG8_BAR; PG8_SCHED;
	v_mfma_f32_16x16x32_bf16 v[62:65], v[150:153], v[196:199], 0
	v_mfma_f32_16x16x32_bf16 v[62:65], v[154:157], v[200:203], v[62:65]
	v_mfma_f32_16x16x32_bf16 v[54:57], v[158:161], v[196:199], 0
	v_mfma_f32_16x16x32_bf16 v[54:57], v[162:165], v[200:203], v[54:57]
	v_mfma_f32_16x16x32_bf16 v[46:49], v[150:153], v[222:225], 0
	v_mfma_f32_16x16x32_bf16 v[46:49], v[154:157], v[226:229], v[46:49]
	v_mfma_f32_16x16x32_bf16 v[38:41], v[158:161], v[222:225], 0
	v_mfma_f32_16x16x32_bf16 v[38:41], v[162:165], v[226:229], v[38:41]
	v_mfma_f32_16x16x32_bf16 v[30:33], v[150:153], v[230:233], 0
	v_mfma_f32_16x16x32_bf16 v[30:33], v[154:157], v[234:237], v[30:33]
	v_mfma_f32_16x16x32_bf16 v[22:25], v[158:161], v[230:233], 0
	v_mfma_f32_16x16x32_bf16 v[22:25], v[162:165], v[234:237], v[22:25]
	v_mfma_f32_16x16x32_bf16 v[14:17], v[150:153], v[238:241], 0
	v_mfma_f32_16x16x32_bf16 v[14:17], v[154:157], v[242:245], v[14:17]
	v_mfma_f32_16x16x32_bf16 v[6:9], v[158:161], v[238:241], 0
	v_mfma_f32_16x16x32_bf16 v[6:9], v[162:165], v[242:245], v[6:9]
	s_setprio 0
	s_setprio 1
	v_mfma_f32_16x16x32_bf16 v[58:61], v[180:183], v[196:199], 0
	v_mfma_f32_16x16x32_bf16 v[58:61], v[184:187], v[200:203], v[58:61]
	v_mfma_f32_16x16x32_bf16 v[50:53], v[188:191], v[196:199], 0
	v_mfma_f32_16x16x32_bf16 v[50:53], v[192:195], v[200:203], v[50:53]
	v_mfma_f32_16x16x32_bf16 v[42:45], v[180:183], v[222:225], 0
	v_mfma_f32_16x16x32_bf16 v[42:45], v[184:187], v[226:229], v[42:45]
	v_mfma_f32_16x16x32_bf16 v[34:37], v[188:191], v[222:225], 0
	v_mfma_f32_16x16x32_bf16 v[34:37], v[192:195], v[226:229], v[34:37]
	v_mfma_f32_16x16x32_bf16 v[26:29], v[180:183], v[230:233], 0
	v_mfma_f32_16x16x32_bf16 v[26:29], v[184:187], v[234:237], v[26:29]
	v_mfma_f32_16x16x32_bf16 v[18:21], v[188:191], v[230:233], 0
	v_mfma_f32_16x16x32_bf16 v[18:21], v[192:195], v[234:237], v[18:21]
	v_mfma_f32_16x16x32_bf16 v[10:13], v[180:183], v[238:241], 0
	v_mfma_f32_16x16x32_bf16 v[10:13], v[184:187], v[242:245], v[10:13]
	s_setprio 2
	s_barrier
	v_mfma_f32_16x16x32_bf16 v[2:5], v[188:191], v[238:241], 0
	v_mfma_f32_16x16x32_bf16 v[2:5], v[192:195], v[242:245], v[2:5]
	s_setprio 0
	v_add_u32_e32 v162, s84, v99
	v_add_u32_e32 v192, s88, v99
	ds_read_b128 v[150:153], v162
	ds_read_b128 v[154:157], v162 offset:1024
	ds_read_b128 v[158:161], v162 offset:2048
	ds_read_b128 v[162:165], v162 offset:3072
	ds_read_b128 v[180:183], v192
	ds_read_b128 v[184:187], v192 offset:1024
	ds_read_b128 v[188:191], v192 offset:2048
	ds_read_b128 v[192:195], v192 offset:3072
	s_mov_b32 m0, s59
	v_lshl_add_u64 v[246:247], s[42:43], 0, v[138:139]
	ds_read_b128 v[196:199], v149 offset:32768
	ds_read_b128 v[200:203], v149 offset:33792
	ds_read_b128 v[222:225], v149 offset:34816
	ds_read_b128 v[226:229], v149 offset:35840
	ds_read_b128 v[230:233], v149 offset:36864
	ds_read_b128 v[234:237], v149 offset:37888
	ds_read_b128 v[238:241], v149 offset:38912
	ds_read_b128 v[242:245], v149 offset:39936
	v_lshl_add_u64 v[172:173], s[44:45], 0, v[138:139]
	s_mov_b32 m0, s57
	v_lshl_add_u64 v[212:213], s[44:45], 0, v[134:135]
	global_load_lds_dwordx4 v[172:173], off
	s_mov_b32 m0, s58
	s_nop 0
	global_load_lds_dwordx4 v[212:213], off
	s_mov_b32 m0, s59
	s_nop 0
	global_load_lds_dwordx4 v[246:247], off
	v_lshl_add_u64 v[246:247], s[42:43], 0, v[134:135]
	s_mov_b32 m0, s60
	s_nop 0
	global_load_lds_dwordx4 v[246:247], off
	s_waitcnt vmcnt(8)
	s_waitcnt lgkmcnt(0)
	s_setprio 1
	s_barrier
; #define PG8_STAGE(bufoff, gbase, voff) do { _Pragma("unroll") for (int _i = 0; _i < 2; ++_i) \
;         __builtin_amdgcn_global_load_lds((const unsigned*)((const char*)(gbase) + (voff)[_i]), (PG8_LAS unsigned*)(lds + (bufoff) + ldsw + _i * 8192), 16, 0, AUX_A); } while (0)
; #define PG8_STAGEB(bufoff, gbase, voff) do { _Pragma("unroll") for (int _i = 0; _i < 2; ++_i) \
;         __builtin_amdgcn_global_load_lds((const unsigned*)((const char*)(gbase) + (voff)[_i]), (PG8_LAS unsigned*)(lds + (bufoff) + ldsw + _i * 8192), 16, 0, AUX_B); } while (0)
; #define PG8_LDA(dst, b, h) do { _Pragma("unroll") for (int m = 0; m < 4; ++m) _Pragma("unroll") for (int k = 0; k < 2; ++k) dst[m][k] = *(const PG8_LAS bf16x8*)(lds + PG8_SA(b, h) + aoff + m * 2048 + k * 1024); } while (0)
; #define PG8_LDB(dst, b, h) do { _Pragma("unroll") for (int n = 0; n < 2; ++n) _Pragma("unroll") for (int k = 0; k < 2; ++k) dst[n][k] = *(const PG8_LAS bf16x8*)(lds + PG8_SB(b, h) + boff + n * 2048 + k * 1024); } while (0)
; #define PG8_MMA(ai, bj, At, Bt) do { __builtin_amdgcn_s_setprio(1); _Pragma("unroll") for (int m = 0; m < 4; ++m) _Pragma("unroll") for (int n = 0; n < 2; ++n) _Pragma("unroll") for (int k = 0; k < 2; ++k) \
;         acc[ai][bj][m][n] = __builtin_amdgcn_mfma_f32_16x16x32_bf16(Bt[n][k], At[m][k], acc[ai][bj][m][n], 0, 0, 0); __builtin_amdgcn_s_setprio(0); } while (0)
; #define PG8_WAIT_V(n) asm volatile("s_waitcnt vmcnt(" #n ")" ::: "memory")
; #define PG8_WAIT_L(n) asm volatile("s_waitcnt lgkmcnt(" #n ")" ::: "memory")
; #define PG8_BAR __builtin_amdgcn_s_barrier()
; #define PG8_SCHED __builtin_amdgcn_sched_barrier(0)
; template <class Epi, class Sched, bool ALIGN_EPI = false, bool SP2 = false>
; __device__ __forceinline__ void gemm_phase(PG8_LAS unsigned char* lds, const Gemm g, const Sched& S, const Epi& E) {
;     ...
;             PG8_LDB(B0, 1, 0); PG8_LDB(B1, 1, 1); PG8_SCHED; PG8_LDA(At, 1, 0); PG8_STAGE(PG8_SA(0, 1), a2 + hstep, voffA);
;             PG8_WAIT_V(8); PG8_WAIT_L(0); PG8_BAR; PG8_MMA(0, 0, At, B0); PG8_MMA(0, 1, At, B1); PG8_BAR; PG8_SCHED;
;             PG8_LDA(At, 1, 1); PG8_STAGEB(PG8_SB(1, 0), b3, voffB); PG8_STAGEB(PG8_SB(1, 1), b3 + hstep, voffB); PG8_STAGE(PG8_SA(1, 0), a3, voffA);
;             PG8_WAIT_V(8); PG8_WAIT_L(0); PG8_BAR; PG8_MMA(1, 0, At, B0); PG8_MMA(1, 1, At, B1); PG8_BAR; PG8_SCHED;
	v_mfma_f32_16x16x32_bf16 v[128:131], v[150:153], v[196:199], v[128:131]
	v_mfma_f32_16x16x32_bf16 v[128:131], v[154:157], v[200:203], v[128:131]
	v_mfma_f32_16x16x32_bf16 v[120:123], v[158:161], v[196:199], v[120:123]
	v_mfma_f32_16x16x32_bf16 v[120:123], v[162:165], v[200:203], v[120:123]
	v_mfma_f32_16x16x32_bf16 v[112:115], v[150:153], v[222:225], v[112:115]
	v_mfma_f32_16x16x32_bf16 v[112:115], v[154:157], v[226:229], v[112:115]
	v_mfma_f32_16x16x32_bf16 v[104:107], v[158:161], v[222:225], v[104:107]
	v_mfma_f32_16x16x32_bf16 v[104:107], v[162:165], v[226:229], v[104:107]
	v_mfma_f32_16x16x32_bf16 v[94:97], v[150:153], v[230:233], v[94:97]
	v_mfma_f32_16x16x32_bf16 v[94:97], v[154:157], v[234:237], v[94:97]
	v_mfma_f32_16x16x32_bf16 v[86:89], v[158:161], v[230:233], v[86:89]
	v_mfma_f32_16x16x32_bf16 v[86:89], v[162:165], v[234:237], v[86:89]
	v_mfma_f32_16x16x32_bf16 v[78:81], v[150:153], v[238:241], v[78:81]
	v_mfma_f32_16x16x32_bf16 v[78:81], v[154:157], v[242:245], v[78:81]
	v_mfma_f32_16x16x32_bf16 v[70:73], v[158:161], v[238:241], v[70:73]
	v_mfma_f32_16x16x32_bf16 v[70:73], v[162:165], v[242:245], v[70:73]
	s_setprio 0
	s_setprio 1
	v_mfma_f32_16x16x32_bf16 v[124:127], v[180:183], v[196:199], v[124:127]
	v_mfma_f32_16x16x32_bf16 v[124:127], v[184:187], v[200:203], v[124:127]
	v_mfma_f32_16x16x32_bf16 v[116:119], v[188:191], v[196:199], v[116:119]
	v_mfma_f32_16x16x32_bf16 v[116:119], v[192:195], v[200:203], v[116:119]
	v_mfma_f32_16x16x32_bf16 v[108:111], v[180:183], v[222:225], v[108:111]
	v_mfma_f32_16x16x32_bf16 v[108:111], v[184:187], v[226:229], v[108:111]
	v_mfma_f32_16x16x32_bf16 v[100:103], v[188:191], v[222:225], v[100:103]
	v_mfma_f32_16x16x32_bf16 v[100:103], v[192:195], v[226:229], v[100:103]
	v_mfma_f32_16x16x32_bf16 v[90:93], v[180:183], v[230:233], v[90:93]
	v_mfma_f32_16x16x32_bf16 v[90:93], v[184:187], v[234:237], v[90:93]
	v_mfma_f32_16x16x32_bf16 v[82:85], v[188:191], v[230:233], v[82:85]
	v_mfma_f32_16x16x32_bf16 v[82:85], v[192:195], v[234:237], v[82:85]
	v_mfma_f32_16x16x32_bf16 v[74:77], v[180:183], v[238:241], v[74:77]
	v_mfma_f32_16x16x32_bf16 v[74:77], v[184:187], v[242:245], v[74:77]
	s_setprio 2
	s_barrier
	v_mfma_f32_16x16x32_bf16 v[66:69], v[188:191], v[238:241], v[66:69]
	v_mfma_f32_16x16x32_bf16 v[66:69], v[192:195], v[242:245], v[66:69]
	s_setprio 0
	s_mov_b32 m0, s1
	v_lshl_add_u64 v[166:167], v[166:167], 0, s[76:77]
	ds_read_b128 v[196:199], v149 offset:49152
	ds_read_b128 v[200:203], v149 offset:50176
	ds_read_b128 v[222:225], v149 offset:51200
	ds_read_b128 v[226:229], v149 offset:52224
	ds_read_b128 v[230:233], v149 offset:53248
	ds_read_b128 v[234:237], v149 offset:54272
	ds_read_b128 v[238:241], v149 offset:55296
	ds_read_b128 v[242:245], v149 offset:56320
	global_load_lds_dwordx4 v[166:167], off
	v_lshl_add_u64 v[166:167], v[168:169], 0, s[76:77]
	s_mov_b32 m0, s0
	s_nop 0
	global_load_lds_dwordx4 v[166:167], off
	v_lshl_add_u64 v[166:167], s[36:37], 0, v[136:137]
	s_mov_b32 m0, s46
	s_nop 0
	global_load_lds_dwordx4 v[166:167], off
	v_lshl_add_u64 v[166:167], s[36:37], 0, v[132:133]
	s_mov_b32 m0, s31
	s_nop 0
	global_load_lds_dwordx4 v[166:167], off
	s_waitcnt vmcnt(6)
	s_waitcnt lgkmcnt(0)
	s_setprio 1
	s_barrier
	v_mfma_f32_16x16x32_bf16 v[62:65], v[150:153], v[196:199], v[62:65]
	v_mfma_f32_16x16x32_bf16 v[62:65], v[154:157], v[200:203], v[62:65]
	v_mfma_f32_16x16x32_bf16 v[54:57], v[158:161], v[196:199], v[54:57]
	v_mfma_f32_16x16x32_bf16 v[54:57], v[162:165], v[200:203], v[54:57]
	v_mfma_f32_16x16x32_bf16 v[46:49], v[150:153], v[222:225], v[46:49]
	v_mfma_f32_16x16x32_bf16 v[46:49], v[154:157], v[226:229], v[46:49]
	v_mfma_f32_16x16x32_bf16 v[38:41], v[158:161], v[222:225], v[38:41]
	v_mfma_f32_16x16x32_bf16 v[38:41], v[162:165], v[226:229], v[38:41]
	v_mfma_f32_16x16x32_bf16 v[30:33], v[150:153], v[230:233], v[30:33]
	v_mfma_f32_16x16x32_bf16 v[30:33], v[154:157], v[234:237], v[30:33]
	v_mfma_f32_16x16x32_bf16 v[22:25], v[158:161], v[230:233], v[22:25]
	v_mfma_f32_16x16x32_bf16 v[22:25], v[162:165], v[234:237], v[22:25]
	v_mfma_f32_16x16x32_bf16 v[14:17], v[150:153], v[238:241], v[14:17]
	v_mfma_f32_16x16x32_bf16 v[14:17], v[154:157], v[242:245], v[14:17]
	v_mfma_f32_16x16x32_bf16 v[6:9], v[158:161], v[238:241], v[6:9]
	v_mfma_f32_16x16x32_bf16 v[6:9], v[162:165], v[242:245], v[6:9]
	s_setprio 0
	s_setprio 1
	v_mfma_f32_16x16x32_bf16 v[58:61], v[180:183], v[196:199], v[58:61]
	v_mfma_f32_16x16x32_bf16 v[58:61], v[184:187], v[200:203], v[58:61]
	v_mfma_f32_16x16x32_bf16 v[50:53], v[188:191], v[196:199], v[50:53]
	v_mfma_f32_16x16x32_bf16 v[50:53], v[192:195], v[200:203], v[50:53]
	v_mfma_f32_16x16x32_bf16 v[42:45], v[180:183], v[222:225], v[42:45]
	v_mfma_f32_16x16x32_bf16 v[42:45], v[184:187], v[226:229], v[42:45]
	v_mfma_f32_16x16x32_bf16 v[34:37], v[188:191], v[222:225], v[34:37]
	v_mfma_f32_16x16x32_bf16 v[34:37], v[192:195], v[226:229], v[34:37]
	v_mfma_f32_16x16x32_bf16 v[26:29], v[180:183], v[230:233], v[26:29]
	v_mfma_f32_16x16x32_bf16 v[26:29], v[184:187], v[234:237], v[26:29]
	v_mfma_f32_16x16x32_bf16 v[18:21], v[188:191], v[230:233], v[18:21]
	v_mfma_f32_16x16x32_bf16 v[18:21], v[192:195], v[234:237], v[18:21]
	v_mfma_f32_16x16x32_bf16 v[10:13], v[180:183], v[238:241], v[10:13]
	v_mfma_f32_16x16x32_bf16 v[10:13], v[184:187], v[242:245], v[10:13]
	s_setprio 2
	s_cmp_gt_u32 s30, 31
	s_cbranch_scc1 .Lq4x_1458p
	s_barrier

; #define PG8_STAGE(bufoff, gbase, voff) do { _Pragma("unroll") for (int _i = 0; _i < 2; ++_i) \
;         __builtin_amdgcn_global_load_lds((const unsigned*)((const char*)(gbase) + (voff)[_i]), (PG8_LAS unsigned*)(lds + (bufoff) + ldsw + _i * 8192), 16, 0, AUX_A); } while (0)
; #define PG8_STAGEB(bufoff, gbase, voff) do { _Pragma("unroll") for (int _i = 0; _i < 2; ++_i) \
;         __builtin_amdgcn_global_load_lds((const unsigned*)((const char*)(gbase) + (voff)[_i]), (PG8_LAS unsigned*)(lds + (bufoff) + ldsw + _i * 8192), 16, 0, AUX_B); } while (0)
; #define PG8_LDA(dst, b, h) do { _Pragma("unroll") for (int m = 0; m < 4; ++m) _Pragma("unroll") for (int k = 0; k < 2; ++k) dst[m][k] = *(const PG8_LAS bf16x8*)(lds + PG8_SA(b, h) + aoff + m * 2048 + k * 1024); } while (0)
; #define PG8_LDB(dst, b, h) do { _Pragma("unroll") for (int n = 0; n < 2; ++n) _Pragma("unroll") for (int k = 0; k < 2; ++k) dst[n][k] = *(const PG8_LAS bf16x8*)(lds + PG8_SB(b, h) + boff + n * 2048 + k * 1024); } while (0)
; #define PG8_WAIT_V(n) asm volatile("s_waitcnt vmcnt(" #n ")" ::: "memory")
; #define PG8_WAIT_L(n) asm volatile("s_waitcnt lgkmcnt(" #n ")" ::: "memory")
; #define PG8_BAR __builtin_amdgcn_s_barrier()
; template <class Epi, class Sched, bool ALIGN_EPI = false, bool SP2 = false>
; __device__ __forceinline__ void gemm_phase(PG8_LAS unsigned char* lds, const Gemm g, const Sched& S, const Epi& E) {
;     ...
;         for (int t = 0; t < nt; t += 2) {
;             const bool last = (t == nt - 2);
;             const char* a1 = PG8_KP(cA, t + 1, rot, nt);
;             const char* a2 = last ? nAr : PG8_KP(cA, t + 2, rot, nt); const char* b2 = last ? nBr : PG8_KP(cB, t + 2, rot, nt);
;             const char* a3 = a2 + kstep; const char* b3 = b2 + kstep;
;             if (last && has_next) S.a_ready(nxt);
;             if constexpr (SP2) {
;             PG8_LDB(B0, 0, 0); PG8_LDB(B1, 0, 1); PG8_SCHED; PG8_LDA(At, 0, 0); PG8_STAGE(PG8_SA(1, 1), a1 + hstep, voffA);
;             PG8_WAIT_V(8); PG8_WAIT_L(0); PG8_BAR; PG8_MMA(0, 0, At, B0); PG8_MMA(0, 1, At, B1); PG8_BAR; PG8_SCHED;
;             PG8_LDA(At, 0, 1); PG8_STAGEB(PG8_SB(0, 0), b2, voffB); PG8_STAGEB(PG8_SB(0, 1), b2 + hstep, voffB); PG8_STAGE(PG8_SA(0, 0), a2, voffA);
;             PG8_WAIT_V(8); PG8_WAIT_L(0); PG8_BAR; PG8_MMA(1, 0, At, B0); PG8_MMA(1, 1, At, B1); PG8_BAR; PG8_SCHED;
.LBB0_1458:
	s_lshl_b32 s100, s29, 7
	s_add_u32 s100, s40, s100
	s_addc_u32 s101, s41, 0
	s_add_u32 s100, s100, 0x80
	s_addc_u32 s101, s101, 0
	s_add_i32 s30, s29, 2
	s_cmp_lt_u32 s29, 30
	s_cselect_b32 s0, 0, 0xffffffe0
	s_add_i32 s0, s30, s0
	s_ashr_i32 s1, s0, 31
	s_lshl_b64 s[0:1], s[0:1], 7
	s_add_u32 s2, s40, s0
	s_addc_u32 s31, s41, s1
	s_add_u32 s0, s34, s0
	s_addc_u32 s1, s35, s1
	s_cmp_eq_u32 s29, 30
	s_cselect_b32 s45, s13, s31
	s_cselect_b32 s44, s15, s2
	s_cselect_b32 s49, s71, s1
	s_cselect_b32 s48, s75, s0
	s_add_i32 s2, 0, 0x10000
	s_add_i32 s78, s2, s56
	s_add_i32 s31, 0, 0x14000
	s_add_i32 s47, s57, 0xe000
	s_add_i32 s81, s78, 0x2000
	s_add_u32 s50, s48, 0x80000
	s_addc_u32 s51, s49, 0
	s_add_i32 s82, s31, s56
	v_add_u32_e32 v162, s2, v99
	v_add_u32_e32 v166, s31, v99
	s_add_i32 s83, s82, 0x2000
	s_add_i32 s84, 0, 0x18000
	s_add_i32 s88, 0, 0x1c000
	ds_read_b128 v[150:153], v162
	ds_read_b128 v[154:157], v162 offset:1024
	ds_read_b128 v[158:161], v162 offset:2048
	ds_read_b128 v[162:165], v162 offset:3072
	ds_read_b128 v[180:183], v166
	ds_read_b128 v[184:187], v166 offset:1024
	ds_read_b128 v[188:191], v166 offset:2048
	ds_read_b128 v[192:195], v166 offset:3072
	s_add_u32 s42, s44, 0x80000
	s_addc_u32 s43, s45, 0
	s_add_i32 s1, s84, s56
	s_add_i32 s0, s1, 0x2000
	s_add_u32 s36, s48, 0x80080
	s_addc_u32 s37, s49, 0
	s_add_i32 s46, s88, s56
	s_add_i32 s31, s46, 0x2000
	ds_read_b128 v[196:199], v149
	ds_read_b128 v[200:203], v149 offset:1024
	ds_read_b128 v[222:225], v149 offset:2048
	ds_read_b128 v[226:229], v149 offset:3072
	ds_read_b128 v[230:233], v149 offset:4096
	ds_read_b128 v[234:237], v149 offset:5120
	ds_read_b128 v[238:241], v149 offset:6144
	ds_read_b128 v[242:245], v149 offset:7168
	v_lshl_add_u64 v[166:167], s[100:101], 0, v[138:139]
	s_mov_b32 m0, s61
	v_lshl_add_u64 v[168:169], s[100:101], 0, v[134:135]
	global_load_lds_dwordx4 v[166:167], off
	s_mov_b32 m0, s62
	s_nop 0
	global_load_lds_dwordx4 v[168:169], off
	s_add_i32 m0, s57, 0xc000
	s_nop 0
	global_load_lds_dwordx4 v[146:147], off
	s_mov_b32 m0, s47
	s_nop 0
	global_load_lds_dwordx4 v[144:145], off
	s_waitcnt vmcnt(8)
	s_waitcnt lgkmcnt(0)
	s_setprio 1
	s_barrier
	v_mfma_f32_16x16x32_bf16 v[128:131], v[150:153], v[196:199], v[128:131]
	v_mfma_f32_16x16x32_bf16 v[128:131], v[154:157], v[200:203], v[128:131]
	v_mfma_f32_16x16x32_bf16 v[120:123], v[158:161], v[196:199], v[120:123]
	v_mfma_f32_16x16x32_bf16 v[120:123], v[162:165], v[200:203], v[120:123]
	v_mfma_f32_16x16x32_bf16 v[112:115], v[150:153], v[222:225], v[112:115]
	v_mfma_f32_16x16x32_bf16 v[112:115], v[154:157], v[226:229], v[112:115]
	v_mfma_f32_16x16x32_bf16 v[104:107], v[158:161], v[222:225], v[104:107]
	v_mfma_f32_16x16x32_bf16 v[104:107], v[162:165], v[226:229], v[104:107]
	v_mfma_f32_16x16x32_bf16 v[94:97], v[150:153], v[230:233], v[94:97]
	v_mfma_f32_16x16x32_bf16 v[94:97], v[154:157], v[234:237], v[94:97]
	v_mfma_f32_16x16x32_bf16 v[86:89], v[158:161], v[230:233], v[86:89]
	v_mfma_f32_16x16x32_bf16 v[86:89], v[162:165], v[234:237], v[86:89]
	v_mfma_f32_16x16x32_bf16 v[78:81], v[150:153], v[238:241], v[78:81]
	v_mfma_f32_16x16x32_bf16 v[78:81], v[154:157], v[242:245], v[78:81]
	v_mfma_f32_16x16x32_bf16 v[70:73], v[158:161], v[238:241], v[70:73]
	v_mfma_f32_16x16x32_bf16 v[70:73], v[162:165], v[242:245], v[70:73]
	s_setprio 0
	s_setprio 1
	v_mfma_f32_16x16x32_bf16 v[124:127], v[180:183], v[196:199], v[124:127]
	v_mfma_f32_16x16x32_bf16 v[124:127], v[184:187], v[200:203], v[124:127]
	v_mfma_f32_16x16x32_bf16 v[116:119], v[188:191], v[196:199], v[116:119]
	v_mfma_f32_16x16x32_bf16 v[116:119], v[192:195], v[200:203], v[116:119]
	v_mfma_f32_16x16x32_bf16 v[108:111], v[180:183], v[222:225], v[108:111]
	v_mfma_f32_16x16x32_bf16 v[108:111], v[184:187], v[226:229], v[108:111]
	v_mfma_f32_16x16x32_bf16 v[100:103], v[188:191], v[222:225], v[100:103]
	v_mfma_f32_16x16x32_bf16 v[100:103], v[192:195], v[226:229], v[100:103]
	v_mfma_f32_16x16x32_bf16 v[90:93], v[180:183], v[230:233], v[90:93]
	v_mfma_f32_16x16x32_bf16 v[90:93], v[184:187], v[234:237], v[90:93]
	v_mfma_f32_16x16x32_bf16 v[82:85], v[188:191], v[230:233], v[82:85]
	v_mfma_f32_16x16x32_bf16 v[82:85], v[192:195], v[234:237], v[82:85]
	v_mfma_f32_16x16x32_bf16 v[74:77], v[180:183], v[238:241], v[74:77]
	v_mfma_f32_16x16x32_bf16 v[74:77], v[184:187], v[242:245], v[74:77]
	s_setprio 2
	s_barrier
	v_mfma_f32_16x16x32_bf16 v[66:69], v[188:191], v[238:241], v[66:69]
	v_mfma_f32_16x16x32_bf16 v[66:69], v[192:195], v[242:245], v[66:69]
	s_setprio 0
	s_mov_b32 m0, s78
	v_lshl_add_u64 v[166:167], s[48:49], 0, v[136:137]
	ds_read_b128 v[196:199], v149 offset:16384
	ds_read_b128 v[200:203], v149 offset:17408
	ds_read_b128 v[222:225], v149 offset:18432
	ds_read_b128 v[226:229], v149 offset:19456
	ds_read_b128 v[230:233], v149 offset:20480
	ds_read_b128 v[234:237], v149 offset:21504
	ds_read_b128 v[238:241], v149 offset:22528
	ds_read_b128 v[242:245], v149 offset:23552
	global_load_lds_dwordx4 v[166:167], off
	v_lshl_add_u64 v[168:169], s[48:49], 0, v[132:133]
	s_mov_b32 m0, s81
	v_lshl_add_u64 v[172:173], s[50:51], 0, v[136:137]
	global_load_lds_dwordx4 v[168:169], off
	s_mov_b32 m0, s82
	global_load_lds_dwordx4 v[172:173], off
	v_lshl_add_u64 v[172:173], s[50:51], 0, v[132:133]
	s_mov_b32 m0, s83
	s_nop 0
	global_load_lds_dwordx4 v[172:173], off
	s_waitcnt vmcnt(6)
	s_waitcnt lgkmcnt(0)
	s_setprio 1
	s_barrier
; #define PG8_STAGE(bufoff, gbase, voff) do { _Pragma("unroll") for (int _i = 0; _i < 2; ++_i) \
;         __builtin_amdgcn_global_load_lds((const unsigned*)((const char*)(gbase) + (voff)[_i]), (PG8_LAS unsigned*)(lds + (bufoff) + ldsw + _i * 8192), 16, 0, AUX_A); } while (0)
; #define PG8_STAGEB(bufoff, gbase, voff) do { _Pragma("unroll") for (int _i = 0; _i < 2; ++_i) \
;         __builtin_amdgcn_global_load_lds((const unsigned*)((const char*)(gbase) + (voff)[_i]), (PG8_LAS unsigned*)(lds + (bufoff) + ldsw + _i * 8192), 16, 0, AUX_B); } while (0)
; #define PG8_LDA(dst, b, h) do { _Pragma("unroll") for (int m = 0; m < 4; ++m) _Pragma("unroll") for (int k = 0; k < 2; ++k) dst[m][k] = *(const PG8_LAS bf16x8*)(lds + PG8_SA(b, h) + aoff + m * 2048 + k * 1024); } while (0)
; #define PG8_LDB(dst, b, h) do { _Pragma("unroll") for (int n = 0; n < 2; ++n) _Pragma("unroll") for (int k = 0; k < 2; ++k) dst[n][k] = *(const PG8_LAS bf16x8*)(lds + PG8_SB(b, h) + boff + n * 2048 + k * 1024); } while (0)
; #define PG8_MMA(ai, bj, At, Bt) do { __builtin_amdgcn_s_setprio(1); _Pragma("unroll") for (int m = 0; m < 4; ++m) _Pragma("unroll") for (int n = 0; n < 2; ++n) _Pragma("unroll") for (int k = 0; k < 2; ++k) \
;         acc[ai][bj][m][n] = __builtin_amdgcn_mfma_f32_16x16x32_bf16(Bt[n][k], At[m][k], acc[ai][bj][m][n], 0, 0, 0); __builtin_amdgcn_s_setprio(0); } while (0)
; template <class Epi, class Sched, bool ALIGN_EPI = false, bool SP2 = false>
; __device__ __forceinline__ void gemm_phase(PG8_LAS unsigned char* lds, const Gemm g, const Sched& S, const Epi& E) {
;     ...
;             if constexpr (SP2) {
;             PG8_LDB(B0, 0, 0); PG8_LDB(B1, 0, 1); PG8_SCHED; PG8_LDA(At, 0, 0); PG8_STAGE(PG8_SA(1, 1), a1 + hstep, voffA);
;             PG8_WAIT_V(8); PG8_WAIT_L(0); PG8_BAR; PG8_MMA(0, 0, At, B0); PG8_MMA(0, 1, At, B1); PG8_BAR; PG8_SCHED;
;             PG8_LDA(At, 0, 1); PG8_STAGEB(PG8_SB(0, 0), b2, voffB); PG8_STAGEB(PG8_SB(0, 1), b2 + hstep, voffB); PG8_STAGE(PG8_SA(0, 0), a2, voffA);
;             PG8_WAIT_V(8); PG8_WAIT_L(0); PG8_BAR; PG8_MMA(1, 0, At, B0); PG8_MMA(1, 1, At, B1); PG8_BAR; PG8_SCHED;
;             PG8_LDB(B0, 1, 0); PG8_LDB(B1, 1, 1); PG8_SCHED; PG8_LDA(At, 1, 0); PG8_STAGE(PG8_SA(0, 1), a2 + hstep, voffA);
;             PG8_WAIT_V(8); PG8_WAIT_L(0); PG8_BAR; PG8_MMA(0, 0, At, B0); PG8_MMA(0, 1, At, B1); PG8_BAR; PG8_SCHED;
	v_mfma_f32_16x16x32_bf16 v[62:65], v[150:153], v[196:199], v[62:65]
	v_mfma_f32_16x16x32_bf16 v[62:65], v[154:157], v[200:203], v[62:65]
	v_mfma_f32_16x16x32_bf16 v[54:57], v[158:161], v[196:199], v[54:57]
	v_mfma_f32_16x16x32_bf16 v[54:57], v[162:165], v[200:203], v[54:57]
	v_mfma_f32_16x16x32_bf16 v[46:49], v[150:153], v[222:225], v[46:49]
	v_mfma_f32_16x16x32_bf16 v[46:49], v[154:157], v[226:229], v[46:49]
	v_mfma_f32_16x16x32_bf16 v[38:41], v[158:161], v[222:225], v[38:41]
	v_mfma_f32_16x16x32_bf16 v[38:41], v[162:165], v[226:229], v[38:41]
	v_mfma_f32_16x16x32_bf16 v[30:33], v[150:153], v[230:233], v[30:33]
	v_mfma_f32_16x16x32_bf16 v[30:33], v[154:157], v[234:237], v[30:33]
	v_mfma_f32_16x16x32_bf16 v[22:25], v[158:161], v[230:233], v[22:25]
	v_mfma_f32_16x16x32_bf16 v[22:25], v[162:165], v[234:237], v[22:25]
	v_mfma_f32_16x16x32_bf16 v[14:17], v[150:153], v[238:241], v[14:17]
	v_mfma_f32_16x16x32_bf16 v[14:17], v[154:157], v[242:245], v[14:17]
	v_mfma_f32_16x16x32_bf16 v[6:9], v[158:161], v[238:241], v[6:9]
	v_mfma_f32_16x16x32_bf16 v[6:9], v[162:165], v[242:245], v[6:9]
	s_setprio 0
	s_setprio 1
	v_mfma_f32_16x16x32_bf16 v[58:61], v[180:183], v[196:199], v[58:61]
	v_mfma_f32_16x16x32_bf16 v[58:61], v[184:187], v[200:203], v[58:61]
	v_mfma_f32_16x16x32_bf16 v[50:53], v[188:191], v[196:199], v[50:53]
	v_mfma_f32_16x16x32_bf16 v[50:53], v[192:195], v[200:203], v[50:53]
	v_mfma_f32_16x16x32_bf16 v[42:45], v[180:183], v[222:225], v[42:45]
	v_mfma_f32_16x16x32_bf16 v[42:45], v[184:187], v[226:229], v[42:45]
	v_mfma_f32_16x16x32_bf16 v[34:37], v[188:191], v[222:225], v[34:37]
	v_mfma_f32_16x16x32_bf16 v[34:37], v[192:195], v[226:229], v[34:37]
	v_mfma_f32_16x16x32_bf16 v[26:29], v[180:183], v[230:233], v[26:29]
	v_mfma_f32_16x16x32_bf16 v[26:29], v[184:187], v[234:237], v[26:29]
	v_mfma_f32_16x16x32_bf16 v[18:21], v[188:191], v[230:233], v[18:21]
	v_mfma_f32_16x16x32_bf16 v[18:21], v[192:195], v[234:237], v[18:21]
	v_mfma_f32_16x16x32_bf16 v[10:13], v[180:183], v[238:241], v[10:13]
	v_mfma_f32_16x16x32_bf16 v[10:13], v[184:187], v[242:245], v[10:13]
	s_setprio 2
	s_barrier
	v_mfma_f32_16x16x32_bf16 v[2:5], v[188:191], v[238:241], v[2:5]
	v_mfma_f32_16x16x32_bf16 v[2:5], v[192:195], v[242:245], v[2:5]
	s_setprio 0
	v_add_u32_e32 v162, s84, v99
	v_add_u32_e32 v192, s88, v99
	ds_read_b128 v[150:153], v162
	ds_read_b128 v[154:157], v162 offset:1024
	ds_read_b128 v[158:161], v162 offset:2048
	ds_read_b128 v[162:165], v162 offset:3072
	ds_read_b128 v[180:183], v192
	ds_read_b128 v[184:187], v192 offset:1024
	ds_read_b128 v[188:191], v192 offset:2048
	ds_read_b128 v[192:195], v192 offset:3072
	s_mov_b32 m0, s59
	v_lshl_add_u64 v[246:247], s[42:43], 0, v[138:139]
	ds_read_b128 v[196:199], v149 offset:32768
	ds_read_b128 v[200:203], v149 offset:33792
	ds_read_b128 v[222:225], v149 offset:34816
	ds_read_b128 v[226:229], v149 offset:35840
	ds_read_b128 v[230:233], v149 offset:36864
	ds_read_b128 v[234:237], v149 offset:37888
	ds_read_b128 v[238:241], v149 offset:38912
	ds_read_b128 v[242:245], v149 offset:39936
	v_lshl_add_u64 v[172:173], s[44:45], 0, v[138:139]
	s_mov_b32 m0, s57
	v_lshl_add_u64 v[212:213], s[44:45], 0, v[134:135]
	global_load_lds_dwordx4 v[172:173], off
	s_mov_b32 m0, s58
	s_nop 0
	global_load_lds_dwordx4 v[212:213], off
	s_mov_b32 m0, s59
	s_nop 0
	global_load_lds_dwordx4 v[246:247], off
	v_lshl_add_u64 v[246:247], s[42:43], 0, v[134:135]
	s_mov_b32 m0, s60
	s_nop 0
	global_load_lds_dwordx4 v[246:247], off
	s_waitcnt vmcnt(8)
	s_waitcnt lgkmcnt(0)
	s_setprio 1
	s_barrier
	v_mfma_f32_16x16x32_bf16 v[128:131], v[150:153], v[196:199], v[128:131]
	v_mfma_f32_16x16x32_bf16 v[128:131], v[154:157], v[200:203], v[128:131]
	v_mfma_f32_16x16x32_bf16 v[120:123], v[158:161], v[196:199], v[120:123]
	v_mfma_f32_16x16x32_bf16 v[120:123], v[162:165], v[200:203], v[120:123]
	v_mfma_f32_16x16x32_bf16 v[112:115], v[150:153], v[222:225], v[112:115]
	v_mfma_f32_16x16x32_bf16 v[112:115], v[154:157], v[226:229], v[112:115]
	v_mfma_f32_16x16x32_bf16 v[104:107], v[158:161], v[222:225], v[104:107]
	v_mfma_f32_16x16x32_bf16 v[104:107], v[162:165], v[226:229], v[104:107]
	v_mfma_f32_16x16x32_bf16 v[94:97], v[150:153], v[230:233], v[94:97]
	v_mfma_f32_16x16x32_bf16 v[94:97], v[154:157], v[234:237], v[94:97]
	v_mfma_f32_16x16x32_bf16 v[86:89], v[158:161], v[230:233], v[86:89]
	v_mfma_f32_16x16x32_bf16 v[86:89], v[162:165], v[234:237], v[86:89]
	v_mfma_f32_16x16x32_bf16 v[78:81], v[150:153], v[238:241], v[78:81]
	v_mfma_f32_16x16x32_bf16 v[78:81], v[154:157], v[242:245], v[78:81]
	v_mfma_f32_16x16x32_bf16 v[70:73], v[158:161], v[238:241], v[70:73]
	v_mfma_f32_16x16x32_bf16 v[70:73], v[162:165], v[242:245], v[70:73]
	s_setprio 0
	s_setprio 1
	v_mfma_f32_16x16x32_bf16 v[124:127], v[180:183], v[196:199], v[124:127]
	v_mfma_f32_16x16x32_bf16 v[124:127], v[184:187], v[200:203], v[124:127]
	v_mfma_f32_16x16x32_bf16 v[116:119], v[188:191], v[196:199], v[116:119]
	v_mfma_f32_16x16x32_bf16 v[116:119], v[192:195], v[200:203], v[116:119]
	v_mfma_f32_16x16x32_bf16 v[108:111], v[180:183], v[222:225], v[108:111]
	v_mfma_f32_16x16x32_bf16 v[108:111], v[184:187], v[226:229], v[108:111]
	v_mfma_f32_16x16x32_bf16 v[100:103], v[188:191], v[222:225], v[100:103]
	v_mfma_f32_16x16x32_bf16 v[100:103], v[192:195], v[226:229], v[100:103]
	v_mfma_f32_16x16x32_bf16 v[90:93], v[180:183], v[230:233], v[90:93]
	v_mfma_f32_16x16x32_bf16 v[90:93], v[184:187], v[234:237], v[90:93]
	v_mfma_f32_16x16x32_bf16 v[82:85], v[188:191], v[230:233], v[82:85]
	v_mfma_f32_16x16x32_bf16 v[82:85], v[192:195], v[234:237], v[82:85]
	v_mfma_f32_16x16x32_bf16 v[74:77], v[180:183], v[238:241], v[74:77]
	v_mfma_f32_16x16x32_bf16 v[74:77], v[184:187], v[242:245], v[74:77]
	s_setprio 2
	s_barrier
; #define PG8_STAGE(bufoff, gbase, voff) do { _Pragma("unroll") for (int _i = 0; _i < 2; ++_i) \
;         __builtin_amdgcn_global_load_lds((const unsigned*)((const char*)(gbase) + (voff)[_i]), (PG8_LAS unsigned*)(lds + (bufoff) + ldsw + _i * 8192), 16, 0, AUX_A); } while (0)
; #define PG8_STAGEB(bufoff, gbase, voff) do { _Pragma("unroll") for (int _i = 0; _i < 2; ++_i) \
;         __builtin_amdgcn_global_load_lds((const unsigned*)((const char*)(gbase) + (voff)[_i]), (PG8_LAS unsigned*)(lds + (bufoff) + ldsw + _i * 8192), 16, 0, AUX_B); } while (0)
; #define PG8_LDA(dst, b, h) do { _Pragma("unroll") for (int m = 0; m < 4; ++m) _Pragma("unroll") for (int k = 0; k < 2; ++k) dst[m][k] = *(const PG8_LAS bf16x8*)(lds + PG8_SA(b, h) + aoff + m * 2048 + k * 1024); } while (0)
; #define PG8_LDB(dst, b, h) do { _Pragma("unroll") for (int n = 0; n < 2; ++n) _Pragma("unroll") for (int k = 0; k < 2; ++k) dst[n][k] = *(const PG8_LAS bf16x8*)(lds + PG8_SB(b, h) + boff + n * 2048 + k * 1024); } while (0)
; #define PG8_MMA(ai, bj, At, Bt) do { __builtin_amdgcn_s_setprio(1); _Pragma("unroll") for (int m = 0; m < 4; ++m) _Pragma("unroll") for (int n = 0; n < 2; ++n) _Pragma("unroll") for (int k = 0; k < 2; ++k) \
;         acc[ai][bj][m][n] = __builtin_amdgcn_mfma_f32_16x16x32_bf16(Bt[n][k], At[m][k], acc[ai][bj][m][n], 0, 0, 0); __builtin_amdgcn_s_setprio(0); } while (0)
; #define PG8_WAIT_V(n) asm volatile("s_waitcnt vmcnt(" #n ")" ::: "memory")
; #define PG8_WAIT_L(n) asm volatile("s_waitcnt lgkmcnt(" #n ")" ::: "memory")
; #define PG8_BAR __builtin_amdgcn_s_barrier()
; #define PG8_SCHED __builtin_amdgcn_sched_barrier(0)
; template <class Epi, class Sched, bool ALIGN_EPI = false, bool SP2 = false>
; __device__ __forceinline__ void gemm_phase(PG8_LAS unsigned char* lds, const Gemm g, const Sched& S, const Epi& E) {
;     ...
;             PG8_LDB(B0, 1, 0); PG8_LDB(B1, 1, 1); PG8_SCHED; PG8_LDA(At, 1, 0); PG8_STAGE(PG8_SA(0, 1), a2 + hstep, voffA);
;             PG8_WAIT_V(8); PG8_WAIT_L(0); PG8_BAR; PG8_MMA(0, 0, At, B0); PG8_MMA(0, 1, At, B1); PG8_BAR; PG8_SCHED;
;             PG8_LDA(At, 1, 1); PG8_STAGEB(PG8_SB(1, 0), b3, voffB); PG8_STAGEB(PG8_SB(1, 1), b3 + hstep, voffB); PG8_STAGE(PG8_SA(1, 0), a3, voffA);
;             PG8_WAIT_V(8); PG8_WAIT_L(0); PG8_BAR; PG8_MMA(1, 0, At, B0); PG8_MMA(1, 1, At, B1); PG8_BAR; PG8_SCHED;
	v_mfma_f32_16x16x32_bf16 v[66:69], v[188:191], v[238:241], v[66:69]
	v_mfma_f32_16x16x32_bf16 v[66:69], v[192:195], v[242:245], v[66:69]
	s_setprio 0
	s_mov_b32 m0, s1
	v_lshl_add_u64 v[166:167], v[166:167], 0, s[76:77]
	ds_read_b128 v[196:199], v149 offset:49152
	ds_read_b128 v[200:203], v149 offset:50176
	ds_read_b128 v[222:225], v149 offset:51200
	ds_read_b128 v[226:229], v149 offset:52224
	ds_read_b128 v[230:233], v149 offset:53248
	ds_read_b128 v[234:237], v149 offset:54272
	ds_read_b128 v[238:241], v149 offset:55296
	ds_read_b128 v[242:245], v149 offset:56320
	global_load_lds_dwordx4 v[166:167], off
	v_lshl_add_u64 v[166:167], v[168:169], 0, s[76:77]
	s_mov_b32 m0, s0
	s_nop 0
	global_load_lds_dwordx4 v[166:167], off
	v_lshl_add_u64 v[166:167], s[36:37], 0, v[136:137]
	s_mov_b32 m0, s46
	s_nop 0
	global_load_lds_dwordx4 v[166:167], off
	v_lshl_add_u64 v[166:167], s[36:37], 0, v[132:133]
	s_mov_b32 m0, s31
	s_nop 0
	global_load_lds_dwordx4 v[166:167], off
	s_waitcnt vmcnt(6)
	s_waitcnt lgkmcnt(0)
	s_setprio 1
	s_barrier
	v_mfma_f32_16x16x32_bf16 v[62:65], v[150:153], v[196:199], v[62:65]
	v_mfma_f32_16x16x32_bf16 v[62:65], v[154:157], v[200:203], v[62:65]
	v_mfma_f32_16x16x32_bf16 v[54:57], v[158:161], v[196:199], v[54:57]
	v_mfma_f32_16x16x32_bf16 v[54:57], v[162:165], v[200:203], v[54:57]
	v_mfma_f32_16x16x32_bf16 v[46:49], v[150:153], v[222:225], v[46:49]
	v_mfma_f32_16x16x32_bf16 v[46:49], v[154:157], v[226:229], v[46:49]
	v_mfma_f32_16x16x32_bf16 v[38:41], v[158:161], v[222:225], v[38:41]
	v_mfma_f32_16x16x32_bf16 v[38:41], v[162:165], v[226:229], v[38:41]
	v_mfma_f32_16x16x32_bf16 v[30:33], v[150:153], v[230:233], v[30:33]
	v_mfma_f32_16x16x32_bf16 v[30:33], v[154:157], v[234:237], v[30:33]
	v_mfma_f32_16x16x32_bf16 v[22:25], v[158:161], v[230:233], v[22:25]
	v_mfma_f32_16x16x32_bf16 v[22:25], v[162:165], v[234:237], v[22:25]
	v_mfma_f32_16x16x32_bf16 v[14:17], v[150:153], v[238:241], v[14:17]
	v_mfma_f32_16x16x32_bf16 v[14:17], v[154:157], v[242:245], v[14:17]
	v_mfma_f32_16x16x32_bf16 v[6:9], v[158:161], v[238:241], v[6:9]
	v_mfma_f32_16x16x32_bf16 v[6:9], v[162:165], v[242:245], v[6:9]
	s_setprio 0
	s_setprio 1
	v_mfma_f32_16x16x32_bf16 v[58:61], v[180:183], v[196:199], v[58:61]
	v_mfma_f32_16x16x32_bf16 v[58:61], v[184:187], v[200:203], v[58:61]
	v_mfma_f32_16x16x32_bf16 v[50:53], v[188:191], v[196:199], v[50:53]
	v_mfma_f32_16x16x32_bf16 v[50:53], v[192:195], v[200:203], v[50:53]
	v_mfma_f32_16x16x32_bf16 v[42:45], v[180:183], v[222:225], v[42:45]
	v_mfma_f32_16x16x32_bf16 v[42:45], v[184:187], v[226:229], v[42:45]
	v_mfma_f32_16x16x32_bf16 v[34:37], v[188:191], v[222:225], v[34:37]
	v_mfma_f32_16x16x32_bf16 v[34:37], v[192:195], v[226:229], v[34:37]
	v_mfma_f32_16x16x32_bf16 v[26:29], v[180:183], v[230:233], v[26:29]
	v_mfma_f32_16x16x32_bf16 v[26:29], v[184:187], v[234:237], v[26:29]
	v_mfma_f32_16x16x32_bf16 v[18:21], v[188:191], v[230:233], v[18:21]
	v_mfma_f32_16x16x32_bf16 v[18:21], v[192:195], v[234:237], v[18:21]
	v_mfma_f32_16x16x32_bf16 v[10:13], v[180:183], v[238:241], v[10:13]
	v_mfma_f32_16x16x32_bf16 v[10:13], v[184:187], v[242:245], v[10:13]
	s_setprio 2
	s_cmp_gt_u32 s30, 31
	s_cbranch_scc1 .Lq4x_1458l
	s_barrier
.Lq4r_1458l:
	v_mfma_f32_16x16x32_bf16 v[2:5], v[188:191], v[238:241], v[2:5]
	v_mfma_f32_16x16x32_bf16 v[2:5], v[192:195], v[242:245], v[2:5]
	s_setprio 0
	v_lshl_add_u64 v[144:145], v[144:145], 0, s[86:87]
	v_lshl_add_u64 v[146:147], v[146:147], 0, s[86:87]
	s_cmp_gt_u32 s30, 31
	s_mov_b32 s29, s30
	s_cbranch_scc0 .LBB0_1458
	s_branch .Lpx_1458

; #define PG8_STAGE(bufoff, gbase, voff) do { _Pragma("unroll") for (int _i = 0; _i < 2; ++_i) \
;         __builtin_amdgcn_global_load_lds((const unsigned*)((const char*)(gbase) + (voff)[_i]), (PG8_LAS unsigned*)(lds + (bufoff) + ldsw + _i * 8192), 16, 0, AUX_A); } while (0)
; #define PG8_STAGEB(bufoff, gbase, voff) do { _Pragma("unroll") for (int _i = 0; _i < 2; ++_i) \
;         __builtin_amdgcn_global_load_lds((const unsigned*)((const char*)(gbase) + (voff)[_i]), (PG8_LAS unsigned*)(lds + (bufoff) + ldsw + _i * 8192), 16, 0, AUX_B); } while (0)
; #define PG8_LDA(dst, b, h) do { _Pragma("unroll") for (int m = 0; m < 4; ++m) _Pragma("unroll") for (int k = 0; k < 2; ++k) dst[m][k] = *(const PG8_LAS bf16x8*)(lds + PG8_SA(b, h) + aoff + m * 2048 + k * 1024); } while (0)
; #define PG8_LDB(dst, b, h) do { _Pragma("unroll") for (int n = 0; n < 2; ++n) _Pragma("unroll") for (int k = 0; k < 2; ++k) dst[n][k] = *(const PG8_LAS bf16x8*)(lds + PG8_SB(b, h) + boff + n * 2048 + k * 1024); } while (0)
; #define PG8_WAIT_V(n) asm volatile("s_waitcnt vmcnt(" #n ")" ::: "memory")
; #define PG8_WAIT_L(n) asm volatile("s_waitcnt lgkmcnt(" #n ")" ::: "memory")
; #define PG8_BAR __builtin_amdgcn_s_barrier()
; template <class Epi, class Sched, bool ALIGN_EPI = false, bool SP2 = false>
; __device__ __forceinline__ void gemm_phase(PG8_LAS unsigned char* lds, const Gemm g, const Sched& S, const Epi& E) {
;     ...
;         for (int t = 0; t < nt; t += 2) {
;             const bool last = (t == nt - 2);
;             const char* a1 = PG8_KP(cA, t + 1, rot, nt);
;             const char* a2 = last ? nAr : PG8_KP(cA, t + 2, rot, nt); const char* b2 = last ? nBr : PG8_KP(cB, t + 2, rot, nt);
;             const char* a3 = a2 + kstep; const char* b3 = b2 + kstep;
;             if (last && has_next) S.a_ready(nxt);
;             if constexpr (SP2) {
;             PG8_LDB(B0, 0, 0); PG8_LDB(B1, 0, 1); PG8_SCHED; PG8_LDA(At, 0, 0); PG8_STAGE(PG8_SA(1, 1), a1 + hstep, voffA);
;             PG8_WAIT_V(8); PG8_WAIT_L(0); PG8_BAR; PG8_MMA(0, 0, At, B0); PG8_MMA(0, 1, At, B1); PG8_BAR; PG8_SCHED;
;             PG8_LDA(At, 0, 1); PG8_STAGEB(PG8_SB(0, 0), b2, voffB); PG8_STAGEB(PG8_SB(0, 1), b2 + hstep, voffB); PG8_STAGE(PG8_SA(0, 0), a2, voffA);
;             PG8_WAIT_V(8); PG8_WAIT_L(0); PG8_BAR; PG8_MMA(1, 0, At, B0); PG8_MMA(1, 1, At, B1); PG8_BAR; PG8_SCHED;
.Lpk_1654:
	s_or_b32 s0, s15, 1
	s_cmp_ge_i32 s0, s82
	s_cselect_b32 s2, s82, 0
	s_add_i32 s15, s15, 2
	s_cmp_ge_i32 s15, s82
	s_cselect_b32 s0, s82, 0
	s_sub_i32 s0, s83, s0
	s_ashr_i32 s1, s0, 31
	s_lshl_b64 s[0:1], s[0:1], 7
	s_add_u32 s29, s38, s0
	s_addc_u32 s42, s39, s1
	s_add_u32 s0, s34, s0
	s_addc_u32 s1, s35, s1
	s_cmp_eq_u32 s82, s83
	s_cselect_b32 s45, s41, s42
	s_cselect_b32 s44, s40, s29
	s_cselect_b32 s43, s19, s1
	s_cselect_b32 s42, s18, s0
	s_add_i32 s29, 0, 0x10000
	s_add_i32 s46, 0, 0x14000
	v_add_u32_e32 v148, s29, v99
	v_add_u32_e32 v168, s46, v99
	ds_read_b128 v[136:139], v148
	ds_read_b128 v[140:143], v148 offset:1024
	ds_read_b128 v[144:147], v148 offset:2048
	ds_read_b128 v[148:151], v148 offset:3072
	ds_read_b128 v[152:155], v168
	ds_read_b128 v[180:183], v168 offset:1024
	ds_read_b128 v[184:187], v168 offset:2048
	ds_read_b128 v[190:193], v168 offset:3072
	v_mad_i64_i32 v[168:169], s[0:1], s2, v220, v[134:135]
	s_add_i32 m0, s50, 0xc000
	ds_read_b128 v[194:197], v189
	ds_read_b128 v[198:201], v189 offset:1024
	ds_read_b128 v[222:225], v189 offset:2048
	ds_read_b128 v[226:229], v189 offset:3072
	ds_read_b128 v[230:233], v189 offset:4096
	ds_read_b128 v[234:237], v189 offset:5120
	ds_read_b128 v[238:241], v189 offset:6144
	ds_read_b128 v[242:245], v189 offset:7168
	global_load_lds_dwordx4 v[168:169], off
	v_mad_i64_i32 v[168:169], s[0:1], s2, v220, v[132:133]
	s_add_i32 m0, s50, 0xe000
	s_nop 0
	global_load_lds_dwordx4 v[168:169], off
	s_waitcnt vmcnt(8)
	s_waitcnt lgkmcnt(0)
	s_setprio 1
	s_barrier
	v_mfma_f32_16x16x32_bf16 v[128:131], v[136:139], v[194:197], 0
	v_mfma_f32_16x16x32_bf16 v[128:131], v[140:143], v[198:201], v[128:131]
	v_mfma_f32_16x16x32_bf16 v[124:127], v[144:147], v[194:197], 0
	v_mfma_f32_16x16x32_bf16 v[124:127], v[148:151], v[198:201], v[124:127]
	v_mfma_f32_16x16x32_bf16 v[120:123], v[136:139], v[222:225], 0
	v_mfma_f32_16x16x32_bf16 v[120:123], v[140:143], v[226:229], v[120:123]
	v_mfma_f32_16x16x32_bf16 v[112:115], v[144:147], v[222:225], 0
	v_mfma_f32_16x16x32_bf16 v[112:115], v[148:151], v[226:229], v[112:115]
	v_mfma_f32_16x16x32_bf16 v[104:107], v[136:139], v[230:233], 0
	v_mfma_f32_16x16x32_bf16 v[104:107], v[140:143], v[234:237], v[104:107]
	v_mfma_f32_16x16x32_bf16 v[94:97], v[144:147], v[230:233], 0
	v_mfma_f32_16x16x32_bf16 v[94:97], v[148:151], v[234:237], v[94:97]
	v_mfma_f32_16x16x32_bf16 v[86:89], v[136:139], v[238:241], 0
	v_mfma_f32_16x16x32_bf16 v[86:89], v[140:143], v[242:245], v[86:89]
	v_mfma_f32_16x16x32_bf16 v[78:81], v[144:147], v[238:241], 0
	v_mfma_f32_16x16x32_bf16 v[78:81], v[148:151], v[242:245], v[78:81]
	s_setprio 0
	s_setprio 1
	v_mfma_f32_16x16x32_bf16 v[116:119], v[152:155], v[194:197], 0
	v_mfma_f32_16x16x32_bf16 v[116:119], v[180:183], v[198:201], v[116:119]
	v_mfma_f32_16x16x32_bf16 v[108:111], v[184:187], v[194:197], 0
	v_mfma_f32_16x16x32_bf16 v[108:111], v[190:193], v[198:201], v[108:111]
	v_mfma_f32_16x16x32_bf16 v[100:103], v[152:155], v[222:225], 0
	v_mfma_f32_16x16x32_bf16 v[100:103], v[180:183], v[226:229], v[100:103]
	v_mfma_f32_16x16x32_bf16 v[90:93], v[184:187], v[222:225], 0
	v_mfma_f32_16x16x32_bf16 v[90:93], v[190:193], v[226:229], v[90:93]
	v_mfma_f32_16x16x32_bf16 v[82:85], v[152:155], v[230:233], 0
	v_mfma_f32_16x16x32_bf16 v[82:85], v[180:183], v[234:237], v[82:85]
	v_mfma_f32_16x16x32_bf16 v[74:77], v[184:187], v[230:233], 0
	v_mfma_f32_16x16x32_bf16 v[74:77], v[190:193], v[234:237], v[74:77]
	v_mfma_f32_16x16x32_bf16 v[70:73], v[152:155], v[238:241], 0
	v_mfma_f32_16x16x32_bf16 v[70:73], v[180:183], v[242:245], v[70:73]
	s_setprio 2
	s_barrier
	v_mfma_f32_16x16x32_bf16 v[66:69], v[184:187], v[238:241], 0
	v_mfma_f32_16x16x32_bf16 v[66:69], v[190:193], v[242:245], v[66:69]
	s_setprio 0
	s_add_i32 s0, s29, s49
	v_lshl_add_u64 v[168:169], s[42:43], 0, v[160:161]
	s_mov_b32 m0, s0
	ds_read_b128 v[194:197], v189 offset:16384
	ds_read_b128 v[198:201], v189 offset:17408
	ds_read_b128 v[222:225], v189 offset:18432
	ds_read_b128 v[226:229], v189 offset:19456
	ds_read_b128 v[230:233], v189 offset:20480
	ds_read_b128 v[234:237], v189 offset:21504
	ds_read_b128 v[238:241], v189 offset:22528
	ds_read_b128 v[242:245], v189 offset:23552
	global_load_lds_dwordx4 v[168:169], off
	s_add_i32 m0, s0, 0x2000
	s_add_u32 s0, s42, 0x160000
	v_lshl_add_u64 v[172:173], s[42:43], 0, v[156:157]
	s_addc_u32 s1, s43, 0
	s_add_i32 s2, s46, s49
	global_load_lds_dwordx4 v[172:173], off
	v_lshl_add_u64 v[202:203], s[0:1], 0, v[160:161]
	s_mov_b32 m0, s2
	v_lshl_add_u64 v[212:213], s[44:45], 0, v[158:159]
	global_load_lds_dwordx4 v[202:203], off
	v_lshl_add_u64 v[202:203], s[0:1], 0, v[156:157]
	s_add_i32 m0, s2, 0x2000
	s_nop 0
	global_load_lds_dwordx4 v[202:203], off
	v_lshl_add_u64 v[202:203], s[44:45], 0, v[162:163]
	s_mov_b32 m0, s50
	s_nop 0
	global_load_lds_dwordx4 v[202:203], off
	s_mov_b32 m0, s51
	s_nop 0
	global_load_lds_dwordx4 v[212:213], off
	s_waitcnt vmcnt(8)
	s_waitcnt lgkmcnt(0)
	s_setprio 1
	s_barrier
; #define PG8_STAGE(bufoff, gbase, voff) do { _Pragma("unroll") for (int _i = 0; _i < 2; ++_i) \
;         __builtin_amdgcn_global_load_lds((const unsigned*)((const char*)(gbase) + (voff)[_i]), (PG8_LAS unsigned*)(lds + (bufoff) + ldsw + _i * 8192), 16, 0, AUX_A); } while (0)
; #define PG8_LDA(dst, b, h) do { _Pragma("unroll") for (int m = 0; m < 4; ++m) _Pragma("unroll") for (int k = 0; k < 2; ++k) dst[m][k] = *(const PG8_LAS bf16x8*)(lds + PG8_SA(b, h) + aoff + m * 2048 + k * 1024); } while (0)
; #define PG8_LDB(dst, b, h) do { _Pragma("unroll") for (int n = 0; n < 2; ++n) _Pragma("unroll") for (int k = 0; k < 2; ++k) dst[n][k] = *(const PG8_LAS bf16x8*)(lds + PG8_SB(b, h) + boff + n * 2048 + k * 1024); } while (0)
; #define PG8_MMA(ai, bj, At, Bt) do { __builtin_amdgcn_s_setprio(1); _Pragma("unroll") for (int m = 0; m < 4; ++m) _Pragma("unroll") for (int n = 0; n < 2; ++n) _Pragma("unroll") for (int k = 0; k < 2; ++k) \
;         acc[ai][bj][m][n] = __builtin_amdgcn_mfma_f32_16x16x32_bf16(Bt[n][k], At[m][k], acc[ai][bj][m][n], 0, 0, 0); __builtin_amdgcn_s_setprio(0); } while (0)
; #define PG8_WAIT_V(n) asm volatile("s_waitcnt vmcnt(" #n ")" ::: "memory")
; #define PG8_WAIT_L(n) asm volatile("s_waitcnt lgkmcnt(" #n ")" ::: "memory")
; #define PG8_BAR __builtin_amdgcn_s_barrier()
; #define PG8_SCHED __builtin_amdgcn_sched_barrier(0)
; template <class Epi, class Sched, bool ALIGN_EPI = false, bool SP2 = false>
; __device__ __forceinline__ void gemm_phase(PG8_LAS unsigned char* lds, const Gemm g, const Sched& S, const Epi& E) {
;     ...
;             PG8_WAIT_V(8); PG8_WAIT_L(0); PG8_BAR; PG8_MMA(1, 0, At, B0); PG8_MMA(1, 1, At, B1); PG8_BAR; PG8_SCHED;
;             PG8_LDB(B0, 1, 0); PG8_LDB(B1, 1, 1); PG8_SCHED; PG8_LDA(At, 1, 0); PG8_STAGE(PG8_SA(0, 1), a2 + hstep, voffA);
;             PG8_WAIT_V(8); PG8_WAIT_L(0); PG8_BAR; PG8_MMA(0, 0, At, B0); PG8_MMA(0, 1, At, B1); PG8_BAR; PG8_SCHED;
	v_mfma_f32_16x16x32_bf16 v[62:65], v[136:139], v[194:197], 0
	v_mfma_f32_16x16x32_bf16 v[62:65], v[140:143], v[198:201], v[62:65]
	v_mfma_f32_16x16x32_bf16 v[58:61], v[144:147], v[194:197], 0
	v_mfma_f32_16x16x32_bf16 v[58:61], v[148:151], v[198:201], v[58:61]
	v_mfma_f32_16x16x32_bf16 v[54:57], v[136:139], v[222:225], 0
	v_mfma_f32_16x16x32_bf16 v[54:57], v[140:143], v[226:229], v[54:57]
	v_mfma_f32_16x16x32_bf16 v[46:49], v[144:147], v[222:225], 0
	v_mfma_f32_16x16x32_bf16 v[46:49], v[148:151], v[226:229], v[46:49]
	v_mfma_f32_16x16x32_bf16 v[38:41], v[136:139], v[230:233], 0
	v_mfma_f32_16x16x32_bf16 v[38:41], v[140:143], v[234:237], v[38:41]
	v_mfma_f32_16x16x32_bf16 v[30:33], v[144:147], v[230:233], 0
	v_mfma_f32_16x16x32_bf16 v[30:33], v[148:151], v[234:237], v[30:33]
	v_mfma_f32_16x16x32_bf16 v[22:25], v[136:139], v[238:241], 0
	v_mfma_f32_16x16x32_bf16 v[22:25], v[140:143], v[242:245], v[22:25]
	v_mfma_f32_16x16x32_bf16 v[14:17], v[144:147], v[238:241], 0
	v_mfma_f32_16x16x32_bf16 v[14:17], v[148:151], v[242:245], v[14:17]
	s_setprio 0
	s_setprio 1
	v_mfma_f32_16x16x32_bf16 v[50:53], v[152:155], v[194:197], 0
	v_mfma_f32_16x16x32_bf16 v[50:53], v[180:183], v[198:201], v[50:53]
	v_mfma_f32_16x16x32_bf16 v[42:45], v[184:187], v[194:197], 0
	v_mfma_f32_16x16x32_bf16 v[42:45], v[190:193], v[198:201], v[42:45]
	v_mfma_f32_16x16x32_bf16 v[34:37], v[152:155], v[222:225], 0
	v_mfma_f32_16x16x32_bf16 v[34:37], v[180:183], v[226:229], v[34:37]
	v_mfma_f32_16x16x32_bf16 v[26:29], v[184:187], v[222:225], 0
	v_mfma_f32_16x16x32_bf16 v[26:29], v[190:193], v[226:229], v[26:29]
	v_mfma_f32_16x16x32_bf16 v[18:21], v[152:155], v[230:233], 0
	v_mfma_f32_16x16x32_bf16 v[18:21], v[180:183], v[234:237], v[18:21]
	v_mfma_f32_16x16x32_bf16 v[10:13], v[184:187], v[230:233], 0
	v_mfma_f32_16x16x32_bf16 v[10:13], v[190:193], v[234:237], v[10:13]
	v_mfma_f32_16x16x32_bf16 v[6:9], v[152:155], v[238:241], 0
	v_mfma_f32_16x16x32_bf16 v[6:9], v[180:183], v[242:245], v[6:9]
	s_setprio 2
	s_barrier
	v_mfma_f32_16x16x32_bf16 v[2:5], v[184:187], v[238:241], 0
	v_mfma_f32_16x16x32_bf16 v[2:5], v[190:193], v[242:245], v[2:5]
	s_setprio 0
	s_add_i32 s2, 0, 0x18000
	s_add_i32 s29, 0, 0x1c000
	v_add_u32_e32 v148, s2, v99
	v_add_u32_e32 v190, s29, v99
	ds_read_b128 v[136:139], v148
	ds_read_b128 v[140:143], v148 offset:1024
	ds_read_b128 v[144:147], v148 offset:2048
	ds_read_b128 v[148:151], v148 offset:3072
	ds_read_b128 v[152:155], v190
	ds_read_b128 v[180:183], v190 offset:1024
	ds_read_b128 v[184:187], v190 offset:2048
	ds_read_b128 v[190:193], v190 offset:3072
	s_add_u32 s0, s44, 0x160000
	s_addc_u32 s1, s45, 0
	s_mov_b32 m0, s52
	v_lshl_add_u64 v[246:247], s[0:1], 0, v[162:163]
	ds_read_b128 v[194:197], v189 offset:32768
	ds_read_b128 v[198:201], v189 offset:33792
	ds_read_b128 v[222:225], v189 offset:34816
	ds_read_b128 v[226:229], v189 offset:35840
	ds_read_b128 v[230:233], v189 offset:36864
	ds_read_b128 v[234:237], v189 offset:37888
	ds_read_b128 v[238:241], v189 offset:38912
	ds_read_b128 v[242:245], v189 offset:39936
	global_load_lds_dwordx4 v[246:247], off
	v_lshl_add_u64 v[246:247], s[0:1], 0, v[158:159]
	s_mov_b32 m0, s53
	s_nop 0
	global_load_lds_dwordx4 v[246:247], off
	s_waitcnt vmcnt(8)
	s_waitcnt lgkmcnt(0)
	s_setprio 1
	s_barrier
	v_mfma_f32_16x16x32_bf16 v[128:131], v[136:139], v[194:197], v[128:131]
	v_mfma_f32_16x16x32_bf16 v[128:131], v[140:143], v[198:201], v[128:131]
	v_mfma_f32_16x16x32_bf16 v[124:127], v[144:147], v[194:197], v[124:127]
	v_mfma_f32_16x16x32_bf16 v[124:127], v[148:151], v[198:201], v[124:127]
	v_mfma_f32_16x16x32_bf16 v[120:123], v[136:139], v[222:225], v[120:123]
	v_mfma_f32_16x16x32_bf16 v[120:123], v[140:143], v[226:229], v[120:123]
	v_mfma_f32_16x16x32_bf16 v[112:115], v[144:147], v[222:225], v[112:115]
	v_mfma_f32_16x16x32_bf16 v[112:115], v[148:151], v[226:229], v[112:115]
	v_mfma_f32_16x16x32_bf16 v[104:107], v[136:139], v[230:233], v[104:107]
	v_mfma_f32_16x16x32_bf16 v[104:107], v[140:143], v[234:237], v[104:107]
	v_mfma_f32_16x16x32_bf16 v[94:97], v[144:147], v[230:233], v[94:97]
	v_mfma_f32_16x16x32_bf16 v[94:97], v[148:151], v[234:237], v[94:97]
	v_mfma_f32_16x16x32_bf16 v[86:89], v[136:139], v[238:241], v[86:89]
	v_mfma_f32_16x16x32_bf16 v[86:89], v[140:143], v[242:245], v[86:89]
	v_mfma_f32_16x16x32_bf16 v[78:81], v[144:147], v[238:241], v[78:81]
	v_mfma_f32_16x16x32_bf16 v[78:81], v[148:151], v[242:245], v[78:81]
	s_setprio 0
	s_setprio 1
	v_mfma_f32_16x16x32_bf16 v[116:119], v[152:155], v[194:197], v[116:119]
	v_mfma_f32_16x16x32_bf16 v[116:119], v[180:183], v[198:201], v[116:119]
	v_mfma_f32_16x16x32_bf16 v[108:111], v[184:187], v[194:197], v[108:111]
	v_mfma_f32_16x16x32_bf16 v[108:111], v[190:193], v[198:201], v[108:111]
	v_mfma_f32_16x16x32_bf16 v[100:103], v[152:155], v[222:225], v[100:103]
	v_mfma_f32_16x16x32_bf16 v[100:103], v[180:183], v[226:229], v[100:103]
	v_mfma_f32_16x16x32_bf16 v[90:93], v[184:187], v[222:225], v[90:93]
	v_mfma_f32_16x16x32_bf16 v[90:93], v[190:193], v[226:229], v[90:93]
	v_mfma_f32_16x16x32_bf16 v[82:85], v[152:155], v[230:233], v[82:85]
	v_mfma_f32_16x16x32_bf16 v[82:85], v[180:183], v[234:237], v[82:85]
	v_mfma_f32_16x16x32_bf16 v[74:77], v[184:187], v[230:233], v[74:77]
	v_mfma_f32_16x16x32_bf16 v[74:77], v[190:193], v[234:237], v[74:77]
	v_mfma_f32_16x16x32_bf16 v[70:73], v[152:155], v[238:241], v[70:73]
	v_mfma_f32_16x16x32_bf16 v[70:73], v[180:183], v[242:245], v[70:73]
	s_setprio 2
	s_barrier
; #define PG8_STAGE(bufoff, gbase, voff) do { _Pragma("unroll") for (int _i = 0; _i < 2; ++_i) \
;         __builtin_amdgcn_global_load_lds((const unsigned*)((const char*)(gbase) + (voff)[_i]), (PG8_LAS unsigned*)(lds + (bufoff) + ldsw + _i * 8192), 16, 0, AUX_A); } while (0)
; #define PG8_STAGEB(bufoff, gbase, voff) do { _Pragma("unroll") for (int _i = 0; _i < 2; ++_i) \
;         __builtin_amdgcn_global_load_lds((const unsigned*)((const char*)(gbase) + (voff)[_i]), (PG8_LAS unsigned*)(lds + (bufoff) + ldsw + _i * 8192), 16, 0, AUX_B); } while (0)
; #define PG8_LDA(dst, b, h) do { _Pragma("unroll") for (int m = 0; m < 4; ++m) _Pragma("unroll") for (int k = 0; k < 2; ++k) dst[m][k] = *(const PG8_LAS bf16x8*)(lds + PG8_SA(b, h) + aoff + m * 2048 + k * 1024); } while (0)
; #define PG8_MMA(ai, bj, At, Bt) do { __builtin_amdgcn_s_setprio(1); _Pragma("unroll") for (int m = 0; m < 4; ++m) _Pragma("unroll") for (int n = 0; n < 2; ++n) _Pragma("unroll") for (int k = 0; k < 2; ++k) \
;         acc[ai][bj][m][n] = __builtin_amdgcn_mfma_f32_16x16x32_bf16(Bt[n][k], At[m][k], acc[ai][bj][m][n], 0, 0, 0); __builtin_amdgcn_s_setprio(0); } while (0)
; #define PG8_WAIT_V(n) asm volatile("s_waitcnt vmcnt(" #n ")" ::: "memory")
; #define PG8_WAIT_L(n) asm volatile("s_waitcnt lgkmcnt(" #n ")" ::: "memory")
; #define PG8_BAR __builtin_amdgcn_s_barrier()
; #define PG8_SCHED __builtin_amdgcn_sched_barrier(0)
; template <class Epi, class Sched, bool ALIGN_EPI = false, bool SP2 = false>
; __device__ __forceinline__ void gemm_phase(PG8_LAS unsigned char* lds, const Gemm g, const Sched& S, const Epi& E) {
;     ...
;             PG8_LDA(At, 1, 1); PG8_STAGEB(PG8_SB(1, 0), b3, voffB); PG8_STAGEB(PG8_SB(1, 1), b3 + hstep, voffB); PG8_STAGE(PG8_SA(1, 0), a3, voffA);
;             PG8_WAIT_V(8); PG8_WAIT_L(0); PG8_BAR; PG8_MMA(1, 0, At, B0); PG8_MMA(1, 1, At, B1); PG8_BAR; PG8_SCHED;
	v_mfma_f32_16x16x32_bf16 v[66:69], v[184:187], v[238:241], v[66:69]
	v_mfma_f32_16x16x32_bf16 v[66:69], v[190:193], v[242:245], v[66:69]
	s_setprio 0
	s_add_i32 s0, s2, s49
	v_lshl_add_u64 v[168:169], v[168:169], 0, s[76:77]
	s_mov_b32 m0, s0
	ds_read_b128 v[194:197], v189 offset:49152
	ds_read_b128 v[198:201], v189 offset:50176
	ds_read_b128 v[222:225], v189 offset:51200
	ds_read_b128 v[226:229], v189 offset:52224
	ds_read_b128 v[230:233], v189 offset:53248
	ds_read_b128 v[234:237], v189 offset:54272
	ds_read_b128 v[238:241], v189 offset:55296
	ds_read_b128 v[242:245], v189 offset:56320
	global_load_lds_dwordx4 v[168:169], off
	s_add_i32 m0, s0, 0x2000
	s_add_u32 s0, s42, 0x160080
	v_lshl_add_u64 v[168:169], v[172:173], 0, s[76:77]
	s_addc_u32 s1, s43, 0
	s_add_i32 s2, s29, s49
	global_load_lds_dwordx4 v[168:169], off
	v_lshl_add_u64 v[168:169], s[0:1], 0, v[160:161]
	s_mov_b32 m0, s2
	s_nop 0
	global_load_lds_dwordx4 v[168:169], off
	v_lshl_add_u64 v[168:169], s[0:1], 0, v[156:157]
	s_add_i32 m0, s2, 0x2000
	s_nop 0
	global_load_lds_dwordx4 v[168:169], off
	v_lshl_add_u64 v[168:169], v[202:203], 0, s[76:77]
	s_mov_b32 m0, s60
	s_nop 0
	global_load_lds_dwordx4 v[168:169], off
	v_lshl_add_u64 v[168:169], v[212:213], 0, s[76:77]
	s_mov_b32 m0, s61
	s_nop 0
	global_load_lds_dwordx4 v[168:169], off
	s_waitcnt vmcnt(8)
	s_waitcnt lgkmcnt(0)
	s_setprio 1
	s_barrier
	v_mfma_f32_16x16x32_bf16 v[62:65], v[136:139], v[194:197], v[62:65]
	v_mfma_f32_16x16x32_bf16 v[62:65], v[140:143], v[198:201], v[62:65]
	v_mfma_f32_16x16x32_bf16 v[58:61], v[144:147], v[194:197], v[58:61]
	v_mfma_f32_16x16x32_bf16 v[58:61], v[148:151], v[198:201], v[58:61]
	v_mfma_f32_16x16x32_bf16 v[54:57], v[136:139], v[222:225], v[54:57]
	v_mfma_f32_16x16x32_bf16 v[54:57], v[140:143], v[226:229], v[54:57]
	v_mfma_f32_16x16x32_bf16 v[46:49], v[144:147], v[222:225], v[46:49]
	v_mfma_f32_16x16x32_bf16 v[46:49], v[148:151], v[226:229], v[46:49]
	v_mfma_f32_16x16x32_bf16 v[38:41], v[136:139], v[230:233], v[38:41]
	v_mfma_f32_16x16x32_bf16 v[38:41], v[140:143], v[234:237], v[38:41]
	v_mfma_f32_16x16x32_bf16 v[30:33], v[144:147], v[230:233], v[30:33]
	v_mfma_f32_16x16x32_bf16 v[30:33], v[148:151], v[234:237], v[30:33]
	v_mfma_f32_16x16x32_bf16 v[22:25], v[136:139], v[238:241], v[22:25]
	v_mfma_f32_16x16x32_bf16 v[22:25], v[140:143], v[242:245], v[22:25]
	v_mfma_f32_16x16x32_bf16 v[14:17], v[144:147], v[238:241], v[14:17]
	v_mfma_f32_16x16x32_bf16 v[14:17], v[148:151], v[242:245], v[14:17]
	s_setprio 0
	s_setprio 1
	v_mfma_f32_16x16x32_bf16 v[50:53], v[152:155], v[194:197], v[50:53]
	v_mfma_f32_16x16x32_bf16 v[50:53], v[180:183], v[198:201], v[50:53]
	v_mfma_f32_16x16x32_bf16 v[42:45], v[184:187], v[194:197], v[42:45]
	v_mfma_f32_16x16x32_bf16 v[42:45], v[190:193], v[198:201], v[42:45]
	v_mfma_f32_16x16x32_bf16 v[34:37], v[152:155], v[222:225], v[34:37]
	v_mfma_f32_16x16x32_bf16 v[34:37], v[180:183], v[226:229], v[34:37]
	v_mfma_f32_16x16x32_bf16 v[26:29], v[184:187], v[222:225], v[26:29]
	v_mfma_f32_16x16x32_bf16 v[26:29], v[190:193], v[226:229], v[26:29]
	v_mfma_f32_16x16x32_bf16 v[18:21], v[152:155], v[230:233], v[18:21]
	v_mfma_f32_16x16x32_bf16 v[18:21], v[180:183], v[234:237], v[18:21]
	v_mfma_f32_16x16x32_bf16 v[10:13], v[184:187], v[230:233], v[10:13]
	v_mfma_f32_16x16x32_bf16 v[10:13], v[190:193], v[234:237], v[10:13]
	v_mfma_f32_16x16x32_bf16 v[6:9], v[152:155], v[238:241], v[6:9]
	v_mfma_f32_16x16x32_bf16 v[6:9], v[180:183], v[242:245], v[6:9]
	s_setprio 2
	s_cmp_ge_i32 s83, s82
	s_cbranch_scc1 .Lq4x_1654p
	s_barrier

; #define PG8_STAGE(bufoff, gbase, voff) do { _Pragma("unroll") for (int _i = 0; _i < 2; ++_i) \
;         __builtin_amdgcn_global_load_lds((const unsigned*)((const char*)(gbase) + (voff)[_i]), (PG8_LAS unsigned*)(lds + (bufoff) + ldsw + _i * 8192), 16, 0, AUX_A); } while (0)
; #define PG8_STAGEB(bufoff, gbase, voff) do { _Pragma("unroll") for (int _i = 0; _i < 2; ++_i) \
;         __builtin_amdgcn_global_load_lds((const unsigned*)((const char*)(gbase) + (voff)[_i]), (PG8_LAS unsigned*)(lds + (bufoff) + ldsw + _i * 8192), 16, 0, AUX_B); } while (0)
; #define PG8_LDA(dst, b, h) do { _Pragma("unroll") for (int m = 0; m < 4; ++m) _Pragma("unroll") for (int k = 0; k < 2; ++k) dst[m][k] = *(const PG8_LAS bf16x8*)(lds + PG8_SA(b, h) + aoff + m * 2048 + k * 1024); } while (0)
; #define PG8_LDB(dst, b, h) do { _Pragma("unroll") for (int n = 0; n < 2; ++n) _Pragma("unroll") for (int k = 0; k < 2; ++k) dst[n][k] = *(const PG8_LAS bf16x8*)(lds + PG8_SB(b, h) + boff + n * 2048 + k * 1024); } while (0)
; #define PG8_WAIT_V(n) asm volatile("s_waitcnt vmcnt(" #n ")" ::: "memory")
; #define PG8_WAIT_L(n) asm volatile("s_waitcnt lgkmcnt(" #n ")" ::: "memory")
; #define PG8_BAR __builtin_amdgcn_s_barrier()
; template <class Epi, class Sched, bool ALIGN_EPI = false, bool SP2 = false>
; __device__ __forceinline__ void gemm_phase(PG8_LAS unsigned char* lds, const Gemm g, const Sched& S, const Epi& E) {
;     ...
;         for (int t = 0; t < nt; t += 2) {
;             const bool last = (t == nt - 2);
;             const char* a1 = PG8_KP(cA, t + 1, rot, nt);
;             const char* a2 = last ? nAr : PG8_KP(cA, t + 2, rot, nt); const char* b2 = last ? nBr : PG8_KP(cB, t + 2, rot, nt);
;             const char* a3 = a2 + kstep; const char* b3 = b2 + kstep;
;             if (last && has_next) S.a_ready(nxt);
;             if constexpr (SP2) {
;             PG8_LDB(B0, 0, 0); PG8_LDB(B1, 0, 1); PG8_SCHED; PG8_LDA(At, 0, 0); PG8_STAGE(PG8_SA(1, 1), a1 + hstep, voffA);
;             PG8_WAIT_V(8); PG8_WAIT_L(0); PG8_BAR; PG8_MMA(0, 0, At, B0); PG8_MMA(0, 1, At, B1); PG8_BAR; PG8_SCHED;
;             PG8_LDA(At, 0, 1); PG8_STAGEB(PG8_SB(0, 0), b2, voffB); PG8_STAGEB(PG8_SB(0, 1), b2 + hstep, voffB); PG8_STAGE(PG8_SA(0, 0), a2, voffA);
;             PG8_WAIT_V(8); PG8_WAIT_L(0); PG8_BAR; PG8_MMA(1, 0, At, B0); PG8_MMA(1, 1, At, B1); PG8_BAR; PG8_SCHED;
.LBB0_1654:
	s_or_b32 s0, s15, 1
	s_cmp_ge_i32 s0, s82
	s_cselect_b32 s2, s82, 0
	s_add_i32 s15, s15, 2
	s_cmp_ge_i32 s15, s82
	s_cselect_b32 s0, s82, 0
	s_sub_i32 s0, s83, s0
	s_ashr_i32 s1, s0, 31
	s_lshl_b64 s[0:1], s[0:1], 7
	s_add_u32 s29, s38, s0
	s_addc_u32 s42, s39, s1
	s_add_u32 s0, s34, s0
	s_addc_u32 s1, s35, s1
	s_cmp_eq_u32 s82, s83
	s_cselect_b32 s45, s41, s42
	s_cselect_b32 s44, s40, s29
	s_cselect_b32 s43, s19, s1
	s_cselect_b32 s42, s18, s0
	s_add_i32 s29, 0, 0x10000
	s_add_i32 s46, 0, 0x14000
	v_add_u32_e32 v148, s29, v99
	v_add_u32_e32 v168, s46, v99
	ds_read_b128 v[136:139], v148
	ds_read_b128 v[140:143], v148 offset:1024
	ds_read_b128 v[144:147], v148 offset:2048
	ds_read_b128 v[148:151], v148 offset:3072
	ds_read_b128 v[152:155], v168
	ds_read_b128 v[180:183], v168 offset:1024
	ds_read_b128 v[184:187], v168 offset:2048
	ds_read_b128 v[190:193], v168 offset:3072
	v_mad_i64_i32 v[168:169], s[0:1], s2, v220, v[134:135]
	s_add_i32 m0, s50, 0xc000
	ds_read_b128 v[194:197], v189
	ds_read_b128 v[198:201], v189 offset:1024
	ds_read_b128 v[222:225], v189 offset:2048
	ds_read_b128 v[226:229], v189 offset:3072
	ds_read_b128 v[230:233], v189 offset:4096
	ds_read_b128 v[234:237], v189 offset:5120
	ds_read_b128 v[238:241], v189 offset:6144
	ds_read_b128 v[242:245], v189 offset:7168
	global_load_lds_dwordx4 v[168:169], off
	v_mad_i64_i32 v[168:169], s[0:1], s2, v220, v[132:133]
	s_add_i32 m0, s50, 0xe000
	s_nop 0
	global_load_lds_dwordx4 v[168:169], off
	s_waitcnt vmcnt(8)
	s_waitcnt lgkmcnt(0)
	s_setprio 1
	s_barrier
	v_mfma_f32_16x16x32_bf16 v[128:131], v[136:139], v[194:197], v[128:131]
	v_mfma_f32_16x16x32_bf16 v[128:131], v[140:143], v[198:201], v[128:131]
	v_mfma_f32_16x16x32_bf16 v[124:127], v[144:147], v[194:197], v[124:127]
	v_mfma_f32_16x16x32_bf16 v[124:127], v[148:151], v[198:201], v[124:127]
	v_mfma_f32_16x16x32_bf16 v[120:123], v[136:139], v[222:225], v[120:123]
	v_mfma_f32_16x16x32_bf16 v[120:123], v[140:143], v[226:229], v[120:123]
	v_mfma_f32_16x16x32_bf16 v[112:115], v[144:147], v[222:225], v[112:115]
	v_mfma_f32_16x16x32_bf16 v[112:115], v[148:151], v[226:229], v[112:115]
	v_mfma_f32_16x16x32_bf16 v[104:107], v[136:139], v[230:233], v[104:107]
	v_mfma_f32_16x16x32_bf16 v[104:107], v[140:143], v[234:237], v[104:107]
	v_mfma_f32_16x16x32_bf16 v[94:97], v[144:147], v[230:233], v[94:97]
	v_mfma_f32_16x16x32_bf16 v[94:97], v[148:151], v[234:237], v[94:97]
	v_mfma_f32_16x16x32_bf16 v[86:89], v[136:139], v[238:241], v[86:89]
	v_mfma_f32_16x16x32_bf16 v[86:89], v[140:143], v[242:245], v[86:89]
	v_mfma_f32_16x16x32_bf16 v[78:81], v[144:147], v[238:241], v[78:81]
	v_mfma_f32_16x16x32_bf16 v[78:81], v[148:151], v[242:245], v[78:81]
	s_setprio 0
	s_setprio 1
	v_mfma_f32_16x16x32_bf16 v[116:119], v[152:155], v[194:197], v[116:119]
	v_mfma_f32_16x16x32_bf16 v[116:119], v[180:183], v[198:201], v[116:119]
	v_mfma_f32_16x16x32_bf16 v[108:111], v[184:187], v[194:197], v[108:111]
	v_mfma_f32_16x16x32_bf16 v[108:111], v[190:193], v[198:201], v[108:111]
	v_mfma_f32_16x16x32_bf16 v[100:103], v[152:155], v[222:225], v[100:103]
	v_mfma_f32_16x16x32_bf16 v[100:103], v[180:183], v[226:229], v[100:103]
	v_mfma_f32_16x16x32_bf16 v[90:93], v[184:187], v[222:225], v[90:93]
	v_mfma_f32_16x16x32_bf16 v[90:93], v[190:193], v[226:229], v[90:93]
	v_mfma_f32_16x16x32_bf16 v[82:85], v[152:155], v[230:233], v[82:85]
	v_mfma_f32_16x16x32_bf16 v[82:85], v[180:183], v[234:237], v[82:85]
	v_mfma_f32_16x16x32_bf16 v[74:77], v[184:187], v[230:233], v[74:77]
	v_mfma_f32_16x16x32_bf16 v[74:77], v[190:193], v[234:237], v[74:77]
	v_mfma_f32_16x16x32_bf16 v[70:73], v[152:155], v[238:241], v[70:73]
	v_mfma_f32_16x16x32_bf16 v[70:73], v[180:183], v[242:245], v[70:73]
	s_setprio 2
	s_barrier
	v_mfma_f32_16x16x32_bf16 v[66:69], v[184:187], v[238:241], v[66:69]
	v_mfma_f32_16x16x32_bf16 v[66:69], v[190:193], v[242:245], v[66:69]
	s_setprio 0
	s_add_i32 s0, s29, s49
	v_lshl_add_u64 v[168:169], s[42:43], 0, v[160:161]
	s_mov_b32 m0, s0
	ds_read_b128 v[194:197], v189 offset:16384
	ds_read_b128 v[198:201], v189 offset:17408
	ds_read_b128 v[222:225], v189 offset:18432
	ds_read_b128 v[226:229], v189 offset:19456
	ds_read_b128 v[230:233], v189 offset:20480
	ds_read_b128 v[234:237], v189 offset:21504
	ds_read_b128 v[238:241], v189 offset:22528
	ds_read_b128 v[242:245], v189 offset:23552
	global_load_lds_dwordx4 v[168:169], off
	s_add_i32 m0, s0, 0x2000
	s_add_u32 s0, s42, 0x160000
	v_lshl_add_u64 v[172:173], s[42:43], 0, v[156:157]
	s_addc_u32 s1, s43, 0
	s_add_i32 s2, s46, s49
	global_load_lds_dwordx4 v[172:173], off
	v_lshl_add_u64 v[202:203], s[0:1], 0, v[160:161]
	s_mov_b32 m0, s2
	v_lshl_add_u64 v[212:213], s[44:45], 0, v[158:159]
	global_load_lds_dwordx4 v[202:203], off
	v_lshl_add_u64 v[202:203], s[0:1], 0, v[156:157]
	s_add_i32 m0, s2, 0x2000
	s_nop 0
	global_load_lds_dwordx4 v[202:203], off
	v_lshl_add_u64 v[202:203], s[44:45], 0, v[162:163]
	s_mov_b32 m0, s50
	s_nop 0
	global_load_lds_dwordx4 v[202:203], off
	s_mov_b32 m0, s51
	s_nop 0
	global_load_lds_dwordx4 v[212:213], off
	s_waitcnt vmcnt(8)
	s_waitcnt lgkmcnt(0)
	s_setprio 1
	s_barrier
; #define PG8_STAGE(bufoff, gbase, voff) do { _Pragma("unroll") for (int _i = 0; _i < 2; ++_i) \
;         __builtin_amdgcn_global_load_lds((const unsigned*)((const char*)(gbase) + (voff)[_i]), (PG8_LAS unsigned*)(lds + (bufoff) + ldsw + _i * 8192), 16, 0, AUX_A); } while (0)
; #define PG8_LDA(dst, b, h) do { _Pragma("unroll") for (int m = 0; m < 4; ++m) _Pragma("unroll") for (int k = 0; k < 2; ++k) dst[m][k] = *(const PG8_LAS bf16x8*)(lds + PG8_SA(b, h) + aoff + m * 2048 + k * 1024); } while (0)
; #define PG8_LDB(dst, b, h) do { _Pragma("unroll") for (int n = 0; n < 2; ++n) _Pragma("unroll") for (int k = 0; k < 2; ++k) dst[n][k] = *(const PG8_LAS bf16x8*)(lds + PG8_SB(b, h) + boff + n * 2048 + k * 1024); } while (0)
; #define PG8_MMA(ai, bj, At, Bt) do { __builtin_amdgcn_s_setprio(1); _Pragma("unroll") for (int m = 0; m < 4; ++m) _Pragma("unroll") for (int n = 0; n < 2; ++n) _Pragma("unroll") for (int k = 0; k < 2; ++k) \
;         acc[ai][bj][m][n] = __builtin_amdgcn_mfma_f32_16x16x32_bf16(Bt[n][k], At[m][k], acc[ai][bj][m][n], 0, 0, 0); __builtin_amdgcn_s_setprio(0); } while (0)
; #define PG8_WAIT_V(n) asm volatile("s_waitcnt vmcnt(" #n ")" ::: "memory")
; #define PG8_WAIT_L(n) asm volatile("s_waitcnt lgkmcnt(" #n ")" ::: "memory")
; #define PG8_BAR __builtin_amdgcn_s_barrier()
; #define PG8_SCHED __builtin_amdgcn_sched_barrier(0)
; template <class Epi, class Sched, bool ALIGN_EPI = false, bool SP2 = false>
; __device__ __forceinline__ void gemm_phase(PG8_LAS unsigned char* lds, const Gemm g, const Sched& S, const Epi& E) {
;     ...
;             PG8_WAIT_V(8); PG8_WAIT_L(0); PG8_BAR; PG8_MMA(1, 0, At, B0); PG8_MMA(1, 1, At, B1); PG8_BAR; PG8_SCHED;
;             PG8_LDB(B0, 1, 0); PG8_LDB(B1, 1, 1); PG8_SCHED; PG8_LDA(At, 1, 0); PG8_STAGE(PG8_SA(0, 1), a2 + hstep, voffA);
;             PG8_WAIT_V(8); PG8_WAIT_L(0); PG8_BAR; PG8_MMA(0, 0, At, B0); PG8_MMA(0, 1, At, B1); PG8_BAR; PG8_SCHED;
	v_mfma_f32_16x16x32_bf16 v[62:65], v[136:139], v[194:197], v[62:65]
	v_mfma_f32_16x16x32_bf16 v[62:65], v[140:143], v[198:201], v[62:65]
	v_mfma_f32_16x16x32_bf16 v[58:61], v[144:147], v[194:197], v[58:61]
	v_mfma_f32_16x16x32_bf16 v[58:61], v[148:151], v[198:201], v[58:61]
	v_mfma_f32_16x16x32_bf16 v[54:57], v[136:139], v[222:225], v[54:57]
	v_mfma_f32_16x16x32_bf16 v[54:57], v[140:143], v[226:229], v[54:57]
	v_mfma_f32_16x16x32_bf16 v[46:49], v[144:147], v[222:225], v[46:49]
	v_mfma_f32_16x16x32_bf16 v[46:49], v[148:151], v[226:229], v[46:49]
	v_mfma_f32_16x16x32_bf16 v[38:41], v[136:139], v[230:233], v[38:41]
	v_mfma_f32_16x16x32_bf16 v[38:41], v[140:143], v[234:237], v[38:41]
	v_mfma_f32_16x16x32_bf16 v[30:33], v[144:147], v[230:233], v[30:33]
	v_mfma_f32_16x16x32_bf16 v[30:33], v[148:151], v[234:237], v[30:33]
	v_mfma_f32_16x16x32_bf16 v[22:25], v[136:139], v[238:241], v[22:25]
	v_mfma_f32_16x16x32_bf16 v[22:25], v[140:143], v[242:245], v[22:25]
	v_mfma_f32_16x16x32_bf16 v[14:17], v[144:147], v[238:241], v[14:17]
	v_mfma_f32_16x16x32_bf16 v[14:17], v[148:151], v[242:245], v[14:17]
	s_setprio 0
	s_setprio 1
	v_mfma_f32_16x16x32_bf16 v[50:53], v[152:155], v[194:197], v[50:53]
	v_mfma_f32_16x16x32_bf16 v[50:53], v[180:183], v[198:201], v[50:53]
	v_mfma_f32_16x16x32_bf16 v[42:45], v[184:187], v[194:197], v[42:45]
	v_mfma_f32_16x16x32_bf16 v[42:45], v[190:193], v[198:201], v[42:45]
	v_mfma_f32_16x16x32_bf16 v[34:37], v[152:155], v[222:225], v[34:37]
	v_mfma_f32_16x16x32_bf16 v[34:37], v[180:183], v[226:229], v[34:37]
	v_mfma_f32_16x16x32_bf16 v[26:29], v[184:187], v[222:225], v[26:29]
	v_mfma_f32_16x16x32_bf16 v[26:29], v[190:193], v[226:229], v[26:29]
	v_mfma_f32_16x16x32_bf16 v[18:21], v[152:155], v[230:233], v[18:21]
	v_mfma_f32_16x16x32_bf16 v[18:21], v[180:183], v[234:237], v[18:21]
	v_mfma_f32_16x16x32_bf16 v[10:13], v[184:187], v[230:233], v[10:13]
	v_mfma_f32_16x16x32_bf16 v[10:13], v[190:193], v[234:237], v[10:13]
	v_mfma_f32_16x16x32_bf16 v[6:9], v[152:155], v[238:241], v[6:9]
	v_mfma_f32_16x16x32_bf16 v[6:9], v[180:183], v[242:245], v[6:9]
	s_setprio 2
	s_barrier
	v_mfma_f32_16x16x32_bf16 v[2:5], v[184:187], v[238:241], v[2:5]
	v_mfma_f32_16x16x32_bf16 v[2:5], v[190:193], v[242:245], v[2:5]
	s_setprio 0
	s_add_i32 s2, 0, 0x18000
	s_add_i32 s29, 0, 0x1c000
	v_add_u32_e32 v148, s2, v99
	v_add_u32_e32 v190, s29, v99
	ds_read_b128 v[136:139], v148
	ds_read_b128 v[140:143], v148 offset:1024
	ds_read_b128 v[144:147], v148 offset:2048
	ds_read_b128 v[148:151], v148 offset:3072
	ds_read_b128 v[152:155], v190
	ds_read_b128 v[180:183], v190 offset:1024
	ds_read_b128 v[184:187], v190 offset:2048
	ds_read_b128 v[190:193], v190 offset:3072
	s_add_u32 s0, s44, 0x160000
	s_addc_u32 s1, s45, 0
	s_mov_b32 m0, s52
	v_lshl_add_u64 v[246:247], s[0:1], 0, v[162:163]
	ds_read_b128 v[194:197], v189 offset:32768
	ds_read_b128 v[198:201], v189 offset:33792
	ds_read_b128 v[222:225], v189 offset:34816
	ds_read_b128 v[226:229], v189 offset:35840
	ds_read_b128 v[230:233], v189 offset:36864
	ds_read_b128 v[234:237], v189 offset:37888
	ds_read_b128 v[238:241], v189 offset:38912
	ds_read_b128 v[242:245], v189 offset:39936
	global_load_lds_dwordx4 v[246:247], off
	v_lshl_add_u64 v[246:247], s[0:1], 0, v[158:159]
	s_mov_b32 m0, s53
	s_nop 0
	global_load_lds_dwordx4 v[246:247], off
	s_waitcnt vmcnt(8)
	s_waitcnt lgkmcnt(0)
	s_setprio 1
	s_barrier
	v_mfma_f32_16x16x32_bf16 v[128:131], v[136:139], v[194:197], v[128:131]
	v_mfma_f32_16x16x32_bf16 v[128:131], v[140:143], v[198:201], v[128:131]
	v_mfma_f32_16x16x32_bf16 v[124:127], v[144:147], v[194:197], v[124:127]
	v_mfma_f32_16x16x32_bf16 v[124:127], v[148:151], v[198:201], v[124:127]
	v_mfma_f32_16x16x32_bf16 v[120:123], v[136:139], v[222:225], v[120:123]
	v_mfma_f32_16x16x32_bf16 v[120:123], v[140:143], v[226:229], v[120:123]
	v_mfma_f32_16x16x32_bf16 v[112:115], v[144:147], v[222:225], v[112:115]
	v_mfma_f32_16x16x32_bf16 v[112:115], v[148:151], v[226:229], v[112:115]
	v_mfma_f32_16x16x32_bf16 v[104:107], v[136:139], v[230:233], v[104:107]
	v_mfma_f32_16x16x32_bf16 v[104:107], v[140:143], v[234:237], v[104:107]
	v_mfma_f32_16x16x32_bf16 v[94:97], v[144:147], v[230:233], v[94:97]
	v_mfma_f32_16x16x32_bf16 v[94:97], v[148:151], v[234:237], v[94:97]
	v_mfma_f32_16x16x32_bf16 v[86:89], v[136:139], v[238:241], v[86:89]
	v_mfma_f32_16x16x32_bf16 v[86:89], v[140:143], v[242:245], v[86:89]
	v_mfma_f32_16x16x32_bf16 v[78:81], v[144:147], v[238:241], v[78:81]
	v_mfma_f32_16x16x32_bf16 v[78:81], v[148:151], v[242:245], v[78:81]
	s_setprio 0
	s_setprio 1
	v_mfma_f32_16x16x32_bf16 v[116:119], v[152:155], v[194:197], v[116:119]
	v_mfma_f32_16x16x32_bf16 v[116:119], v[180:183], v[198:201], v[116:119]
	v_mfma_f32_16x16x32_bf16 v[108:111], v[184:187], v[194:197], v[108:111]
	v_mfma_f32_16x16x32_bf16 v[108:111], v[190:193], v[198:201], v[108:111]
	v_mfma_f32_16x16x32_bf16 v[100:103], v[152:155], v[222:225], v[100:103]
	v_mfma_f32_16x16x32_bf16 v[100:103], v[180:183], v[226:229], v[100:103]
	v_mfma_f32_16x16x32_bf16 v[90:93], v[184:187], v[222:225], v[90:93]
	v_mfma_f32_16x16x32_bf16 v[90:93], v[190:193], v[226:229], v[90:93]
	v_mfma_f32_16x16x32_bf16 v[82:85], v[152:155], v[230:233], v[82:85]
	v_mfma_f32_16x16x32_bf16 v[82:85], v[180:183], v[234:237], v[82:85]
	v_mfma_f32_16x16x32_bf16 v[74:77], v[184:187], v[230:233], v[74:77]
	v_mfma_f32_16x16x32_bf16 v[74:77], v[190:193], v[234:237], v[74:77]
	v_mfma_f32_16x16x32_bf16 v[70:73], v[152:155], v[238:241], v[70:73]
	v_mfma_f32_16x16x32_bf16 v[70:73], v[180:183], v[242:245], v[70:73]
	s_setprio 2
	s_barrier
; #define PG8_STAGE(bufoff, gbase, voff) do { _Pragma("unroll") for (int _i = 0; _i < 2; ++_i) \
;         __builtin_amdgcn_global_load_lds((const unsigned*)((const char*)(gbase) + (voff)[_i]), (PG8_LAS unsigned*)(lds + (bufoff) + ldsw + _i * 8192), 16, 0, AUX_A); } while (0)
; #define PG8_STAGEB(bufoff, gbase, voff) do { _Pragma("unroll") for (int _i = 0; _i < 2; ++_i) \
;         __builtin_amdgcn_global_load_lds((const unsigned*)((const char*)(gbase) + (voff)[_i]), (PG8_LAS unsigned*)(lds + (bufoff) + ldsw + _i * 8192), 16, 0, AUX_B); } while (0)
; #define PG8_LDA(dst, b, h) do { _Pragma("unroll") for (int m = 0; m < 4; ++m) _Pragma("unroll") for (int k = 0; k < 2; ++k) dst[m][k] = *(const PG8_LAS bf16x8*)(lds + PG8_SA(b, h) + aoff + m * 2048 + k * 1024); } while (0)
; #define PG8_MMA(ai, bj, At, Bt) do { __builtin_amdgcn_s_setprio(1); _Pragma("unroll") for (int m = 0; m < 4; ++m) _Pragma("unroll") for (int n = 0; n < 2; ++n) _Pragma("unroll") for (int k = 0; k < 2; ++k) \
;         acc[ai][bj][m][n] = __builtin_amdgcn_mfma_f32_16x16x32_bf16(Bt[n][k], At[m][k], acc[ai][bj][m][n], 0, 0, 0); __builtin_amdgcn_s_setprio(0); } while (0)
; #define PG8_WAIT_V(n) asm volatile("s_waitcnt vmcnt(" #n ")" ::: "memory")
; #define PG8_WAIT_L(n) asm volatile("s_waitcnt lgkmcnt(" #n ")" ::: "memory")
; #define PG8_BAR __builtin_amdgcn_s_barrier()
; #define PG8_SCHED __builtin_amdgcn_sched_barrier(0)
; template <class Epi, class Sched, bool ALIGN_EPI = false, bool SP2 = false>
; __device__ __forceinline__ void gemm_phase(PG8_LAS unsigned char* lds, const Gemm g, const Sched& S, const Epi& E) {
;     ...
;         for (int t = 0; t < nt; t += 2) {
;     ...
;             PG8_LDA(At, 1, 1); PG8_STAGEB(PG8_SB(1, 0), b3, voffB); PG8_STAGEB(PG8_SB(1, 1), b3 + hstep, voffB); PG8_STAGE(PG8_SA(1, 0), a3, voffA);
;             PG8_WAIT_V(8); PG8_WAIT_L(0); PG8_BAR; PG8_MMA(1, 0, At, B0); PG8_MMA(1, 1, At, B1); PG8_BAR; PG8_SCHED;
	v_mfma_f32_16x16x32_bf16 v[66:69], v[184:187], v[238:241], v[66:69]
	v_mfma_f32_16x16x32_bf16 v[66:69], v[190:193], v[242:245], v[66:69]
	s_setprio 0
	s_add_i32 s0, s2, s49
	v_lshl_add_u64 v[168:169], v[168:169], 0, s[76:77]
	s_mov_b32 m0, s0
	ds_read_b128 v[194:197], v189 offset:49152
	ds_read_b128 v[198:201], v189 offset:50176
	ds_read_b128 v[222:225], v189 offset:51200
	ds_read_b128 v[226:229], v189 offset:52224
	ds_read_b128 v[230:233], v189 offset:53248
	ds_read_b128 v[234:237], v189 offset:54272
	ds_read_b128 v[238:241], v189 offset:55296
	ds_read_b128 v[242:245], v189 offset:56320
	global_load_lds_dwordx4 v[168:169], off
	s_add_i32 m0, s0, 0x2000
	s_add_u32 s0, s42, 0x160080
	v_lshl_add_u64 v[168:169], v[172:173], 0, s[76:77]
	s_addc_u32 s1, s43, 0
	s_add_i32 s2, s29, s49
	global_load_lds_dwordx4 v[168:169], off
	v_lshl_add_u64 v[168:169], s[0:1], 0, v[160:161]
	s_mov_b32 m0, s2
	s_nop 0
	global_load_lds_dwordx4 v[168:169], off
	v_lshl_add_u64 v[168:169], s[0:1], 0, v[156:157]
	s_add_i32 m0, s2, 0x2000
	s_nop 0
	global_load_lds_dwordx4 v[168:169], off
	v_lshl_add_u64 v[168:169], v[202:203], 0, s[76:77]
	s_mov_b32 m0, s60
	s_nop 0
	global_load_lds_dwordx4 v[168:169], off
	v_lshl_add_u64 v[168:169], v[212:213], 0, s[76:77]
	s_mov_b32 m0, s61
	s_nop 0
	global_load_lds_dwordx4 v[168:169], off
	s_waitcnt vmcnt(8)
	s_waitcnt lgkmcnt(0)
	s_setprio 1
	s_barrier
	v_mfma_f32_16x16x32_bf16 v[62:65], v[136:139], v[194:197], v[62:65]
	v_mfma_f32_16x16x32_bf16 v[62:65], v[140:143], v[198:201], v[62:65]
	v_mfma_f32_16x16x32_bf16 v[58:61], v[144:147], v[194:197], v[58:61]
	v_mfma_f32_16x16x32_bf16 v[58:61], v[148:151], v[198:201], v[58:61]
	v_mfma_f32_16x16x32_bf16 v[54:57], v[136:139], v[222:225], v[54:57]
	v_mfma_f32_16x16x32_bf16 v[54:57], v[140:143], v[226:229], v[54:57]
	v_mfma_f32_16x16x32_bf16 v[46:49], v[144:147], v[222:225], v[46:49]
	v_mfma_f32_16x16x32_bf16 v[46:49], v[148:151], v[226:229], v[46:49]
	v_mfma_f32_16x16x32_bf16 v[38:41], v[136:139], v[230:233], v[38:41]
	v_mfma_f32_16x16x32_bf16 v[38:41], v[140:143], v[234:237], v[38:41]
	v_mfma_f32_16x16x32_bf16 v[30:33], v[144:147], v[230:233], v[30:33]
	v_mfma_f32_16x16x32_bf16 v[30:33], v[148:151], v[234:237], v[30:33]
	v_mfma_f32_16x16x32_bf16 v[22:25], v[136:139], v[238:241], v[22:25]
	v_mfma_f32_16x16x32_bf16 v[22:25], v[140:143], v[242:245], v[22:25]
	v_mfma_f32_16x16x32_bf16 v[14:17], v[144:147], v[238:241], v[14:17]
	v_mfma_f32_16x16x32_bf16 v[14:17], v[148:151], v[242:245], v[14:17]
	s_setprio 0
	s_setprio 1
	v_mfma_f32_16x16x32_bf16 v[50:53], v[152:155], v[194:197], v[50:53]
	v_mfma_f32_16x16x32_bf16 v[50:53], v[180:183], v[198:201], v[50:53]
	v_mfma_f32_16x16x32_bf16 v[42:45], v[184:187], v[194:197], v[42:45]
	v_mfma_f32_16x16x32_bf16 v[42:45], v[190:193], v[198:201], v[42:45]
	v_mfma_f32_16x16x32_bf16 v[34:37], v[152:155], v[222:225], v[34:37]
	v_mfma_f32_16x16x32_bf16 v[34:37], v[180:183], v[226:229], v[34:37]
	v_mfma_f32_16x16x32_bf16 v[26:29], v[184:187], v[222:225], v[26:29]
	v_mfma_f32_16x16x32_bf16 v[26:29], v[190:193], v[226:229], v[26:29]
	v_mfma_f32_16x16x32_bf16 v[18:21], v[152:155], v[230:233], v[18:21]
	v_mfma_f32_16x16x32_bf16 v[18:21], v[180:183], v[234:237], v[18:21]
	v_mfma_f32_16x16x32_bf16 v[10:13], v[184:187], v[230:233], v[10:13]
	v_mfma_f32_16x16x32_bf16 v[10:13], v[190:193], v[234:237], v[10:13]
	v_mfma_f32_16x16x32_bf16 v[6:9], v[152:155], v[238:241], v[6:9]
	v_mfma_f32_16x16x32_bf16 v[6:9], v[180:183], v[242:245], v[6:9]
	s_setprio 2
	s_cmp_ge_i32 s83, s82
	s_cbranch_scc1 .Lq4x_1654l
	s_barrier
.Lq4r_1654l:
	v_mfma_f32_16x16x32_bf16 v[2:5], v[184:187], v[238:241], v[2:5]
	v_mfma_f32_16x16x32_bf16 v[2:5], v[190:193], v[242:245], v[2:5]
	s_setprio 0
	s_add_i32 s0, s83, 2
	v_lshl_add_u64 v[132:133], v[132:133], 0, s[86:87]
	v_lshl_add_u64 v[134:135], v[134:135], 0, s[86:87]
	s_cmp_ge_i32 s83, s82
	s_mov_b32 s83, s0
	s_cbranch_scc0 .LBB0_1654
	s_branch .Lpx_1654
